# v050 plus fused residual epilogues of P9/P12/P15 software-pipelined (row-group loads two groups ahead into spare registers, counted vmcnt)
# speedup vs baseline: 1.0063x; 1.0006x over previous
; DI unsigned pk_bf16(float lo, float hi) { f32x2 v = {lo, hi}; bf16x2_t b = __builtin_convertvector(v, bf16x2_t); return __builtin_bit_cast(unsigned, b); }
; DI float bflo(unsigned w) { return __uint_as_float(w << 16); }
; DI float bfhi(unsigned w) { return __uint_as_float(w & 0xffff0000u); }
;     __device__ __forceinline__ void fused(f32x4 (&acc)[2][2][4][2], const pg8::Unit& u, int wr, int wc, int fr, int fq, PG8_LAS unsigned char* lds, int wid, int lane) const {
;     ...
;         const int colb = u.pn * 256 + wc * 32 + 8 * fq;
;         f32x4 gv[2][2];
; #pragma unroll
;         for (int bj = 0; bj < 2; ++bj)
; #pragma unroll
;             for (int n = 0; n < 2; ++n) gv[bj][n] = *(const f32x4*)(gA + colb + bj * 128 + 4 * n);
; #pragma unroll
;         for (int ai = 0; ai < 2; ++ai)
; #pragma unroll
;             for (int m = 0; m < 4; ++m) {
;                 const int rl = ai * 128 + wr * 64 + m * 16 + fr; const size_t row = (size_t)u.pm * 256 + rl;
;                 const float rm = 1.f / sqrtf(__hip_atomic_load(ssqm + row, __ATOMIC_RELAXED, __HIP_MEMORY_SCOPE_AGENT) * (1.f / DM) + RMS_EPS);
;                 float sh = 0.f;
; #pragma unroll
;                 for (int bj = 0; bj < 2; ++bj) {
;                     const size_t off = row * DM + colb + bj * 128;
;                     f32x4 h0, h1;
;                     if (IN16) { const u32x4 hw = *(const u32x4*)((const bf16_t*)hin + off); h0 = (f32x4){bflo(hw.x), bfhi(hw.x), bflo(hw.y), bfhi(hw.y)}; h1 = (f32x4){bflo(hw.z), bfhi(hw.z), bflo(hw.w), bfhi(hw.w)}; }
;                     else { h0 = *(const f32x4*)((const float*)hin + off); h1 = *(const f32x4*)((const float*)hin + off + 4); }
;                     h0 = h0 + acc[ai][bj][m][0] * rm * gv[bj][0]; h1 = h1 + acc[ai][bj][m][1] * rm * gv[bj][1];
;                     sh += ((h0[0] * h0[0] + h0[1] * h0[1]) + (h0[2] * h0[2] + h0[3] * h0[3])) + ((h1[0] * h1[0] + h1[1] * h1[1]) + (h1[2] * h1[2] + h1[3] * h1[3]));
;                     if (OUT16) { u32x4 w; w.x = pk_bf16(h0[0], h0[1]); w.y = pk_bf16(h0[2], h0[3]); w.z = pk_bf16(h1[0], h1[1]); w.w = pk_bf16(h1[2], h1[3]); *(u32x4*)((bf16_t*)hout + off) = w; }
;                     else { *(f32x4*)((float*)hout + off) = h0; *(f32x4*)((float*)hout + off + 4) = h1; }
;                 }
;                 if (ssqh) { sh += __shfl_xor(sh, 16); sh += __shfl_xor(sh, 32); if (fq == 0) red[rl * 4 + wc] = sh; }
.LBB0_1147:
	s_or_b64 exec, exec, s[0:1]
	s_lshl_b32 s0, s37, 5
	s_lshl_b32 s1, s33, 8
	s_or_b32 s0, s1, s0
	v_mov_b32_e32 v159, 0
	v_or_b32_e32 v156, s0, v160
	s_lshl_b64 s[18:19], s[16:17], 8
	v_mov_b32_e32 v153, v159
	v_ashrrev_i32_e32 v157, 31, v156
	v_lshl_add_u64 v[168:169], s[18:19], 0, v[152:153]
	v_lshl_add_u64 v[108:109], v[156:157], 2, s[14:15]
	v_lshl_add_u64 v[170:171], v[168:169], 2, s[12:13]
	s_barrier
	global_load_dwordx4 v[100:103], v[108:109], off offset:16
	global_load_dwordx4 v[104:107], v[108:109], off
	global_load_dwordx4 v[96:99], v[108:109], off offset:528
	s_nop 0
	global_load_dwordx4 v[108:111], v[108:109], off offset:512
	v_lshlrev_b64 v[168:169], 11, v[168:169]
	v_or_b32_e32 v254, 0, v152
	v_mov_b32_e32 v255, 0
	v_lshl_add_u64 v[254:255], s[18:19], 0, v[254:255]
	v_lshlrev_b64 v[240:241], 11, v[254:255]
	v_lshl_add_u64 v[240:241], s[10:11], 0, v[240:241]
	v_lshl_add_u64 v[240:241], v[156:157], 1, v[240:241]
	v_lshl_add_u64 v[254:255], v[254:255], 2, s[12:13]
	global_load_dword v252, v[254:255], off sc1
	global_load_dwordx4 v[234:237], v[240:241], off
	global_load_dwordx4 v[238:241], v[240:241], off offset:256
	v_or_b32_e32 v254, 16, v152
	v_mov_b32_e32 v255, 0
	v_lshl_add_u64 v[254:255], s[18:19], 0, v[254:255]
	v_lshlrev_b64 v[248:249], 11, v[254:255]
	v_lshl_add_u64 v[248:249], s[10:11], 0, v[248:249]
	v_lshl_add_u64 v[248:249], v[156:157], 1, v[248:249]
	v_lshl_add_u64 v[254:255], v[254:255], 2, s[12:13]
	global_load_dword v253, v[254:255], off sc1
	global_load_dwordx4 v[242:245], v[248:249], off
	global_load_dwordx4 v[246:249], v[248:249], off offset:256
	s_nop 0
	v_lshl_add_u64 v[168:169], s[10:11], 0, v[168:169]
	v_lshl_add_u64 v[176:177], v[156:157], 1, v[168:169]
	s_nop 0
	s_nop 0
	v_mov_b32_e32 v153, 0x358637bd
	s_mov_b32 s2, 0xf800000
	v_mov_b32_e32 v151, 0x260
	s_waitcnt vmcnt(3)
	v_fmamk_f32 v158, v252, 0x3a800000, v153
	v_mul_f32_e32 v184, 0x4f800000, v158
	v_cmp_gt_f32_e32 vcc, s2, v158
	v_lshlrev_b32_e32 v178, 16, v234
	v_and_b32_e32 v179, 0xffff0000, v234
	v_cndmask_b32_e32 v158, v158, v184, vcc
	v_sqrt_f32_e32 v186, v158
	v_lshlrev_b32_e32 v168, 16, v235
	v_and_b32_e32 v169, 0xffff0000, v235
	v_lshlrev_b32_e32 v180, 16, v236
	v_add_u32_e32 v187, -1, v186
	v_add_u32_e32 v188, 1, v186
	v_fma_f32 v189, -v187, v186, v158
	v_fma_f32 v190, -v188, v186, v158
	v_cmp_ge_f32_e64 s[0:1], 0, v189
	v_and_b32_e32 v181, 0xffff0000, v236
	v_lshlrev_b32_e32 v170, 16, v237
	v_cndmask_b32_e64 v186, v186, v187, s[0:1]
	v_cmp_lt_f32_e64 s[0:1], 0, v190
	v_and_b32_e32 v171, 0xffff0000, v237
	v_lshlrev_b32_e32 v182, 16, v238
	v_cndmask_b32_e64 v186, v186, v188, s[0:1]
	v_mul_f32_e32 v187, 0x37800000, v186
	v_cndmask_b32_e32 v186, v186, v187, vcc
	v_cmp_class_f32_e32 vcc, v158, v151
	v_and_b32_e32 v183, 0xffff0000, v238
	v_lshlrev_b32_e32 v172, 16, v239
	v_cndmask_b32_e32 v158, v186, v158, vcc
	v_div_scale_f32 v186, s[0:1], v158, v158, 1.0
	v_rcp_f32_e32 v187, v186
	v_div_scale_f32 v188, vcc, 1.0, v158, 1.0
	v_and_b32_e32 v173, 0xffff0000, v239
	v_fma_f32 v189, -v186, v187, 1.0
	v_fmac_f32_e32 v187, v189, v187
	v_mul_f32_e32 v189, v188, v187
	v_fma_f32 v190, -v186, v189, v188
	v_fmac_f32_e32 v189, v190, v187
	v_fma_f32 v186, -v186, v189, v188
	v_div_fmas_f32 v186, v186, v187, v189
	v_div_fixup_f32 v158, v186, v158, 1.0
	v_lshlrev_b32_e32 v184, 16, v240
	v_and_b32_e32 v185, 0xffff0000, v240
	v_lshlrev_b32_e32 v174, 16, v241
	v_and_b32_e32 v175, 0xffff0000, v241
	v_or_b32_e32 v254, 32, v152
	v_mov_b32_e32 v255, 0
	v_lshl_add_u64 v[254:255], s[18:19], 0, v[254:255]
	v_lshlrev_b64 v[240:241], 11, v[254:255]
	v_lshl_add_u64 v[240:241], s[10:11], 0, v[240:241]
	v_lshl_add_u64 v[240:241], v[156:157], 1, v[240:241]
	v_lshl_add_u64 v[254:255], v[254:255], 2, s[12:13]
	global_load_dword v252, v[254:255], off sc1
	global_load_dwordx4 v[234:237], v[240:241], off
	global_load_dwordx4 v[238:241], v[240:241], off offset:256
	v_pk_mul_f32 v[140:141], v[140:141], v[158:159] op_sel_hi:[1,0]
	v_pk_mul_f32 v[142:143], v[142:143], v[158:159] op_sel_hi:[1,0]
	v_pk_mul_f32 v[136:137], v[136:137], v[158:159] op_sel_hi:[1,0]
	v_pk_mul_f32 v[138:139], v[138:139], v[158:159] op_sel_hi:[1,0]
	v_pk_mul_f32 v[132:133], v[132:133], v[158:159] op_sel_hi:[1,0]
	v_pk_mul_f32 v[134:135], v[134:135], v[158:159] op_sel_hi:[1,0]
	v_pk_mul_f32 v[128:129], v[128:129], v[158:159] op_sel_hi:[1,0]
	v_pk_mul_f32 v[130:131], v[130:131], v[158:159] op_sel_hi:[1,0]
	v_pk_fma_f32 v[142:143], v[106:107], v[142:143], v[168:169]
	v_pk_fma_f32 v[140:141], v[104:105], v[140:141], v[178:179]
	v_pk_fma_f32 v[138:139], v[102:103], v[138:139], v[170:171]
	v_pk_fma_f32 v[136:137], v[100:101], v[136:137], v[180:181]
	v_pk_fma_f32 v[134:135], v[110:111], v[134:135], v[172:173]
	v_pk_fma_f32 v[132:133], v[108:109], v[132:133], v[182:183]
	v_pk_fma_f32 v[168:169], v[98:99], v[130:131], v[174:175]
	v_pk_fma_f32 v[170:171], v[96:97], v[128:129], v[184:185]
	v_cvt_pk_bf16_f32 v128, v140, v141
	v_cvt_pk_bf16_f32 v129, v142, v143
	v_mul_f32_e32 v130, v141, v141
	v_mul_f32_e32 v131, v143, v143
	v_mul_f32_e32 v141, v137, v137
	v_mul_f32_e32 v143, v139, v139
	v_mul_f32_e32 v158, v133, v133
	v_mul_f32_e32 v172, v135, v135
	v_mul_f32_e32 v173, v171, v171
	v_mul_f32_e32 v174, v169, v169
	v_fmac_f32_e32 v130, v140, v140
	v_fmac_f32_e32 v131, v142, v142
	v_fmac_f32_e32 v141, v136, v136
	v_fmac_f32_e32 v143, v138, v138
	v_fmac_f32_e32 v158, v132, v132
	v_fmac_f32_e32 v172, v134, v134
	v_fmac_f32_e32 v173, v170, v170
	v_fmac_f32_e32 v174, v168, v168
	v_add_f32_e32 v130, v130, v131
	v_add_f32_e32 v131, v141, v143
	v_add_f32_e32 v140, v158, v172
	v_add_f32_e32 v141, v173, v174
	v_add_f32_e32 v130, v130, v131
	v_add_f32_e32 v131, v140, v141
	v_add_f32_e32 v140, v130, v131
	ds_bpermute_b32 v141, v145, v140
	v_cvt_pk_bf16_f32 v130, v136, v137
	v_cvt_pk_bf16_f32 v131, v138, v139
	global_store_dwordx4 v[176:177], v[128:131], off
	s_waitcnt lgkmcnt(0)
	s_nop 0
	v_add_f32_e32 v128, v140, v141
	ds_bpermute_b32 v129, v147, v128
	v_cvt_pk_bf16_f32 v130, v132, v133
	v_cvt_pk_bf16_f32 v131, v134, v135
	v_cvt_pk_bf16_f32 v132, v170, v171
	v_cvt_pk_bf16_f32 v133, v168, v169
	global_store_dwordx4 v[176:177], v[130:133], off offset:256
	s_and_saveexec_b64 s[0:1], s[4:5]
	s_cbranch_execz .LBB0_1149
	v_lshl_add_u32 v130, v152, 4, s22
	s_waitcnt lgkmcnt(0)
	v_add_f32_e32 v128, v128, v129
	ds_write_b32 v130, v128
; DI unsigned pk_bf16(float lo, float hi) { f32x2 v = {lo, hi}; bf16x2_t b = __builtin_convertvector(v, bf16x2_t); return __builtin_bit_cast(unsigned, b); }
; DI float bflo(unsigned w) { return __uint_as_float(w << 16); }
; DI float bfhi(unsigned w) { return __uint_as_float(w & 0xffff0000u); }
;     __device__ __forceinline__ void fused(f32x4 (&acc)[2][2][4][2], const pg8::Unit& u, int wr, int wc, int fr, int fq, PG8_LAS unsigned char* lds, int wid, int lane) const {
;     ...
;             for (int m = 0; m < 4; ++m) {
;                 const int rl = ai * 128 + wr * 64 + m * 16 + fr; const size_t row = (size_t)u.pm * 256 + rl;
;                 const float rm = 1.f / sqrtf(__hip_atomic_load(ssqm + row, __ATOMIC_RELAXED, __HIP_MEMORY_SCOPE_AGENT) * (1.f / DM) + RMS_EPS);
;                 float sh = 0.f;
; #pragma unroll
;                 for (int bj = 0; bj < 2; ++bj) {
;                     const size_t off = row * DM + colb + bj * 128;
;                     f32x4 h0, h1;
;                     if (IN16) { const u32x4 hw = *(const u32x4*)((const bf16_t*)hin + off); h0 = (f32x4){bflo(hw.x), bfhi(hw.x), bflo(hw.y), bfhi(hw.y)}; h1 = (f32x4){bflo(hw.z), bfhi(hw.z), bflo(hw.w), bfhi(hw.w)}; }
;                     else { h0 = *(const f32x4*)((const float*)hin + off); h1 = *(const f32x4*)((const float*)hin + off + 4); }
;                     h0 = h0 + acc[ai][bj][m][0] * rm * gv[bj][0]; h1 = h1 + acc[ai][bj][m][1] * rm * gv[bj][1];
;                     sh += ((h0[0] * h0[0] + h0[1] * h0[1]) + (h0[2] * h0[2] + h0[3] * h0[3])) + ((h1[0] * h1[0] + h1[1] * h1[1]) + (h1[2] * h1[2] + h1[3] * h1[3]));
;                     if (OUT16) { u32x4 w; w.x = pk_bf16(h0[0], h0[1]); w.y = pk_bf16(h0[2], h0[3]); w.z = pk_bf16(h1[0], h1[1]); w.w = pk_bf16(h1[2], h1[3]); *(u32x4*)((bf16_t*)hout + off) = w; }
;                     else { *(f32x4*)((float*)hout + off) = h0; *(f32x4*)((float*)hout + off + 4) = h1; }
;                 }
;                 if (ssqh) { sh += __shfl_xor(sh, 16); sh += __shfl_xor(sh, 32); if (fq == 0) red[rl * 4 + wc] = sh; }
.LBB0_1149:
	s_or_b64 exec, exec, s[0:1]
	v_or_b32_e32 v158, 16, v152
	s_waitcnt lgkmcnt(0)
	v_lshl_add_u64 v[128:129], s[18:19], 0, v[158:159]
	v_lshl_add_u64 v[130:131], v[128:129], 2, s[12:13]
	s_nop 0
	v_lshlrev_b64 v[128:129], 11, v[128:129]
	v_lshl_add_u64 v[128:129], s[10:11], 0, v[128:129]
	v_lshl_add_u64 v[136:137], v[156:157], 1, v[128:129]
	s_nop 0
	s_nop 0
	s_waitcnt vmcnt(5)
	v_fmac_f32_e32 v153, 0x3a800000, v253
	v_mul_f32_e32 v138, 0x4f800000, v153
	v_cmp_gt_f32_e32 vcc, s2, v153
	v_and_b32_e32 v139, 0xffff0000, v242
	v_lshlrev_b32_e32 v140, 16, v244
	v_cndmask_b32_e32 v153, v153, v138, vcc
	v_sqrt_f32_e32 v159, v153
	v_lshlrev_b32_e32 v138, 16, v242
	v_lshlrev_b32_e32 v128, 16, v243
	v_and_b32_e32 v129, 0xffff0000, v243
	v_add_u32_e32 v170, -1, v159
	v_add_u32_e32 v171, 1, v159
	v_fma_f32 v172, -v170, v159, v153
	v_fma_f32 v173, -v171, v159, v153
	v_cmp_ge_f32_e64 s[0:1], 0, v172
	v_and_b32_e32 v141, 0xffff0000, v244
	v_lshlrev_b32_e32 v130, 16, v245
	v_cndmask_b32_e64 v159, v159, v170, s[0:1]
	v_cmp_lt_f32_e64 s[0:1], 0, v173
	v_and_b32_e32 v131, 0xffff0000, v245
	v_lshlrev_b32_e32 v142, 16, v246
	v_cndmask_b32_e64 v159, v159, v171, s[0:1]
	v_mul_f32_e32 v170, 0x37800000, v159
	v_cndmask_b32_e32 v159, v159, v170, vcc
	v_cmp_class_f32_e32 vcc, v153, v151
	v_and_b32_e32 v143, 0xffff0000, v246
	v_lshlrev_b32_e32 v132, 16, v247
	v_cndmask_b32_e32 v151, v159, v153, vcc
	v_div_scale_f32 v153, s[0:1], v151, v151, 1.0
	v_rcp_f32_e32 v159, v153
	v_div_scale_f32 v170, vcc, 1.0, v151, 1.0
	v_and_b32_e32 v133, 0xffff0000, v247
	v_fma_f32 v171, -v153, v159, 1.0
	v_fmac_f32_e32 v159, v171, v159
	v_mul_f32_e32 v171, v170, v159
	v_fma_f32 v172, -v153, v171, v170
	v_fmac_f32_e32 v171, v172, v159
	v_fma_f32 v153, -v153, v171, v170
	v_div_fmas_f32 v153, v153, v159, v171
	v_div_fixup_f32 v170, v153, v151, 1.0
	v_lshlrev_b32_e32 v168, 16, v248
	v_and_b32_e32 v169, 0xffff0000, v248
	v_lshlrev_b32_e32 v134, 16, v249
	v_and_b32_e32 v135, 0xffff0000, v249
	v_or_b32_e32 v254, 48, v152
	v_mov_b32_e32 v255, 0
	v_lshl_add_u64 v[254:255], s[18:19], 0, v[254:255]
	v_lshlrev_b64 v[248:249], 11, v[254:255]
	v_lshl_add_u64 v[248:249], s[10:11], 0, v[248:249]
	v_lshl_add_u64 v[248:249], v[156:157], 1, v[248:249]
	v_lshl_add_u64 v[254:255], v[254:255], 2, s[12:13]
	global_load_dword v253, v[254:255], off sc1
	global_load_dwordx4 v[242:245], v[248:249], off
	global_load_dwordx4 v[246:249], v[248:249], off offset:256
	v_pk_mul_f32 v[124:125], v[124:125], v[170:171] op_sel_hi:[1,0]
	v_pk_mul_f32 v[126:127], v[126:127], v[170:171] op_sel_hi:[1,0]
	v_pk_mul_f32 v[120:121], v[120:121], v[170:171] op_sel_hi:[1,0]
	v_pk_mul_f32 v[122:123], v[122:123], v[170:171] op_sel_hi:[1,0]
	v_pk_mul_f32 v[116:117], v[116:117], v[170:171] op_sel_hi:[1,0]
	v_pk_mul_f32 v[118:119], v[118:119], v[170:171] op_sel_hi:[1,0]
	v_pk_mul_f32 v[112:113], v[112:113], v[170:171] op_sel_hi:[1,0]
	v_pk_mul_f32 v[114:115], v[114:115], v[170:171] op_sel_hi:[1,0]
	v_pk_fma_f32 v[126:127], v[106:107], v[126:127], v[128:129]
	v_pk_fma_f32 v[124:125], v[104:105], v[124:125], v[138:139]
	v_pk_fma_f32 v[122:123], v[102:103], v[122:123], v[130:131]
	v_pk_fma_f32 v[120:121], v[100:101], v[120:121], v[140:141]
	v_pk_fma_f32 v[118:119], v[110:111], v[118:119], v[132:133]
	v_pk_fma_f32 v[116:117], v[108:109], v[116:117], v[142:143]
	v_pk_fma_f32 v[128:129], v[98:99], v[114:115], v[134:135]
	v_pk_fma_f32 v[130:131], v[96:97], v[112:113], v[168:169]
	v_cvt_pk_bf16_f32 v112, v124, v125
	v_cvt_pk_bf16_f32 v113, v126, v127
	v_mul_f32_e32 v114, v125, v125
	v_mul_f32_e32 v115, v127, v127
	v_mul_f32_e32 v125, v121, v121
	v_mul_f32_e32 v127, v123, v123
	v_mul_f32_e32 v132, v117, v117
	v_mul_f32_e32 v133, v119, v119
	v_mul_f32_e32 v134, v131, v131
	v_mul_f32_e32 v135, v129, v129
	v_fmac_f32_e32 v114, v124, v124
	v_fmac_f32_e32 v115, v126, v126
	v_fmac_f32_e32 v125, v120, v120
	v_fmac_f32_e32 v127, v122, v122
	v_fmac_f32_e32 v132, v116, v116
	v_fmac_f32_e32 v133, v118, v118
	v_fmac_f32_e32 v134, v130, v130
	v_fmac_f32_e32 v135, v128, v128
	v_add_f32_e32 v114, v114, v115
	v_add_f32_e32 v115, v125, v127
	v_add_f32_e32 v124, v132, v133
	v_add_f32_e32 v125, v134, v135
	v_add_f32_e32 v114, v114, v115
	v_add_f32_e32 v115, v124, v125
	v_add_f32_e32 v124, v114, v115
	ds_bpermute_b32 v125, v145, v124
	v_cvt_pk_bf16_f32 v114, v120, v121
	v_cvt_pk_bf16_f32 v115, v122, v123
	global_store_dwordx4 v[136:137], v[112:115], off
	s_waitcnt lgkmcnt(0)
	s_nop 0
	v_add_f32_e32 v112, v124, v125
	ds_bpermute_b32 v113, v147, v112
	v_cvt_pk_bf16_f32 v114, v116, v117
	v_cvt_pk_bf16_f32 v115, v118, v119
	v_cvt_pk_bf16_f32 v116, v130, v131
	v_cvt_pk_bf16_f32 v117, v128, v129
	global_store_dwordx4 v[136:137], v[114:117], off offset:256
	s_and_saveexec_b64 s[0:1], s[4:5]
	s_cbranch_execz .LBB0_1151
	v_lshl_add_u32 v114, v158, 4, s22
	s_waitcnt lgkmcnt(0)
	v_add_f32_e32 v112, v112, v113
	ds_write_b32 v114, v112
; DI unsigned pk_bf16(float lo, float hi) { f32x2 v = {lo, hi}; bf16x2_t b = __builtin_convertvector(v, bf16x2_t); return __builtin_bit_cast(unsigned, b); }
; DI float bflo(unsigned w) { return __uint_as_float(w << 16); }
; DI float bfhi(unsigned w) { return __uint_as_float(w & 0xffff0000u); }
;     __device__ __forceinline__ void fused(f32x4 (&acc)[2][2][4][2], const pg8::Unit& u, int wr, int wc, int fr, int fq, PG8_LAS unsigned char* lds, int wid, int lane) const {
;     ...
;             for (int m = 0; m < 4; ++m) {
;                 const int rl = ai * 128 + wr * 64 + m * 16 + fr; const size_t row = (size_t)u.pm * 256 + rl;
;                 const float rm = 1.f / sqrtf(__hip_atomic_load(ssqm + row, __ATOMIC_RELAXED, __HIP_MEMORY_SCOPE_AGENT) * (1.f / DM) + RMS_EPS);
;                 float sh = 0.f;
; #pragma unroll
;                 for (int bj = 0; bj < 2; ++bj) {
;                     const size_t off = row * DM + colb + bj * 128;
;                     f32x4 h0, h1;
;                     if (IN16) { const u32x4 hw = *(const u32x4*)((const bf16_t*)hin + off); h0 = (f32x4){bflo(hw.x), bfhi(hw.x), bflo(hw.y), bfhi(hw.y)}; h1 = (f32x4){bflo(hw.z), bfhi(hw.z), bflo(hw.w), bfhi(hw.w)}; }
;                     else { h0 = *(const f32x4*)((const float*)hin + off); h1 = *(const f32x4*)((const float*)hin + off + 4); }
;                     h0 = h0 + acc[ai][bj][m][0] * rm * gv[bj][0]; h1 = h1 + acc[ai][bj][m][1] * rm * gv[bj][1];
;                     sh += ((h0[0] * h0[0] + h0[1] * h0[1]) + (h0[2] * h0[2] + h0[3] * h0[3])) + ((h1[0] * h1[0] + h1[1] * h1[1]) + (h1[2] * h1[2] + h1[3] * h1[3]));
;                     if (OUT16) { u32x4 w; w.x = pk_bf16(h0[0], h0[1]); w.y = pk_bf16(h0[2], h0[3]); w.z = pk_bf16(h1[0], h1[1]); w.w = pk_bf16(h1[2], h1[3]); *(u32x4*)((bf16_t*)hout + off) = w; }
;                     else { *(f32x4*)((float*)hout + off) = h0; *(f32x4*)((float*)hout + off + 4) = h1; }
;                 }
;                 if (ssqh) { sh += __shfl_xor(sh, 16); sh += __shfl_xor(sh, 32); if (fq == 0) red[rl * 4 + wc] = sh; }
.LBB0_1151:
	s_or_b64 exec, exec, s[0:1]
	v_or_b32_e32 v112, 32, v152
	s_waitcnt lgkmcnt(0)
	v_mov_b32_e32 v113, 0
	v_lshl_add_u64 v[114:115], s[18:19], 0, v[112:113]
	v_lshl_add_u64 v[116:117], v[114:115], 2, s[12:13]
	s_nop 0
	v_lshlrev_b64 v[114:115], 11, v[114:115]
	v_lshl_add_u64 v[114:115], s[10:11], 0, v[114:115]
	v_lshl_add_u64 v[124:125], v[156:157], 1, v[114:115]
	s_nop 0
	s_nop 0
	v_mov_b32_e32 v115, 0x358637bd
	v_mov_b32_e32 v114, 0x260
	s_waitcnt vmcnt(7)
	v_fmamk_f32 v126, v252, 0x3a800000, v115
	v_mul_f32_e32 v127, 0x4f800000, v126
	v_cmp_gt_f32_e32 vcc, s2, v126
	v_lshlrev_b32_e32 v128, 16, v236
	v_and_b32_e32 v129, 0xffff0000, v236
	v_cndmask_b32_e32 v134, v126, v127, vcc
	v_sqrt_f32_e32 v135, v134
	v_lshlrev_b32_e32 v126, 16, v234
	v_and_b32_e32 v127, 0xffff0000, v234
	v_lshlrev_b32_e32 v116, 16, v235
	v_add_u32_e32 v136, -1, v135
	v_add_u32_e32 v137, 1, v135
	v_fma_f32 v138, -v136, v135, v134
	v_fma_f32 v139, -v137, v135, v134
	v_cmp_ge_f32_e64 s[0:1], 0, v138
	v_and_b32_e32 v117, 0xffff0000, v235
	v_lshlrev_b32_e32 v118, 16, v237
	v_cndmask_b32_e64 v135, v135, v136, s[0:1]
	v_cmp_lt_f32_e64 s[0:1], 0, v139
	v_and_b32_e32 v119, 0xffff0000, v237
	v_lshlrev_b32_e32 v130, 16, v238
	v_cndmask_b32_e64 v135, v135, v137, s[0:1]
	v_mul_f32_e32 v136, 0x37800000, v135
	v_cndmask_b32_e32 v135, v135, v136, vcc
	v_cmp_class_f32_e32 vcc, v134, v114
	v_and_b32_e32 v131, 0xffff0000, v238
	v_lshlrev_b32_e32 v120, 16, v239
	v_cndmask_b32_e32 v134, v135, v134, vcc
	v_div_scale_f32 v135, s[0:1], v134, v134, 1.0
	v_rcp_f32_e32 v136, v135
	v_div_scale_f32 v137, vcc, 1.0, v134, 1.0
	v_and_b32_e32 v121, 0xffff0000, v239
	v_fma_f32 v138, -v135, v136, 1.0
	v_fmac_f32_e32 v136, v138, v136
	v_mul_f32_e32 v138, v137, v136
	v_fma_f32 v139, -v135, v138, v137
	v_fmac_f32_e32 v138, v139, v136
	v_fma_f32 v135, -v135, v138, v137
	v_div_fmas_f32 v135, v135, v136, v138
	v_div_fixup_f32 v134, v135, v134, 1.0
	v_lshlrev_b32_e32 v132, 16, v240
	v_and_b32_e32 v133, 0xffff0000, v240
	v_lshlrev_b32_e32 v122, 16, v241
	v_and_b32_e32 v123, 0xffff0000, v241
	v_or_b32_e32 v254, 128, v152
	v_mov_b32_e32 v255, 0
	v_lshl_add_u64 v[254:255], s[18:19], 0, v[254:255]
	v_lshlrev_b64 v[240:241], 11, v[254:255]
	v_lshl_add_u64 v[240:241], s[10:11], 0, v[240:241]
	v_lshl_add_u64 v[240:241], v[156:157], 1, v[240:241]
	v_lshl_add_u64 v[254:255], v[254:255], 2, s[12:13]
	global_load_dword v252, v[254:255], off sc1
	global_load_dwordx4 v[234:237], v[240:241], off
	global_load_dwordx4 v[238:241], v[240:241], off offset:256
	v_pk_mul_f32 v[92:93], v[92:93], v[134:135] op_sel_hi:[1,0]
	v_pk_mul_f32 v[94:95], v[94:95], v[134:135] op_sel_hi:[1,0]
	v_pk_mul_f32 v[88:89], v[88:89], v[134:135] op_sel_hi:[1,0]
	v_pk_mul_f32 v[90:91], v[90:91], v[134:135] op_sel_hi:[1,0]
	v_pk_mul_f32 v[84:85], v[84:85], v[134:135] op_sel_hi:[1,0]
	v_pk_mul_f32 v[86:87], v[86:87], v[134:135] op_sel_hi:[1,0]
	v_pk_mul_f32 v[80:81], v[80:81], v[134:135] op_sel_hi:[1,0]
	v_pk_mul_f32 v[82:83], v[82:83], v[134:135] op_sel_hi:[1,0]
	v_pk_fma_f32 v[94:95], v[106:107], v[94:95], v[116:117]
	v_pk_fma_f32 v[92:93], v[104:105], v[92:93], v[126:127]
	v_pk_fma_f32 v[90:91], v[102:103], v[90:91], v[118:119]
	v_pk_fma_f32 v[88:89], v[100:101], v[88:89], v[128:129]
	v_pk_fma_f32 v[86:87], v[110:111], v[86:87], v[120:121]
	v_pk_fma_f32 v[84:85], v[108:109], v[84:85], v[130:131]
	v_pk_fma_f32 v[116:117], v[98:99], v[82:83], v[122:123]
	v_pk_fma_f32 v[118:119], v[96:97], v[80:81], v[132:133]
	v_cvt_pk_bf16_f32 v80, v92, v93
	v_cvt_pk_bf16_f32 v81, v94, v95
	v_mul_f32_e32 v82, v93, v93
	v_mul_f32_e32 v83, v95, v95
	v_mul_f32_e32 v93, v89, v89
	v_mul_f32_e32 v95, v91, v91
	v_mul_f32_e32 v120, v85, v85
	v_mul_f32_e32 v121, v87, v87
	v_mul_f32_e32 v122, v119, v119
	v_mul_f32_e32 v123, v117, v117
	v_fmac_f32_e32 v82, v92, v92
	v_fmac_f32_e32 v83, v94, v94
	v_fmac_f32_e32 v93, v88, v88
	v_fmac_f32_e32 v95, v90, v90
	v_fmac_f32_e32 v120, v84, v84
	v_fmac_f32_e32 v121, v86, v86
	v_fmac_f32_e32 v122, v118, v118
	v_fmac_f32_e32 v123, v116, v116
	v_add_f32_e32 v82, v82, v83
	v_add_f32_e32 v83, v93, v95
	v_add_f32_e32 v92, v120, v121
	v_add_f32_e32 v93, v122, v123
	v_add_f32_e32 v82, v82, v83
	v_add_f32_e32 v83, v92, v93
	v_add_f32_e32 v92, v82, v83
	ds_bpermute_b32 v93, v145, v92
	v_cvt_pk_bf16_f32 v82, v88, v89
	v_cvt_pk_bf16_f32 v83, v90, v91
	global_store_dwordx4 v[124:125], v[80:83], off
	s_waitcnt lgkmcnt(0)
	s_nop 0
	v_add_f32_e32 v80, v92, v93
	ds_bpermute_b32 v81, v147, v80
	v_cvt_pk_bf16_f32 v82, v84, v85
	v_cvt_pk_bf16_f32 v83, v86, v87
	v_cvt_pk_bf16_f32 v84, v118, v119
	v_cvt_pk_bf16_f32 v85, v116, v117
	global_store_dwordx4 v[124:125], v[82:85], off offset:256
	s_and_saveexec_b64 s[0:1], s[4:5]
	s_cbranch_execz .LBB0_1153
	v_lshl_add_u32 v82, v112, 4, s22
	s_waitcnt lgkmcnt(0)
	v_add_f32_e32 v80, v80, v81
	ds_write_b32 v82, v80
; DI unsigned pk_bf16(float lo, float hi) { f32x2 v = {lo, hi}; bf16x2_t b = __builtin_convertvector(v, bf16x2_t); return __builtin_bit_cast(unsigned, b); }
; DI float bflo(unsigned w) { return __uint_as_float(w << 16); }
; DI float bfhi(unsigned w) { return __uint_as_float(w & 0xffff0000u); }
;     __device__ __forceinline__ void fused(f32x4 (&acc)[2][2][4][2], const pg8::Unit& u, int wr, int wc, int fr, int fq, PG8_LAS unsigned char* lds, int wid, int lane) const {
;     ...
;             for (int m = 0; m < 4; ++m) {
;                 const int rl = ai * 128 + wr * 64 + m * 16 + fr; const size_t row = (size_t)u.pm * 256 + rl;
;                 const float rm = 1.f / sqrtf(__hip_atomic_load(ssqm + row, __ATOMIC_RELAXED, __HIP_MEMORY_SCOPE_AGENT) * (1.f / DM) + RMS_EPS);
;                 float sh = 0.f;
; #pragma unroll
;                 for (int bj = 0; bj < 2; ++bj) {
;                     const size_t off = row * DM + colb + bj * 128;
;                     f32x4 h0, h1;
;                     if (IN16) { const u32x4 hw = *(const u32x4*)((const bf16_t*)hin + off); h0 = (f32x4){bflo(hw.x), bfhi(hw.x), bflo(hw.y), bfhi(hw.y)}; h1 = (f32x4){bflo(hw.z), bfhi(hw.z), bflo(hw.w), bfhi(hw.w)}; }
;                     else { h0 = *(const f32x4*)((const float*)hin + off); h1 = *(const f32x4*)((const float*)hin + off + 4); }
;                     h0 = h0 + acc[ai][bj][m][0] * rm * gv[bj][0]; h1 = h1 + acc[ai][bj][m][1] * rm * gv[bj][1];
;                     sh += ((h0[0] * h0[0] + h0[1] * h0[1]) + (h0[2] * h0[2] + h0[3] * h0[3])) + ((h1[0] * h1[0] + h1[1] * h1[1]) + (h1[2] * h1[2] + h1[3] * h1[3]));
;                     if (OUT16) { u32x4 w; w.x = pk_bf16(h0[0], h0[1]); w.y = pk_bf16(h0[2], h0[3]); w.z = pk_bf16(h1[0], h1[1]); w.w = pk_bf16(h1[2], h1[3]); *(u32x4*)((bf16_t*)hout + off) = w; }
;                     else { *(f32x4*)((float*)hout + off) = h0; *(f32x4*)((float*)hout + off + 4) = h1; }
;                 }
;                 if (ssqh) { sh += __shfl_xor(sh, 16); sh += __shfl_xor(sh, 32); if (fq == 0) red[rl * 4 + wc] = sh; }
.LBB0_1153:
	s_or_b64 exec, exec, s[0:1]
	v_or_b32_e32 v112, 48, v152
	s_waitcnt lgkmcnt(0)
	v_lshl_add_u64 v[80:81], s[18:19], 0, v[112:113]
	v_lshl_add_u64 v[82:83], v[80:81], 2, s[12:13]
	s_nop 0
	v_lshlrev_b64 v[80:81], 11, v[80:81]
	v_lshl_add_u64 v[80:81], s[10:11], 0, v[80:81]
	v_lshl_add_u64 v[88:89], v[156:157], 1, v[80:81]
	s_nop 0
	s_nop 0
	s_waitcnt vmcnt(7)
	v_fmac_f32_e32 v115, 0x3a800000, v253
	v_mul_f32_e32 v90, 0x4f800000, v115
	v_cmp_gt_f32_e32 vcc, s2, v115
	v_and_b32_e32 v91, 0xffff0000, v242
	v_lshlrev_b32_e32 v92, 16, v244
	v_cndmask_b32_e32 v113, v115, v90, vcc
	v_sqrt_f32_e32 v115, v113
	v_lshlrev_b32_e32 v90, 16, v242
	v_lshlrev_b32_e32 v80, 16, v243
	v_and_b32_e32 v81, 0xffff0000, v243
	v_add_u32_e32 v118, -1, v115
	v_add_u32_e32 v119, 1, v115
	v_fma_f32 v120, -v118, v115, v113
	v_fma_f32 v121, -v119, v115, v113
	v_cmp_ge_f32_e64 s[0:1], 0, v120
	v_and_b32_e32 v93, 0xffff0000, v244
	v_lshlrev_b32_e32 v82, 16, v245
	v_cndmask_b32_e64 v115, v115, v118, s[0:1]
	v_cmp_lt_f32_e64 s[0:1], 0, v121
	v_and_b32_e32 v83, 0xffff0000, v245
	v_lshlrev_b32_e32 v94, 16, v246
	v_cndmask_b32_e64 v115, v115, v119, s[0:1]
	v_mul_f32_e32 v118, 0x37800000, v115
	v_cndmask_b32_e32 v115, v115, v118, vcc
	v_cmp_class_f32_e32 vcc, v113, v114
	v_and_b32_e32 v95, 0xffff0000, v246
	v_lshlrev_b32_e32 v84, 16, v247
	v_cndmask_b32_e32 v113, v115, v113, vcc
	v_div_scale_f32 v114, s[0:1], v113, v113, 1.0
	v_rcp_f32_e32 v115, v114
	v_div_scale_f32 v118, vcc, 1.0, v113, 1.0
	v_and_b32_e32 v85, 0xffff0000, v247
	v_fma_f32 v119, -v114, v115, 1.0
	v_fmac_f32_e32 v115, v119, v115
	v_mul_f32_e32 v119, v118, v115
	v_fma_f32 v120, -v114, v119, v118
	v_fmac_f32_e32 v119, v120, v115
	v_fma_f32 v114, -v114, v119, v118
	v_div_fmas_f32 v114, v114, v115, v119
	v_div_fixup_f32 v114, v114, v113, 1.0
	v_lshlrev_b32_e32 v116, 16, v248
	v_and_b32_e32 v117, 0xffff0000, v248
	v_lshlrev_b32_e32 v86, 16, v249
	v_and_b32_e32 v87, 0xffff0000, v249
	v_or_b32_e32 v254, 144, v152
	v_mov_b32_e32 v255, 0
	v_lshl_add_u64 v[254:255], s[18:19], 0, v[254:255]
	v_lshlrev_b64 v[248:249], 11, v[254:255]
	v_lshl_add_u64 v[248:249], s[10:11], 0, v[248:249]
	v_lshl_add_u64 v[248:249], v[156:157], 1, v[248:249]
	v_lshl_add_u64 v[254:255], v[254:255], 2, s[12:13]
	global_load_dword v253, v[254:255], off sc1
	global_load_dwordx4 v[242:245], v[248:249], off
	global_load_dwordx4 v[246:249], v[248:249], off offset:256
	v_pk_mul_f32 v[76:77], v[76:77], v[114:115] op_sel_hi:[1,0]
	v_pk_mul_f32 v[78:79], v[78:79], v[114:115] op_sel_hi:[1,0]
	v_pk_mul_f32 v[72:73], v[72:73], v[114:115] op_sel_hi:[1,0]
	v_pk_mul_f32 v[74:75], v[74:75], v[114:115] op_sel_hi:[1,0]
	v_pk_mul_f32 v[68:69], v[68:69], v[114:115] op_sel_hi:[1,0]
	v_pk_mul_f32 v[70:71], v[70:71], v[114:115] op_sel_hi:[1,0]
	v_pk_mul_f32 v[64:65], v[64:65], v[114:115] op_sel_hi:[1,0]
	v_pk_mul_f32 v[66:67], v[66:67], v[114:115] op_sel_hi:[1,0]
	v_pk_fma_f32 v[78:79], v[106:107], v[78:79], v[80:81]
	v_pk_fma_f32 v[76:77], v[104:105], v[76:77], v[90:91]
	v_pk_fma_f32 v[74:75], v[102:103], v[74:75], v[82:83]
	v_pk_fma_f32 v[72:73], v[100:101], v[72:73], v[92:93]
	v_pk_fma_f32 v[70:71], v[110:111], v[70:71], v[84:85]
	v_pk_fma_f32 v[68:69], v[108:109], v[68:69], v[94:95]
	v_pk_fma_f32 v[80:81], v[98:99], v[66:67], v[86:87]
	v_pk_fma_f32 v[82:83], v[96:97], v[64:65], v[116:117]
	v_cvt_pk_bf16_f32 v64, v76, v77
	v_cvt_pk_bf16_f32 v65, v78, v79
	v_mul_f32_e32 v66, v77, v77
	v_mul_f32_e32 v67, v79, v79
	v_mul_f32_e32 v77, v73, v73
	v_mul_f32_e32 v79, v75, v75
	v_mul_f32_e32 v84, v69, v69
	v_mul_f32_e32 v85, v71, v71
	v_mul_f32_e32 v86, v83, v83
	v_mul_f32_e32 v87, v81, v81
	v_fmac_f32_e32 v66, v76, v76
	v_fmac_f32_e32 v67, v78, v78
	v_fmac_f32_e32 v77, v72, v72
	v_fmac_f32_e32 v79, v74, v74
	v_fmac_f32_e32 v84, v68, v68
	v_fmac_f32_e32 v85, v70, v70
	v_fmac_f32_e32 v86, v82, v82
	v_fmac_f32_e32 v87, v80, v80
	v_add_f32_e32 v66, v66, v67
	v_add_f32_e32 v67, v77, v79
	v_add_f32_e32 v76, v84, v85
	v_add_f32_e32 v77, v86, v87
	v_add_f32_e32 v66, v66, v67
	v_add_f32_e32 v67, v76, v77
	v_add_f32_e32 v76, v66, v67
	ds_bpermute_b32 v77, v145, v76
	v_cvt_pk_bf16_f32 v66, v72, v73
	v_cvt_pk_bf16_f32 v67, v74, v75
	global_store_dwordx4 v[88:89], v[64:67], off
	s_waitcnt lgkmcnt(0)
	s_nop 0
	v_add_f32_e32 v64, v76, v77
	ds_bpermute_b32 v65, v147, v64
	v_cvt_pk_bf16_f32 v66, v68, v69
	v_cvt_pk_bf16_f32 v67, v70, v71
	v_cvt_pk_bf16_f32 v68, v82, v83
	v_cvt_pk_bf16_f32 v69, v80, v81
	global_store_dwordx4 v[88:89], v[66:69], off offset:256
	s_and_saveexec_b64 s[0:1], s[4:5]
	s_cbranch_execz .LBB0_1155
	v_lshl_add_u32 v66, v112, 4, s22
	s_waitcnt lgkmcnt(0)
	v_add_f32_e32 v64, v64, v65
	ds_write_b32 v66, v64
; DI unsigned pk_bf16(float lo, float hi) { f32x2 v = {lo, hi}; bf16x2_t b = __builtin_convertvector(v, bf16x2_t); return __builtin_bit_cast(unsigned, b); }
; DI float bflo(unsigned w) { return __uint_as_float(w << 16); }
; DI float bfhi(unsigned w) { return __uint_as_float(w & 0xffff0000u); }
;     __device__ __forceinline__ void fused(f32x4 (&acc)[2][2][4][2], const pg8::Unit& u, int wr, int wc, int fr, int fq, PG8_LAS unsigned char* lds, int wid, int lane) const {
;     ...
;             for (int m = 0; m < 4; ++m) {
;                 const int rl = ai * 128 + wr * 64 + m * 16 + fr; const size_t row = (size_t)u.pm * 256 + rl;
;                 const float rm = 1.f / sqrtf(__hip_atomic_load(ssqm + row, __ATOMIC_RELAXED, __HIP_MEMORY_SCOPE_AGENT) * (1.f / DM) + RMS_EPS);
;                 float sh = 0.f;
; #pragma unroll
;                 for (int bj = 0; bj < 2; ++bj) {
;                     const size_t off = row * DM + colb + bj * 128;
;                     f32x4 h0, h1;
;                     if (IN16) { const u32x4 hw = *(const u32x4*)((const bf16_t*)hin + off); h0 = (f32x4){bflo(hw.x), bfhi(hw.x), bflo(hw.y), bfhi(hw.y)}; h1 = (f32x4){bflo(hw.z), bfhi(hw.z), bflo(hw.w), bfhi(hw.w)}; }
;                     else { h0 = *(const f32x4*)((const float*)hin + off); h1 = *(const f32x4*)((const float*)hin + off + 4); }
;                     h0 = h0 + acc[ai][bj][m][0] * rm * gv[bj][0]; h1 = h1 + acc[ai][bj][m][1] * rm * gv[bj][1];
;                     sh += ((h0[0] * h0[0] + h0[1] * h0[1]) + (h0[2] * h0[2] + h0[3] * h0[3])) + ((h1[0] * h1[0] + h1[1] * h1[1]) + (h1[2] * h1[2] + h1[3] * h1[3]));
;                     if (OUT16) { u32x4 w; w.x = pk_bf16(h0[0], h0[1]); w.y = pk_bf16(h0[2], h0[3]); w.z = pk_bf16(h1[0], h1[1]); w.w = pk_bf16(h1[2], h1[3]); *(u32x4*)((bf16_t*)hout + off) = w; }
;                     else { *(f32x4*)((float*)hout + off) = h0; *(f32x4*)((float*)hout + off + 4) = h1; }
;                 }
;                 if (ssqh) { sh += __shfl_xor(sh, 16); sh += __shfl_xor(sh, 32); if (fq == 0) red[rl * 4 + wc] = sh; }
.LBB0_1155:
	s_or_b64 exec, exec, s[0:1]
	v_add_u32_e32 v64, 0x80, v152
	s_waitcnt lgkmcnt(0)
	v_mov_b32_e32 v65, 0
	v_lshl_add_u64 v[66:67], s[18:19], 0, v[64:65]
	v_lshl_add_u64 v[68:69], v[66:67], 2, s[12:13]
	s_nop 0
	v_lshlrev_b64 v[66:67], 11, v[66:67]
	v_lshl_add_u64 v[66:67], s[10:11], 0, v[66:67]
	v_lshl_add_u64 v[76:77], v[156:157], 1, v[66:67]
	s_nop 0
	s_nop 0
	v_mov_b32_e32 v67, 0x358637bd
	v_mov_b32_e32 v66, 0x260
	s_waitcnt vmcnt(7)
	v_fmamk_f32 v78, v252, 0x3a800000, v67
	v_mul_f32_e32 v79, 0x4f800000, v78
	v_cmp_gt_f32_e32 vcc, s2, v78
	v_lshlrev_b32_e32 v80, 16, v236
	v_and_b32_e32 v81, 0xffff0000, v236
	v_cndmask_b32_e32 v86, v78, v79, vcc
	v_sqrt_f32_e32 v87, v86
	v_lshlrev_b32_e32 v78, 16, v234
	v_and_b32_e32 v79, 0xffff0000, v234
	v_lshlrev_b32_e32 v68, 16, v235
	v_add_u32_e32 v88, -1, v87
	v_add_u32_e32 v89, 1, v87
	v_fma_f32 v90, -v88, v87, v86
	v_fma_f32 v91, -v89, v87, v86
	v_cmp_ge_f32_e64 s[0:1], 0, v90
	v_and_b32_e32 v69, 0xffff0000, v235
	v_lshlrev_b32_e32 v70, 16, v237
	v_cndmask_b32_e64 v87, v87, v88, s[0:1]
	v_cmp_lt_f32_e64 s[0:1], 0, v91
	v_and_b32_e32 v71, 0xffff0000, v237
	v_lshlrev_b32_e32 v82, 16, v238
	v_cndmask_b32_e64 v87, v87, v89, s[0:1]
	v_mul_f32_e32 v88, 0x37800000, v87
	v_cndmask_b32_e32 v87, v87, v88, vcc
	v_cmp_class_f32_e32 vcc, v86, v66
	v_and_b32_e32 v83, 0xffff0000, v238
	v_lshlrev_b32_e32 v72, 16, v239
	v_cndmask_b32_e32 v86, v87, v86, vcc
	v_div_scale_f32 v87, s[0:1], v86, v86, 1.0
	v_rcp_f32_e32 v88, v87
	v_div_scale_f32 v89, vcc, 1.0, v86, 1.0
	v_and_b32_e32 v73, 0xffff0000, v239
	v_fma_f32 v90, -v87, v88, 1.0
	v_fmac_f32_e32 v88, v90, v88
	v_mul_f32_e32 v90, v89, v88
	v_fma_f32 v91, -v87, v90, v89
	v_fmac_f32_e32 v90, v91, v88
	v_fma_f32 v87, -v87, v90, v89
	v_div_fmas_f32 v87, v87, v88, v90
	v_div_fixup_f32 v86, v87, v86, 1.0
	v_lshlrev_b32_e32 v84, 16, v240
	v_and_b32_e32 v85, 0xffff0000, v240
	v_lshlrev_b32_e32 v74, 16, v241
	v_and_b32_e32 v75, 0xffff0000, v241
	v_or_b32_e32 v254, 160, v152
	v_mov_b32_e32 v255, 0
	v_lshl_add_u64 v[254:255], s[18:19], 0, v[254:255]
	v_lshlrev_b64 v[240:241], 11, v[254:255]
	v_lshl_add_u64 v[240:241], s[10:11], 0, v[240:241]
	v_lshl_add_u64 v[240:241], v[156:157], 1, v[240:241]
	v_lshl_add_u64 v[254:255], v[254:255], 2, s[12:13]
	global_load_dword v252, v[254:255], off sc1
	global_load_dwordx4 v[234:237], v[240:241], off
	global_load_dwordx4 v[238:241], v[240:241], off offset:256
	v_pk_mul_f32 v[60:61], v[60:61], v[86:87] op_sel_hi:[1,0]
	v_pk_mul_f32 v[62:63], v[62:63], v[86:87] op_sel_hi:[1,0]
	v_pk_mul_f32 v[56:57], v[56:57], v[86:87] op_sel_hi:[1,0]
	v_pk_mul_f32 v[58:59], v[58:59], v[86:87] op_sel_hi:[1,0]
	v_pk_mul_f32 v[52:53], v[52:53], v[86:87] op_sel_hi:[1,0]
	v_pk_mul_f32 v[54:55], v[54:55], v[86:87] op_sel_hi:[1,0]
	v_pk_mul_f32 v[48:49], v[48:49], v[86:87] op_sel_hi:[1,0]
	v_pk_mul_f32 v[50:51], v[50:51], v[86:87] op_sel_hi:[1,0]
	v_pk_fma_f32 v[62:63], v[106:107], v[62:63], v[68:69]
	v_pk_fma_f32 v[60:61], v[104:105], v[60:61], v[78:79]
	v_pk_fma_f32 v[58:59], v[102:103], v[58:59], v[70:71]
	v_pk_fma_f32 v[56:57], v[100:101], v[56:57], v[80:81]
	v_pk_fma_f32 v[54:55], v[110:111], v[54:55], v[72:73]
	v_pk_fma_f32 v[52:53], v[108:109], v[52:53], v[82:83]
	v_pk_fma_f32 v[68:69], v[98:99], v[50:51], v[74:75]
	v_pk_fma_f32 v[70:71], v[96:97], v[48:49], v[84:85]
	v_cvt_pk_bf16_f32 v48, v60, v61
	v_cvt_pk_bf16_f32 v49, v62, v63
	v_mul_f32_e32 v50, v61, v61
	v_mul_f32_e32 v51, v63, v63
	v_mul_f32_e32 v61, v57, v57
	v_mul_f32_e32 v63, v59, v59
	v_mul_f32_e32 v72, v53, v53
	v_mul_f32_e32 v73, v55, v55
	v_mul_f32_e32 v74, v71, v71
	v_mul_f32_e32 v75, v69, v69
	v_fmac_f32_e32 v50, v60, v60
	v_fmac_f32_e32 v51, v62, v62
	v_fmac_f32_e32 v61, v56, v56
	v_fmac_f32_e32 v63, v58, v58
	v_fmac_f32_e32 v72, v52, v52
	v_fmac_f32_e32 v73, v54, v54
	v_fmac_f32_e32 v74, v70, v70
	v_fmac_f32_e32 v75, v68, v68
	v_add_f32_e32 v50, v50, v51
	v_add_f32_e32 v51, v61, v63
	v_add_f32_e32 v60, v72, v73
	v_add_f32_e32 v61, v74, v75
	v_add_f32_e32 v50, v50, v51
	v_add_f32_e32 v51, v60, v61
	v_add_f32_e32 v60, v50, v51
	ds_bpermute_b32 v61, v145, v60
	v_cvt_pk_bf16_f32 v50, v56, v57
	v_cvt_pk_bf16_f32 v51, v58, v59
	global_store_dwordx4 v[76:77], v[48:51], off
	s_waitcnt lgkmcnt(0)
	s_nop 0
	v_add_f32_e32 v48, v60, v61
	ds_bpermute_b32 v49, v147, v48
	v_cvt_pk_bf16_f32 v50, v52, v53
	v_cvt_pk_bf16_f32 v51, v54, v55
	v_cvt_pk_bf16_f32 v52, v70, v71
	v_cvt_pk_bf16_f32 v53, v68, v69
	global_store_dwordx4 v[76:77], v[50:53], off offset:256
	s_and_saveexec_b64 s[0:1], s[4:5]
	s_cbranch_execz .LBB0_1157
	v_lshl_add_u32 v50, v64, 4, s22
	s_waitcnt lgkmcnt(0)
	v_add_f32_e32 v48, v48, v49
	ds_write_b32 v50, v48
; DI unsigned pk_bf16(float lo, float hi) { f32x2 v = {lo, hi}; bf16x2_t b = __builtin_convertvector(v, bf16x2_t); return __builtin_bit_cast(unsigned, b); }
; DI float bflo(unsigned w) { return __uint_as_float(w << 16); }
; DI float bfhi(unsigned w) { return __uint_as_float(w & 0xffff0000u); }
;     __device__ __forceinline__ void fused(f32x4 (&acc)[2][2][4][2], const pg8::Unit& u, int wr, int wc, int fr, int fq, PG8_LAS unsigned char* lds, int wid, int lane) const {
;     ...
;             for (int m = 0; m < 4; ++m) {
;                 const int rl = ai * 128 + wr * 64 + m * 16 + fr; const size_t row = (size_t)u.pm * 256 + rl;
;                 const float rm = 1.f / sqrtf(__hip_atomic_load(ssqm + row, __ATOMIC_RELAXED, __HIP_MEMORY_SCOPE_AGENT) * (1.f / DM) + RMS_EPS);
;                 float sh = 0.f;
; #pragma unroll
;                 for (int bj = 0; bj < 2; ++bj) {
;                     const size_t off = row * DM + colb + bj * 128;
;                     f32x4 h0, h1;
;                     if (IN16) { const u32x4 hw = *(const u32x4*)((const bf16_t*)hin + off); h0 = (f32x4){bflo(hw.x), bfhi(hw.x), bflo(hw.y), bfhi(hw.y)}; h1 = (f32x4){bflo(hw.z), bfhi(hw.z), bflo(hw.w), bfhi(hw.w)}; }
;                     else { h0 = *(const f32x4*)((const float*)hin + off); h1 = *(const f32x4*)((const float*)hin + off + 4); }
;                     h0 = h0 + acc[ai][bj][m][0] * rm * gv[bj][0]; h1 = h1 + acc[ai][bj][m][1] * rm * gv[bj][1];
;                     sh += ((h0[0] * h0[0] + h0[1] * h0[1]) + (h0[2] * h0[2] + h0[3] * h0[3])) + ((h1[0] * h1[0] + h1[1] * h1[1]) + (h1[2] * h1[2] + h1[3] * h1[3]));
;                     if (OUT16) { u32x4 w; w.x = pk_bf16(h0[0], h0[1]); w.y = pk_bf16(h0[2], h0[3]); w.z = pk_bf16(h1[0], h1[1]); w.w = pk_bf16(h1[2], h1[3]); *(u32x4*)((bf16_t*)hout + off) = w; }
;                     else { *(f32x4*)((float*)hout + off) = h0; *(f32x4*)((float*)hout + off + 4) = h1; }
;                 }
;                 if (ssqh) { sh += __shfl_xor(sh, 16); sh += __shfl_xor(sh, 32); if (fq == 0) red[rl * 4 + wc] = sh; }
.LBB0_1157:
	s_or_b64 exec, exec, s[0:1]
	v_add_u32_e32 v64, 0x90, v152
	s_waitcnt lgkmcnt(0)
	v_lshl_add_u64 v[48:49], s[18:19], 0, v[64:65]
	v_lshl_add_u64 v[50:51], v[48:49], 2, s[12:13]
	s_nop 0
	v_lshlrev_b64 v[48:49], 11, v[48:49]
	v_lshl_add_u64 v[48:49], s[10:11], 0, v[48:49]
	v_lshl_add_u64 v[56:57], v[156:157], 1, v[48:49]
	s_nop 0
	s_nop 0
	s_waitcnt vmcnt(7)
	v_fmac_f32_e32 v67, 0x3a800000, v253
	v_mul_f32_e32 v58, 0x4f800000, v67
	v_cmp_gt_f32_e32 vcc, s2, v67
	v_and_b32_e32 v59, 0xffff0000, v242
	v_lshlrev_b32_e32 v60, 16, v244
	v_cndmask_b32_e32 v65, v67, v58, vcc
	v_sqrt_f32_e32 v67, v65
	v_lshlrev_b32_e32 v58, 16, v242
	v_lshlrev_b32_e32 v48, 16, v243
	v_and_b32_e32 v49, 0xffff0000, v243
	v_add_u32_e32 v70, -1, v67
	v_add_u32_e32 v71, 1, v67
	v_fma_f32 v72, -v70, v67, v65
	v_fma_f32 v73, -v71, v67, v65
	v_cmp_ge_f32_e64 s[0:1], 0, v72
	v_and_b32_e32 v61, 0xffff0000, v244
	v_lshlrev_b32_e32 v50, 16, v245
	v_cndmask_b32_e64 v67, v67, v70, s[0:1]
	v_cmp_lt_f32_e64 s[0:1], 0, v73
	v_and_b32_e32 v51, 0xffff0000, v245
	v_lshlrev_b32_e32 v62, 16, v246
	v_cndmask_b32_e64 v67, v67, v71, s[0:1]
	v_mul_f32_e32 v70, 0x37800000, v67
	v_cndmask_b32_e32 v67, v67, v70, vcc
	v_cmp_class_f32_e32 vcc, v65, v66
	v_and_b32_e32 v63, 0xffff0000, v246
	v_lshlrev_b32_e32 v52, 16, v247
	v_cndmask_b32_e32 v65, v67, v65, vcc
	v_div_scale_f32 v66, s[0:1], v65, v65, 1.0
	v_rcp_f32_e32 v67, v66
	v_div_scale_f32 v70, vcc, 1.0, v65, 1.0
	v_and_b32_e32 v53, 0xffff0000, v247
	v_fma_f32 v71, -v66, v67, 1.0
	v_fmac_f32_e32 v67, v71, v67
	v_mul_f32_e32 v71, v70, v67
	v_fma_f32 v72, -v66, v71, v70
	v_fmac_f32_e32 v71, v72, v67
	v_fma_f32 v66, -v66, v71, v70
	v_div_fmas_f32 v66, v66, v67, v71
	v_div_fixup_f32 v66, v66, v65, 1.0
	v_lshlrev_b32_e32 v68, 16, v248
	v_and_b32_e32 v69, 0xffff0000, v248
	v_lshlrev_b32_e32 v54, 16, v249
	v_and_b32_e32 v55, 0xffff0000, v249
	v_or_b32_e32 v254, 176, v152
	v_mov_b32_e32 v255, 0
	v_lshl_add_u64 v[254:255], s[18:19], 0, v[254:255]
	v_lshlrev_b64 v[248:249], 11, v[254:255]
	v_lshl_add_u64 v[248:249], s[10:11], 0, v[248:249]
	v_lshl_add_u64 v[248:249], v[156:157], 1, v[248:249]
	v_lshl_add_u64 v[254:255], v[254:255], 2, s[12:13]
	global_load_dword v253, v[254:255], off sc1
	global_load_dwordx4 v[242:245], v[248:249], off
	global_load_dwordx4 v[246:249], v[248:249], off offset:256
	v_pk_mul_f32 v[44:45], v[44:45], v[66:67] op_sel_hi:[1,0]
	v_pk_mul_f32 v[46:47], v[46:47], v[66:67] op_sel_hi:[1,0]
	v_pk_mul_f32 v[40:41], v[40:41], v[66:67] op_sel_hi:[1,0]
	v_pk_mul_f32 v[42:43], v[42:43], v[66:67] op_sel_hi:[1,0]
	v_pk_mul_f32 v[36:37], v[36:37], v[66:67] op_sel_hi:[1,0]
	v_pk_mul_f32 v[38:39], v[38:39], v[66:67] op_sel_hi:[1,0]
	v_pk_mul_f32 v[32:33], v[32:33], v[66:67] op_sel_hi:[1,0]
	v_pk_mul_f32 v[34:35], v[34:35], v[66:67] op_sel_hi:[1,0]
	v_pk_fma_f32 v[46:47], v[106:107], v[46:47], v[48:49]
	v_pk_fma_f32 v[44:45], v[104:105], v[44:45], v[58:59]
	v_pk_fma_f32 v[42:43], v[102:103], v[42:43], v[50:51]
	v_pk_fma_f32 v[40:41], v[100:101], v[40:41], v[60:61]
	v_pk_fma_f32 v[38:39], v[110:111], v[38:39], v[52:53]
	v_pk_fma_f32 v[36:37], v[108:109], v[36:37], v[62:63]
	v_pk_fma_f32 v[48:49], v[98:99], v[34:35], v[54:55]
	v_pk_fma_f32 v[50:51], v[96:97], v[32:33], v[68:69]
	v_cvt_pk_bf16_f32 v32, v44, v45
	v_cvt_pk_bf16_f32 v33, v46, v47
	v_mul_f32_e32 v34, v45, v45
	v_mul_f32_e32 v35, v47, v47
	v_mul_f32_e32 v45, v41, v41
	v_mul_f32_e32 v47, v43, v43
	v_mul_f32_e32 v52, v37, v37
	v_mul_f32_e32 v53, v39, v39
	v_mul_f32_e32 v54, v51, v51
	v_mul_f32_e32 v55, v49, v49
	v_fmac_f32_e32 v34, v44, v44
	v_fmac_f32_e32 v35, v46, v46
	v_fmac_f32_e32 v45, v40, v40
	v_fmac_f32_e32 v47, v42, v42
	v_fmac_f32_e32 v52, v36, v36
	v_fmac_f32_e32 v53, v38, v38
	v_fmac_f32_e32 v54, v50, v50
	v_fmac_f32_e32 v55, v48, v48
	v_add_f32_e32 v34, v34, v35
	v_add_f32_e32 v35, v45, v47
	v_add_f32_e32 v44, v52, v53
	v_add_f32_e32 v45, v54, v55
	v_add_f32_e32 v34, v34, v35
	v_add_f32_e32 v35, v44, v45
	v_add_f32_e32 v44, v34, v35
	ds_bpermute_b32 v45, v145, v44
	v_cvt_pk_bf16_f32 v34, v40, v41
	v_cvt_pk_bf16_f32 v35, v42, v43
	global_store_dwordx4 v[56:57], v[32:35], off
	s_waitcnt lgkmcnt(0)
	s_nop 0
	v_add_f32_e32 v32, v44, v45
	ds_bpermute_b32 v33, v147, v32
	v_cvt_pk_bf16_f32 v34, v36, v37
	v_cvt_pk_bf16_f32 v35, v38, v39
	v_cvt_pk_bf16_f32 v36, v50, v51
	v_cvt_pk_bf16_f32 v37, v48, v49
	global_store_dwordx4 v[56:57], v[34:37], off offset:256
	s_and_saveexec_b64 s[0:1], s[4:5]
	s_cbranch_execz .LBB0_1159
	v_lshl_add_u32 v34, v64, 4, s22
	s_waitcnt lgkmcnt(0)
	v_add_f32_e32 v32, v32, v33
	ds_write_b32 v34, v32
; DI unsigned pk_bf16(float lo, float hi) { f32x2 v = {lo, hi}; bf16x2_t b = __builtin_convertvector(v, bf16x2_t); return __builtin_bit_cast(unsigned, b); }
; DI float bflo(unsigned w) { return __uint_as_float(w << 16); }
; DI float bfhi(unsigned w) { return __uint_as_float(w & 0xffff0000u); }
;     __device__ __forceinline__ void fused(f32x4 (&acc)[2][2][4][2], const pg8::Unit& u, int wr, int wc, int fr, int fq, PG8_LAS unsigned char* lds, int wid, int lane) const {
;     ...
;             for (int m = 0; m < 4; ++m) {
;                 const int rl = ai * 128 + wr * 64 + m * 16 + fr; const size_t row = (size_t)u.pm * 256 + rl;
;                 const float rm = 1.f / sqrtf(__hip_atomic_load(ssqm + row, __ATOMIC_RELAXED, __HIP_MEMORY_SCOPE_AGENT) * (1.f / DM) + RMS_EPS);
;                 float sh = 0.f;
; #pragma unroll
;                 for (int bj = 0; bj < 2; ++bj) {
;                     const size_t off = row * DM + colb + bj * 128;
;                     f32x4 h0, h1;
;                     if (IN16) { const u32x4 hw = *(const u32x4*)((const bf16_t*)hin + off); h0 = (f32x4){bflo(hw.x), bfhi(hw.x), bflo(hw.y), bfhi(hw.y)}; h1 = (f32x4){bflo(hw.z), bfhi(hw.z), bflo(hw.w), bfhi(hw.w)}; }
;                     else { h0 = *(const f32x4*)((const float*)hin + off); h1 = *(const f32x4*)((const float*)hin + off + 4); }
;                     h0 = h0 + acc[ai][bj][m][0] * rm * gv[bj][0]; h1 = h1 + acc[ai][bj][m][1] * rm * gv[bj][1];
;                     sh += ((h0[0] * h0[0] + h0[1] * h0[1]) + (h0[2] * h0[2] + h0[3] * h0[3])) + ((h1[0] * h1[0] + h1[1] * h1[1]) + (h1[2] * h1[2] + h1[3] * h1[3]));
;                     if (OUT16) { u32x4 w; w.x = pk_bf16(h0[0], h0[1]); w.y = pk_bf16(h0[2], h0[3]); w.z = pk_bf16(h1[0], h1[1]); w.w = pk_bf16(h1[2], h1[3]); *(u32x4*)((bf16_t*)hout + off) = w; }
;                     else { *(f32x4*)((float*)hout + off) = h0; *(f32x4*)((float*)hout + off + 4) = h1; }
;                 }
;                 if (ssqh) { sh += __shfl_xor(sh, 16); sh += __shfl_xor(sh, 32); if (fq == 0) red[rl * 4 + wc] = sh; }
.LBB0_1159:
	s_or_b64 exec, exec, s[0:1]
	v_add_u32_e32 v32, 0xa0, v152
	s_waitcnt lgkmcnt(0)
	v_mov_b32_e32 v33, 0
	v_lshl_add_u64 v[34:35], s[18:19], 0, v[32:33]
	v_lshl_add_u64 v[36:37], v[34:35], 2, s[12:13]
	s_nop 0
	v_lshlrev_b64 v[34:35], 11, v[34:35]
	v_lshl_add_u64 v[34:35], s[10:11], 0, v[34:35]
	v_lshl_add_u64 v[44:45], v[156:157], 1, v[34:35]
	s_nop 0
	s_nop 0
	v_mov_b32_e32 v35, 0x358637bd
	v_mov_b32_e32 v34, 0x260
	s_waitcnt vmcnt(7)
	v_fmamk_f32 v46, v252, 0x3a800000, v35
	v_mul_f32_e32 v47, 0x4f800000, v46
	v_cmp_gt_f32_e32 vcc, s2, v46
	v_lshlrev_b32_e32 v48, 16, v236
	v_and_b32_e32 v49, 0xffff0000, v236
	v_cndmask_b32_e32 v54, v46, v47, vcc
	v_sqrt_f32_e32 v55, v54
	v_lshlrev_b32_e32 v46, 16, v234
	v_and_b32_e32 v47, 0xffff0000, v234
	v_lshlrev_b32_e32 v36, 16, v235
	v_add_u32_e32 v56, -1, v55
	v_add_u32_e32 v57, 1, v55
	v_fma_f32 v58, -v56, v55, v54
	v_fma_f32 v59, -v57, v55, v54
	v_cmp_ge_f32_e64 s[0:1], 0, v58
	v_and_b32_e32 v37, 0xffff0000, v235
	v_lshlrev_b32_e32 v38, 16, v237
	v_cndmask_b32_e64 v55, v55, v56, s[0:1]
	v_cmp_lt_f32_e64 s[0:1], 0, v59
	v_and_b32_e32 v39, 0xffff0000, v237
	v_lshlrev_b32_e32 v50, 16, v238
	v_cndmask_b32_e64 v55, v55, v57, s[0:1]
	v_mul_f32_e32 v56, 0x37800000, v55
	v_cndmask_b32_e32 v55, v55, v56, vcc
	v_cmp_class_f32_e32 vcc, v54, v34
	v_and_b32_e32 v51, 0xffff0000, v238
	v_lshlrev_b32_e32 v40, 16, v239
	v_cndmask_b32_e32 v54, v55, v54, vcc
	v_div_scale_f32 v55, s[0:1], v54, v54, 1.0
	v_rcp_f32_e32 v56, v55
	v_div_scale_f32 v57, vcc, 1.0, v54, 1.0
	v_and_b32_e32 v41, 0xffff0000, v239
	v_fma_f32 v58, -v55, v56, 1.0
	v_fmac_f32_e32 v56, v58, v56
	v_mul_f32_e32 v58, v57, v56
	v_fma_f32 v59, -v55, v58, v57
	v_fmac_f32_e32 v58, v59, v56
	v_fma_f32 v55, -v55, v58, v57
	v_div_fmas_f32 v55, v55, v56, v58
	v_div_fixup_f32 v54, v55, v54, 1.0
	v_lshlrev_b32_e32 v52, 16, v240
	v_and_b32_e32 v53, 0xffff0000, v240
	v_lshlrev_b32_e32 v42, 16, v241
	v_and_b32_e32 v43, 0xffff0000, v241
	v_pk_mul_f32 v[28:29], v[28:29], v[54:55] op_sel_hi:[1,0]
	v_pk_mul_f32 v[30:31], v[30:31], v[54:55] op_sel_hi:[1,0]
	v_pk_mul_f32 v[24:25], v[24:25], v[54:55] op_sel_hi:[1,0]
	v_pk_mul_f32 v[26:27], v[26:27], v[54:55] op_sel_hi:[1,0]
	v_pk_mul_f32 v[20:21], v[20:21], v[54:55] op_sel_hi:[1,0]
	v_pk_mul_f32 v[22:23], v[22:23], v[54:55] op_sel_hi:[1,0]
	v_pk_mul_f32 v[16:17], v[16:17], v[54:55] op_sel_hi:[1,0]
	v_pk_mul_f32 v[18:19], v[18:19], v[54:55] op_sel_hi:[1,0]
	v_pk_fma_f32 v[30:31], v[106:107], v[30:31], v[36:37]
	v_pk_fma_f32 v[28:29], v[104:105], v[28:29], v[46:47]
	v_pk_fma_f32 v[26:27], v[102:103], v[26:27], v[38:39]
	v_pk_fma_f32 v[24:25], v[100:101], v[24:25], v[48:49]
	v_pk_fma_f32 v[22:23], v[110:111], v[22:23], v[40:41]
	v_pk_fma_f32 v[20:21], v[108:109], v[20:21], v[50:51]
	v_pk_fma_f32 v[36:37], v[98:99], v[18:19], v[42:43]
	v_pk_fma_f32 v[38:39], v[96:97], v[16:17], v[52:53]
	v_cvt_pk_bf16_f32 v16, v28, v29
	v_cvt_pk_bf16_f32 v17, v30, v31
	v_mul_f32_e32 v18, v29, v29
	v_mul_f32_e32 v19, v31, v31
	v_mul_f32_e32 v29, v25, v25
	v_mul_f32_e32 v31, v27, v27
	v_mul_f32_e32 v40, v21, v21
	v_mul_f32_e32 v41, v23, v23
	v_mul_f32_e32 v42, v39, v39
	v_mul_f32_e32 v43, v37, v37
	v_fmac_f32_e32 v18, v28, v28
	v_fmac_f32_e32 v19, v30, v30
	v_fmac_f32_e32 v29, v24, v24
	v_fmac_f32_e32 v31, v26, v26
	v_fmac_f32_e32 v40, v20, v20
	v_fmac_f32_e32 v41, v22, v22
	v_fmac_f32_e32 v42, v38, v38
	v_fmac_f32_e32 v43, v36, v36
	v_add_f32_e32 v18, v18, v19
	v_add_f32_e32 v19, v29, v31
	v_add_f32_e32 v28, v40, v41
	v_add_f32_e32 v29, v42, v43
	v_add_f32_e32 v18, v18, v19
	v_add_f32_e32 v19, v28, v29
	v_add_f32_e32 v28, v18, v19
	ds_bpermute_b32 v29, v145, v28
	v_cvt_pk_bf16_f32 v18, v24, v25
	v_cvt_pk_bf16_f32 v19, v26, v27
	global_store_dwordx4 v[44:45], v[16:19], off
	s_waitcnt lgkmcnt(0)
	s_nop 0
	v_add_f32_e32 v16, v28, v29
	ds_bpermute_b32 v17, v147, v16
	v_cvt_pk_bf16_f32 v18, v20, v21
	v_cvt_pk_bf16_f32 v19, v22, v23
	v_cvt_pk_bf16_f32 v20, v38, v39
	v_cvt_pk_bf16_f32 v21, v36, v37
	global_store_dwordx4 v[44:45], v[18:21], off offset:256
	s_and_saveexec_b64 s[0:1], s[4:5]
	s_cbranch_execz .LBB0_1161
	v_lshl_add_u32 v18, v32, 4, s22
	s_waitcnt lgkmcnt(0)
	v_add_f32_e32 v16, v16, v17
	ds_write_b32 v18, v16
; DI unsigned pk_bf16(float lo, float hi) { f32x2 v = {lo, hi}; bf16x2_t b = __builtin_convertvector(v, bf16x2_t); return __builtin_bit_cast(unsigned, b); }
; DI float bflo(unsigned w) { return __uint_as_float(w << 16); }
; DI float bfhi(unsigned w) { return __uint_as_float(w & 0xffff0000u); }
;     __device__ __forceinline__ void fused(f32x4 (&acc)[2][2][4][2], const pg8::Unit& u, int wr, int wc, int fr, int fq, PG8_LAS unsigned char* lds, int wid, int lane) const {
;     ...
;             for (int m = 0; m < 4; ++m) {
;                 const int rl = ai * 128 + wr * 64 + m * 16 + fr; const size_t row = (size_t)u.pm * 256 + rl;
;                 const float rm = 1.f / sqrtf(__hip_atomic_load(ssqm + row, __ATOMIC_RELAXED, __HIP_MEMORY_SCOPE_AGENT) * (1.f / DM) + RMS_EPS);
;                 float sh = 0.f;
; #pragma unroll
;                 for (int bj = 0; bj < 2; ++bj) {
;                     const size_t off = row * DM + colb + bj * 128;
;                     f32x4 h0, h1;
;                     if (IN16) { const u32x4 hw = *(const u32x4*)((const bf16_t*)hin + off); h0 = (f32x4){bflo(hw.x), bfhi(hw.x), bflo(hw.y), bfhi(hw.y)}; h1 = (f32x4){bflo(hw.z), bfhi(hw.z), bflo(hw.w), bfhi(hw.w)}; }
;                     else { h0 = *(const f32x4*)((const float*)hin + off); h1 = *(const f32x4*)((const float*)hin + off + 4); }
;                     h0 = h0 + acc[ai][bj][m][0] * rm * gv[bj][0]; h1 = h1 + acc[ai][bj][m][1] * rm * gv[bj][1];
;                     sh += ((h0[0] * h0[0] + h0[1] * h0[1]) + (h0[2] * h0[2] + h0[3] * h0[3])) + ((h1[0] * h1[0] + h1[1] * h1[1]) + (h1[2] * h1[2] + h1[3] * h1[3]));
;                     if (OUT16) { u32x4 w; w.x = pk_bf16(h0[0], h0[1]); w.y = pk_bf16(h0[2], h0[3]); w.z = pk_bf16(h1[0], h1[1]); w.w = pk_bf16(h1[2], h1[3]); *(u32x4*)((bf16_t*)hout + off) = w; }
;                     else { *(f32x4*)((float*)hout + off) = h0; *(f32x4*)((float*)hout + off + 4) = h1; }
;                 }
;                 if (ssqh) { sh += __shfl_xor(sh, 16); sh += __shfl_xor(sh, 32); if (fq == 0) red[rl * 4 + wc] = sh; }
.LBB0_1161:
	s_or_b64 exec, exec, s[0:1]
	v_add_u32_e32 v32, 0xb0, v152
	s_waitcnt lgkmcnt(0)
	v_lshl_add_u64 v[16:17], s[18:19], 0, v[32:33]
	v_lshl_add_u64 v[18:19], v[16:17], 2, s[12:13]
	s_nop 0
	v_lshlrev_b64 v[16:17], 11, v[16:17]
	v_lshl_add_u64 v[16:17], s[10:11], 0, v[16:17]
	v_lshl_add_u64 v[24:25], v[156:157], 1, v[16:17]
	s_nop 0
	s_nop 0
	s_waitcnt vmcnt(4)
	v_fmac_f32_e32 v35, 0x3a800000, v253
	v_mul_f32_e32 v26, 0x4f800000, v35
	v_cmp_gt_f32_e32 vcc, s2, v35
	v_and_b32_e32 v27, 0xffff0000, v242
	v_lshlrev_b32_e32 v28, 16, v244
	v_cndmask_b32_e32 v33, v35, v26, vcc
	v_sqrt_f32_e32 v35, v33
	v_lshlrev_b32_e32 v26, 16, v242
	v_lshlrev_b32_e32 v16, 16, v243
	v_and_b32_e32 v17, 0xffff0000, v243
	v_add_u32_e32 v38, -1, v35
	v_add_u32_e32 v39, 1, v35
	v_fma_f32 v40, -v38, v35, v33
	v_fma_f32 v41, -v39, v35, v33
	v_cmp_ge_f32_e64 s[0:1], 0, v40
	v_and_b32_e32 v29, 0xffff0000, v244
	v_lshlrev_b32_e32 v18, 16, v245
	v_cndmask_b32_e64 v35, v35, v38, s[0:1]
	v_cmp_lt_f32_e64 s[0:1], 0, v41
	v_and_b32_e32 v19, 0xffff0000, v245
	v_lshlrev_b32_e32 v30, 16, v246
	v_cndmask_b32_e64 v35, v35, v39, s[0:1]
	v_mul_f32_e32 v38, 0x37800000, v35
	v_cndmask_b32_e32 v35, v35, v38, vcc
	v_cmp_class_f32_e32 vcc, v33, v34
	v_and_b32_e32 v31, 0xffff0000, v246
	v_lshlrev_b32_e32 v20, 16, v247
	v_cndmask_b32_e32 v33, v35, v33, vcc
	v_div_scale_f32 v34, s[0:1], v33, v33, 1.0
	v_rcp_f32_e32 v35, v34
	v_div_scale_f32 v38, vcc, 1.0, v33, 1.0
	v_and_b32_e32 v21, 0xffff0000, v247
	v_fma_f32 v39, -v34, v35, 1.0
	v_fmac_f32_e32 v35, v39, v35
	v_mul_f32_e32 v39, v38, v35
	v_fma_f32 v40, -v34, v39, v38
	v_fmac_f32_e32 v39, v40, v35
	v_fma_f32 v34, -v34, v39, v38
	v_div_fmas_f32 v34, v34, v35, v39
	v_div_fixup_f32 v34, v34, v33, 1.0
	v_lshlrev_b32_e32 v36, 16, v248
	v_and_b32_e32 v37, 0xffff0000, v248
	v_lshlrev_b32_e32 v22, 16, v249
	v_and_b32_e32 v23, 0xffff0000, v249
	v_pk_mul_f32 v[12:13], v[12:13], v[34:35] op_sel_hi:[1,0]
	v_pk_mul_f32 v[14:15], v[14:15], v[34:35] op_sel_hi:[1,0]
	v_pk_mul_f32 v[8:9], v[8:9], v[34:35] op_sel_hi:[1,0]
	v_pk_mul_f32 v[10:11], v[10:11], v[34:35] op_sel_hi:[1,0]
	v_pk_mul_f32 v[4:5], v[4:5], v[34:35] op_sel_hi:[1,0]
	v_pk_mul_f32 v[6:7], v[6:7], v[34:35] op_sel_hi:[1,0]
	v_pk_mul_f32 v[0:1], v[0:1], v[34:35] op_sel_hi:[1,0]
	v_pk_mul_f32 v[2:3], v[2:3], v[34:35] op_sel_hi:[1,0]
	v_pk_fma_f32 v[14:15], v[106:107], v[14:15], v[16:17]
	v_pk_fma_f32 v[12:13], v[104:105], v[12:13], v[26:27]
	v_pk_fma_f32 v[10:11], v[102:103], v[10:11], v[18:19]
	v_pk_fma_f32 v[8:9], v[100:101], v[8:9], v[28:29]
	v_pk_fma_f32 v[6:7], v[110:111], v[6:7], v[20:21]
	v_pk_fma_f32 v[4:5], v[108:109], v[4:5], v[30:31]
	v_pk_fma_f32 v[16:17], v[98:99], v[2:3], v[22:23]
	v_pk_fma_f32 v[18:19], v[96:97], v[0:1], v[36:37]
	v_cvt_pk_bf16_f32 v0, v12, v13
	v_cvt_pk_bf16_f32 v1, v14, v15
	v_mul_f32_e32 v2, v13, v13
	v_mul_f32_e32 v3, v15, v15
	v_mul_f32_e32 v13, v9, v9
	v_mul_f32_e32 v15, v11, v11
	v_mul_f32_e32 v20, v5, v5
	v_mul_f32_e32 v21, v7, v7
	v_mul_f32_e32 v22, v19, v19
	v_mul_f32_e32 v23, v17, v17
	v_fmac_f32_e32 v2, v12, v12
	v_fmac_f32_e32 v3, v14, v14
	v_fmac_f32_e32 v13, v8, v8
	v_fmac_f32_e32 v15, v10, v10
	v_fmac_f32_e32 v20, v4, v4
	v_fmac_f32_e32 v21, v6, v6
	v_fmac_f32_e32 v22, v18, v18
	v_fmac_f32_e32 v23, v16, v16
	v_add_f32_e32 v2, v2, v3
	v_add_f32_e32 v3, v13, v15
	v_add_f32_e32 v12, v20, v21
	v_add_f32_e32 v13, v22, v23
	v_add_f32_e32 v2, v2, v3
	v_add_f32_e32 v3, v12, v13
	v_add_f32_e32 v12, v2, v3
	ds_bpermute_b32 v13, v145, v12
	v_cvt_pk_bf16_f32 v2, v8, v9
	v_cvt_pk_bf16_f32 v3, v10, v11
	global_store_dwordx4 v[24:25], v[0:3], off
	s_waitcnt lgkmcnt(0)
	s_nop 0
	v_add_f32_e32 v0, v12, v13
	ds_bpermute_b32 v1, v147, v0
	v_cvt_pk_bf16_f32 v2, v4, v5
	v_cvt_pk_bf16_f32 v3, v6, v7
	v_cvt_pk_bf16_f32 v4, v18, v19
	v_cvt_pk_bf16_f32 v5, v16, v17
	global_store_dwordx4 v[24:25], v[2:5], off offset:256
	s_and_saveexec_b64 s[0:1], s[4:5]
	s_cbranch_execz .LBB0_1163
	v_lshl_add_u32 v2, v32, 4, s22
	s_waitcnt lgkmcnt(0)
	v_add_f32_e32 v0, v0, v1
	ds_write_b32 v2, v0

; DI unsigned pk_bf16(float lo, float hi) { f32x2 v = {lo, hi}; bf16x2_t b = __builtin_convertvector(v, bf16x2_t); return __builtin_bit_cast(unsigned, b); }
; DI float bflo(unsigned w) { return __uint_as_float(w << 16); }
; DI float bfhi(unsigned w) { return __uint_as_float(w & 0xffff0000u); }
;     __device__ __forceinline__ void fused(f32x4 (&acc)[2][2][4][2], const pg8::Unit& u, int wr, int wc, int fr, int fq, PG8_LAS unsigned char* lds, int wid, int lane) const {
;     ...
;         const int colb = u.pn * 256 + wc * 32 + 8 * fq;
;         f32x4 gv[2][2];
; #pragma unroll
;         for (int bj = 0; bj < 2; ++bj)
; #pragma unroll
;             for (int n = 0; n < 2; ++n) gv[bj][n] = *(const f32x4*)(gA + colb + bj * 128 + 4 * n);
; #pragma unroll
;         for (int ai = 0; ai < 2; ++ai)
; #pragma unroll
;             for (int m = 0; m < 4; ++m) {
;                 const int rl = ai * 128 + wr * 64 + m * 16 + fr; const size_t row = (size_t)u.pm * 256 + rl;
;                 const float rm = 1.f / sqrtf(__hip_atomic_load(ssqm + row, __ATOMIC_RELAXED, __HIP_MEMORY_SCOPE_AGENT) * (1.f / DM) + RMS_EPS);
;                 float sh = 0.f;
; #pragma unroll
;                 for (int bj = 0; bj < 2; ++bj) {
;                     const size_t off = row * DM + colb + bj * 128;
;                     f32x4 h0, h1;
;                     if (IN16) { const u32x4 hw = *(const u32x4*)((const bf16_t*)hin + off); h0 = (f32x4){bflo(hw.x), bfhi(hw.x), bflo(hw.y), bfhi(hw.y)}; h1 = (f32x4){bflo(hw.z), bfhi(hw.z), bflo(hw.w), bfhi(hw.w)}; }
;                     else { h0 = *(const f32x4*)((const float*)hin + off); h1 = *(const f32x4*)((const float*)hin + off + 4); }
;                     h0 = h0 + acc[ai][bj][m][0] * rm * gv[bj][0]; h1 = h1 + acc[ai][bj][m][1] * rm * gv[bj][1];
;                     sh += ((h0[0] * h0[0] + h0[1] * h0[1]) + (h0[2] * h0[2] + h0[3] * h0[3])) + ((h1[0] * h1[0] + h1[1] * h1[1]) + (h1[2] * h1[2] + h1[3] * h1[3]));
;                     if (OUT16) { u32x4 w; w.x = pk_bf16(h0[0], h0[1]); w.y = pk_bf16(h0[2], h0[3]); w.z = pk_bf16(h1[0], h1[1]); w.w = pk_bf16(h1[2], h1[3]); *(u32x4*)((bf16_t*)hout + off) = w; }
;                     else { *(f32x4*)((float*)hout + off) = h0; *(f32x4*)((float*)hout + off + 4) = h1; }
;                 }
;                 if (ssqh) { sh += __shfl_xor(sh, 16); sh += __shfl_xor(sh, 32); if (fq == 0) red[rl * 4 + wc] = sh; }
.LBB0_1202:
	s_or_b64 exec, exec, s[0:1]
	s_lshl_b32 s0, s28, 5
	s_lshl_b32 s1, s33, 8
	s_or_b32 s0, s1, s0
	v_or_b32_e32 v146, s0, v160
	v_ashrrev_i32_e32 v147, 31, v146
	v_mov_b32_e32 v149, 0
	v_lshl_add_u64 v[108:109], v[146:147], 2, s[14:15]
	s_lshl_b64 s[14:15], s[16:17], 8
	v_mov_b32_e32 v153, v149
	v_lshl_add_u64 v[156:157], s[14:15], 0, v[152:153]
	v_lshl_add_u64 v[158:159], v[156:157], 2, s[12:13]
	s_barrier
	global_load_dwordx4 v[100:103], v[108:109], off offset:16
	global_load_dwordx4 v[104:107], v[108:109], off
	global_load_dwordx4 v[96:99], v[108:109], off offset:528
	s_nop 0
	global_load_dwordx4 v[108:111], v[108:109], off offset:512
	v_lshlrev_b64 v[156:157], 11, v[156:157]
	v_or_b32_e32 v254, 0, v152
	v_mov_b32_e32 v255, 0
	v_lshl_add_u64 v[254:255], s[14:15], 0, v[254:255]
	v_lshlrev_b64 v[240:241], 11, v[254:255]
	v_lshl_add_u64 v[240:241], s[10:11], 0, v[240:241]
	v_lshl_add_u64 v[240:241], v[146:147], 1, v[240:241]
	v_lshl_add_u64 v[254:255], v[254:255], 2, s[12:13]
	global_load_dword v252, v[254:255], off sc1
	global_load_dwordx4 v[234:237], v[240:241], off
	global_load_dwordx4 v[238:241], v[240:241], off offset:256
	v_or_b32_e32 v254, 16, v152
	v_mov_b32_e32 v255, 0
	v_lshl_add_u64 v[254:255], s[14:15], 0, v[254:255]
	v_lshlrev_b64 v[248:249], 11, v[254:255]
	v_lshl_add_u64 v[248:249], s[10:11], 0, v[248:249]
	v_lshl_add_u64 v[248:249], v[146:147], 1, v[248:249]
	v_lshl_add_u64 v[254:255], v[254:255], 2, s[12:13]
	global_load_dword v253, v[254:255], off sc1
	global_load_dwordx4 v[242:245], v[248:249], off
	global_load_dwordx4 v[246:249], v[248:249], off offset:256
	s_nop 0
	v_lshl_add_u64 v[156:157], s[10:11], 0, v[156:157]
	v_lshl_add_u64 v[164:165], v[146:147], 1, v[156:157]
	s_nop 0
	s_nop 0
	v_mov_b32_e32 v155, 0x358637bd
	s_mov_b32 s2, 0xf800000
	v_mov_b32_e32 v153, 0x260
	s_waitcnt vmcnt(3)
	v_fmamk_f32 v148, v252, 0x3a800000, v155
	v_mul_f32_e32 v172, 0x4f800000, v148
	v_cmp_gt_f32_e32 vcc, s2, v148
	v_lshlrev_b32_e32 v166, 16, v234
	v_and_b32_e32 v167, 0xffff0000, v234
	v_cndmask_b32_e32 v148, v148, v172, vcc
	v_sqrt_f32_e32 v174, v148
	v_lshlrev_b32_e32 v156, 16, v235
	v_and_b32_e32 v157, 0xffff0000, v235
	v_lshlrev_b32_e32 v168, 16, v236
	v_add_u32_e32 v175, -1, v174
	v_add_u32_e32 v176, 1, v174
	v_fma_f32 v177, -v175, v174, v148
	v_fma_f32 v178, -v176, v174, v148
	v_cmp_ge_f32_e64 s[0:1], 0, v177
	v_and_b32_e32 v169, 0xffff0000, v236
	v_lshlrev_b32_e32 v158, 16, v237
	v_cndmask_b32_e64 v174, v174, v175, s[0:1]
	v_cmp_lt_f32_e64 s[0:1], 0, v178
	v_and_b32_e32 v159, 0xffff0000, v237
	v_lshlrev_b32_e32 v170, 16, v238
	v_cndmask_b32_e64 v174, v174, v176, s[0:1]
	v_mul_f32_e32 v175, 0x37800000, v174
	v_cndmask_b32_e32 v174, v174, v175, vcc
	v_cmp_class_f32_e32 vcc, v148, v153
	v_and_b32_e32 v171, 0xffff0000, v238
	v_lshlrev_b32_e32 v160, 16, v239
	v_cndmask_b32_e32 v148, v174, v148, vcc
	v_div_scale_f32 v174, s[0:1], v148, v148, 1.0
	v_rcp_f32_e32 v175, v174
	v_div_scale_f32 v176, vcc, 1.0, v148, 1.0
	v_and_b32_e32 v161, 0xffff0000, v239
	v_fma_f32 v177, -v174, v175, 1.0
	v_fmac_f32_e32 v175, v177, v175
	v_mul_f32_e32 v177, v176, v175
	v_fma_f32 v178, -v174, v177, v176
	v_fmac_f32_e32 v177, v178, v175
	v_fma_f32 v174, -v174, v177, v176
	v_div_fmas_f32 v174, v174, v175, v177
	v_div_fixup_f32 v148, v174, v148, 1.0
	v_lshlrev_b32_e32 v172, 16, v240
	v_and_b32_e32 v173, 0xffff0000, v240
	v_lshlrev_b32_e32 v162, 16, v241
	v_and_b32_e32 v163, 0xffff0000, v241
	v_or_b32_e32 v254, 32, v152
	v_mov_b32_e32 v255, 0
	v_lshl_add_u64 v[254:255], s[14:15], 0, v[254:255]
	v_lshlrev_b64 v[240:241], 11, v[254:255]
	v_lshl_add_u64 v[240:241], s[10:11], 0, v[240:241]
	v_lshl_add_u64 v[240:241], v[146:147], 1, v[240:241]
	v_lshl_add_u64 v[254:255], v[254:255], 2, s[12:13]
	global_load_dword v252, v[254:255], off sc1
	global_load_dwordx4 v[234:237], v[240:241], off
	global_load_dwordx4 v[238:241], v[240:241], off offset:256
	v_pk_mul_f32 v[140:141], v[140:141], v[148:149] op_sel_hi:[1,0]
	v_pk_mul_f32 v[142:143], v[142:143], v[148:149] op_sel_hi:[1,0]
	v_pk_mul_f32 v[136:137], v[136:137], v[148:149] op_sel_hi:[1,0]
	v_pk_mul_f32 v[138:139], v[138:139], v[148:149] op_sel_hi:[1,0]
	v_pk_mul_f32 v[132:133], v[132:133], v[148:149] op_sel_hi:[1,0]
	v_pk_mul_f32 v[134:135], v[134:135], v[148:149] op_sel_hi:[1,0]
	v_pk_mul_f32 v[128:129], v[128:129], v[148:149] op_sel_hi:[1,0]
	v_pk_mul_f32 v[130:131], v[130:131], v[148:149] op_sel_hi:[1,0]
	v_pk_fma_f32 v[142:143], v[106:107], v[142:143], v[156:157]
	v_pk_fma_f32 v[140:141], v[104:105], v[140:141], v[166:167]
	v_pk_fma_f32 v[138:139], v[102:103], v[138:139], v[158:159]
	v_pk_fma_f32 v[136:137], v[100:101], v[136:137], v[168:169]
	v_pk_fma_f32 v[134:135], v[110:111], v[134:135], v[160:161]
	v_pk_fma_f32 v[132:133], v[108:109], v[132:133], v[170:171]
	v_pk_fma_f32 v[156:157], v[98:99], v[130:131], v[162:163]
	v_pk_fma_f32 v[158:159], v[96:97], v[128:129], v[172:173]
	v_cvt_pk_bf16_f32 v128, v140, v141
	v_cvt_pk_bf16_f32 v129, v142, v143
	v_mul_f32_e32 v130, v141, v141
	v_mul_f32_e32 v131, v143, v143
	v_mul_f32_e32 v141, v137, v137
	v_mul_f32_e32 v143, v139, v139
	v_mul_f32_e32 v148, v133, v133
	v_mul_f32_e32 v160, v135, v135
	v_mul_f32_e32 v161, v159, v159
	v_mul_f32_e32 v162, v157, v157
	v_fmac_f32_e32 v130, v140, v140
	v_fmac_f32_e32 v131, v142, v142
	v_fmac_f32_e32 v141, v136, v136
	v_fmac_f32_e32 v143, v138, v138
	v_fmac_f32_e32 v148, v132, v132
	v_fmac_f32_e32 v160, v134, v134
	v_fmac_f32_e32 v161, v158, v158
	v_fmac_f32_e32 v162, v156, v156
	v_add_f32_e32 v130, v130, v131
	v_add_f32_e32 v131, v141, v143
	v_add_f32_e32 v140, v148, v160
	v_add_f32_e32 v141, v161, v162
	v_add_f32_e32 v130, v130, v131
	v_add_f32_e32 v131, v140, v141
	v_add_f32_e32 v140, v130, v131
	ds_bpermute_b32 v141, v150, v140
	v_cvt_pk_bf16_f32 v130, v136, v137
	v_cvt_pk_bf16_f32 v131, v138, v139
	global_store_dwordx4 v[164:165], v[128:131], off
	s_waitcnt lgkmcnt(0)
	s_nop 0
	v_add_f32_e32 v128, v140, v141
	ds_bpermute_b32 v129, v151, v128
	v_cvt_pk_bf16_f32 v130, v132, v133
	v_cvt_pk_bf16_f32 v131, v134, v135
	v_cvt_pk_bf16_f32 v132, v158, v159
	v_cvt_pk_bf16_f32 v133, v156, v157
	global_store_dwordx4 v[164:165], v[130:133], off offset:256
	s_and_saveexec_b64 s[0:1], s[4:5]
	s_cbranch_execz .LBB0_1204
	v_lshl_add_u32 v130, v152, 4, s22
	s_waitcnt lgkmcnt(0)
	v_add_f32_e32 v128, v128, v129
	ds_write_b32 v130, v128
; DI unsigned pk_bf16(float lo, float hi) { f32x2 v = {lo, hi}; bf16x2_t b = __builtin_convertvector(v, bf16x2_t); return __builtin_bit_cast(unsigned, b); }
; DI float bflo(unsigned w) { return __uint_as_float(w << 16); }
; DI float bfhi(unsigned w) { return __uint_as_float(w & 0xffff0000u); }
;     __device__ __forceinline__ void fused(f32x4 (&acc)[2][2][4][2], const pg8::Unit& u, int wr, int wc, int fr, int fq, PG8_LAS unsigned char* lds, int wid, int lane) const {
;     ...
;             for (int m = 0; m < 4; ++m) {
;                 const int rl = ai * 128 + wr * 64 + m * 16 + fr; const size_t row = (size_t)u.pm * 256 + rl;
;                 const float rm = 1.f / sqrtf(__hip_atomic_load(ssqm + row, __ATOMIC_RELAXED, __HIP_MEMORY_SCOPE_AGENT) * (1.f / DM) + RMS_EPS);
;                 float sh = 0.f;
; #pragma unroll
;                 for (int bj = 0; bj < 2; ++bj) {
;                     const size_t off = row * DM + colb + bj * 128;
;                     f32x4 h0, h1;
;                     if (IN16) { const u32x4 hw = *(const u32x4*)((const bf16_t*)hin + off); h0 = (f32x4){bflo(hw.x), bfhi(hw.x), bflo(hw.y), bfhi(hw.y)}; h1 = (f32x4){bflo(hw.z), bfhi(hw.z), bflo(hw.w), bfhi(hw.w)}; }
;                     else { h0 = *(const f32x4*)((const float*)hin + off); h1 = *(const f32x4*)((const float*)hin + off + 4); }
;                     h0 = h0 + acc[ai][bj][m][0] * rm * gv[bj][0]; h1 = h1 + acc[ai][bj][m][1] * rm * gv[bj][1];
;                     sh += ((h0[0] * h0[0] + h0[1] * h0[1]) + (h0[2] * h0[2] + h0[3] * h0[3])) + ((h1[0] * h1[0] + h1[1] * h1[1]) + (h1[2] * h1[2] + h1[3] * h1[3]));
;                     if (OUT16) { u32x4 w; w.x = pk_bf16(h0[0], h0[1]); w.y = pk_bf16(h0[2], h0[3]); w.z = pk_bf16(h1[0], h1[1]); w.w = pk_bf16(h1[2], h1[3]); *(u32x4*)((bf16_t*)hout + off) = w; }
;                     else { *(f32x4*)((float*)hout + off) = h0; *(f32x4*)((float*)hout + off + 4) = h1; }
;                 }
;                 if (ssqh) { sh += __shfl_xor(sh, 16); sh += __shfl_xor(sh, 32); if (fq == 0) red[rl * 4 + wc] = sh; }
.LBB0_1204:
	s_or_b64 exec, exec, s[0:1]
	v_or_b32_e32 v148, 16, v152
	s_waitcnt lgkmcnt(0)
	v_lshl_add_u64 v[128:129], s[14:15], 0, v[148:149]
	v_lshl_add_u64 v[130:131], v[128:129], 2, s[12:13]
	s_nop 0
	v_lshlrev_b64 v[128:129], 11, v[128:129]
	v_lshl_add_u64 v[128:129], s[10:11], 0, v[128:129]
	v_lshl_add_u64 v[136:137], v[146:147], 1, v[128:129]
	s_nop 0
	s_nop 0
	s_waitcnt vmcnt(5)
	v_fmac_f32_e32 v155, 0x3a800000, v253
	v_mul_f32_e32 v138, 0x4f800000, v155
	v_cmp_gt_f32_e32 vcc, s2, v155
	v_and_b32_e32 v139, 0xffff0000, v242
	v_lshlrev_b32_e32 v140, 16, v244
	v_cndmask_b32_e32 v149, v155, v138, vcc
	v_sqrt_f32_e32 v155, v149
	v_lshlrev_b32_e32 v138, 16, v242
	v_lshlrev_b32_e32 v128, 16, v243
	v_and_b32_e32 v129, 0xffff0000, v243
	v_add_u32_e32 v158, -1, v155
	v_add_u32_e32 v159, 1, v155
	v_fma_f32 v160, -v158, v155, v149
	v_fma_f32 v161, -v159, v155, v149
	v_cmp_ge_f32_e64 s[0:1], 0, v160
	v_and_b32_e32 v141, 0xffff0000, v244
	v_lshlrev_b32_e32 v130, 16, v245
	v_cndmask_b32_e64 v155, v155, v158, s[0:1]
	v_cmp_lt_f32_e64 s[0:1], 0, v161
	v_and_b32_e32 v131, 0xffff0000, v245
	v_lshlrev_b32_e32 v142, 16, v246
	v_cndmask_b32_e64 v155, v155, v159, s[0:1]
	v_mul_f32_e32 v158, 0x37800000, v155
	v_cndmask_b32_e32 v155, v155, v158, vcc
	v_cmp_class_f32_e32 vcc, v149, v153
	v_and_b32_e32 v143, 0xffff0000, v246
	v_lshlrev_b32_e32 v132, 16, v247
	v_cndmask_b32_e32 v149, v155, v149, vcc
	v_div_scale_f32 v153, s[0:1], v149, v149, 1.0
	v_rcp_f32_e32 v155, v153
	v_div_scale_f32 v158, vcc, 1.0, v149, 1.0
	v_and_b32_e32 v133, 0xffff0000, v247
	v_fma_f32 v159, -v153, v155, 1.0
	v_fmac_f32_e32 v155, v159, v155
	v_mul_f32_e32 v159, v158, v155
	v_fma_f32 v160, -v153, v159, v158
	v_fmac_f32_e32 v159, v160, v155
	v_fma_f32 v153, -v153, v159, v158
	v_div_fmas_f32 v153, v153, v155, v159
	v_div_fixup_f32 v158, v153, v149, 1.0
	v_lshlrev_b32_e32 v156, 16, v248
	v_and_b32_e32 v157, 0xffff0000, v248
	v_lshlrev_b32_e32 v134, 16, v249
	v_and_b32_e32 v135, 0xffff0000, v249
	v_or_b32_e32 v254, 48, v152
	v_mov_b32_e32 v255, 0
	v_lshl_add_u64 v[254:255], s[14:15], 0, v[254:255]
	v_lshlrev_b64 v[248:249], 11, v[254:255]
	v_lshl_add_u64 v[248:249], s[10:11], 0, v[248:249]
	v_lshl_add_u64 v[248:249], v[146:147], 1, v[248:249]
	v_lshl_add_u64 v[254:255], v[254:255], 2, s[12:13]
	global_load_dword v253, v[254:255], off sc1
	global_load_dwordx4 v[242:245], v[248:249], off
	global_load_dwordx4 v[246:249], v[248:249], off offset:256
	v_pk_mul_f32 v[124:125], v[124:125], v[158:159] op_sel_hi:[1,0]
	v_pk_mul_f32 v[126:127], v[126:127], v[158:159] op_sel_hi:[1,0]
	v_pk_mul_f32 v[120:121], v[120:121], v[158:159] op_sel_hi:[1,0]
	v_pk_mul_f32 v[122:123], v[122:123], v[158:159] op_sel_hi:[1,0]
	v_pk_mul_f32 v[116:117], v[116:117], v[158:159] op_sel_hi:[1,0]
	v_pk_mul_f32 v[118:119], v[118:119], v[158:159] op_sel_hi:[1,0]
	v_pk_mul_f32 v[112:113], v[112:113], v[158:159] op_sel_hi:[1,0]
	v_pk_mul_f32 v[114:115], v[114:115], v[158:159] op_sel_hi:[1,0]
	v_pk_fma_f32 v[126:127], v[106:107], v[126:127], v[128:129]
	v_pk_fma_f32 v[124:125], v[104:105], v[124:125], v[138:139]
	v_pk_fma_f32 v[122:123], v[102:103], v[122:123], v[130:131]
	v_pk_fma_f32 v[120:121], v[100:101], v[120:121], v[140:141]
	v_pk_fma_f32 v[118:119], v[110:111], v[118:119], v[132:133]
	v_pk_fma_f32 v[116:117], v[108:109], v[116:117], v[142:143]
	v_pk_fma_f32 v[128:129], v[98:99], v[114:115], v[134:135]
	v_pk_fma_f32 v[130:131], v[96:97], v[112:113], v[156:157]
	v_cvt_pk_bf16_f32 v112, v124, v125
	v_cvt_pk_bf16_f32 v113, v126, v127
	v_mul_f32_e32 v114, v125, v125
	v_mul_f32_e32 v115, v127, v127
	v_mul_f32_e32 v125, v121, v121
	v_mul_f32_e32 v127, v123, v123
	v_mul_f32_e32 v132, v117, v117
	v_mul_f32_e32 v133, v119, v119
	v_mul_f32_e32 v134, v131, v131
	v_mul_f32_e32 v135, v129, v129
	v_fmac_f32_e32 v114, v124, v124
	v_fmac_f32_e32 v115, v126, v126
	v_fmac_f32_e32 v125, v120, v120
	v_fmac_f32_e32 v127, v122, v122
	v_fmac_f32_e32 v132, v116, v116
	v_fmac_f32_e32 v133, v118, v118
	v_fmac_f32_e32 v134, v130, v130
	v_fmac_f32_e32 v135, v128, v128
	v_add_f32_e32 v114, v114, v115
	v_add_f32_e32 v115, v125, v127
	v_add_f32_e32 v124, v132, v133
	v_add_f32_e32 v125, v134, v135
	v_add_f32_e32 v114, v114, v115
	v_add_f32_e32 v115, v124, v125
	v_add_f32_e32 v124, v114, v115
	ds_bpermute_b32 v125, v150, v124
	v_cvt_pk_bf16_f32 v114, v120, v121
	v_cvt_pk_bf16_f32 v115, v122, v123
	global_store_dwordx4 v[136:137], v[112:115], off
	s_waitcnt lgkmcnt(0)
	s_nop 0
	v_add_f32_e32 v112, v124, v125
	ds_bpermute_b32 v113, v151, v112
	v_cvt_pk_bf16_f32 v114, v116, v117
	v_cvt_pk_bf16_f32 v115, v118, v119
	v_cvt_pk_bf16_f32 v116, v130, v131
	v_cvt_pk_bf16_f32 v117, v128, v129
	global_store_dwordx4 v[136:137], v[114:117], off offset:256
	s_and_saveexec_b64 s[0:1], s[4:5]
	s_cbranch_execz .LBB0_1206
	v_lshl_add_u32 v114, v148, 4, s22
	s_waitcnt lgkmcnt(0)
	v_add_f32_e32 v112, v112, v113
	ds_write_b32 v114, v112
; DI unsigned pk_bf16(float lo, float hi) { f32x2 v = {lo, hi}; bf16x2_t b = __builtin_convertvector(v, bf16x2_t); return __builtin_bit_cast(unsigned, b); }
; DI float bflo(unsigned w) { return __uint_as_float(w << 16); }
; DI float bfhi(unsigned w) { return __uint_as_float(w & 0xffff0000u); }
;     __device__ __forceinline__ void fused(f32x4 (&acc)[2][2][4][2], const pg8::Unit& u, int wr, int wc, int fr, int fq, PG8_LAS unsigned char* lds, int wid, int lane) const {
;     ...
;             for (int m = 0; m < 4; ++m) {
;                 const int rl = ai * 128 + wr * 64 + m * 16 + fr; const size_t row = (size_t)u.pm * 256 + rl;
;                 const float rm = 1.f / sqrtf(__hip_atomic_load(ssqm + row, __ATOMIC_RELAXED, __HIP_MEMORY_SCOPE_AGENT) * (1.f / DM) + RMS_EPS);
;                 float sh = 0.f;
; #pragma unroll
;                 for (int bj = 0; bj < 2; ++bj) {
;                     const size_t off = row * DM + colb + bj * 128;
;                     f32x4 h0, h1;
;                     if (IN16) { const u32x4 hw = *(const u32x4*)((const bf16_t*)hin + off); h0 = (f32x4){bflo(hw.x), bfhi(hw.x), bflo(hw.y), bfhi(hw.y)}; h1 = (f32x4){bflo(hw.z), bfhi(hw.z), bflo(hw.w), bfhi(hw.w)}; }
;                     else { h0 = *(const f32x4*)((const float*)hin + off); h1 = *(const f32x4*)((const float*)hin + off + 4); }
;                     h0 = h0 + acc[ai][bj][m][0] * rm * gv[bj][0]; h1 = h1 + acc[ai][bj][m][1] * rm * gv[bj][1];
;                     sh += ((h0[0] * h0[0] + h0[1] * h0[1]) + (h0[2] * h0[2] + h0[3] * h0[3])) + ((h1[0] * h1[0] + h1[1] * h1[1]) + (h1[2] * h1[2] + h1[3] * h1[3]));
;                     if (OUT16) { u32x4 w; w.x = pk_bf16(h0[0], h0[1]); w.y = pk_bf16(h0[2], h0[3]); w.z = pk_bf16(h1[0], h1[1]); w.w = pk_bf16(h1[2], h1[3]); *(u32x4*)((bf16_t*)hout + off) = w; }
;                     else { *(f32x4*)((float*)hout + off) = h0; *(f32x4*)((float*)hout + off + 4) = h1; }
;                 }
;                 if (ssqh) { sh += __shfl_xor(sh, 16); sh += __shfl_xor(sh, 32); if (fq == 0) red[rl * 4 + wc] = sh; }
.LBB0_1206:
	s_or_b64 exec, exec, s[0:1]
	v_or_b32_e32 v112, 32, v152
	s_waitcnt lgkmcnt(0)
	v_mov_b32_e32 v113, 0
	v_lshl_add_u64 v[114:115], s[14:15], 0, v[112:113]
	v_lshl_add_u64 v[116:117], v[114:115], 2, s[12:13]
	s_nop 0
	v_lshlrev_b64 v[114:115], 11, v[114:115]
	v_lshl_add_u64 v[114:115], s[10:11], 0, v[114:115]
	v_lshl_add_u64 v[124:125], v[146:147], 1, v[114:115]
	s_nop 0
	s_nop 0
	v_mov_b32_e32 v115, 0x358637bd
	v_mov_b32_e32 v114, 0x260
	s_waitcnt vmcnt(7)
	v_fmamk_f32 v126, v252, 0x3a800000, v115
	v_mul_f32_e32 v127, 0x4f800000, v126
	v_cmp_gt_f32_e32 vcc, s2, v126
	v_lshlrev_b32_e32 v128, 16, v236
	v_and_b32_e32 v129, 0xffff0000, v236
	v_cndmask_b32_e32 v134, v126, v127, vcc
	v_sqrt_f32_e32 v135, v134
	v_lshlrev_b32_e32 v126, 16, v234
	v_and_b32_e32 v127, 0xffff0000, v234
	v_lshlrev_b32_e32 v116, 16, v235
	v_add_u32_e32 v136, -1, v135
	v_add_u32_e32 v137, 1, v135
	v_fma_f32 v138, -v136, v135, v134
	v_fma_f32 v139, -v137, v135, v134
	v_cmp_ge_f32_e64 s[0:1], 0, v138
	v_and_b32_e32 v117, 0xffff0000, v235
	v_lshlrev_b32_e32 v118, 16, v237
	v_cndmask_b32_e64 v135, v135, v136, s[0:1]
	v_cmp_lt_f32_e64 s[0:1], 0, v139
	v_and_b32_e32 v119, 0xffff0000, v237
	v_lshlrev_b32_e32 v130, 16, v238
	v_cndmask_b32_e64 v135, v135, v137, s[0:1]
	v_mul_f32_e32 v136, 0x37800000, v135
	v_cndmask_b32_e32 v135, v135, v136, vcc
	v_cmp_class_f32_e32 vcc, v134, v114
	v_and_b32_e32 v131, 0xffff0000, v238
	v_lshlrev_b32_e32 v120, 16, v239
	v_cndmask_b32_e32 v134, v135, v134, vcc
	v_div_scale_f32 v135, s[0:1], v134, v134, 1.0
	v_rcp_f32_e32 v136, v135
	v_div_scale_f32 v137, vcc, 1.0, v134, 1.0
	v_and_b32_e32 v121, 0xffff0000, v239
	v_fma_f32 v138, -v135, v136, 1.0
	v_fmac_f32_e32 v136, v138, v136
	v_mul_f32_e32 v138, v137, v136
	v_fma_f32 v139, -v135, v138, v137
	v_fmac_f32_e32 v138, v139, v136
	v_fma_f32 v135, -v135, v138, v137
	v_div_fmas_f32 v135, v135, v136, v138
	v_div_fixup_f32 v134, v135, v134, 1.0
	v_lshlrev_b32_e32 v132, 16, v240
	v_and_b32_e32 v133, 0xffff0000, v240
	v_lshlrev_b32_e32 v122, 16, v241
	v_and_b32_e32 v123, 0xffff0000, v241
	v_or_b32_e32 v254, 128, v152
	v_mov_b32_e32 v255, 0
	v_lshl_add_u64 v[254:255], s[14:15], 0, v[254:255]
	v_lshlrev_b64 v[240:241], 11, v[254:255]
	v_lshl_add_u64 v[240:241], s[10:11], 0, v[240:241]
	v_lshl_add_u64 v[240:241], v[146:147], 1, v[240:241]
	v_lshl_add_u64 v[254:255], v[254:255], 2, s[12:13]
	global_load_dword v252, v[254:255], off sc1
	global_load_dwordx4 v[234:237], v[240:241], off
	global_load_dwordx4 v[238:241], v[240:241], off offset:256
	v_pk_mul_f32 v[92:93], v[92:93], v[134:135] op_sel_hi:[1,0]
	v_pk_mul_f32 v[94:95], v[94:95], v[134:135] op_sel_hi:[1,0]
	v_pk_mul_f32 v[88:89], v[88:89], v[134:135] op_sel_hi:[1,0]
	v_pk_mul_f32 v[90:91], v[90:91], v[134:135] op_sel_hi:[1,0]
	v_pk_mul_f32 v[84:85], v[84:85], v[134:135] op_sel_hi:[1,0]
	v_pk_mul_f32 v[86:87], v[86:87], v[134:135] op_sel_hi:[1,0]
	v_pk_mul_f32 v[80:81], v[80:81], v[134:135] op_sel_hi:[1,0]
	v_pk_mul_f32 v[82:83], v[82:83], v[134:135] op_sel_hi:[1,0]
	v_pk_fma_f32 v[94:95], v[106:107], v[94:95], v[116:117]
	v_pk_fma_f32 v[92:93], v[104:105], v[92:93], v[126:127]
	v_pk_fma_f32 v[90:91], v[102:103], v[90:91], v[118:119]
	v_pk_fma_f32 v[88:89], v[100:101], v[88:89], v[128:129]
	v_pk_fma_f32 v[86:87], v[110:111], v[86:87], v[120:121]
	v_pk_fma_f32 v[84:85], v[108:109], v[84:85], v[130:131]
	v_pk_fma_f32 v[116:117], v[98:99], v[82:83], v[122:123]
	v_pk_fma_f32 v[118:119], v[96:97], v[80:81], v[132:133]
	v_cvt_pk_bf16_f32 v80, v92, v93
	v_cvt_pk_bf16_f32 v81, v94, v95
	v_mul_f32_e32 v82, v93, v93
	v_mul_f32_e32 v83, v95, v95
	v_mul_f32_e32 v93, v89, v89
	v_mul_f32_e32 v95, v91, v91
	v_mul_f32_e32 v120, v85, v85
	v_mul_f32_e32 v121, v87, v87
	v_mul_f32_e32 v122, v119, v119
	v_mul_f32_e32 v123, v117, v117
	v_fmac_f32_e32 v82, v92, v92
	v_fmac_f32_e32 v83, v94, v94
	v_fmac_f32_e32 v93, v88, v88
	v_fmac_f32_e32 v95, v90, v90
	v_fmac_f32_e32 v120, v84, v84
	v_fmac_f32_e32 v121, v86, v86
	v_fmac_f32_e32 v122, v118, v118
	v_fmac_f32_e32 v123, v116, v116
	v_add_f32_e32 v82, v82, v83
	v_add_f32_e32 v83, v93, v95
	v_add_f32_e32 v92, v120, v121
	v_add_f32_e32 v93, v122, v123
	v_add_f32_e32 v82, v82, v83
	v_add_f32_e32 v83, v92, v93
	v_add_f32_e32 v92, v82, v83
	ds_bpermute_b32 v93, v150, v92
	v_cvt_pk_bf16_f32 v82, v88, v89
	v_cvt_pk_bf16_f32 v83, v90, v91
	global_store_dwordx4 v[124:125], v[80:83], off
	s_waitcnt lgkmcnt(0)
	s_nop 0
	v_add_f32_e32 v80, v92, v93
	ds_bpermute_b32 v81, v151, v80
	v_cvt_pk_bf16_f32 v82, v84, v85
	v_cvt_pk_bf16_f32 v83, v86, v87
	v_cvt_pk_bf16_f32 v84, v118, v119
	v_cvt_pk_bf16_f32 v85, v116, v117
	global_store_dwordx4 v[124:125], v[82:85], off offset:256
	s_and_saveexec_b64 s[0:1], s[4:5]
	s_cbranch_execz .LBB0_1208
	v_lshl_add_u32 v82, v112, 4, s22
	s_waitcnt lgkmcnt(0)
	v_add_f32_e32 v80, v80, v81
	ds_write_b32 v82, v80
; DI unsigned pk_bf16(float lo, float hi) { f32x2 v = {lo, hi}; bf16x2_t b = __builtin_convertvector(v, bf16x2_t); return __builtin_bit_cast(unsigned, b); }
; DI float bflo(unsigned w) { return __uint_as_float(w << 16); }
; DI float bfhi(unsigned w) { return __uint_as_float(w & 0xffff0000u); }
;     __device__ __forceinline__ void fused(f32x4 (&acc)[2][2][4][2], const pg8::Unit& u, int wr, int wc, int fr, int fq, PG8_LAS unsigned char* lds, int wid, int lane) const {
;     ...
;             for (int m = 0; m < 4; ++m) {
;                 const int rl = ai * 128 + wr * 64 + m * 16 + fr; const size_t row = (size_t)u.pm * 256 + rl;
;                 const float rm = 1.f / sqrtf(__hip_atomic_load(ssqm + row, __ATOMIC_RELAXED, __HIP_MEMORY_SCOPE_AGENT) * (1.f / DM) + RMS_EPS);
;                 float sh = 0.f;
; #pragma unroll
;                 for (int bj = 0; bj < 2; ++bj) {
;                     const size_t off = row * DM + colb + bj * 128;
;                     f32x4 h0, h1;
;                     if (IN16) { const u32x4 hw = *(const u32x4*)((const bf16_t*)hin + off); h0 = (f32x4){bflo(hw.x), bfhi(hw.x), bflo(hw.y), bfhi(hw.y)}; h1 = (f32x4){bflo(hw.z), bfhi(hw.z), bflo(hw.w), bfhi(hw.w)}; }
;                     else { h0 = *(const f32x4*)((const float*)hin + off); h1 = *(const f32x4*)((const float*)hin + off + 4); }
;                     h0 = h0 + acc[ai][bj][m][0] * rm * gv[bj][0]; h1 = h1 + acc[ai][bj][m][1] * rm * gv[bj][1];
;                     sh += ((h0[0] * h0[0] + h0[1] * h0[1]) + (h0[2] * h0[2] + h0[3] * h0[3])) + ((h1[0] * h1[0] + h1[1] * h1[1]) + (h1[2] * h1[2] + h1[3] * h1[3]));
;                     if (OUT16) { u32x4 w; w.x = pk_bf16(h0[0], h0[1]); w.y = pk_bf16(h0[2], h0[3]); w.z = pk_bf16(h1[0], h1[1]); w.w = pk_bf16(h1[2], h1[3]); *(u32x4*)((bf16_t*)hout + off) = w; }
;                     else { *(f32x4*)((float*)hout + off) = h0; *(f32x4*)((float*)hout + off + 4) = h1; }
;                 }
;                 if (ssqh) { sh += __shfl_xor(sh, 16); sh += __shfl_xor(sh, 32); if (fq == 0) red[rl * 4 + wc] = sh; }
.LBB0_1208:
	s_or_b64 exec, exec, s[0:1]
	v_or_b32_e32 v112, 48, v152
	s_waitcnt lgkmcnt(0)
	v_lshl_add_u64 v[80:81], s[14:15], 0, v[112:113]
	v_lshl_add_u64 v[82:83], v[80:81], 2, s[12:13]
	s_nop 0
	v_lshlrev_b64 v[80:81], 11, v[80:81]
	v_lshl_add_u64 v[80:81], s[10:11], 0, v[80:81]
	v_lshl_add_u64 v[88:89], v[146:147], 1, v[80:81]
	s_nop 0
	s_nop 0
	s_waitcnt vmcnt(7)
	v_fmac_f32_e32 v115, 0x3a800000, v253
	v_mul_f32_e32 v90, 0x4f800000, v115
	v_cmp_gt_f32_e32 vcc, s2, v115
	v_and_b32_e32 v91, 0xffff0000, v242
	v_lshlrev_b32_e32 v92, 16, v244
	v_cndmask_b32_e32 v113, v115, v90, vcc
	v_sqrt_f32_e32 v115, v113
	v_lshlrev_b32_e32 v90, 16, v242
	v_lshlrev_b32_e32 v80, 16, v243
	v_and_b32_e32 v81, 0xffff0000, v243
	v_add_u32_e32 v118, -1, v115
	v_add_u32_e32 v119, 1, v115
	v_fma_f32 v120, -v118, v115, v113
	v_fma_f32 v121, -v119, v115, v113
	v_cmp_ge_f32_e64 s[0:1], 0, v120
	v_and_b32_e32 v93, 0xffff0000, v244
	v_lshlrev_b32_e32 v82, 16, v245
	v_cndmask_b32_e64 v115, v115, v118, s[0:1]
	v_cmp_lt_f32_e64 s[0:1], 0, v121
	v_and_b32_e32 v83, 0xffff0000, v245
	v_lshlrev_b32_e32 v94, 16, v246
	v_cndmask_b32_e64 v115, v115, v119, s[0:1]
	v_mul_f32_e32 v118, 0x37800000, v115
	v_cndmask_b32_e32 v115, v115, v118, vcc
	v_cmp_class_f32_e32 vcc, v113, v114
	v_and_b32_e32 v95, 0xffff0000, v246
	v_lshlrev_b32_e32 v84, 16, v247
	v_cndmask_b32_e32 v113, v115, v113, vcc
	v_div_scale_f32 v114, s[0:1], v113, v113, 1.0
	v_rcp_f32_e32 v115, v114
	v_div_scale_f32 v118, vcc, 1.0, v113, 1.0
	v_and_b32_e32 v85, 0xffff0000, v247
	v_fma_f32 v119, -v114, v115, 1.0
	v_fmac_f32_e32 v115, v119, v115
	v_mul_f32_e32 v119, v118, v115
	v_fma_f32 v120, -v114, v119, v118
	v_fmac_f32_e32 v119, v120, v115
	v_fma_f32 v114, -v114, v119, v118
	v_div_fmas_f32 v114, v114, v115, v119
	v_div_fixup_f32 v114, v114, v113, 1.0
	v_lshlrev_b32_e32 v116, 16, v248
	v_and_b32_e32 v117, 0xffff0000, v248
	v_lshlrev_b32_e32 v86, 16, v249
	v_and_b32_e32 v87, 0xffff0000, v249
	v_or_b32_e32 v254, 144, v152
	v_mov_b32_e32 v255, 0
	v_lshl_add_u64 v[254:255], s[14:15], 0, v[254:255]
	v_lshlrev_b64 v[248:249], 11, v[254:255]
	v_lshl_add_u64 v[248:249], s[10:11], 0, v[248:249]
	v_lshl_add_u64 v[248:249], v[146:147], 1, v[248:249]
	v_lshl_add_u64 v[254:255], v[254:255], 2, s[12:13]
	global_load_dword v253, v[254:255], off sc1
	global_load_dwordx4 v[242:245], v[248:249], off
	global_load_dwordx4 v[246:249], v[248:249], off offset:256
	v_pk_mul_f32 v[76:77], v[76:77], v[114:115] op_sel_hi:[1,0]
	v_pk_mul_f32 v[78:79], v[78:79], v[114:115] op_sel_hi:[1,0]
	v_pk_mul_f32 v[72:73], v[72:73], v[114:115] op_sel_hi:[1,0]
	v_pk_mul_f32 v[74:75], v[74:75], v[114:115] op_sel_hi:[1,0]
	v_pk_mul_f32 v[68:69], v[68:69], v[114:115] op_sel_hi:[1,0]
	v_pk_mul_f32 v[70:71], v[70:71], v[114:115] op_sel_hi:[1,0]
	v_pk_mul_f32 v[64:65], v[64:65], v[114:115] op_sel_hi:[1,0]
	v_pk_mul_f32 v[66:67], v[66:67], v[114:115] op_sel_hi:[1,0]
	v_pk_fma_f32 v[78:79], v[106:107], v[78:79], v[80:81]
	v_pk_fma_f32 v[76:77], v[104:105], v[76:77], v[90:91]
	v_pk_fma_f32 v[74:75], v[102:103], v[74:75], v[82:83]
	v_pk_fma_f32 v[72:73], v[100:101], v[72:73], v[92:93]
	v_pk_fma_f32 v[70:71], v[110:111], v[70:71], v[84:85]
	v_pk_fma_f32 v[68:69], v[108:109], v[68:69], v[94:95]
	v_pk_fma_f32 v[80:81], v[98:99], v[66:67], v[86:87]
	v_pk_fma_f32 v[82:83], v[96:97], v[64:65], v[116:117]
	v_cvt_pk_bf16_f32 v64, v76, v77
	v_cvt_pk_bf16_f32 v65, v78, v79
	v_mul_f32_e32 v66, v77, v77
	v_mul_f32_e32 v67, v79, v79
	v_mul_f32_e32 v77, v73, v73
	v_mul_f32_e32 v79, v75, v75
	v_mul_f32_e32 v84, v69, v69
	v_mul_f32_e32 v85, v71, v71
	v_mul_f32_e32 v86, v83, v83
	v_mul_f32_e32 v87, v81, v81
	v_fmac_f32_e32 v66, v76, v76
	v_fmac_f32_e32 v67, v78, v78
	v_fmac_f32_e32 v77, v72, v72
	v_fmac_f32_e32 v79, v74, v74
	v_fmac_f32_e32 v84, v68, v68
	v_fmac_f32_e32 v85, v70, v70
	v_fmac_f32_e32 v86, v82, v82
	v_fmac_f32_e32 v87, v80, v80
	v_add_f32_e32 v66, v66, v67
	v_add_f32_e32 v67, v77, v79
	v_add_f32_e32 v76, v84, v85
	v_add_f32_e32 v77, v86, v87
	v_add_f32_e32 v66, v66, v67
	v_add_f32_e32 v67, v76, v77
	v_add_f32_e32 v76, v66, v67
	ds_bpermute_b32 v77, v150, v76
	v_cvt_pk_bf16_f32 v66, v72, v73
	v_cvt_pk_bf16_f32 v67, v74, v75
	global_store_dwordx4 v[88:89], v[64:67], off
	s_waitcnt lgkmcnt(0)
	s_nop 0
	v_add_f32_e32 v64, v76, v77
	ds_bpermute_b32 v65, v151, v64
	v_cvt_pk_bf16_f32 v66, v68, v69
	v_cvt_pk_bf16_f32 v67, v70, v71
	v_cvt_pk_bf16_f32 v68, v82, v83
	v_cvt_pk_bf16_f32 v69, v80, v81
	global_store_dwordx4 v[88:89], v[66:69], off offset:256
	s_and_saveexec_b64 s[0:1], s[4:5]
	s_cbranch_execz .LBB0_1210
	v_lshl_add_u32 v66, v112, 4, s22
	s_waitcnt lgkmcnt(0)
	v_add_f32_e32 v64, v64, v65
	ds_write_b32 v66, v64
; DI unsigned pk_bf16(float lo, float hi) { f32x2 v = {lo, hi}; bf16x2_t b = __builtin_convertvector(v, bf16x2_t); return __builtin_bit_cast(unsigned, b); }
; DI float bflo(unsigned w) { return __uint_as_float(w << 16); }
; DI float bfhi(unsigned w) { return __uint_as_float(w & 0xffff0000u); }
;     __device__ __forceinline__ void fused(f32x4 (&acc)[2][2][4][2], const pg8::Unit& u, int wr, int wc, int fr, int fq, PG8_LAS unsigned char* lds, int wid, int lane) const {
;     ...
;             for (int m = 0; m < 4; ++m) {
;                 const int rl = ai * 128 + wr * 64 + m * 16 + fr; const size_t row = (size_t)u.pm * 256 + rl;
;                 const float rm = 1.f / sqrtf(__hip_atomic_load(ssqm + row, __ATOMIC_RELAXED, __HIP_MEMORY_SCOPE_AGENT) * (1.f / DM) + RMS_EPS);
;                 float sh = 0.f;
; #pragma unroll
;                 for (int bj = 0; bj < 2; ++bj) {
;                     const size_t off = row * DM + colb + bj * 128;
;                     f32x4 h0, h1;
;                     if (IN16) { const u32x4 hw = *(const u32x4*)((const bf16_t*)hin + off); h0 = (f32x4){bflo(hw.x), bfhi(hw.x), bflo(hw.y), bfhi(hw.y)}; h1 = (f32x4){bflo(hw.z), bfhi(hw.z), bflo(hw.w), bfhi(hw.w)}; }
;                     else { h0 = *(const f32x4*)((const float*)hin + off); h1 = *(const f32x4*)((const float*)hin + off + 4); }
;                     h0 = h0 + acc[ai][bj][m][0] * rm * gv[bj][0]; h1 = h1 + acc[ai][bj][m][1] * rm * gv[bj][1];
;                     sh += ((h0[0] * h0[0] + h0[1] * h0[1]) + (h0[2] * h0[2] + h0[3] * h0[3])) + ((h1[0] * h1[0] + h1[1] * h1[1]) + (h1[2] * h1[2] + h1[3] * h1[3]));
;                     if (OUT16) { u32x4 w; w.x = pk_bf16(h0[0], h0[1]); w.y = pk_bf16(h0[2], h0[3]); w.z = pk_bf16(h1[0], h1[1]); w.w = pk_bf16(h1[2], h1[3]); *(u32x4*)((bf16_t*)hout + off) = w; }
;                     else { *(f32x4*)((float*)hout + off) = h0; *(f32x4*)((float*)hout + off + 4) = h1; }
;                 }
;                 if (ssqh) { sh += __shfl_xor(sh, 16); sh += __shfl_xor(sh, 32); if (fq == 0) red[rl * 4 + wc] = sh; }
.LBB0_1210:
	s_or_b64 exec, exec, s[0:1]
	v_add_u32_e32 v64, 0x80, v152
	s_waitcnt lgkmcnt(0)
	v_mov_b32_e32 v65, 0
	v_lshl_add_u64 v[66:67], s[14:15], 0, v[64:65]
	v_lshl_add_u64 v[68:69], v[66:67], 2, s[12:13]
	s_nop 0
	v_lshlrev_b64 v[66:67], 11, v[66:67]
	v_lshl_add_u64 v[66:67], s[10:11], 0, v[66:67]
	v_lshl_add_u64 v[76:77], v[146:147], 1, v[66:67]
	s_nop 0
	s_nop 0
	v_mov_b32_e32 v67, 0x358637bd
	v_mov_b32_e32 v66, 0x260
	s_waitcnt vmcnt(7)
	v_fmamk_f32 v78, v252, 0x3a800000, v67
	v_mul_f32_e32 v79, 0x4f800000, v78
	v_cmp_gt_f32_e32 vcc, s2, v78
	v_lshlrev_b32_e32 v80, 16, v236
	v_and_b32_e32 v81, 0xffff0000, v236
	v_cndmask_b32_e32 v86, v78, v79, vcc
	v_sqrt_f32_e32 v87, v86
	v_lshlrev_b32_e32 v78, 16, v234
	v_and_b32_e32 v79, 0xffff0000, v234
	v_lshlrev_b32_e32 v68, 16, v235
	v_add_u32_e32 v88, -1, v87
	v_add_u32_e32 v89, 1, v87
	v_fma_f32 v90, -v88, v87, v86
	v_fma_f32 v91, -v89, v87, v86
	v_cmp_ge_f32_e64 s[0:1], 0, v90
	v_and_b32_e32 v69, 0xffff0000, v235
	v_lshlrev_b32_e32 v70, 16, v237
	v_cndmask_b32_e64 v87, v87, v88, s[0:1]
	v_cmp_lt_f32_e64 s[0:1], 0, v91
	v_and_b32_e32 v71, 0xffff0000, v237
	v_lshlrev_b32_e32 v82, 16, v238
	v_cndmask_b32_e64 v87, v87, v89, s[0:1]
	v_mul_f32_e32 v88, 0x37800000, v87
	v_cndmask_b32_e32 v87, v87, v88, vcc
	v_cmp_class_f32_e32 vcc, v86, v66
	v_and_b32_e32 v83, 0xffff0000, v238
	v_lshlrev_b32_e32 v72, 16, v239
	v_cndmask_b32_e32 v86, v87, v86, vcc
	v_div_scale_f32 v87, s[0:1], v86, v86, 1.0
	v_rcp_f32_e32 v88, v87
	v_div_scale_f32 v89, vcc, 1.0, v86, 1.0
	v_and_b32_e32 v73, 0xffff0000, v239
	v_fma_f32 v90, -v87, v88, 1.0
	v_fmac_f32_e32 v88, v90, v88
	v_mul_f32_e32 v90, v89, v88
	v_fma_f32 v91, -v87, v90, v89
	v_fmac_f32_e32 v90, v91, v88
	v_fma_f32 v87, -v87, v90, v89
	v_div_fmas_f32 v87, v87, v88, v90
	v_div_fixup_f32 v86, v87, v86, 1.0
	v_lshlrev_b32_e32 v84, 16, v240
	v_and_b32_e32 v85, 0xffff0000, v240
	v_lshlrev_b32_e32 v74, 16, v241
	v_and_b32_e32 v75, 0xffff0000, v241
	v_or_b32_e32 v254, 160, v152
	v_mov_b32_e32 v255, 0
	v_lshl_add_u64 v[254:255], s[14:15], 0, v[254:255]
	v_lshlrev_b64 v[240:241], 11, v[254:255]
	v_lshl_add_u64 v[240:241], s[10:11], 0, v[240:241]
	v_lshl_add_u64 v[240:241], v[146:147], 1, v[240:241]
	v_lshl_add_u64 v[254:255], v[254:255], 2, s[12:13]
	global_load_dword v252, v[254:255], off sc1
	global_load_dwordx4 v[234:237], v[240:241], off
	global_load_dwordx4 v[238:241], v[240:241], off offset:256
	v_pk_mul_f32 v[60:61], v[60:61], v[86:87] op_sel_hi:[1,0]
	v_pk_mul_f32 v[62:63], v[62:63], v[86:87] op_sel_hi:[1,0]
	v_pk_mul_f32 v[56:57], v[56:57], v[86:87] op_sel_hi:[1,0]
	v_pk_mul_f32 v[58:59], v[58:59], v[86:87] op_sel_hi:[1,0]
	v_pk_mul_f32 v[52:53], v[52:53], v[86:87] op_sel_hi:[1,0]
	v_pk_mul_f32 v[54:55], v[54:55], v[86:87] op_sel_hi:[1,0]
	v_pk_mul_f32 v[48:49], v[48:49], v[86:87] op_sel_hi:[1,0]
	v_pk_mul_f32 v[50:51], v[50:51], v[86:87] op_sel_hi:[1,0]
	v_pk_fma_f32 v[62:63], v[106:107], v[62:63], v[68:69]
	v_pk_fma_f32 v[60:61], v[104:105], v[60:61], v[78:79]
	v_pk_fma_f32 v[58:59], v[102:103], v[58:59], v[70:71]
	v_pk_fma_f32 v[56:57], v[100:101], v[56:57], v[80:81]
	v_pk_fma_f32 v[54:55], v[110:111], v[54:55], v[72:73]
	v_pk_fma_f32 v[52:53], v[108:109], v[52:53], v[82:83]
	v_pk_fma_f32 v[68:69], v[98:99], v[50:51], v[74:75]
	v_pk_fma_f32 v[70:71], v[96:97], v[48:49], v[84:85]
	v_cvt_pk_bf16_f32 v48, v60, v61
	v_cvt_pk_bf16_f32 v49, v62, v63
	v_mul_f32_e32 v50, v61, v61
	v_mul_f32_e32 v51, v63, v63
	v_mul_f32_e32 v61, v57, v57
	v_mul_f32_e32 v63, v59, v59
	v_mul_f32_e32 v72, v53, v53
	v_mul_f32_e32 v73, v55, v55
	v_mul_f32_e32 v74, v71, v71
	v_mul_f32_e32 v75, v69, v69
	v_fmac_f32_e32 v50, v60, v60
	v_fmac_f32_e32 v51, v62, v62
	v_fmac_f32_e32 v61, v56, v56
	v_fmac_f32_e32 v63, v58, v58
	v_fmac_f32_e32 v72, v52, v52
	v_fmac_f32_e32 v73, v54, v54
	v_fmac_f32_e32 v74, v70, v70
	v_fmac_f32_e32 v75, v68, v68
	v_add_f32_e32 v50, v50, v51
	v_add_f32_e32 v51, v61, v63
	v_add_f32_e32 v60, v72, v73
	v_add_f32_e32 v61, v74, v75
	v_add_f32_e32 v50, v50, v51
	v_add_f32_e32 v51, v60, v61
	v_add_f32_e32 v60, v50, v51
	ds_bpermute_b32 v61, v150, v60
	v_cvt_pk_bf16_f32 v50, v56, v57
	v_cvt_pk_bf16_f32 v51, v58, v59
	global_store_dwordx4 v[76:77], v[48:51], off
	s_waitcnt lgkmcnt(0)
	s_nop 0
	v_add_f32_e32 v48, v60, v61
	ds_bpermute_b32 v49, v151, v48
	v_cvt_pk_bf16_f32 v50, v52, v53
	v_cvt_pk_bf16_f32 v51, v54, v55
	v_cvt_pk_bf16_f32 v52, v70, v71
	v_cvt_pk_bf16_f32 v53, v68, v69
	global_store_dwordx4 v[76:77], v[50:53], off offset:256
	s_and_saveexec_b64 s[0:1], s[4:5]
	s_cbranch_execz .LBB0_1212
	v_lshl_add_u32 v50, v64, 4, s22
	s_waitcnt lgkmcnt(0)
	v_add_f32_e32 v48, v48, v49
	ds_write_b32 v50, v48
; DI unsigned pk_bf16(float lo, float hi) { f32x2 v = {lo, hi}; bf16x2_t b = __builtin_convertvector(v, bf16x2_t); return __builtin_bit_cast(unsigned, b); }
; DI float bflo(unsigned w) { return __uint_as_float(w << 16); }
; DI float bfhi(unsigned w) { return __uint_as_float(w & 0xffff0000u); }
;     __device__ __forceinline__ void fused(f32x4 (&acc)[2][2][4][2], const pg8::Unit& u, int wr, int wc, int fr, int fq, PG8_LAS unsigned char* lds, int wid, int lane) const {
;     ...
;             for (int m = 0; m < 4; ++m) {
;                 const int rl = ai * 128 + wr * 64 + m * 16 + fr; const size_t row = (size_t)u.pm * 256 + rl;
;                 const float rm = 1.f / sqrtf(__hip_atomic_load(ssqm + row, __ATOMIC_RELAXED, __HIP_MEMORY_SCOPE_AGENT) * (1.f / DM) + RMS_EPS);
;                 float sh = 0.f;
; #pragma unroll
;                 for (int bj = 0; bj < 2; ++bj) {
;                     const size_t off = row * DM + colb + bj * 128;
;                     f32x4 h0, h1;
;                     if (IN16) { const u32x4 hw = *(const u32x4*)((const bf16_t*)hin + off); h0 = (f32x4){bflo(hw.x), bfhi(hw.x), bflo(hw.y), bfhi(hw.y)}; h1 = (f32x4){bflo(hw.z), bfhi(hw.z), bflo(hw.w), bfhi(hw.w)}; }
;                     else { h0 = *(const f32x4*)((const float*)hin + off); h1 = *(const f32x4*)((const float*)hin + off + 4); }
;                     h0 = h0 + acc[ai][bj][m][0] * rm * gv[bj][0]; h1 = h1 + acc[ai][bj][m][1] * rm * gv[bj][1];
;                     sh += ((h0[0] * h0[0] + h0[1] * h0[1]) + (h0[2] * h0[2] + h0[3] * h0[3])) + ((h1[0] * h1[0] + h1[1] * h1[1]) + (h1[2] * h1[2] + h1[3] * h1[3]));
;                     if (OUT16) { u32x4 w; w.x = pk_bf16(h0[0], h0[1]); w.y = pk_bf16(h0[2], h0[3]); w.z = pk_bf16(h1[0], h1[1]); w.w = pk_bf16(h1[2], h1[3]); *(u32x4*)((bf16_t*)hout + off) = w; }
;                     else { *(f32x4*)((float*)hout + off) = h0; *(f32x4*)((float*)hout + off + 4) = h1; }
;                 }
;                 if (ssqh) { sh += __shfl_xor(sh, 16); sh += __shfl_xor(sh, 32); if (fq == 0) red[rl * 4 + wc] = sh; }
.LBB0_1212:
	s_or_b64 exec, exec, s[0:1]
	v_add_u32_e32 v64, 0x90, v152
	s_waitcnt lgkmcnt(0)
	v_lshl_add_u64 v[48:49], s[14:15], 0, v[64:65]
	v_lshl_add_u64 v[50:51], v[48:49], 2, s[12:13]
	s_nop 0
	v_lshlrev_b64 v[48:49], 11, v[48:49]
	v_lshl_add_u64 v[48:49], s[10:11], 0, v[48:49]
	v_lshl_add_u64 v[56:57], v[146:147], 1, v[48:49]
	s_nop 0
	s_nop 0
	s_waitcnt vmcnt(7)
	v_fmac_f32_e32 v67, 0x3a800000, v253
	v_mul_f32_e32 v58, 0x4f800000, v67
	v_cmp_gt_f32_e32 vcc, s2, v67
	v_and_b32_e32 v59, 0xffff0000, v242
	v_lshlrev_b32_e32 v60, 16, v244
	v_cndmask_b32_e32 v65, v67, v58, vcc
	v_sqrt_f32_e32 v67, v65
	v_lshlrev_b32_e32 v58, 16, v242
	v_lshlrev_b32_e32 v48, 16, v243
	v_and_b32_e32 v49, 0xffff0000, v243
	v_add_u32_e32 v70, -1, v67
	v_add_u32_e32 v71, 1, v67
	v_fma_f32 v72, -v70, v67, v65
	v_fma_f32 v73, -v71, v67, v65
	v_cmp_ge_f32_e64 s[0:1], 0, v72
	v_and_b32_e32 v61, 0xffff0000, v244
	v_lshlrev_b32_e32 v50, 16, v245
	v_cndmask_b32_e64 v67, v67, v70, s[0:1]
	v_cmp_lt_f32_e64 s[0:1], 0, v73
	v_and_b32_e32 v51, 0xffff0000, v245
	v_lshlrev_b32_e32 v62, 16, v246
	v_cndmask_b32_e64 v67, v67, v71, s[0:1]
	v_mul_f32_e32 v70, 0x37800000, v67
	v_cndmask_b32_e32 v67, v67, v70, vcc
	v_cmp_class_f32_e32 vcc, v65, v66
	v_and_b32_e32 v63, 0xffff0000, v246
	v_lshlrev_b32_e32 v52, 16, v247
	v_cndmask_b32_e32 v65, v67, v65, vcc
	v_div_scale_f32 v66, s[0:1], v65, v65, 1.0
	v_rcp_f32_e32 v67, v66
	v_div_scale_f32 v70, vcc, 1.0, v65, 1.0
	v_and_b32_e32 v53, 0xffff0000, v247
	v_fma_f32 v71, -v66, v67, 1.0
	v_fmac_f32_e32 v67, v71, v67
	v_mul_f32_e32 v71, v70, v67
	v_fma_f32 v72, -v66, v71, v70
	v_fmac_f32_e32 v71, v72, v67
	v_fma_f32 v66, -v66, v71, v70
	v_div_fmas_f32 v66, v66, v67, v71
	v_div_fixup_f32 v66, v66, v65, 1.0
	v_lshlrev_b32_e32 v68, 16, v248
	v_and_b32_e32 v69, 0xffff0000, v248
	v_lshlrev_b32_e32 v54, 16, v249
	v_and_b32_e32 v55, 0xffff0000, v249
	v_or_b32_e32 v254, 176, v152
	v_mov_b32_e32 v255, 0
	v_lshl_add_u64 v[254:255], s[14:15], 0, v[254:255]
	v_lshlrev_b64 v[248:249], 11, v[254:255]
	v_lshl_add_u64 v[248:249], s[10:11], 0, v[248:249]
	v_lshl_add_u64 v[248:249], v[146:147], 1, v[248:249]
	v_lshl_add_u64 v[254:255], v[254:255], 2, s[12:13]
	global_load_dword v253, v[254:255], off sc1
	global_load_dwordx4 v[242:245], v[248:249], off
	global_load_dwordx4 v[246:249], v[248:249], off offset:256
	v_pk_mul_f32 v[44:45], v[44:45], v[66:67] op_sel_hi:[1,0]
	v_pk_mul_f32 v[46:47], v[46:47], v[66:67] op_sel_hi:[1,0]
	v_pk_mul_f32 v[40:41], v[40:41], v[66:67] op_sel_hi:[1,0]
	v_pk_mul_f32 v[42:43], v[42:43], v[66:67] op_sel_hi:[1,0]
	v_pk_mul_f32 v[36:37], v[36:37], v[66:67] op_sel_hi:[1,0]
	v_pk_mul_f32 v[38:39], v[38:39], v[66:67] op_sel_hi:[1,0]
	v_pk_mul_f32 v[32:33], v[32:33], v[66:67] op_sel_hi:[1,0]
	v_pk_mul_f32 v[34:35], v[34:35], v[66:67] op_sel_hi:[1,0]
	v_pk_fma_f32 v[46:47], v[106:107], v[46:47], v[48:49]
	v_pk_fma_f32 v[44:45], v[104:105], v[44:45], v[58:59]
	v_pk_fma_f32 v[42:43], v[102:103], v[42:43], v[50:51]
	v_pk_fma_f32 v[40:41], v[100:101], v[40:41], v[60:61]
	v_pk_fma_f32 v[38:39], v[110:111], v[38:39], v[52:53]
	v_pk_fma_f32 v[36:37], v[108:109], v[36:37], v[62:63]
	v_pk_fma_f32 v[48:49], v[98:99], v[34:35], v[54:55]
	v_pk_fma_f32 v[50:51], v[96:97], v[32:33], v[68:69]
	v_cvt_pk_bf16_f32 v32, v44, v45
	v_cvt_pk_bf16_f32 v33, v46, v47
	v_mul_f32_e32 v34, v45, v45
	v_mul_f32_e32 v35, v47, v47
	v_mul_f32_e32 v45, v41, v41
	v_mul_f32_e32 v47, v43, v43
	v_mul_f32_e32 v52, v37, v37
	v_mul_f32_e32 v53, v39, v39
	v_mul_f32_e32 v54, v51, v51
	v_mul_f32_e32 v55, v49, v49
	v_fmac_f32_e32 v34, v44, v44
	v_fmac_f32_e32 v35, v46, v46
	v_fmac_f32_e32 v45, v40, v40
	v_fmac_f32_e32 v47, v42, v42
	v_fmac_f32_e32 v52, v36, v36
	v_fmac_f32_e32 v53, v38, v38
	v_fmac_f32_e32 v54, v50, v50
	v_fmac_f32_e32 v55, v48, v48
	v_add_f32_e32 v34, v34, v35
	v_add_f32_e32 v35, v45, v47
	v_add_f32_e32 v44, v52, v53
	v_add_f32_e32 v45, v54, v55
	v_add_f32_e32 v34, v34, v35
	v_add_f32_e32 v35, v44, v45
	v_add_f32_e32 v44, v34, v35
	ds_bpermute_b32 v45, v150, v44
	v_cvt_pk_bf16_f32 v34, v40, v41
	v_cvt_pk_bf16_f32 v35, v42, v43
	global_store_dwordx4 v[56:57], v[32:35], off
	s_waitcnt lgkmcnt(0)
	s_nop 0
	v_add_f32_e32 v32, v44, v45
	ds_bpermute_b32 v33, v151, v32
	v_cvt_pk_bf16_f32 v34, v36, v37
	v_cvt_pk_bf16_f32 v35, v38, v39
	v_cvt_pk_bf16_f32 v36, v50, v51
	v_cvt_pk_bf16_f32 v37, v48, v49
	global_store_dwordx4 v[56:57], v[34:37], off offset:256
	s_and_saveexec_b64 s[0:1], s[4:5]
	s_cbranch_execz .LBB0_1214
	v_lshl_add_u32 v34, v64, 4, s22
	s_waitcnt lgkmcnt(0)
	v_add_f32_e32 v32, v32, v33
	ds_write_b32 v34, v32
; DI unsigned pk_bf16(float lo, float hi) { f32x2 v = {lo, hi}; bf16x2_t b = __builtin_convertvector(v, bf16x2_t); return __builtin_bit_cast(unsigned, b); }
; DI float bflo(unsigned w) { return __uint_as_float(w << 16); }
; DI float bfhi(unsigned w) { return __uint_as_float(w & 0xffff0000u); }
;     __device__ __forceinline__ void fused(f32x4 (&acc)[2][2][4][2], const pg8::Unit& u, int wr, int wc, int fr, int fq, PG8_LAS unsigned char* lds, int wid, int lane) const {
;     ...
;             for (int m = 0; m < 4; ++m) {
;                 const int rl = ai * 128 + wr * 64 + m * 16 + fr; const size_t row = (size_t)u.pm * 256 + rl;
;                 const float rm = 1.f / sqrtf(__hip_atomic_load(ssqm + row, __ATOMIC_RELAXED, __HIP_MEMORY_SCOPE_AGENT) * (1.f / DM) + RMS_EPS);
;                 float sh = 0.f;
; #pragma unroll
;                 for (int bj = 0; bj < 2; ++bj) {
;                     const size_t off = row * DM + colb + bj * 128;
;                     f32x4 h0, h1;
;                     if (IN16) { const u32x4 hw = *(const u32x4*)((const bf16_t*)hin + off); h0 = (f32x4){bflo(hw.x), bfhi(hw.x), bflo(hw.y), bfhi(hw.y)}; h1 = (f32x4){bflo(hw.z), bfhi(hw.z), bflo(hw.w), bfhi(hw.w)}; }
;                     else { h0 = *(const f32x4*)((const float*)hin + off); h1 = *(const f32x4*)((const float*)hin + off + 4); }
;                     h0 = h0 + acc[ai][bj][m][0] * rm * gv[bj][0]; h1 = h1 + acc[ai][bj][m][1] * rm * gv[bj][1];
;                     sh += ((h0[0] * h0[0] + h0[1] * h0[1]) + (h0[2] * h0[2] + h0[3] * h0[3])) + ((h1[0] * h1[0] + h1[1] * h1[1]) + (h1[2] * h1[2] + h1[3] * h1[3]));
;                     if (OUT16) { u32x4 w; w.x = pk_bf16(h0[0], h0[1]); w.y = pk_bf16(h0[2], h0[3]); w.z = pk_bf16(h1[0], h1[1]); w.w = pk_bf16(h1[2], h1[3]); *(u32x4*)((bf16_t*)hout + off) = w; }
;                     else { *(f32x4*)((float*)hout + off) = h0; *(f32x4*)((float*)hout + off + 4) = h1; }
;                 }
;                 if (ssqh) { sh += __shfl_xor(sh, 16); sh += __shfl_xor(sh, 32); if (fq == 0) red[rl * 4 + wc] = sh; }
.LBB0_1214:
	s_or_b64 exec, exec, s[0:1]
	v_add_u32_e32 v32, 0xa0, v152
	s_waitcnt lgkmcnt(0)
	v_mov_b32_e32 v33, 0
	v_lshl_add_u64 v[34:35], s[14:15], 0, v[32:33]
	v_lshl_add_u64 v[36:37], v[34:35], 2, s[12:13]
	s_nop 0
	v_lshlrev_b64 v[34:35], 11, v[34:35]
	v_lshl_add_u64 v[34:35], s[10:11], 0, v[34:35]
	v_lshl_add_u64 v[44:45], v[146:147], 1, v[34:35]
	s_nop 0
	s_nop 0
	v_mov_b32_e32 v35, 0x358637bd
	v_mov_b32_e32 v34, 0x260
	s_waitcnt vmcnt(7)
	v_fmamk_f32 v46, v252, 0x3a800000, v35
	v_mul_f32_e32 v47, 0x4f800000, v46
	v_cmp_gt_f32_e32 vcc, s2, v46
	v_lshlrev_b32_e32 v48, 16, v236
	v_and_b32_e32 v49, 0xffff0000, v236
	v_cndmask_b32_e32 v54, v46, v47, vcc
	v_sqrt_f32_e32 v55, v54
	v_lshlrev_b32_e32 v46, 16, v234
	v_and_b32_e32 v47, 0xffff0000, v234
	v_lshlrev_b32_e32 v36, 16, v235
	v_add_u32_e32 v56, -1, v55
	v_add_u32_e32 v57, 1, v55
	v_fma_f32 v58, -v56, v55, v54
	v_fma_f32 v59, -v57, v55, v54
	v_cmp_ge_f32_e64 s[0:1], 0, v58
	v_and_b32_e32 v37, 0xffff0000, v235
	v_lshlrev_b32_e32 v38, 16, v237
	v_cndmask_b32_e64 v55, v55, v56, s[0:1]
	v_cmp_lt_f32_e64 s[0:1], 0, v59
	v_and_b32_e32 v39, 0xffff0000, v237
	v_lshlrev_b32_e32 v50, 16, v238
	v_cndmask_b32_e64 v55, v55, v57, s[0:1]
	v_mul_f32_e32 v56, 0x37800000, v55
	v_cndmask_b32_e32 v55, v55, v56, vcc
	v_cmp_class_f32_e32 vcc, v54, v34
	v_and_b32_e32 v51, 0xffff0000, v238
	v_lshlrev_b32_e32 v40, 16, v239
	v_cndmask_b32_e32 v54, v55, v54, vcc
	v_div_scale_f32 v55, s[0:1], v54, v54, 1.0
	v_rcp_f32_e32 v56, v55
	v_div_scale_f32 v57, vcc, 1.0, v54, 1.0
	v_and_b32_e32 v41, 0xffff0000, v239
	v_fma_f32 v58, -v55, v56, 1.0
	v_fmac_f32_e32 v56, v58, v56
	v_mul_f32_e32 v58, v57, v56
	v_fma_f32 v59, -v55, v58, v57
	v_fmac_f32_e32 v58, v59, v56
	v_fma_f32 v55, -v55, v58, v57
	v_div_fmas_f32 v55, v55, v56, v58
	v_div_fixup_f32 v54, v55, v54, 1.0
	v_lshlrev_b32_e32 v52, 16, v240
	v_and_b32_e32 v53, 0xffff0000, v240
	v_lshlrev_b32_e32 v42, 16, v241
	v_and_b32_e32 v43, 0xffff0000, v241
	v_pk_mul_f32 v[28:29], v[28:29], v[54:55] op_sel_hi:[1,0]
	v_pk_mul_f32 v[30:31], v[30:31], v[54:55] op_sel_hi:[1,0]
	v_pk_mul_f32 v[24:25], v[24:25], v[54:55] op_sel_hi:[1,0]
	v_pk_mul_f32 v[26:27], v[26:27], v[54:55] op_sel_hi:[1,0]
	v_pk_mul_f32 v[20:21], v[20:21], v[54:55] op_sel_hi:[1,0]
	v_pk_mul_f32 v[22:23], v[22:23], v[54:55] op_sel_hi:[1,0]
	v_pk_mul_f32 v[16:17], v[16:17], v[54:55] op_sel_hi:[1,0]
	v_pk_mul_f32 v[18:19], v[18:19], v[54:55] op_sel_hi:[1,0]
	v_pk_fma_f32 v[30:31], v[106:107], v[30:31], v[36:37]
	v_pk_fma_f32 v[28:29], v[104:105], v[28:29], v[46:47]
	v_pk_fma_f32 v[26:27], v[102:103], v[26:27], v[38:39]
	v_pk_fma_f32 v[24:25], v[100:101], v[24:25], v[48:49]
	v_pk_fma_f32 v[22:23], v[110:111], v[22:23], v[40:41]
	v_pk_fma_f32 v[20:21], v[108:109], v[20:21], v[50:51]
	v_pk_fma_f32 v[36:37], v[98:99], v[18:19], v[42:43]
	v_pk_fma_f32 v[38:39], v[96:97], v[16:17], v[52:53]
	v_cvt_pk_bf16_f32 v16, v28, v29
	v_cvt_pk_bf16_f32 v17, v30, v31
	v_mul_f32_e32 v18, v29, v29
	v_mul_f32_e32 v19, v31, v31
	v_mul_f32_e32 v29, v25, v25
	v_mul_f32_e32 v31, v27, v27
	v_mul_f32_e32 v40, v21, v21
	v_mul_f32_e32 v41, v23, v23
	v_mul_f32_e32 v42, v39, v39
	v_mul_f32_e32 v43, v37, v37
	v_fmac_f32_e32 v18, v28, v28
	v_fmac_f32_e32 v19, v30, v30
	v_fmac_f32_e32 v29, v24, v24
	v_fmac_f32_e32 v31, v26, v26
	v_fmac_f32_e32 v40, v20, v20
	v_fmac_f32_e32 v41, v22, v22
	v_fmac_f32_e32 v42, v38, v38
	v_fmac_f32_e32 v43, v36, v36
	v_add_f32_e32 v18, v18, v19
	v_add_f32_e32 v19, v29, v31
	v_add_f32_e32 v28, v40, v41
	v_add_f32_e32 v29, v42, v43
	v_add_f32_e32 v18, v18, v19
	v_add_f32_e32 v19, v28, v29
	v_add_f32_e32 v28, v18, v19
	ds_bpermute_b32 v29, v150, v28
	v_cvt_pk_bf16_f32 v18, v24, v25
	v_cvt_pk_bf16_f32 v19, v26, v27
	global_store_dwordx4 v[44:45], v[16:19], off
	s_waitcnt lgkmcnt(0)
	s_nop 0
	v_add_f32_e32 v16, v28, v29
	ds_bpermute_b32 v17, v151, v16
	v_cvt_pk_bf16_f32 v18, v20, v21
	v_cvt_pk_bf16_f32 v19, v22, v23
	v_cvt_pk_bf16_f32 v20, v38, v39
	v_cvt_pk_bf16_f32 v21, v36, v37
	global_store_dwordx4 v[44:45], v[18:21], off offset:256
	s_and_saveexec_b64 s[0:1], s[4:5]
	s_cbranch_execz .LBB0_1216
	v_lshl_add_u32 v18, v32, 4, s22
	s_waitcnt lgkmcnt(0)
	v_add_f32_e32 v16, v16, v17
	ds_write_b32 v18, v16
; DI unsigned pk_bf16(float lo, float hi) { f32x2 v = {lo, hi}; bf16x2_t b = __builtin_convertvector(v, bf16x2_t); return __builtin_bit_cast(unsigned, b); }
; DI float bflo(unsigned w) { return __uint_as_float(w << 16); }
; DI float bfhi(unsigned w) { return __uint_as_float(w & 0xffff0000u); }
;     __device__ __forceinline__ void fused(f32x4 (&acc)[2][2][4][2], const pg8::Unit& u, int wr, int wc, int fr, int fq, PG8_LAS unsigned char* lds, int wid, int lane) const {
;     ...
;             for (int m = 0; m < 4; ++m) {
;                 const int rl = ai * 128 + wr * 64 + m * 16 + fr; const size_t row = (size_t)u.pm * 256 + rl;
;                 const float rm = 1.f / sqrtf(__hip_atomic_load(ssqm + row, __ATOMIC_RELAXED, __HIP_MEMORY_SCOPE_AGENT) * (1.f / DM) + RMS_EPS);
;                 float sh = 0.f;
; #pragma unroll
;                 for (int bj = 0; bj < 2; ++bj) {
;                     const size_t off = row * DM + colb + bj * 128;
;                     f32x4 h0, h1;
;                     if (IN16) { const u32x4 hw = *(const u32x4*)((const bf16_t*)hin + off); h0 = (f32x4){bflo(hw.x), bfhi(hw.x), bflo(hw.y), bfhi(hw.y)}; h1 = (f32x4){bflo(hw.z), bfhi(hw.z), bflo(hw.w), bfhi(hw.w)}; }
;                     else { h0 = *(const f32x4*)((const float*)hin + off); h1 = *(const f32x4*)((const float*)hin + off + 4); }
;                     h0 = h0 + acc[ai][bj][m][0] * rm * gv[bj][0]; h1 = h1 + acc[ai][bj][m][1] * rm * gv[bj][1];
;                     sh += ((h0[0] * h0[0] + h0[1] * h0[1]) + (h0[2] * h0[2] + h0[3] * h0[3])) + ((h1[0] * h1[0] + h1[1] * h1[1]) + (h1[2] * h1[2] + h1[3] * h1[3]));
;                     if (OUT16) { u32x4 w; w.x = pk_bf16(h0[0], h0[1]); w.y = pk_bf16(h0[2], h0[3]); w.z = pk_bf16(h1[0], h1[1]); w.w = pk_bf16(h1[2], h1[3]); *(u32x4*)((bf16_t*)hout + off) = w; }
;                     else { *(f32x4*)((float*)hout + off) = h0; *(f32x4*)((float*)hout + off + 4) = h1; }
;                 }
;                 if (ssqh) { sh += __shfl_xor(sh, 16); sh += __shfl_xor(sh, 32); if (fq == 0) red[rl * 4 + wc] = sh; }
.LBB0_1216:
	s_or_b64 exec, exec, s[0:1]
	v_add_u32_e32 v32, 0xb0, v152
	s_waitcnt lgkmcnt(0)
	v_lshl_add_u64 v[16:17], s[14:15], 0, v[32:33]
	v_lshl_add_u64 v[18:19], v[16:17], 2, s[12:13]
	s_nop 0
	v_lshlrev_b64 v[16:17], 11, v[16:17]
	v_lshl_add_u64 v[16:17], s[10:11], 0, v[16:17]
	v_lshl_add_u64 v[24:25], v[146:147], 1, v[16:17]
	s_nop 0
	s_nop 0
	s_waitcnt vmcnt(4)
	v_fmac_f32_e32 v35, 0x3a800000, v253
	v_mul_f32_e32 v26, 0x4f800000, v35
	v_cmp_gt_f32_e32 vcc, s2, v35
	v_and_b32_e32 v27, 0xffff0000, v242
	v_lshlrev_b32_e32 v28, 16, v244
	v_cndmask_b32_e32 v33, v35, v26, vcc
	v_sqrt_f32_e32 v35, v33
	v_lshlrev_b32_e32 v26, 16, v242
	v_lshlrev_b32_e32 v16, 16, v243
	v_and_b32_e32 v17, 0xffff0000, v243
	v_add_u32_e32 v38, -1, v35
	v_add_u32_e32 v39, 1, v35
	v_fma_f32 v40, -v38, v35, v33
	v_fma_f32 v41, -v39, v35, v33
	v_cmp_ge_f32_e64 s[0:1], 0, v40
	v_and_b32_e32 v29, 0xffff0000, v244
	v_lshlrev_b32_e32 v18, 16, v245
	v_cndmask_b32_e64 v35, v35, v38, s[0:1]
	v_cmp_lt_f32_e64 s[0:1], 0, v41
	v_and_b32_e32 v19, 0xffff0000, v245
	v_lshlrev_b32_e32 v30, 16, v246
	v_cndmask_b32_e64 v35, v35, v39, s[0:1]
	v_mul_f32_e32 v38, 0x37800000, v35
	v_cndmask_b32_e32 v35, v35, v38, vcc
	v_cmp_class_f32_e32 vcc, v33, v34
	v_and_b32_e32 v31, 0xffff0000, v246
	v_lshlrev_b32_e32 v20, 16, v247
	v_cndmask_b32_e32 v33, v35, v33, vcc
	v_div_scale_f32 v34, s[0:1], v33, v33, 1.0
	v_rcp_f32_e32 v35, v34
	v_div_scale_f32 v38, vcc, 1.0, v33, 1.0
	v_and_b32_e32 v21, 0xffff0000, v247
	v_fma_f32 v39, -v34, v35, 1.0
	v_fmac_f32_e32 v35, v39, v35
	v_mul_f32_e32 v39, v38, v35
	v_fma_f32 v40, -v34, v39, v38
	v_fmac_f32_e32 v39, v40, v35
	v_fma_f32 v34, -v34, v39, v38
	v_div_fmas_f32 v34, v34, v35, v39
	v_div_fixup_f32 v34, v34, v33, 1.0
	v_lshlrev_b32_e32 v36, 16, v248
	v_and_b32_e32 v37, 0xffff0000, v248
	v_lshlrev_b32_e32 v22, 16, v249
	v_and_b32_e32 v23, 0xffff0000, v249
	v_pk_mul_f32 v[12:13], v[12:13], v[34:35] op_sel_hi:[1,0]
	v_pk_mul_f32 v[14:15], v[14:15], v[34:35] op_sel_hi:[1,0]
	v_pk_mul_f32 v[8:9], v[8:9], v[34:35] op_sel_hi:[1,0]
	v_pk_mul_f32 v[10:11], v[10:11], v[34:35] op_sel_hi:[1,0]
	v_pk_mul_f32 v[4:5], v[4:5], v[34:35] op_sel_hi:[1,0]
	v_pk_mul_f32 v[6:7], v[6:7], v[34:35] op_sel_hi:[1,0]
	v_pk_mul_f32 v[0:1], v[0:1], v[34:35] op_sel_hi:[1,0]
	v_pk_mul_f32 v[2:3], v[2:3], v[34:35] op_sel_hi:[1,0]
	v_pk_fma_f32 v[14:15], v[106:107], v[14:15], v[16:17]
	v_pk_fma_f32 v[12:13], v[104:105], v[12:13], v[26:27]
	v_pk_fma_f32 v[10:11], v[102:103], v[10:11], v[18:19]
	v_pk_fma_f32 v[8:9], v[100:101], v[8:9], v[28:29]
	v_pk_fma_f32 v[6:7], v[110:111], v[6:7], v[20:21]
	v_pk_fma_f32 v[4:5], v[108:109], v[4:5], v[30:31]
	v_pk_fma_f32 v[16:17], v[98:99], v[2:3], v[22:23]
	v_pk_fma_f32 v[18:19], v[96:97], v[0:1], v[36:37]
	v_cvt_pk_bf16_f32 v0, v12, v13
	v_cvt_pk_bf16_f32 v1, v14, v15
	v_mul_f32_e32 v2, v13, v13
	v_mul_f32_e32 v3, v15, v15
	v_mul_f32_e32 v13, v9, v9
	v_mul_f32_e32 v15, v11, v11
	v_mul_f32_e32 v20, v5, v5
	v_mul_f32_e32 v21, v7, v7
	v_mul_f32_e32 v22, v19, v19
	v_mul_f32_e32 v23, v17, v17
	v_fmac_f32_e32 v2, v12, v12
	v_fmac_f32_e32 v3, v14, v14
	v_fmac_f32_e32 v13, v8, v8
	v_fmac_f32_e32 v15, v10, v10
	v_fmac_f32_e32 v20, v4, v4
	v_fmac_f32_e32 v21, v6, v6
	v_fmac_f32_e32 v22, v18, v18
	v_fmac_f32_e32 v23, v16, v16
	v_add_f32_e32 v2, v2, v3
	v_add_f32_e32 v3, v13, v15
	v_add_f32_e32 v12, v20, v21
	v_add_f32_e32 v13, v22, v23
	v_add_f32_e32 v2, v2, v3
	v_add_f32_e32 v3, v12, v13
	v_add_f32_e32 v12, v2, v3
	ds_bpermute_b32 v13, v150, v12
	v_cvt_pk_bf16_f32 v2, v8, v9
	v_cvt_pk_bf16_f32 v3, v10, v11
	global_store_dwordx4 v[24:25], v[0:3], off
	s_waitcnt lgkmcnt(0)
	s_nop 0
	v_add_f32_e32 v0, v12, v13
	ds_bpermute_b32 v1, v151, v0
	v_cvt_pk_bf16_f32 v2, v4, v5
	v_cvt_pk_bf16_f32 v3, v6, v7
	v_cvt_pk_bf16_f32 v4, v18, v19
	v_cvt_pk_bf16_f32 v5, v16, v17
	global_store_dwordx4 v[24:25], v[2:5], off offset:256
	s_and_saveexec_b64 s[0:1], s[4:5]
	s_cbranch_execz .LBB0_1218
	v_lshl_add_u32 v2, v32, 4, s22
	s_waitcnt lgkmcnt(0)
	v_add_f32_e32 v0, v0, v1
	ds_write_b32 v2, v0

; DI unsigned pk_bf16(float lo, float hi) { f32x2 v = {lo, hi}; bf16x2_t b = __builtin_convertvector(v, bf16x2_t); return __builtin_bit_cast(unsigned, b); }
; DI float bflo(unsigned w) { return __uint_as_float(w << 16); }
; DI float bfhi(unsigned w) { return __uint_as_float(w & 0xffff0000u); }
;     __device__ __forceinline__ void fused(f32x4 (&acc)[2][2][4][2], const pg8::Unit& u, int wr, int wc, int fr, int fq, PG8_LAS unsigned char* lds, int wid, int lane) const {
;     ...
;         const int colb = u.pn * 256 + wc * 32 + 8 * fq;
;         f32x4 gv[2][2];
; #pragma unroll
;         for (int bj = 0; bj < 2; ++bj)
; #pragma unroll
;             for (int n = 0; n < 2; ++n) gv[bj][n] = *(const f32x4*)(gA + colb + bj * 128 + 4 * n);
; #pragma unroll
;         for (int ai = 0; ai < 2; ++ai)
; #pragma unroll
;             for (int m = 0; m < 4; ++m) {
;                 const int rl = ai * 128 + wr * 64 + m * 16 + fr; const size_t row = (size_t)u.pm * 256 + rl;
;                 const float rm = 1.f / sqrtf(__hip_atomic_load(ssqm + row, __ATOMIC_RELAXED, __HIP_MEMORY_SCOPE_AGENT) * (1.f / DM) + RMS_EPS);
;                 float sh = 0.f;
; #pragma unroll
;                 for (int bj = 0; bj < 2; ++bj) {
;                     const size_t off = row * DM + colb + bj * 128;
;                     f32x4 h0, h1;
;                     if (IN16) { const u32x4 hw = *(const u32x4*)((const bf16_t*)hin + off); h0 = (f32x4){bflo(hw.x), bfhi(hw.x), bflo(hw.y), bfhi(hw.y)}; h1 = (f32x4){bflo(hw.z), bfhi(hw.z), bflo(hw.w), bfhi(hw.w)}; }
;                     else { h0 = *(const f32x4*)((const float*)hin + off); h1 = *(const f32x4*)((const float*)hin + off + 4); }
;                     h0 = h0 + acc[ai][bj][m][0] * rm * gv[bj][0]; h1 = h1 + acc[ai][bj][m][1] * rm * gv[bj][1];
;                     sh += ((h0[0] * h0[0] + h0[1] * h0[1]) + (h0[2] * h0[2] + h0[3] * h0[3])) + ((h1[0] * h1[0] + h1[1] * h1[1]) + (h1[2] * h1[2] + h1[3] * h1[3]));
;                     if (OUT16) { u32x4 w; w.x = pk_bf16(h0[0], h0[1]); w.y = pk_bf16(h0[2], h0[3]); w.z = pk_bf16(h1[0], h1[1]); w.w = pk_bf16(h1[2], h1[3]); *(u32x4*)((bf16_t*)hout + off) = w; }
;                     else { *(f32x4*)((float*)hout + off) = h0; *(f32x4*)((float*)hout + off + 4) = h1; }
;                 }
;                 if (ssqh) { sh += __shfl_xor(sh, 16); sh += __shfl_xor(sh, 32); if (fq == 0) red[rl * 4 + wc] = sh; }
.LBB0_1393:
	s_or_b64 exec, exec, s[2:3]
	s_lshl_b32 s1, s1, 5
	s_lshl_b32 s0, s0, 8
	s_or_b32 s0, s0, s1
	v_mov_b32_e32 v159, 0
	v_or_b32_e32 v156, s0, v160
	s_lshl_b64 s[18:19], s[16:17], 8
	v_mov_b32_e32 v153, v159
	v_ashrrev_i32_e32 v157, 31, v156
	v_lshl_add_u64 v[164:165], s[18:19], 0, v[152:153]
	v_lshl_add_u64 v[108:109], v[156:157], 2, s[14:15]
	v_lshl_add_u64 v[166:167], v[164:165], 2, s[12:13]
	s_barrier
	global_load_dwordx4 v[100:103], v[108:109], off offset:16
	global_load_dwordx4 v[104:107], v[108:109], off
	global_load_dwordx4 v[96:99], v[108:109], off offset:528
	s_nop 0
	global_load_dwordx4 v[108:111], v[108:109], off offset:512
	v_lshlrev_b64 v[164:165], 11, v[164:165]
	v_or_b32_e32 v254, 0, v152
	v_mov_b32_e32 v255, 0
	v_lshl_add_u64 v[254:255], s[18:19], 0, v[254:255]
	v_lshlrev_b64 v[240:241], 11, v[254:255]
	v_lshl_add_u64 v[240:241], s[10:11], 0, v[240:241]
	v_lshl_add_u64 v[240:241], v[156:157], 1, v[240:241]
	v_lshl_add_u64 v[254:255], v[254:255], 2, s[12:13]
	global_load_dword v252, v[254:255], off sc1
	global_load_dwordx4 v[234:237], v[240:241], off
	global_load_dwordx4 v[238:241], v[240:241], off offset:256
	v_or_b32_e32 v254, 16, v152
	v_mov_b32_e32 v255, 0
	v_lshl_add_u64 v[254:255], s[18:19], 0, v[254:255]
	v_lshlrev_b64 v[248:249], 11, v[254:255]
	v_lshl_add_u64 v[248:249], s[10:11], 0, v[248:249]
	v_lshl_add_u64 v[248:249], v[156:157], 1, v[248:249]
	v_lshl_add_u64 v[254:255], v[254:255], 2, s[12:13]
	global_load_dword v253, v[254:255], off sc1
	global_load_dwordx4 v[242:245], v[248:249], off
	global_load_dwordx4 v[246:249], v[248:249], off offset:256
	s_nop 0
	v_lshl_add_u64 v[164:165], s[10:11], 0, v[164:165]
	v_lshl_add_u64 v[172:173], v[156:157], 1, v[164:165]
	s_nop 0
	s_nop 0
	v_mov_b32_e32 v153, 0x358637bd
	s_mov_b32 s2, 0xf800000
	v_mov_b32_e32 v151, 0x260
	s_waitcnt vmcnt(3)
	v_fmamk_f32 v158, v252, 0x3a800000, v153
	v_mul_f32_e32 v180, 0x4f800000, v158
	v_cmp_gt_f32_e32 vcc, s2, v158
	v_lshlrev_b32_e32 v174, 16, v234
	v_and_b32_e32 v175, 0xffff0000, v234
	v_cndmask_b32_e32 v158, v158, v180, vcc
	v_sqrt_f32_e32 v182, v158
	v_lshlrev_b32_e32 v164, 16, v235
	v_and_b32_e32 v165, 0xffff0000, v235
	v_lshlrev_b32_e32 v176, 16, v236
	v_add_u32_e32 v183, -1, v182
	v_add_u32_e32 v184, 1, v182
	v_fma_f32 v185, -v183, v182, v158
	v_fma_f32 v186, -v184, v182, v158
	v_cmp_ge_f32_e64 s[0:1], 0, v185
	v_and_b32_e32 v177, 0xffff0000, v236
	v_lshlrev_b32_e32 v166, 16, v237
	v_cndmask_b32_e64 v182, v182, v183, s[0:1]
	v_cmp_lt_f32_e64 s[0:1], 0, v186
	v_and_b32_e32 v167, 0xffff0000, v237
	v_lshlrev_b32_e32 v178, 16, v238
	v_cndmask_b32_e64 v182, v182, v184, s[0:1]
	v_mul_f32_e32 v183, 0x37800000, v182
	v_cndmask_b32_e32 v182, v182, v183, vcc
	v_cmp_class_f32_e32 vcc, v158, v151
	v_and_b32_e32 v179, 0xffff0000, v238
	v_lshlrev_b32_e32 v168, 16, v239
	v_cndmask_b32_e32 v158, v182, v158, vcc
	v_div_scale_f32 v182, s[0:1], v158, v158, 1.0
	v_rcp_f32_e32 v183, v182
	v_div_scale_f32 v184, vcc, 1.0, v158, 1.0
	v_and_b32_e32 v169, 0xffff0000, v239
	v_fma_f32 v185, -v182, v183, 1.0
	v_fmac_f32_e32 v183, v185, v183
	v_mul_f32_e32 v185, v184, v183
	v_fma_f32 v186, -v182, v185, v184
	v_fmac_f32_e32 v185, v186, v183
	v_fma_f32 v182, -v182, v185, v184
	v_div_fmas_f32 v182, v182, v183, v185
	v_div_fixup_f32 v158, v182, v158, 1.0
	v_lshlrev_b32_e32 v180, 16, v240
	v_and_b32_e32 v181, 0xffff0000, v240
	v_lshlrev_b32_e32 v170, 16, v241
	v_and_b32_e32 v171, 0xffff0000, v241
	v_or_b32_e32 v254, 32, v152
	v_mov_b32_e32 v255, 0
	v_lshl_add_u64 v[254:255], s[18:19], 0, v[254:255]
	v_lshlrev_b64 v[240:241], 11, v[254:255]
	v_lshl_add_u64 v[240:241], s[10:11], 0, v[240:241]
	v_lshl_add_u64 v[240:241], v[156:157], 1, v[240:241]
	v_lshl_add_u64 v[254:255], v[254:255], 2, s[12:13]
	global_load_dword v252, v[254:255], off sc1
	global_load_dwordx4 v[234:237], v[240:241], off
	global_load_dwordx4 v[238:241], v[240:241], off offset:256
	v_pk_mul_f32 v[140:141], v[140:141], v[158:159] op_sel_hi:[1,0]
	v_pk_mul_f32 v[142:143], v[142:143], v[158:159] op_sel_hi:[1,0]
	v_pk_mul_f32 v[136:137], v[136:137], v[158:159] op_sel_hi:[1,0]
	v_pk_mul_f32 v[138:139], v[138:139], v[158:159] op_sel_hi:[1,0]
	v_pk_mul_f32 v[132:133], v[132:133], v[158:159] op_sel_hi:[1,0]
	v_pk_mul_f32 v[134:135], v[134:135], v[158:159] op_sel_hi:[1,0]
	v_pk_mul_f32 v[128:129], v[128:129], v[158:159] op_sel_hi:[1,0]
	v_pk_mul_f32 v[130:131], v[130:131], v[158:159] op_sel_hi:[1,0]
	v_pk_fma_f32 v[142:143], v[106:107], v[142:143], v[164:165]
	v_pk_fma_f32 v[140:141], v[104:105], v[140:141], v[174:175]
	v_pk_fma_f32 v[138:139], v[102:103], v[138:139], v[166:167]
	v_pk_fma_f32 v[136:137], v[100:101], v[136:137], v[176:177]
	v_pk_fma_f32 v[134:135], v[110:111], v[134:135], v[168:169]
	v_pk_fma_f32 v[132:133], v[108:109], v[132:133], v[178:179]
	v_pk_fma_f32 v[164:165], v[98:99], v[130:131], v[170:171]
	v_pk_fma_f32 v[166:167], v[96:97], v[128:129], v[180:181]
	v_cvt_pk_bf16_f32 v128, v140, v141
	v_cvt_pk_bf16_f32 v129, v142, v143
	v_mul_f32_e32 v130, v141, v141
	v_mul_f32_e32 v131, v143, v143
	v_mul_f32_e32 v141, v137, v137
	v_mul_f32_e32 v143, v139, v139
	v_mul_f32_e32 v158, v133, v133
	v_mul_f32_e32 v168, v135, v135
	v_mul_f32_e32 v169, v167, v167
	v_mul_f32_e32 v170, v165, v165
	v_fmac_f32_e32 v130, v140, v140
	v_fmac_f32_e32 v131, v142, v142
	v_fmac_f32_e32 v141, v136, v136
	v_fmac_f32_e32 v143, v138, v138
	v_fmac_f32_e32 v158, v132, v132
	v_fmac_f32_e32 v168, v134, v134
	v_fmac_f32_e32 v169, v166, v166
	v_fmac_f32_e32 v170, v164, v164
	v_add_f32_e32 v130, v130, v131
	v_add_f32_e32 v131, v141, v143
	v_add_f32_e32 v140, v158, v168
	v_add_f32_e32 v141, v169, v170
	v_add_f32_e32 v130, v130, v131
	v_add_f32_e32 v131, v140, v141
	v_add_f32_e32 v140, v130, v131
	ds_bpermute_b32 v141, v145, v140
	v_cvt_pk_bf16_f32 v130, v136, v137
	v_cvt_pk_bf16_f32 v131, v138, v139
	global_store_dwordx4 v[172:173], v[128:131], off
	s_waitcnt lgkmcnt(0)
	s_nop 0
	v_add_f32_e32 v128, v140, v141
	ds_bpermute_b32 v129, v147, v128
	v_cvt_pk_bf16_f32 v130, v132, v133
	v_cvt_pk_bf16_f32 v131, v134, v135
	v_cvt_pk_bf16_f32 v132, v166, v167
	v_cvt_pk_bf16_f32 v133, v164, v165
	global_store_dwordx4 v[172:173], v[130:133], off offset:256
	s_and_saveexec_b64 s[0:1], s[4:5]
	s_cbranch_execz .LBB0_1395
	v_lshl_add_u32 v130, v152, 4, s24
	s_waitcnt lgkmcnt(0)
	v_add_f32_e32 v128, v128, v129
	ds_write_b32 v130, v128
; DI unsigned pk_bf16(float lo, float hi) { f32x2 v = {lo, hi}; bf16x2_t b = __builtin_convertvector(v, bf16x2_t); return __builtin_bit_cast(unsigned, b); }
; DI float bflo(unsigned w) { return __uint_as_float(w << 16); }
; DI float bfhi(unsigned w) { return __uint_as_float(w & 0xffff0000u); }
;     __device__ __forceinline__ void fused(f32x4 (&acc)[2][2][4][2], const pg8::Unit& u, int wr, int wc, int fr, int fq, PG8_LAS unsigned char* lds, int wid, int lane) const {
;     ...
;             for (int m = 0; m < 4; ++m) {
;                 const int rl = ai * 128 + wr * 64 + m * 16 + fr; const size_t row = (size_t)u.pm * 256 + rl;
;                 const float rm = 1.f / sqrtf(__hip_atomic_load(ssqm + row, __ATOMIC_RELAXED, __HIP_MEMORY_SCOPE_AGENT) * (1.f / DM) + RMS_EPS);
;                 float sh = 0.f;
; #pragma unroll
;                 for (int bj = 0; bj < 2; ++bj) {
;                     const size_t off = row * DM + colb + bj * 128;
;                     f32x4 h0, h1;
;                     if (IN16) { const u32x4 hw = *(const u32x4*)((const bf16_t*)hin + off); h0 = (f32x4){bflo(hw.x), bfhi(hw.x), bflo(hw.y), bfhi(hw.y)}; h1 = (f32x4){bflo(hw.z), bfhi(hw.z), bflo(hw.w), bfhi(hw.w)}; }
;                     else { h0 = *(const f32x4*)((const float*)hin + off); h1 = *(const f32x4*)((const float*)hin + off + 4); }
;                     h0 = h0 + acc[ai][bj][m][0] * rm * gv[bj][0]; h1 = h1 + acc[ai][bj][m][1] * rm * gv[bj][1];
;                     sh += ((h0[0] * h0[0] + h0[1] * h0[1]) + (h0[2] * h0[2] + h0[3] * h0[3])) + ((h1[0] * h1[0] + h1[1] * h1[1]) + (h1[2] * h1[2] + h1[3] * h1[3]));
;                     if (OUT16) { u32x4 w; w.x = pk_bf16(h0[0], h0[1]); w.y = pk_bf16(h0[2], h0[3]); w.z = pk_bf16(h1[0], h1[1]); w.w = pk_bf16(h1[2], h1[3]); *(u32x4*)((bf16_t*)hout + off) = w; }
;                     else { *(f32x4*)((float*)hout + off) = h0; *(f32x4*)((float*)hout + off + 4) = h1; }
;                 }
;                 if (ssqh) { sh += __shfl_xor(sh, 16); sh += __shfl_xor(sh, 32); if (fq == 0) red[rl * 4 + wc] = sh; }
.LBB0_1395:
	s_or_b64 exec, exec, s[0:1]
	v_or_b32_e32 v158, 16, v152
	s_waitcnt lgkmcnt(0)
	v_lshl_add_u64 v[128:129], s[18:19], 0, v[158:159]
	v_lshl_add_u64 v[130:131], v[128:129], 2, s[12:13]
	s_nop 0
	v_lshlrev_b64 v[128:129], 11, v[128:129]
	v_lshl_add_u64 v[128:129], s[10:11], 0, v[128:129]
	v_lshl_add_u64 v[136:137], v[156:157], 1, v[128:129]
	s_nop 0
	s_nop 0
	s_waitcnt vmcnt(5)
	v_fmac_f32_e32 v153, 0x3a800000, v253
	v_mul_f32_e32 v138, 0x4f800000, v153
	v_cmp_gt_f32_e32 vcc, s2, v153
	v_and_b32_e32 v139, 0xffff0000, v242
	v_lshlrev_b32_e32 v140, 16, v244
	v_cndmask_b32_e32 v153, v153, v138, vcc
	v_sqrt_f32_e32 v159, v153
	v_lshlrev_b32_e32 v138, 16, v242
	v_lshlrev_b32_e32 v128, 16, v243
	v_and_b32_e32 v129, 0xffff0000, v243
	v_add_u32_e32 v166, -1, v159
	v_add_u32_e32 v167, 1, v159
	v_fma_f32 v168, -v166, v159, v153
	v_fma_f32 v169, -v167, v159, v153
	v_cmp_ge_f32_e64 s[0:1], 0, v168
	v_and_b32_e32 v141, 0xffff0000, v244
	v_lshlrev_b32_e32 v130, 16, v245
	v_cndmask_b32_e64 v159, v159, v166, s[0:1]
	v_cmp_lt_f32_e64 s[0:1], 0, v169
	v_and_b32_e32 v131, 0xffff0000, v245
	v_lshlrev_b32_e32 v142, 16, v246
	v_cndmask_b32_e64 v159, v159, v167, s[0:1]
	v_mul_f32_e32 v166, 0x37800000, v159
	v_cndmask_b32_e32 v159, v159, v166, vcc
	v_cmp_class_f32_e32 vcc, v153, v151
	v_and_b32_e32 v143, 0xffff0000, v246
	v_lshlrev_b32_e32 v132, 16, v247
	v_cndmask_b32_e32 v151, v159, v153, vcc
	v_div_scale_f32 v153, s[0:1], v151, v151, 1.0
	v_rcp_f32_e32 v159, v153
	v_div_scale_f32 v166, vcc, 1.0, v151, 1.0
	v_and_b32_e32 v133, 0xffff0000, v247
	v_fma_f32 v167, -v153, v159, 1.0
	v_fmac_f32_e32 v159, v167, v159
	v_mul_f32_e32 v167, v166, v159
	v_fma_f32 v168, -v153, v167, v166
	v_fmac_f32_e32 v167, v168, v159
	v_fma_f32 v153, -v153, v167, v166
	v_div_fmas_f32 v153, v153, v159, v167
	v_div_fixup_f32 v166, v153, v151, 1.0
	v_lshlrev_b32_e32 v164, 16, v248
	v_and_b32_e32 v165, 0xffff0000, v248
	v_lshlrev_b32_e32 v134, 16, v249
	v_and_b32_e32 v135, 0xffff0000, v249
	v_or_b32_e32 v254, 48, v152
	v_mov_b32_e32 v255, 0
	v_lshl_add_u64 v[254:255], s[18:19], 0, v[254:255]
	v_lshlrev_b64 v[248:249], 11, v[254:255]
	v_lshl_add_u64 v[248:249], s[10:11], 0, v[248:249]
	v_lshl_add_u64 v[248:249], v[156:157], 1, v[248:249]
	v_lshl_add_u64 v[254:255], v[254:255], 2, s[12:13]
	global_load_dword v253, v[254:255], off sc1
	global_load_dwordx4 v[242:245], v[248:249], off
	global_load_dwordx4 v[246:249], v[248:249], off offset:256
	v_pk_mul_f32 v[124:125], v[124:125], v[166:167] op_sel_hi:[1,0]
	v_pk_mul_f32 v[126:127], v[126:127], v[166:167] op_sel_hi:[1,0]
	v_pk_mul_f32 v[120:121], v[120:121], v[166:167] op_sel_hi:[1,0]
	v_pk_mul_f32 v[122:123], v[122:123], v[166:167] op_sel_hi:[1,0]
	v_pk_mul_f32 v[116:117], v[116:117], v[166:167] op_sel_hi:[1,0]
	v_pk_mul_f32 v[118:119], v[118:119], v[166:167] op_sel_hi:[1,0]
	v_pk_mul_f32 v[112:113], v[112:113], v[166:167] op_sel_hi:[1,0]
	v_pk_mul_f32 v[114:115], v[114:115], v[166:167] op_sel_hi:[1,0]
	v_pk_fma_f32 v[126:127], v[106:107], v[126:127], v[128:129]
	v_pk_fma_f32 v[124:125], v[104:105], v[124:125], v[138:139]
	v_pk_fma_f32 v[122:123], v[102:103], v[122:123], v[130:131]
	v_pk_fma_f32 v[120:121], v[100:101], v[120:121], v[140:141]
	v_pk_fma_f32 v[118:119], v[110:111], v[118:119], v[132:133]
	v_pk_fma_f32 v[116:117], v[108:109], v[116:117], v[142:143]
	v_pk_fma_f32 v[128:129], v[98:99], v[114:115], v[134:135]
	v_pk_fma_f32 v[130:131], v[96:97], v[112:113], v[164:165]
	v_cvt_pk_bf16_f32 v112, v124, v125
	v_cvt_pk_bf16_f32 v113, v126, v127
	v_mul_f32_e32 v114, v125, v125
	v_mul_f32_e32 v115, v127, v127
	v_mul_f32_e32 v125, v121, v121
	v_mul_f32_e32 v127, v123, v123
	v_mul_f32_e32 v132, v117, v117
	v_mul_f32_e32 v133, v119, v119
	v_mul_f32_e32 v134, v131, v131
	v_mul_f32_e32 v135, v129, v129
	v_fmac_f32_e32 v114, v124, v124
	v_fmac_f32_e32 v115, v126, v126
	v_fmac_f32_e32 v125, v120, v120
	v_fmac_f32_e32 v127, v122, v122
	v_fmac_f32_e32 v132, v116, v116
	v_fmac_f32_e32 v133, v118, v118
	v_fmac_f32_e32 v134, v130, v130
	v_fmac_f32_e32 v135, v128, v128
	v_add_f32_e32 v114, v114, v115
	v_add_f32_e32 v115, v125, v127
	v_add_f32_e32 v124, v132, v133
	v_add_f32_e32 v125, v134, v135
	v_add_f32_e32 v114, v114, v115
	v_add_f32_e32 v115, v124, v125
	v_add_f32_e32 v124, v114, v115
	ds_bpermute_b32 v125, v145, v124
	v_cvt_pk_bf16_f32 v114, v120, v121
	v_cvt_pk_bf16_f32 v115, v122, v123
	global_store_dwordx4 v[136:137], v[112:115], off
	s_waitcnt lgkmcnt(0)
	s_nop 0
	v_add_f32_e32 v112, v124, v125
	ds_bpermute_b32 v113, v147, v112
	v_cvt_pk_bf16_f32 v114, v116, v117
	v_cvt_pk_bf16_f32 v115, v118, v119
	v_cvt_pk_bf16_f32 v116, v130, v131
	v_cvt_pk_bf16_f32 v117, v128, v129
	global_store_dwordx4 v[136:137], v[114:117], off offset:256
	s_and_saveexec_b64 s[0:1], s[4:5]
	s_cbranch_execz .LBB0_1397
	v_lshl_add_u32 v114, v158, 4, s24
	s_waitcnt lgkmcnt(0)
	v_add_f32_e32 v112, v112, v113
	ds_write_b32 v114, v112
; DI unsigned pk_bf16(float lo, float hi) { f32x2 v = {lo, hi}; bf16x2_t b = __builtin_convertvector(v, bf16x2_t); return __builtin_bit_cast(unsigned, b); }
; DI float bflo(unsigned w) { return __uint_as_float(w << 16); }
; DI float bfhi(unsigned w) { return __uint_as_float(w & 0xffff0000u); }
;     __device__ __forceinline__ void fused(f32x4 (&acc)[2][2][4][2], const pg8::Unit& u, int wr, int wc, int fr, int fq, PG8_LAS unsigned char* lds, int wid, int lane) const {
;     ...
;             for (int m = 0; m < 4; ++m) {
;                 const int rl = ai * 128 + wr * 64 + m * 16 + fr; const size_t row = (size_t)u.pm * 256 + rl;
;                 const float rm = 1.f / sqrtf(__hip_atomic_load(ssqm + row, __ATOMIC_RELAXED, __HIP_MEMORY_SCOPE_AGENT) * (1.f / DM) + RMS_EPS);
;                 float sh = 0.f;
; #pragma unroll
;                 for (int bj = 0; bj < 2; ++bj) {
;                     const size_t off = row * DM + colb + bj * 128;
;                     f32x4 h0, h1;
;                     if (IN16) { const u32x4 hw = *(const u32x4*)((const bf16_t*)hin + off); h0 = (f32x4){bflo(hw.x), bfhi(hw.x), bflo(hw.y), bfhi(hw.y)}; h1 = (f32x4){bflo(hw.z), bfhi(hw.z), bflo(hw.w), bfhi(hw.w)}; }
;                     else { h0 = *(const f32x4*)((const float*)hin + off); h1 = *(const f32x4*)((const float*)hin + off + 4); }
;                     h0 = h0 + acc[ai][bj][m][0] * rm * gv[bj][0]; h1 = h1 + acc[ai][bj][m][1] * rm * gv[bj][1];
;                     sh += ((h0[0] * h0[0] + h0[1] * h0[1]) + (h0[2] * h0[2] + h0[3] * h0[3])) + ((h1[0] * h1[0] + h1[1] * h1[1]) + (h1[2] * h1[2] + h1[3] * h1[3]));
;                     if (OUT16) { u32x4 w; w.x = pk_bf16(h0[0], h0[1]); w.y = pk_bf16(h0[2], h0[3]); w.z = pk_bf16(h1[0], h1[1]); w.w = pk_bf16(h1[2], h1[3]); *(u32x4*)((bf16_t*)hout + off) = w; }
;                     else { *(f32x4*)((float*)hout + off) = h0; *(f32x4*)((float*)hout + off + 4) = h1; }
;                 }
;                 if (ssqh) { sh += __shfl_xor(sh, 16); sh += __shfl_xor(sh, 32); if (fq == 0) red[rl * 4 + wc] = sh; }
.LBB0_1397:
	s_or_b64 exec, exec, s[0:1]
	v_or_b32_e32 v112, 32, v152
	s_waitcnt lgkmcnt(0)
	v_mov_b32_e32 v113, 0
	v_lshl_add_u64 v[114:115], s[18:19], 0, v[112:113]
	v_lshl_add_u64 v[116:117], v[114:115], 2, s[12:13]
	s_nop 0
	v_lshlrev_b64 v[114:115], 11, v[114:115]
	v_lshl_add_u64 v[114:115], s[10:11], 0, v[114:115]
	v_lshl_add_u64 v[124:125], v[156:157], 1, v[114:115]
	s_nop 0
	s_nop 0
	v_mov_b32_e32 v115, 0x358637bd
	v_mov_b32_e32 v114, 0x260
	s_waitcnt vmcnt(7)
	v_fmamk_f32 v126, v252, 0x3a800000, v115
	v_mul_f32_e32 v127, 0x4f800000, v126
	v_cmp_gt_f32_e32 vcc, s2, v126
	v_lshlrev_b32_e32 v128, 16, v236
	v_and_b32_e32 v129, 0xffff0000, v236
	v_cndmask_b32_e32 v134, v126, v127, vcc
	v_sqrt_f32_e32 v135, v134
	v_lshlrev_b32_e32 v126, 16, v234
	v_and_b32_e32 v127, 0xffff0000, v234
	v_lshlrev_b32_e32 v116, 16, v235
	v_add_u32_e32 v136, -1, v135
	v_add_u32_e32 v137, 1, v135
	v_fma_f32 v138, -v136, v135, v134
	v_fma_f32 v139, -v137, v135, v134
	v_cmp_ge_f32_e64 s[0:1], 0, v138
	v_and_b32_e32 v117, 0xffff0000, v235
	v_lshlrev_b32_e32 v118, 16, v237
	v_cndmask_b32_e64 v135, v135, v136, s[0:1]
	v_cmp_lt_f32_e64 s[0:1], 0, v139
	v_and_b32_e32 v119, 0xffff0000, v237
	v_lshlrev_b32_e32 v130, 16, v238
	v_cndmask_b32_e64 v135, v135, v137, s[0:1]
	v_mul_f32_e32 v136, 0x37800000, v135
	v_cndmask_b32_e32 v135, v135, v136, vcc
	v_cmp_class_f32_e32 vcc, v134, v114
	v_and_b32_e32 v131, 0xffff0000, v238
	v_lshlrev_b32_e32 v120, 16, v239
	v_cndmask_b32_e32 v134, v135, v134, vcc
	v_div_scale_f32 v135, s[0:1], v134, v134, 1.0
	v_rcp_f32_e32 v136, v135
	v_div_scale_f32 v137, vcc, 1.0, v134, 1.0
	v_and_b32_e32 v121, 0xffff0000, v239
	v_fma_f32 v138, -v135, v136, 1.0
	v_fmac_f32_e32 v136, v138, v136
	v_mul_f32_e32 v138, v137, v136
	v_fma_f32 v139, -v135, v138, v137
	v_fmac_f32_e32 v138, v139, v136
	v_fma_f32 v135, -v135, v138, v137
	v_div_fmas_f32 v135, v135, v136, v138
	v_div_fixup_f32 v134, v135, v134, 1.0
	v_lshlrev_b32_e32 v132, 16, v240
	v_and_b32_e32 v133, 0xffff0000, v240
	v_lshlrev_b32_e32 v122, 16, v241
	v_and_b32_e32 v123, 0xffff0000, v241
	v_or_b32_e32 v254, 128, v152
	v_mov_b32_e32 v255, 0
	v_lshl_add_u64 v[254:255], s[18:19], 0, v[254:255]
	v_lshlrev_b64 v[240:241], 11, v[254:255]
	v_lshl_add_u64 v[240:241], s[10:11], 0, v[240:241]
	v_lshl_add_u64 v[240:241], v[156:157], 1, v[240:241]
	v_lshl_add_u64 v[254:255], v[254:255], 2, s[12:13]
	global_load_dword v252, v[254:255], off sc1
	global_load_dwordx4 v[234:237], v[240:241], off
	global_load_dwordx4 v[238:241], v[240:241], off offset:256
	v_pk_mul_f32 v[92:93], v[92:93], v[134:135] op_sel_hi:[1,0]
	v_pk_mul_f32 v[94:95], v[94:95], v[134:135] op_sel_hi:[1,0]
	v_pk_mul_f32 v[88:89], v[88:89], v[134:135] op_sel_hi:[1,0]
	v_pk_mul_f32 v[90:91], v[90:91], v[134:135] op_sel_hi:[1,0]
	v_pk_mul_f32 v[84:85], v[84:85], v[134:135] op_sel_hi:[1,0]
	v_pk_mul_f32 v[86:87], v[86:87], v[134:135] op_sel_hi:[1,0]
	v_pk_mul_f32 v[80:81], v[80:81], v[134:135] op_sel_hi:[1,0]
	v_pk_mul_f32 v[82:83], v[82:83], v[134:135] op_sel_hi:[1,0]
	v_pk_fma_f32 v[94:95], v[106:107], v[94:95], v[116:117]
	v_pk_fma_f32 v[92:93], v[104:105], v[92:93], v[126:127]
	v_pk_fma_f32 v[90:91], v[102:103], v[90:91], v[118:119]
	v_pk_fma_f32 v[88:89], v[100:101], v[88:89], v[128:129]
	v_pk_fma_f32 v[86:87], v[110:111], v[86:87], v[120:121]
	v_pk_fma_f32 v[84:85], v[108:109], v[84:85], v[130:131]
	v_pk_fma_f32 v[116:117], v[98:99], v[82:83], v[122:123]
	v_pk_fma_f32 v[118:119], v[96:97], v[80:81], v[132:133]
	v_cvt_pk_bf16_f32 v80, v92, v93
	v_cvt_pk_bf16_f32 v81, v94, v95
	v_mul_f32_e32 v82, v93, v93
	v_mul_f32_e32 v83, v95, v95
	v_mul_f32_e32 v93, v89, v89
	v_mul_f32_e32 v95, v91, v91
	v_mul_f32_e32 v120, v85, v85
	v_mul_f32_e32 v121, v87, v87
	v_mul_f32_e32 v122, v119, v119
	v_mul_f32_e32 v123, v117, v117
	v_fmac_f32_e32 v82, v92, v92
	v_fmac_f32_e32 v83, v94, v94
	v_fmac_f32_e32 v93, v88, v88
	v_fmac_f32_e32 v95, v90, v90
	v_fmac_f32_e32 v120, v84, v84
	v_fmac_f32_e32 v121, v86, v86
	v_fmac_f32_e32 v122, v118, v118
	v_fmac_f32_e32 v123, v116, v116
	v_add_f32_e32 v82, v82, v83
	v_add_f32_e32 v83, v93, v95
	v_add_f32_e32 v92, v120, v121
	v_add_f32_e32 v93, v122, v123
	v_add_f32_e32 v82, v82, v83
	v_add_f32_e32 v83, v92, v93
	v_add_f32_e32 v92, v82, v83
	ds_bpermute_b32 v93, v145, v92
	v_cvt_pk_bf16_f32 v82, v88, v89
	v_cvt_pk_bf16_f32 v83, v90, v91
	global_store_dwordx4 v[124:125], v[80:83], off
	s_waitcnt lgkmcnt(0)
	s_nop 0
	v_add_f32_e32 v80, v92, v93
	ds_bpermute_b32 v81, v147, v80
	v_cvt_pk_bf16_f32 v82, v84, v85
	v_cvt_pk_bf16_f32 v83, v86, v87
	v_cvt_pk_bf16_f32 v84, v118, v119
	v_cvt_pk_bf16_f32 v85, v116, v117
	global_store_dwordx4 v[124:125], v[82:85], off offset:256
	s_and_saveexec_b64 s[0:1], s[4:5]
	s_cbranch_execz .LBB0_1399
	v_lshl_add_u32 v82, v112, 4, s24
	s_waitcnt lgkmcnt(0)
	v_add_f32_e32 v80, v80, v81
	ds_write_b32 v82, v80
; DI unsigned pk_bf16(float lo, float hi) { f32x2 v = {lo, hi}; bf16x2_t b = __builtin_convertvector(v, bf16x2_t); return __builtin_bit_cast(unsigned, b); }
; DI float bflo(unsigned w) { return __uint_as_float(w << 16); }
; DI float bfhi(unsigned w) { return __uint_as_float(w & 0xffff0000u); }
;     __device__ __forceinline__ void fused(f32x4 (&acc)[2][2][4][2], const pg8::Unit& u, int wr, int wc, int fr, int fq, PG8_LAS unsigned char* lds, int wid, int lane) const {
;     ...
;             for (int m = 0; m < 4; ++m) {
;                 const int rl = ai * 128 + wr * 64 + m * 16 + fr; const size_t row = (size_t)u.pm * 256 + rl;
;                 const float rm = 1.f / sqrtf(__hip_atomic_load(ssqm + row, __ATOMIC_RELAXED, __HIP_MEMORY_SCOPE_AGENT) * (1.f / DM) + RMS_EPS);
;                 float sh = 0.f;
; #pragma unroll
;                 for (int bj = 0; bj < 2; ++bj) {
;                     const size_t off = row * DM + colb + bj * 128;
;                     f32x4 h0, h1;
;                     if (IN16) { const u32x4 hw = *(const u32x4*)((const bf16_t*)hin + off); h0 = (f32x4){bflo(hw.x), bfhi(hw.x), bflo(hw.y), bfhi(hw.y)}; h1 = (f32x4){bflo(hw.z), bfhi(hw.z), bflo(hw.w), bfhi(hw.w)}; }
;                     else { h0 = *(const f32x4*)((const float*)hin + off); h1 = *(const f32x4*)((const float*)hin + off + 4); }
;                     h0 = h0 + acc[ai][bj][m][0] * rm * gv[bj][0]; h1 = h1 + acc[ai][bj][m][1] * rm * gv[bj][1];
;                     sh += ((h0[0] * h0[0] + h0[1] * h0[1]) + (h0[2] * h0[2] + h0[3] * h0[3])) + ((h1[0] * h1[0] + h1[1] * h1[1]) + (h1[2] * h1[2] + h1[3] * h1[3]));
;                     if (OUT16) { u32x4 w; w.x = pk_bf16(h0[0], h0[1]); w.y = pk_bf16(h0[2], h0[3]); w.z = pk_bf16(h1[0], h1[1]); w.w = pk_bf16(h1[2], h1[3]); *(u32x4*)((bf16_t*)hout + off) = w; }
;                     else { *(f32x4*)((float*)hout + off) = h0; *(f32x4*)((float*)hout + off + 4) = h1; }
;                 }
;                 if (ssqh) { sh += __shfl_xor(sh, 16); sh += __shfl_xor(sh, 32); if (fq == 0) red[rl * 4 + wc] = sh; }
.LBB0_1399:
	s_or_b64 exec, exec, s[0:1]
	v_or_b32_e32 v112, 48, v152
	s_waitcnt lgkmcnt(0)
	v_lshl_add_u64 v[80:81], s[18:19], 0, v[112:113]
	v_lshl_add_u64 v[82:83], v[80:81], 2, s[12:13]
	s_nop 0
	v_lshlrev_b64 v[80:81], 11, v[80:81]
	v_lshl_add_u64 v[80:81], s[10:11], 0, v[80:81]
	v_lshl_add_u64 v[88:89], v[156:157], 1, v[80:81]
	s_nop 0
	s_nop 0
	s_waitcnt vmcnt(7)
	v_fmac_f32_e32 v115, 0x3a800000, v253
	v_mul_f32_e32 v90, 0x4f800000, v115
	v_cmp_gt_f32_e32 vcc, s2, v115
	v_and_b32_e32 v91, 0xffff0000, v242
	v_lshlrev_b32_e32 v92, 16, v244
	v_cndmask_b32_e32 v113, v115, v90, vcc
	v_sqrt_f32_e32 v115, v113
	v_lshlrev_b32_e32 v90, 16, v242
	v_lshlrev_b32_e32 v80, 16, v243
	v_and_b32_e32 v81, 0xffff0000, v243
	v_add_u32_e32 v118, -1, v115
	v_add_u32_e32 v119, 1, v115
	v_fma_f32 v120, -v118, v115, v113
	v_fma_f32 v121, -v119, v115, v113
	v_cmp_ge_f32_e64 s[0:1], 0, v120
	v_and_b32_e32 v93, 0xffff0000, v244
	v_lshlrev_b32_e32 v82, 16, v245
	v_cndmask_b32_e64 v115, v115, v118, s[0:1]
	v_cmp_lt_f32_e64 s[0:1], 0, v121
	v_and_b32_e32 v83, 0xffff0000, v245
	v_lshlrev_b32_e32 v94, 16, v246
	v_cndmask_b32_e64 v115, v115, v119, s[0:1]
	v_mul_f32_e32 v118, 0x37800000, v115
	v_cndmask_b32_e32 v115, v115, v118, vcc
	v_cmp_class_f32_e32 vcc, v113, v114
	v_and_b32_e32 v95, 0xffff0000, v246
	v_lshlrev_b32_e32 v84, 16, v247
	v_cndmask_b32_e32 v113, v115, v113, vcc
	v_div_scale_f32 v114, s[0:1], v113, v113, 1.0
	v_rcp_f32_e32 v115, v114
	v_div_scale_f32 v118, vcc, 1.0, v113, 1.0
	v_and_b32_e32 v85, 0xffff0000, v247
	v_fma_f32 v119, -v114, v115, 1.0
	v_fmac_f32_e32 v115, v119, v115
	v_mul_f32_e32 v119, v118, v115
	v_fma_f32 v120, -v114, v119, v118
	v_fmac_f32_e32 v119, v120, v115
	v_fma_f32 v114, -v114, v119, v118
	v_div_fmas_f32 v114, v114, v115, v119
	v_div_fixup_f32 v114, v114, v113, 1.0
	v_lshlrev_b32_e32 v116, 16, v248
	v_and_b32_e32 v117, 0xffff0000, v248
	v_lshlrev_b32_e32 v86, 16, v249
	v_and_b32_e32 v87, 0xffff0000, v249
	v_or_b32_e32 v254, 144, v152
	v_mov_b32_e32 v255, 0
	v_lshl_add_u64 v[254:255], s[18:19], 0, v[254:255]
	v_lshlrev_b64 v[248:249], 11, v[254:255]
	v_lshl_add_u64 v[248:249], s[10:11], 0, v[248:249]
	v_lshl_add_u64 v[248:249], v[156:157], 1, v[248:249]
	v_lshl_add_u64 v[254:255], v[254:255], 2, s[12:13]
	global_load_dword v253, v[254:255], off sc1
	global_load_dwordx4 v[242:245], v[248:249], off
	global_load_dwordx4 v[246:249], v[248:249], off offset:256
	v_pk_mul_f32 v[76:77], v[76:77], v[114:115] op_sel_hi:[1,0]
	v_pk_mul_f32 v[78:79], v[78:79], v[114:115] op_sel_hi:[1,0]
	v_pk_mul_f32 v[72:73], v[72:73], v[114:115] op_sel_hi:[1,0]
	v_pk_mul_f32 v[74:75], v[74:75], v[114:115] op_sel_hi:[1,0]
	v_pk_mul_f32 v[68:69], v[68:69], v[114:115] op_sel_hi:[1,0]
	v_pk_mul_f32 v[70:71], v[70:71], v[114:115] op_sel_hi:[1,0]
	v_pk_mul_f32 v[64:65], v[64:65], v[114:115] op_sel_hi:[1,0]
	v_pk_mul_f32 v[66:67], v[66:67], v[114:115] op_sel_hi:[1,0]
	v_pk_fma_f32 v[78:79], v[106:107], v[78:79], v[80:81]
	v_pk_fma_f32 v[76:77], v[104:105], v[76:77], v[90:91]
	v_pk_fma_f32 v[74:75], v[102:103], v[74:75], v[82:83]
	v_pk_fma_f32 v[72:73], v[100:101], v[72:73], v[92:93]
	v_pk_fma_f32 v[70:71], v[110:111], v[70:71], v[84:85]
	v_pk_fma_f32 v[68:69], v[108:109], v[68:69], v[94:95]
	v_pk_fma_f32 v[80:81], v[98:99], v[66:67], v[86:87]
	v_pk_fma_f32 v[82:83], v[96:97], v[64:65], v[116:117]
	v_cvt_pk_bf16_f32 v64, v76, v77
	v_cvt_pk_bf16_f32 v65, v78, v79
	v_mul_f32_e32 v66, v77, v77
	v_mul_f32_e32 v67, v79, v79
	v_mul_f32_e32 v77, v73, v73
	v_mul_f32_e32 v79, v75, v75
	v_mul_f32_e32 v84, v69, v69
	v_mul_f32_e32 v85, v71, v71
	v_mul_f32_e32 v86, v83, v83
	v_mul_f32_e32 v87, v81, v81
	v_fmac_f32_e32 v66, v76, v76
	v_fmac_f32_e32 v67, v78, v78
	v_fmac_f32_e32 v77, v72, v72
	v_fmac_f32_e32 v79, v74, v74
	v_fmac_f32_e32 v84, v68, v68
	v_fmac_f32_e32 v85, v70, v70
	v_fmac_f32_e32 v86, v82, v82
	v_fmac_f32_e32 v87, v80, v80
	v_add_f32_e32 v66, v66, v67
	v_add_f32_e32 v67, v77, v79
	v_add_f32_e32 v76, v84, v85
	v_add_f32_e32 v77, v86, v87
	v_add_f32_e32 v66, v66, v67
	v_add_f32_e32 v67, v76, v77
	v_add_f32_e32 v76, v66, v67
	ds_bpermute_b32 v77, v145, v76
	v_cvt_pk_bf16_f32 v66, v72, v73
	v_cvt_pk_bf16_f32 v67, v74, v75
	global_store_dwordx4 v[88:89], v[64:67], off
	s_waitcnt lgkmcnt(0)
	s_nop 0
	v_add_f32_e32 v64, v76, v77
	ds_bpermute_b32 v65, v147, v64
	v_cvt_pk_bf16_f32 v66, v68, v69
	v_cvt_pk_bf16_f32 v67, v70, v71
	v_cvt_pk_bf16_f32 v68, v82, v83
	v_cvt_pk_bf16_f32 v69, v80, v81
	global_store_dwordx4 v[88:89], v[66:69], off offset:256
	s_and_saveexec_b64 s[0:1], s[4:5]
	s_cbranch_execz .LBB0_1401
	v_lshl_add_u32 v66, v112, 4, s24
	s_waitcnt lgkmcnt(0)
	v_add_f32_e32 v64, v64, v65
	ds_write_b32 v66, v64
; DI unsigned pk_bf16(float lo, float hi) { f32x2 v = {lo, hi}; bf16x2_t b = __builtin_convertvector(v, bf16x2_t); return __builtin_bit_cast(unsigned, b); }
; DI float bflo(unsigned w) { return __uint_as_float(w << 16); }
; DI float bfhi(unsigned w) { return __uint_as_float(w & 0xffff0000u); }
;     __device__ __forceinline__ void fused(f32x4 (&acc)[2][2][4][2], const pg8::Unit& u, int wr, int wc, int fr, int fq, PG8_LAS unsigned char* lds, int wid, int lane) const {
;     ...
;             for (int m = 0; m < 4; ++m) {
;                 const int rl = ai * 128 + wr * 64 + m * 16 + fr; const size_t row = (size_t)u.pm * 256 + rl;
;                 const float rm = 1.f / sqrtf(__hip_atomic_load(ssqm + row, __ATOMIC_RELAXED, __HIP_MEMORY_SCOPE_AGENT) * (1.f / DM) + RMS_EPS);
;                 float sh = 0.f;
; #pragma unroll
;                 for (int bj = 0; bj < 2; ++bj) {
;                     const size_t off = row * DM + colb + bj * 128;
;                     f32x4 h0, h1;
;                     if (IN16) { const u32x4 hw = *(const u32x4*)((const bf16_t*)hin + off); h0 = (f32x4){bflo(hw.x), bfhi(hw.x), bflo(hw.y), bfhi(hw.y)}; h1 = (f32x4){bflo(hw.z), bfhi(hw.z), bflo(hw.w), bfhi(hw.w)}; }
;                     else { h0 = *(const f32x4*)((const float*)hin + off); h1 = *(const f32x4*)((const float*)hin + off + 4); }
;                     h0 = h0 + acc[ai][bj][m][0] * rm * gv[bj][0]; h1 = h1 + acc[ai][bj][m][1] * rm * gv[bj][1];
;                     sh += ((h0[0] * h0[0] + h0[1] * h0[1]) + (h0[2] * h0[2] + h0[3] * h0[3])) + ((h1[0] * h1[0] + h1[1] * h1[1]) + (h1[2] * h1[2] + h1[3] * h1[3]));
;                     if (OUT16) { u32x4 w; w.x = pk_bf16(h0[0], h0[1]); w.y = pk_bf16(h0[2], h0[3]); w.z = pk_bf16(h1[0], h1[1]); w.w = pk_bf16(h1[2], h1[3]); *(u32x4*)((bf16_t*)hout + off) = w; }
;                     else { *(f32x4*)((float*)hout + off) = h0; *(f32x4*)((float*)hout + off + 4) = h1; }
;                 }
;                 if (ssqh) { sh += __shfl_xor(sh, 16); sh += __shfl_xor(sh, 32); if (fq == 0) red[rl * 4 + wc] = sh; }
.LBB0_1401:
	s_or_b64 exec, exec, s[0:1]
	v_add_u32_e32 v64, 0x80, v152
	s_waitcnt lgkmcnt(0)
	v_mov_b32_e32 v65, 0
	v_lshl_add_u64 v[66:67], s[18:19], 0, v[64:65]
	v_lshl_add_u64 v[68:69], v[66:67], 2, s[12:13]
	s_nop 0
	v_lshlrev_b64 v[66:67], 11, v[66:67]
	v_lshl_add_u64 v[66:67], s[10:11], 0, v[66:67]
	v_lshl_add_u64 v[76:77], v[156:157], 1, v[66:67]
	s_nop 0
	s_nop 0
	v_mov_b32_e32 v67, 0x358637bd
	v_mov_b32_e32 v66, 0x260
	s_waitcnt vmcnt(7)
	v_fmamk_f32 v78, v252, 0x3a800000, v67
	v_mul_f32_e32 v79, 0x4f800000, v78
	v_cmp_gt_f32_e32 vcc, s2, v78
	v_lshlrev_b32_e32 v80, 16, v236
	v_and_b32_e32 v81, 0xffff0000, v236
	v_cndmask_b32_e32 v86, v78, v79, vcc
	v_sqrt_f32_e32 v87, v86
	v_lshlrev_b32_e32 v78, 16, v234
	v_and_b32_e32 v79, 0xffff0000, v234
	v_lshlrev_b32_e32 v68, 16, v235
	v_add_u32_e32 v88, -1, v87
	v_add_u32_e32 v89, 1, v87
	v_fma_f32 v90, -v88, v87, v86
	v_fma_f32 v91, -v89, v87, v86
	v_cmp_ge_f32_e64 s[0:1], 0, v90
	v_and_b32_e32 v69, 0xffff0000, v235
	v_lshlrev_b32_e32 v70, 16, v237
	v_cndmask_b32_e64 v87, v87, v88, s[0:1]
	v_cmp_lt_f32_e64 s[0:1], 0, v91
	v_and_b32_e32 v71, 0xffff0000, v237
	v_lshlrev_b32_e32 v82, 16, v238
	v_cndmask_b32_e64 v87, v87, v89, s[0:1]
	v_mul_f32_e32 v88, 0x37800000, v87
	v_cndmask_b32_e32 v87, v87, v88, vcc
	v_cmp_class_f32_e32 vcc, v86, v66
	v_and_b32_e32 v83, 0xffff0000, v238
	v_lshlrev_b32_e32 v72, 16, v239
	v_cndmask_b32_e32 v86, v87, v86, vcc
	v_div_scale_f32 v87, s[0:1], v86, v86, 1.0
	v_rcp_f32_e32 v88, v87
	v_div_scale_f32 v89, vcc, 1.0, v86, 1.0
	v_and_b32_e32 v73, 0xffff0000, v239
	v_fma_f32 v90, -v87, v88, 1.0
	v_fmac_f32_e32 v88, v90, v88
	v_mul_f32_e32 v90, v89, v88
	v_fma_f32 v91, -v87, v90, v89
	v_fmac_f32_e32 v90, v91, v88
	v_fma_f32 v87, -v87, v90, v89
	v_div_fmas_f32 v87, v87, v88, v90
	v_div_fixup_f32 v86, v87, v86, 1.0
	v_lshlrev_b32_e32 v84, 16, v240
	v_and_b32_e32 v85, 0xffff0000, v240
	v_lshlrev_b32_e32 v74, 16, v241
	v_and_b32_e32 v75, 0xffff0000, v241
	v_or_b32_e32 v254, 160, v152
	v_mov_b32_e32 v255, 0
	v_lshl_add_u64 v[254:255], s[18:19], 0, v[254:255]
	v_lshlrev_b64 v[240:241], 11, v[254:255]
	v_lshl_add_u64 v[240:241], s[10:11], 0, v[240:241]
	v_lshl_add_u64 v[240:241], v[156:157], 1, v[240:241]
	v_lshl_add_u64 v[254:255], v[254:255], 2, s[12:13]
	global_load_dword v252, v[254:255], off sc1
	global_load_dwordx4 v[234:237], v[240:241], off
	global_load_dwordx4 v[238:241], v[240:241], off offset:256
	v_pk_mul_f32 v[60:61], v[60:61], v[86:87] op_sel_hi:[1,0]
	v_pk_mul_f32 v[62:63], v[62:63], v[86:87] op_sel_hi:[1,0]
	v_pk_mul_f32 v[56:57], v[56:57], v[86:87] op_sel_hi:[1,0]
	v_pk_mul_f32 v[58:59], v[58:59], v[86:87] op_sel_hi:[1,0]
	v_pk_mul_f32 v[52:53], v[52:53], v[86:87] op_sel_hi:[1,0]
	v_pk_mul_f32 v[54:55], v[54:55], v[86:87] op_sel_hi:[1,0]
	v_pk_mul_f32 v[48:49], v[48:49], v[86:87] op_sel_hi:[1,0]
	v_pk_mul_f32 v[50:51], v[50:51], v[86:87] op_sel_hi:[1,0]
	v_pk_fma_f32 v[62:63], v[106:107], v[62:63], v[68:69]
	v_pk_fma_f32 v[60:61], v[104:105], v[60:61], v[78:79]
	v_pk_fma_f32 v[58:59], v[102:103], v[58:59], v[70:71]
	v_pk_fma_f32 v[56:57], v[100:101], v[56:57], v[80:81]
	v_pk_fma_f32 v[54:55], v[110:111], v[54:55], v[72:73]
	v_pk_fma_f32 v[52:53], v[108:109], v[52:53], v[82:83]
	v_pk_fma_f32 v[68:69], v[98:99], v[50:51], v[74:75]
	v_pk_fma_f32 v[70:71], v[96:97], v[48:49], v[84:85]
	v_cvt_pk_bf16_f32 v48, v60, v61
	v_cvt_pk_bf16_f32 v49, v62, v63
	v_mul_f32_e32 v50, v61, v61
	v_mul_f32_e32 v51, v63, v63
	v_mul_f32_e32 v61, v57, v57
	v_mul_f32_e32 v63, v59, v59
	v_mul_f32_e32 v72, v53, v53
	v_mul_f32_e32 v73, v55, v55
	v_mul_f32_e32 v74, v71, v71
	v_mul_f32_e32 v75, v69, v69
	v_fmac_f32_e32 v50, v60, v60
	v_fmac_f32_e32 v51, v62, v62
	v_fmac_f32_e32 v61, v56, v56
	v_fmac_f32_e32 v63, v58, v58
	v_fmac_f32_e32 v72, v52, v52
	v_fmac_f32_e32 v73, v54, v54
	v_fmac_f32_e32 v74, v70, v70
	v_fmac_f32_e32 v75, v68, v68
	v_add_f32_e32 v50, v50, v51
	v_add_f32_e32 v51, v61, v63
	v_add_f32_e32 v60, v72, v73
	v_add_f32_e32 v61, v74, v75
	v_add_f32_e32 v50, v50, v51
	v_add_f32_e32 v51, v60, v61
	v_add_f32_e32 v60, v50, v51
	ds_bpermute_b32 v61, v145, v60
	v_cvt_pk_bf16_f32 v50, v56, v57
	v_cvt_pk_bf16_f32 v51, v58, v59
	global_store_dwordx4 v[76:77], v[48:51], off
	s_waitcnt lgkmcnt(0)
	s_nop 0
	v_add_f32_e32 v48, v60, v61
	ds_bpermute_b32 v49, v147, v48
	v_cvt_pk_bf16_f32 v50, v52, v53
	v_cvt_pk_bf16_f32 v51, v54, v55
	v_cvt_pk_bf16_f32 v52, v70, v71
	v_cvt_pk_bf16_f32 v53, v68, v69
	global_store_dwordx4 v[76:77], v[50:53], off offset:256
	s_and_saveexec_b64 s[0:1], s[4:5]
	s_cbranch_execz .LBB0_1403
	v_lshl_add_u32 v50, v64, 4, s24
	s_waitcnt lgkmcnt(0)
	v_add_f32_e32 v48, v48, v49
	ds_write_b32 v50, v48
; DI unsigned pk_bf16(float lo, float hi) { f32x2 v = {lo, hi}; bf16x2_t b = __builtin_convertvector(v, bf16x2_t); return __builtin_bit_cast(unsigned, b); }
; DI float bflo(unsigned w) { return __uint_as_float(w << 16); }
; DI float bfhi(unsigned w) { return __uint_as_float(w & 0xffff0000u); }
;     __device__ __forceinline__ void fused(f32x4 (&acc)[2][2][4][2], const pg8::Unit& u, int wr, int wc, int fr, int fq, PG8_LAS unsigned char* lds, int wid, int lane) const {
;     ...
;             for (int m = 0; m < 4; ++m) {
;                 const int rl = ai * 128 + wr * 64 + m * 16 + fr; const size_t row = (size_t)u.pm * 256 + rl;
;                 const float rm = 1.f / sqrtf(__hip_atomic_load(ssqm + row, __ATOMIC_RELAXED, __HIP_MEMORY_SCOPE_AGENT) * (1.f / DM) + RMS_EPS);
;                 float sh = 0.f;
; #pragma unroll
;                 for (int bj = 0; bj < 2; ++bj) {
;                     const size_t off = row * DM + colb + bj * 128;
;                     f32x4 h0, h1;
;                     if (IN16) { const u32x4 hw = *(const u32x4*)((const bf16_t*)hin + off); h0 = (f32x4){bflo(hw.x), bfhi(hw.x), bflo(hw.y), bfhi(hw.y)}; h1 = (f32x4){bflo(hw.z), bfhi(hw.z), bflo(hw.w), bfhi(hw.w)}; }
;                     else { h0 = *(const f32x4*)((const float*)hin + off); h1 = *(const f32x4*)((const float*)hin + off + 4); }
;                     h0 = h0 + acc[ai][bj][m][0] * rm * gv[bj][0]; h1 = h1 + acc[ai][bj][m][1] * rm * gv[bj][1];
;                     sh += ((h0[0] * h0[0] + h0[1] * h0[1]) + (h0[2] * h0[2] + h0[3] * h0[3])) + ((h1[0] * h1[0] + h1[1] * h1[1]) + (h1[2] * h1[2] + h1[3] * h1[3]));
;                     if (OUT16) { u32x4 w; w.x = pk_bf16(h0[0], h0[1]); w.y = pk_bf16(h0[2], h0[3]); w.z = pk_bf16(h1[0], h1[1]); w.w = pk_bf16(h1[2], h1[3]); *(u32x4*)((bf16_t*)hout + off) = w; }
;                     else { *(f32x4*)((float*)hout + off) = h0; *(f32x4*)((float*)hout + off + 4) = h1; }
;                 }
;                 if (ssqh) { sh += __shfl_xor(sh, 16); sh += __shfl_xor(sh, 32); if (fq == 0) red[rl * 4 + wc] = sh; }
.LBB0_1403:
	s_or_b64 exec, exec, s[0:1]
	v_add_u32_e32 v64, 0x90, v152
	s_waitcnt lgkmcnt(0)
	v_lshl_add_u64 v[48:49], s[18:19], 0, v[64:65]
	v_lshl_add_u64 v[50:51], v[48:49], 2, s[12:13]
	s_nop 0
	v_lshlrev_b64 v[48:49], 11, v[48:49]
	v_lshl_add_u64 v[48:49], s[10:11], 0, v[48:49]
	v_lshl_add_u64 v[56:57], v[156:157], 1, v[48:49]
	s_nop 0
	s_nop 0
	s_waitcnt vmcnt(7)
	v_fmac_f32_e32 v67, 0x3a800000, v253
	v_mul_f32_e32 v58, 0x4f800000, v67
	v_cmp_gt_f32_e32 vcc, s2, v67
	v_and_b32_e32 v59, 0xffff0000, v242
	v_lshlrev_b32_e32 v60, 16, v244
	v_cndmask_b32_e32 v65, v67, v58, vcc
	v_sqrt_f32_e32 v67, v65
	v_lshlrev_b32_e32 v58, 16, v242
	v_lshlrev_b32_e32 v48, 16, v243
	v_and_b32_e32 v49, 0xffff0000, v243
	v_add_u32_e32 v70, -1, v67
	v_add_u32_e32 v71, 1, v67
	v_fma_f32 v72, -v70, v67, v65
	v_fma_f32 v73, -v71, v67, v65
	v_cmp_ge_f32_e64 s[0:1], 0, v72
	v_and_b32_e32 v61, 0xffff0000, v244
	v_lshlrev_b32_e32 v50, 16, v245
	v_cndmask_b32_e64 v67, v67, v70, s[0:1]
	v_cmp_lt_f32_e64 s[0:1], 0, v73
	v_and_b32_e32 v51, 0xffff0000, v245
	v_lshlrev_b32_e32 v62, 16, v246
	v_cndmask_b32_e64 v67, v67, v71, s[0:1]
	v_mul_f32_e32 v70, 0x37800000, v67
	v_cndmask_b32_e32 v67, v67, v70, vcc
	v_cmp_class_f32_e32 vcc, v65, v66
	v_and_b32_e32 v63, 0xffff0000, v246
	v_lshlrev_b32_e32 v52, 16, v247
	v_cndmask_b32_e32 v65, v67, v65, vcc
	v_div_scale_f32 v66, s[0:1], v65, v65, 1.0
	v_rcp_f32_e32 v67, v66
	v_div_scale_f32 v70, vcc, 1.0, v65, 1.0
	v_and_b32_e32 v53, 0xffff0000, v247
	v_fma_f32 v71, -v66, v67, 1.0
	v_fmac_f32_e32 v67, v71, v67
	v_mul_f32_e32 v71, v70, v67
	v_fma_f32 v72, -v66, v71, v70
	v_fmac_f32_e32 v71, v72, v67
	v_fma_f32 v66, -v66, v71, v70
	v_div_fmas_f32 v66, v66, v67, v71
	v_div_fixup_f32 v66, v66, v65, 1.0
	v_lshlrev_b32_e32 v68, 16, v248
	v_and_b32_e32 v69, 0xffff0000, v248
	v_lshlrev_b32_e32 v54, 16, v249
	v_and_b32_e32 v55, 0xffff0000, v249
	v_or_b32_e32 v254, 176, v152
	v_mov_b32_e32 v255, 0
	v_lshl_add_u64 v[254:255], s[18:19], 0, v[254:255]
	v_lshlrev_b64 v[248:249], 11, v[254:255]
	v_lshl_add_u64 v[248:249], s[10:11], 0, v[248:249]
	v_lshl_add_u64 v[248:249], v[156:157], 1, v[248:249]
	v_lshl_add_u64 v[254:255], v[254:255], 2, s[12:13]
	global_load_dword v253, v[254:255], off sc1
	global_load_dwordx4 v[242:245], v[248:249], off
	global_load_dwordx4 v[246:249], v[248:249], off offset:256
	v_pk_mul_f32 v[44:45], v[44:45], v[66:67] op_sel_hi:[1,0]
	v_pk_mul_f32 v[46:47], v[46:47], v[66:67] op_sel_hi:[1,0]
	v_pk_mul_f32 v[40:41], v[40:41], v[66:67] op_sel_hi:[1,0]
	v_pk_mul_f32 v[42:43], v[42:43], v[66:67] op_sel_hi:[1,0]
	v_pk_mul_f32 v[36:37], v[36:37], v[66:67] op_sel_hi:[1,0]
	v_pk_mul_f32 v[38:39], v[38:39], v[66:67] op_sel_hi:[1,0]
	v_pk_mul_f32 v[32:33], v[32:33], v[66:67] op_sel_hi:[1,0]
	v_pk_mul_f32 v[34:35], v[34:35], v[66:67] op_sel_hi:[1,0]
	v_pk_fma_f32 v[46:47], v[106:107], v[46:47], v[48:49]
	v_pk_fma_f32 v[44:45], v[104:105], v[44:45], v[58:59]
	v_pk_fma_f32 v[42:43], v[102:103], v[42:43], v[50:51]
	v_pk_fma_f32 v[40:41], v[100:101], v[40:41], v[60:61]
	v_pk_fma_f32 v[38:39], v[110:111], v[38:39], v[52:53]
	v_pk_fma_f32 v[36:37], v[108:109], v[36:37], v[62:63]
	v_pk_fma_f32 v[48:49], v[98:99], v[34:35], v[54:55]
	v_pk_fma_f32 v[50:51], v[96:97], v[32:33], v[68:69]
	v_cvt_pk_bf16_f32 v32, v44, v45
	v_cvt_pk_bf16_f32 v33, v46, v47
	v_mul_f32_e32 v34, v45, v45
	v_mul_f32_e32 v35, v47, v47
	v_mul_f32_e32 v45, v41, v41
	v_mul_f32_e32 v47, v43, v43
	v_mul_f32_e32 v52, v37, v37
	v_mul_f32_e32 v53, v39, v39
	v_mul_f32_e32 v54, v51, v51
	v_mul_f32_e32 v55, v49, v49
	v_fmac_f32_e32 v34, v44, v44
	v_fmac_f32_e32 v35, v46, v46
	v_fmac_f32_e32 v45, v40, v40
	v_fmac_f32_e32 v47, v42, v42
	v_fmac_f32_e32 v52, v36, v36
	v_fmac_f32_e32 v53, v38, v38
	v_fmac_f32_e32 v54, v50, v50
	v_fmac_f32_e32 v55, v48, v48
	v_add_f32_e32 v34, v34, v35
	v_add_f32_e32 v35, v45, v47
	v_add_f32_e32 v44, v52, v53
	v_add_f32_e32 v45, v54, v55
	v_add_f32_e32 v34, v34, v35
	v_add_f32_e32 v35, v44, v45
	v_add_f32_e32 v44, v34, v35
	ds_bpermute_b32 v45, v145, v44
	v_cvt_pk_bf16_f32 v34, v40, v41
	v_cvt_pk_bf16_f32 v35, v42, v43
	global_store_dwordx4 v[56:57], v[32:35], off
	s_waitcnt lgkmcnt(0)
	s_nop 0
	v_add_f32_e32 v32, v44, v45
	ds_bpermute_b32 v33, v147, v32
	v_cvt_pk_bf16_f32 v34, v36, v37
	v_cvt_pk_bf16_f32 v35, v38, v39
	v_cvt_pk_bf16_f32 v36, v50, v51
	v_cvt_pk_bf16_f32 v37, v48, v49
	global_store_dwordx4 v[56:57], v[34:37], off offset:256
	s_and_saveexec_b64 s[0:1], s[4:5]
	s_cbranch_execz .LBB0_1405
	v_lshl_add_u32 v34, v64, 4, s24
	s_waitcnt lgkmcnt(0)
	v_add_f32_e32 v32, v32, v33
	ds_write_b32 v34, v32
; DI unsigned pk_bf16(float lo, float hi) { f32x2 v = {lo, hi}; bf16x2_t b = __builtin_convertvector(v, bf16x2_t); return __builtin_bit_cast(unsigned, b); }
; DI float bflo(unsigned w) { return __uint_as_float(w << 16); }
; DI float bfhi(unsigned w) { return __uint_as_float(w & 0xffff0000u); }
;     __device__ __forceinline__ void fused(f32x4 (&acc)[2][2][4][2], const pg8::Unit& u, int wr, int wc, int fr, int fq, PG8_LAS unsigned char* lds, int wid, int lane) const {
;     ...
;             for (int m = 0; m < 4; ++m) {
;                 const int rl = ai * 128 + wr * 64 + m * 16 + fr; const size_t row = (size_t)u.pm * 256 + rl;
;                 const float rm = 1.f / sqrtf(__hip_atomic_load(ssqm + row, __ATOMIC_RELAXED, __HIP_MEMORY_SCOPE_AGENT) * (1.f / DM) + RMS_EPS);
;                 float sh = 0.f;
; #pragma unroll
;                 for (int bj = 0; bj < 2; ++bj) {
;                     const size_t off = row * DM + colb + bj * 128;
;                     f32x4 h0, h1;
;                     if (IN16) { const u32x4 hw = *(const u32x4*)((const bf16_t*)hin + off); h0 = (f32x4){bflo(hw.x), bfhi(hw.x), bflo(hw.y), bfhi(hw.y)}; h1 = (f32x4){bflo(hw.z), bfhi(hw.z), bflo(hw.w), bfhi(hw.w)}; }
;                     else { h0 = *(const f32x4*)((const float*)hin + off); h1 = *(const f32x4*)((const float*)hin + off + 4); }
;                     h0 = h0 + acc[ai][bj][m][0] * rm * gv[bj][0]; h1 = h1 + acc[ai][bj][m][1] * rm * gv[bj][1];
;                     sh += ((h0[0] * h0[0] + h0[1] * h0[1]) + (h0[2] * h0[2] + h0[3] * h0[3])) + ((h1[0] * h1[0] + h1[1] * h1[1]) + (h1[2] * h1[2] + h1[3] * h1[3]));
;                     if (OUT16) { u32x4 w; w.x = pk_bf16(h0[0], h0[1]); w.y = pk_bf16(h0[2], h0[3]); w.z = pk_bf16(h1[0], h1[1]); w.w = pk_bf16(h1[2], h1[3]); *(u32x4*)((bf16_t*)hout + off) = w; }
;                     else { *(f32x4*)((float*)hout + off) = h0; *(f32x4*)((float*)hout + off + 4) = h1; }
;                 }
;                 if (ssqh) { sh += __shfl_xor(sh, 16); sh += __shfl_xor(sh, 32); if (fq == 0) red[rl * 4 + wc] = sh; }
.LBB0_1405:
	s_or_b64 exec, exec, s[0:1]
	v_add_u32_e32 v32, 0xa0, v152
	s_waitcnt lgkmcnt(0)
	v_mov_b32_e32 v33, 0
	v_lshl_add_u64 v[34:35], s[18:19], 0, v[32:33]
	v_lshl_add_u64 v[36:37], v[34:35], 2, s[12:13]
	s_nop 0
	v_lshlrev_b64 v[34:35], 11, v[34:35]
	v_lshl_add_u64 v[34:35], s[10:11], 0, v[34:35]
	v_lshl_add_u64 v[44:45], v[156:157], 1, v[34:35]
	s_nop 0
	s_nop 0
	v_mov_b32_e32 v35, 0x358637bd
	v_mov_b32_e32 v34, 0x260
	s_waitcnt vmcnt(7)
	v_fmamk_f32 v46, v252, 0x3a800000, v35
	v_mul_f32_e32 v47, 0x4f800000, v46
	v_cmp_gt_f32_e32 vcc, s2, v46
	v_lshlrev_b32_e32 v48, 16, v236
	v_and_b32_e32 v49, 0xffff0000, v236
	v_cndmask_b32_e32 v54, v46, v47, vcc
	v_sqrt_f32_e32 v55, v54
	v_lshlrev_b32_e32 v46, 16, v234
	v_and_b32_e32 v47, 0xffff0000, v234
	v_lshlrev_b32_e32 v36, 16, v235
	v_add_u32_e32 v56, -1, v55
	v_add_u32_e32 v57, 1, v55
	v_fma_f32 v58, -v56, v55, v54
	v_fma_f32 v59, -v57, v55, v54
	v_cmp_ge_f32_e64 s[0:1], 0, v58
	v_and_b32_e32 v37, 0xffff0000, v235
	v_lshlrev_b32_e32 v38, 16, v237
	v_cndmask_b32_e64 v55, v55, v56, s[0:1]
	v_cmp_lt_f32_e64 s[0:1], 0, v59
	v_and_b32_e32 v39, 0xffff0000, v237
	v_lshlrev_b32_e32 v50, 16, v238
	v_cndmask_b32_e64 v55, v55, v57, s[0:1]
	v_mul_f32_e32 v56, 0x37800000, v55
	v_cndmask_b32_e32 v55, v55, v56, vcc
	v_cmp_class_f32_e32 vcc, v54, v34
	v_and_b32_e32 v51, 0xffff0000, v238
	v_lshlrev_b32_e32 v40, 16, v239
	v_cndmask_b32_e32 v54, v55, v54, vcc
	v_div_scale_f32 v55, s[0:1], v54, v54, 1.0
	v_rcp_f32_e32 v56, v55
	v_div_scale_f32 v57, vcc, 1.0, v54, 1.0
	v_and_b32_e32 v41, 0xffff0000, v239
	v_fma_f32 v58, -v55, v56, 1.0
	v_fmac_f32_e32 v56, v58, v56
	v_mul_f32_e32 v58, v57, v56
	v_fma_f32 v59, -v55, v58, v57
	v_fmac_f32_e32 v58, v59, v56
	v_fma_f32 v55, -v55, v58, v57
	v_div_fmas_f32 v55, v55, v56, v58
	v_div_fixup_f32 v54, v55, v54, 1.0
	v_lshlrev_b32_e32 v52, 16, v240
	v_and_b32_e32 v53, 0xffff0000, v240
	v_lshlrev_b32_e32 v42, 16, v241
	v_and_b32_e32 v43, 0xffff0000, v241
	v_pk_mul_f32 v[28:29], v[28:29], v[54:55] op_sel_hi:[1,0]
	v_pk_mul_f32 v[30:31], v[30:31], v[54:55] op_sel_hi:[1,0]
	v_pk_mul_f32 v[24:25], v[24:25], v[54:55] op_sel_hi:[1,0]
	v_pk_mul_f32 v[26:27], v[26:27], v[54:55] op_sel_hi:[1,0]
	v_pk_mul_f32 v[20:21], v[20:21], v[54:55] op_sel_hi:[1,0]
	v_pk_mul_f32 v[22:23], v[22:23], v[54:55] op_sel_hi:[1,0]
	v_pk_mul_f32 v[16:17], v[16:17], v[54:55] op_sel_hi:[1,0]
	v_pk_mul_f32 v[18:19], v[18:19], v[54:55] op_sel_hi:[1,0]
	v_pk_fma_f32 v[30:31], v[106:107], v[30:31], v[36:37]
	v_pk_fma_f32 v[28:29], v[104:105], v[28:29], v[46:47]
	v_pk_fma_f32 v[26:27], v[102:103], v[26:27], v[38:39]
	v_pk_fma_f32 v[24:25], v[100:101], v[24:25], v[48:49]
	v_pk_fma_f32 v[22:23], v[110:111], v[22:23], v[40:41]
	v_pk_fma_f32 v[20:21], v[108:109], v[20:21], v[50:51]
	v_pk_fma_f32 v[36:37], v[98:99], v[18:19], v[42:43]
	v_pk_fma_f32 v[38:39], v[96:97], v[16:17], v[52:53]
	v_cvt_pk_bf16_f32 v16, v28, v29
	v_cvt_pk_bf16_f32 v17, v30, v31
	v_mul_f32_e32 v18, v29, v29
	v_mul_f32_e32 v19, v31, v31
	v_mul_f32_e32 v29, v25, v25
	v_mul_f32_e32 v31, v27, v27
	v_mul_f32_e32 v40, v21, v21
	v_mul_f32_e32 v41, v23, v23
	v_mul_f32_e32 v42, v39, v39
	v_mul_f32_e32 v43, v37, v37
	v_fmac_f32_e32 v18, v28, v28
	v_fmac_f32_e32 v19, v30, v30
	v_fmac_f32_e32 v29, v24, v24
	v_fmac_f32_e32 v31, v26, v26
	v_fmac_f32_e32 v40, v20, v20
	v_fmac_f32_e32 v41, v22, v22
	v_fmac_f32_e32 v42, v38, v38
	v_fmac_f32_e32 v43, v36, v36
	v_add_f32_e32 v18, v18, v19
	v_add_f32_e32 v19, v29, v31
	v_add_f32_e32 v28, v40, v41
	v_add_f32_e32 v29, v42, v43
	v_add_f32_e32 v18, v18, v19
	v_add_f32_e32 v19, v28, v29
	v_add_f32_e32 v28, v18, v19
	ds_bpermute_b32 v29, v145, v28
	v_cvt_pk_bf16_f32 v18, v24, v25
	v_cvt_pk_bf16_f32 v19, v26, v27
	global_store_dwordx4 v[44:45], v[16:19], off
	s_waitcnt lgkmcnt(0)
	s_nop 0
	v_add_f32_e32 v16, v28, v29
	ds_bpermute_b32 v17, v147, v16
	v_cvt_pk_bf16_f32 v18, v20, v21
	v_cvt_pk_bf16_f32 v19, v22, v23
	v_cvt_pk_bf16_f32 v20, v38, v39
	v_cvt_pk_bf16_f32 v21, v36, v37
	global_store_dwordx4 v[44:45], v[18:21], off offset:256
	s_and_saveexec_b64 s[0:1], s[4:5]
	s_cbranch_execz .LBB0_1407
	v_lshl_add_u32 v18, v32, 4, s24
	s_waitcnt lgkmcnt(0)
	v_add_f32_e32 v16, v16, v17
	ds_write_b32 v18, v16
; DI unsigned pk_bf16(float lo, float hi) { f32x2 v = {lo, hi}; bf16x2_t b = __builtin_convertvector(v, bf16x2_t); return __builtin_bit_cast(unsigned, b); }
; DI float bflo(unsigned w) { return __uint_as_float(w << 16); }
; DI float bfhi(unsigned w) { return __uint_as_float(w & 0xffff0000u); }
;     __device__ __forceinline__ void fused(f32x4 (&acc)[2][2][4][2], const pg8::Unit& u, int wr, int wc, int fr, int fq, PG8_LAS unsigned char* lds, int wid, int lane) const {
;     ...
;                 const int rl = ai * 128 + wr * 64 + m * 16 + fr; const size_t row = (size_t)u.pm * 256 + rl;
;                 const float rm = 1.f / sqrtf(__hip_atomic_load(ssqm + row, __ATOMIC_RELAXED, __HIP_MEMORY_SCOPE_AGENT) * (1.f / DM) + RMS_EPS);
;                 float sh = 0.f;
; #pragma unroll
;                 for (int bj = 0; bj < 2; ++bj) {
;                     const size_t off = row * DM + colb + bj * 128;
;                     f32x4 h0, h1;
;                     if (IN16) { const u32x4 hw = *(const u32x4*)((const bf16_t*)hin + off); h0 = (f32x4){bflo(hw.x), bfhi(hw.x), bflo(hw.y), bfhi(hw.y)}; h1 = (f32x4){bflo(hw.z), bfhi(hw.z), bflo(hw.w), bfhi(hw.w)}; }
;                     else { h0 = *(const f32x4*)((const float*)hin + off); h1 = *(const f32x4*)((const float*)hin + off + 4); }
;                     h0 = h0 + acc[ai][bj][m][0] * rm * gv[bj][0]; h1 = h1 + acc[ai][bj][m][1] * rm * gv[bj][1];
;                     sh += ((h0[0] * h0[0] + h0[1] * h0[1]) + (h0[2] * h0[2] + h0[3] * h0[3])) + ((h1[0] * h1[0] + h1[1] * h1[1]) + (h1[2] * h1[2] + h1[3] * h1[3]));
;                     if (OUT16) { u32x4 w; w.x = pk_bf16(h0[0], h0[1]); w.y = pk_bf16(h0[2], h0[3]); w.z = pk_bf16(h1[0], h1[1]); w.w = pk_bf16(h1[2], h1[3]); *(u32x4*)((bf16_t*)hout + off) = w; }
;                     else { *(f32x4*)((float*)hout + off) = h0; *(f32x4*)((float*)hout + off + 4) = h1; }
;                 }
;                 if (ssqh) { sh += __shfl_xor(sh, 16); sh += __shfl_xor(sh, 32); if (fq == 0) red[rl * 4 + wc] = sh; }
.LBB0_1407:
	s_or_b64 exec, exec, s[0:1]
	v_add_u32_e32 v32, 0xb0, v152
	s_waitcnt lgkmcnt(0)
	v_lshl_add_u64 v[16:17], s[18:19], 0, v[32:33]
	v_lshl_add_u64 v[18:19], v[16:17], 2, s[12:13]
	s_nop 0
	v_lshlrev_b64 v[16:17], 11, v[16:17]
	v_lshl_add_u64 v[16:17], s[10:11], 0, v[16:17]
	v_lshl_add_u64 v[24:25], v[156:157], 1, v[16:17]
	s_nop 0
	s_nop 0
	s_waitcnt vmcnt(4)
	v_fmac_f32_e32 v35, 0x3a800000, v253
	v_mul_f32_e32 v26, 0x4f800000, v35
	v_cmp_gt_f32_e32 vcc, s2, v35
	v_and_b32_e32 v27, 0xffff0000, v242
	v_lshlrev_b32_e32 v28, 16, v244
	v_cndmask_b32_e32 v33, v35, v26, vcc
	v_sqrt_f32_e32 v35, v33
	v_lshlrev_b32_e32 v26, 16, v242
	v_lshlrev_b32_e32 v16, 16, v243
	v_and_b32_e32 v17, 0xffff0000, v243
	v_add_u32_e32 v38, -1, v35
	v_add_u32_e32 v39, 1, v35
	v_fma_f32 v40, -v38, v35, v33
	v_fma_f32 v41, -v39, v35, v33
	v_cmp_ge_f32_e64 s[0:1], 0, v40
	v_and_b32_e32 v29, 0xffff0000, v244
	v_lshlrev_b32_e32 v18, 16, v245
	v_cndmask_b32_e64 v35, v35, v38, s[0:1]
	v_cmp_lt_f32_e64 s[0:1], 0, v41
	v_and_b32_e32 v19, 0xffff0000, v245
	v_lshlrev_b32_e32 v30, 16, v246
	v_cndmask_b32_e64 v35, v35, v39, s[0:1]
	v_mul_f32_e32 v38, 0x37800000, v35
	v_cndmask_b32_e32 v35, v35, v38, vcc
	v_cmp_class_f32_e32 vcc, v33, v34
	v_and_b32_e32 v31, 0xffff0000, v246
	v_lshlrev_b32_e32 v20, 16, v247
	v_cndmask_b32_e32 v33, v35, v33, vcc
	v_div_scale_f32 v34, s[0:1], v33, v33, 1.0
	v_rcp_f32_e32 v35, v34
	v_div_scale_f32 v38, vcc, 1.0, v33, 1.0
	v_and_b32_e32 v21, 0xffff0000, v247
	v_fma_f32 v39, -v34, v35, 1.0
	v_fmac_f32_e32 v35, v39, v35
	v_mul_f32_e32 v39, v38, v35
	v_fma_f32 v40, -v34, v39, v38
	v_fmac_f32_e32 v39, v40, v35
	v_fma_f32 v34, -v34, v39, v38
	v_div_fmas_f32 v34, v34, v35, v39
	v_div_fixup_f32 v34, v34, v33, 1.0
	v_lshlrev_b32_e32 v36, 16, v248
	v_and_b32_e32 v37, 0xffff0000, v248
	v_lshlrev_b32_e32 v22, 16, v249
	v_and_b32_e32 v23, 0xffff0000, v249
	v_pk_mul_f32 v[12:13], v[12:13], v[34:35] op_sel_hi:[1,0]
	v_pk_mul_f32 v[14:15], v[14:15], v[34:35] op_sel_hi:[1,0]
	v_pk_mul_f32 v[8:9], v[8:9], v[34:35] op_sel_hi:[1,0]
	v_pk_mul_f32 v[10:11], v[10:11], v[34:35] op_sel_hi:[1,0]
	v_pk_mul_f32 v[4:5], v[4:5], v[34:35] op_sel_hi:[1,0]
	v_pk_mul_f32 v[6:7], v[6:7], v[34:35] op_sel_hi:[1,0]
	v_pk_mul_f32 v[0:1], v[0:1], v[34:35] op_sel_hi:[1,0]
	v_pk_mul_f32 v[2:3], v[2:3], v[34:35] op_sel_hi:[1,0]
	v_pk_fma_f32 v[14:15], v[106:107], v[14:15], v[16:17]
	v_pk_fma_f32 v[12:13], v[104:105], v[12:13], v[26:27]
	v_pk_fma_f32 v[10:11], v[102:103], v[10:11], v[18:19]
	v_pk_fma_f32 v[8:9], v[100:101], v[8:9], v[28:29]
	v_pk_fma_f32 v[6:7], v[110:111], v[6:7], v[20:21]
	v_pk_fma_f32 v[4:5], v[108:109], v[4:5], v[30:31]
	v_pk_fma_f32 v[16:17], v[98:99], v[2:3], v[22:23]
	v_pk_fma_f32 v[18:19], v[96:97], v[0:1], v[36:37]
	v_cvt_pk_bf16_f32 v0, v12, v13
	v_cvt_pk_bf16_f32 v1, v14, v15
	v_mul_f32_e32 v2, v13, v13
	v_mul_f32_e32 v3, v15, v15
	v_mul_f32_e32 v13, v9, v9
	v_mul_f32_e32 v15, v11, v11
	v_mul_f32_e32 v20, v5, v5
	v_mul_f32_e32 v21, v7, v7
	v_mul_f32_e32 v22, v19, v19
	v_mul_f32_e32 v23, v17, v17
	v_fmac_f32_e32 v2, v12, v12
	v_fmac_f32_e32 v3, v14, v14
	v_fmac_f32_e32 v13, v8, v8
	v_fmac_f32_e32 v15, v10, v10
	v_fmac_f32_e32 v20, v4, v4
	v_fmac_f32_e32 v21, v6, v6
	v_fmac_f32_e32 v22, v18, v18
	v_fmac_f32_e32 v23, v16, v16
	v_add_f32_e32 v2, v2, v3
	v_add_f32_e32 v3, v13, v15
	v_add_f32_e32 v12, v20, v21
	v_add_f32_e32 v13, v22, v23
	v_add_f32_e32 v2, v2, v3
	v_add_f32_e32 v3, v12, v13
	v_add_f32_e32 v12, v2, v3
	ds_bpermute_b32 v13, v145, v12
	v_cvt_pk_bf16_f32 v2, v8, v9
	v_cvt_pk_bf16_f32 v3, v10, v11
	global_store_dwordx4 v[24:25], v[0:3], off
	s_waitcnt lgkmcnt(0)
	s_nop 0
	v_add_f32_e32 v0, v12, v13
	ds_bpermute_b32 v1, v147, v0
	v_cvt_pk_bf16_f32 v2, v4, v5
	v_cvt_pk_bf16_f32 v3, v6, v7
	v_cvt_pk_bf16_f32 v4, v18, v19
	v_cvt_pk_bf16_f32 v5, v16, v17
	global_store_dwordx4 v[24:25], v[2:5], off offset:256
	s_and_saveexec_b64 s[0:1], s[4:5]
	s_cbranch_execz .LBB0_1409
	v_lshl_add_u32 v2, v32, 4, s24
	s_waitcnt lgkmcnt(0)
	v_add_f32_e32 v0, v0, v1
	ds_write_b32 v2, v0

; DI unsigned pk_bf16(float lo, float hi) { f32x2 v = {lo, hi}; bf16x2_t b = __builtin_convertvector(v, bf16x2_t); return __builtin_bit_cast(unsigned, b); }
; DI float bflo(unsigned w) { return __uint_as_float(w << 16); }
; DI float bfhi(unsigned w) { return __uint_as_float(w & 0xffff0000u); }
;     __device__ __forceinline__ void fused(f32x4 (&acc)[2][2][4][2], const pg8::Unit& u, int wr, int wc, int fr, int fq, PG8_LAS unsigned char* lds, int wid, int lane) const {
;     ...
;         const int colb = u.pn * 256 + wc * 32 + 8 * fq;
;         f32x4 gv[2][2];
; #pragma unroll
;         for (int bj = 0; bj < 2; ++bj)
; #pragma unroll
;             for (int n = 0; n < 2; ++n) gv[bj][n] = *(const f32x4*)(gA + colb + bj * 128 + 4 * n);
; #pragma unroll
;         for (int ai = 0; ai < 2; ++ai)
; #pragma unroll
;             for (int m = 0; m < 4; ++m) {
;                 const int rl = ai * 128 + wr * 64 + m * 16 + fr; const size_t row = (size_t)u.pm * 256 + rl;
;                 const float rm = 1.f / sqrtf(__hip_atomic_load(ssqm + row, __ATOMIC_RELAXED, __HIP_MEMORY_SCOPE_AGENT) * (1.f / DM) + RMS_EPS);
;                 float sh = 0.f;
; #pragma unroll
;                 for (int bj = 0; bj < 2; ++bj) {
;                     const size_t off = row * DM + colb + bj * 128;
;                     f32x4 h0, h1;
;                     if (IN16) { const u32x4 hw = *(const u32x4*)((const bf16_t*)hin + off); h0 = (f32x4){bflo(hw.x), bfhi(hw.x), bflo(hw.y), bfhi(hw.y)}; h1 = (f32x4){bflo(hw.z), bfhi(hw.z), bflo(hw.w), bfhi(hw.w)}; }
;                     else { h0 = *(const f32x4*)((const float*)hin + off); h1 = *(const f32x4*)((const float*)hin + off + 4); }
;                     h0 = h0 + acc[ai][bj][m][0] * rm * gv[bj][0]; h1 = h1 + acc[ai][bj][m][1] * rm * gv[bj][1];
;                     sh += ((h0[0] * h0[0] + h0[1] * h0[1]) + (h0[2] * h0[2] + h0[3] * h0[3])) + ((h1[0] * h1[0] + h1[1] * h1[1]) + (h1[2] * h1[2] + h1[3] * h1[3]));
;                     if (OUT16) { u32x4 w; w.x = pk_bf16(h0[0], h0[1]); w.y = pk_bf16(h0[2], h0[3]); w.z = pk_bf16(h1[0], h1[1]); w.w = pk_bf16(h1[2], h1[3]); *(u32x4*)((bf16_t*)hout + off) = w; }
;                     else { *(f32x4*)((float*)hout + off) = h0; *(f32x4*)((float*)hout + off + 4) = h1; }
;                 }
;                 if (ssqh) { sh += __shfl_xor(sh, 16); sh += __shfl_xor(sh, 32); if (fq == 0) red[rl * 4 + wc] = sh; }
.LBB0_1448:
	s_or_b64 exec, exec, s[2:3]
	s_lshl_b32 s1, s1, 5
	s_lshl_b32 s0, s0, 8
	s_or_b32 s0, s0, s1
	v_or_b32_e32 v146, s0, v160
	v_ashrrev_i32_e32 v147, 31, v146
	v_mov_b32_e32 v149, 0
	v_lshl_add_u64 v[108:109], v[146:147], 2, s[14:15]
	s_lshl_b64 s[14:15], s[16:17], 8
	v_mov_b32_e32 v153, v149
	v_lshl_add_u64 v[156:157], s[14:15], 0, v[152:153]
	v_lshl_add_u64 v[158:159], v[156:157], 2, s[12:13]
	s_barrier
	global_load_dwordx4 v[100:103], v[108:109], off offset:16
	global_load_dwordx4 v[104:107], v[108:109], off
	global_load_dwordx4 v[96:99], v[108:109], off offset:528
	s_nop 0
	global_load_dwordx4 v[108:111], v[108:109], off offset:512
	v_lshlrev_b64 v[156:157], 11, v[156:157]
	v_or_b32_e32 v254, 0, v152
	v_mov_b32_e32 v255, 0
	v_lshl_add_u64 v[254:255], s[14:15], 0, v[254:255]
	v_lshlrev_b64 v[240:241], 11, v[254:255]
	v_lshl_add_u64 v[240:241], s[10:11], 0, v[240:241]
	v_lshl_add_u64 v[240:241], v[146:147], 1, v[240:241]
	v_lshl_add_u64 v[254:255], v[254:255], 2, s[12:13]
	global_load_dword v252, v[254:255], off sc1
	global_load_dwordx4 v[234:237], v[240:241], off
	global_load_dwordx4 v[238:241], v[240:241], off offset:256
	v_or_b32_e32 v254, 16, v152
	v_mov_b32_e32 v255, 0
	v_lshl_add_u64 v[254:255], s[14:15], 0, v[254:255]
	v_lshlrev_b64 v[248:249], 11, v[254:255]
	v_lshl_add_u64 v[248:249], s[10:11], 0, v[248:249]
	v_lshl_add_u64 v[248:249], v[146:147], 1, v[248:249]
	v_lshl_add_u64 v[254:255], v[254:255], 2, s[12:13]
	global_load_dword v253, v[254:255], off sc1
	global_load_dwordx4 v[242:245], v[248:249], off
	global_load_dwordx4 v[246:249], v[248:249], off offset:256
	s_nop 0
	v_lshl_add_u64 v[156:157], s[10:11], 0, v[156:157]
	v_lshl_add_u64 v[164:165], v[146:147], 1, v[156:157]
	s_nop 0
	s_nop 0
	v_mov_b32_e32 v155, 0x358637bd
	s_mov_b32 s2, 0xf800000
	v_mov_b32_e32 v153, 0x260
	s_waitcnt vmcnt(3)
	v_fmamk_f32 v148, v252, 0x3a800000, v155
	v_mul_f32_e32 v172, 0x4f800000, v148
	v_cmp_gt_f32_e32 vcc, s2, v148
	v_lshlrev_b32_e32 v166, 16, v234
	v_and_b32_e32 v167, 0xffff0000, v234
	v_cndmask_b32_e32 v148, v148, v172, vcc
	v_sqrt_f32_e32 v174, v148
	v_lshlrev_b32_e32 v156, 16, v235
	v_and_b32_e32 v157, 0xffff0000, v235
	v_lshlrev_b32_e32 v168, 16, v236
	v_add_u32_e32 v175, -1, v174
	v_add_u32_e32 v176, 1, v174
	v_fma_f32 v177, -v175, v174, v148
	v_fma_f32 v178, -v176, v174, v148
	v_cmp_ge_f32_e64 s[0:1], 0, v177
	v_and_b32_e32 v169, 0xffff0000, v236
	v_lshlrev_b32_e32 v158, 16, v237
	v_cndmask_b32_e64 v174, v174, v175, s[0:1]
	v_cmp_lt_f32_e64 s[0:1], 0, v178
	v_and_b32_e32 v159, 0xffff0000, v237
	v_lshlrev_b32_e32 v170, 16, v238
	v_cndmask_b32_e64 v174, v174, v176, s[0:1]
	v_mul_f32_e32 v175, 0x37800000, v174
	v_cndmask_b32_e32 v174, v174, v175, vcc
	v_cmp_class_f32_e32 vcc, v148, v153
	v_and_b32_e32 v171, 0xffff0000, v238
	v_lshlrev_b32_e32 v160, 16, v239
	v_cndmask_b32_e32 v148, v174, v148, vcc
	v_div_scale_f32 v174, s[0:1], v148, v148, 1.0
	v_rcp_f32_e32 v175, v174
	v_div_scale_f32 v176, vcc, 1.0, v148, 1.0
	v_and_b32_e32 v161, 0xffff0000, v239
	v_fma_f32 v177, -v174, v175, 1.0
	v_fmac_f32_e32 v175, v177, v175
	v_mul_f32_e32 v177, v176, v175
	v_fma_f32 v178, -v174, v177, v176
	v_fmac_f32_e32 v177, v178, v175
	v_fma_f32 v174, -v174, v177, v176
	v_div_fmas_f32 v174, v174, v175, v177
	v_div_fixup_f32 v148, v174, v148, 1.0
	v_lshlrev_b32_e32 v172, 16, v240
	v_and_b32_e32 v173, 0xffff0000, v240
	v_lshlrev_b32_e32 v162, 16, v241
	v_and_b32_e32 v163, 0xffff0000, v241
	v_or_b32_e32 v254, 32, v152
	v_mov_b32_e32 v255, 0
	v_lshl_add_u64 v[254:255], s[14:15], 0, v[254:255]
	v_lshlrev_b64 v[240:241], 11, v[254:255]
	v_lshl_add_u64 v[240:241], s[10:11], 0, v[240:241]
	v_lshl_add_u64 v[240:241], v[146:147], 1, v[240:241]
	v_lshl_add_u64 v[254:255], v[254:255], 2, s[12:13]
	global_load_dword v252, v[254:255], off sc1
	global_load_dwordx4 v[234:237], v[240:241], off
	global_load_dwordx4 v[238:241], v[240:241], off offset:256
	v_pk_mul_f32 v[140:141], v[140:141], v[148:149] op_sel_hi:[1,0]
	v_pk_mul_f32 v[142:143], v[142:143], v[148:149] op_sel_hi:[1,0]
	v_pk_mul_f32 v[136:137], v[136:137], v[148:149] op_sel_hi:[1,0]
	v_pk_mul_f32 v[138:139], v[138:139], v[148:149] op_sel_hi:[1,0]
	v_pk_mul_f32 v[132:133], v[132:133], v[148:149] op_sel_hi:[1,0]
	v_pk_mul_f32 v[134:135], v[134:135], v[148:149] op_sel_hi:[1,0]
	v_pk_mul_f32 v[128:129], v[128:129], v[148:149] op_sel_hi:[1,0]
	v_pk_mul_f32 v[130:131], v[130:131], v[148:149] op_sel_hi:[1,0]
	v_pk_fma_f32 v[142:143], v[106:107], v[142:143], v[156:157]
	v_pk_fma_f32 v[140:141], v[104:105], v[140:141], v[166:167]
	v_pk_fma_f32 v[138:139], v[102:103], v[138:139], v[158:159]
	v_pk_fma_f32 v[136:137], v[100:101], v[136:137], v[168:169]
	v_pk_fma_f32 v[134:135], v[110:111], v[134:135], v[160:161]
	v_pk_fma_f32 v[132:133], v[108:109], v[132:133], v[170:171]
	v_pk_fma_f32 v[156:157], v[98:99], v[130:131], v[162:163]
	v_pk_fma_f32 v[158:159], v[96:97], v[128:129], v[172:173]
	v_cvt_pk_bf16_f32 v128, v140, v141
	v_cvt_pk_bf16_f32 v129, v142, v143
	v_mul_f32_e32 v130, v141, v141
	v_mul_f32_e32 v131, v143, v143
	v_mul_f32_e32 v141, v137, v137
	v_mul_f32_e32 v143, v139, v139
	v_mul_f32_e32 v148, v133, v133
	v_mul_f32_e32 v160, v135, v135
	v_mul_f32_e32 v161, v159, v159
	v_mul_f32_e32 v162, v157, v157
	v_fmac_f32_e32 v130, v140, v140
	v_fmac_f32_e32 v131, v142, v142
	v_fmac_f32_e32 v141, v136, v136
	v_fmac_f32_e32 v143, v138, v138
	v_fmac_f32_e32 v148, v132, v132
	v_fmac_f32_e32 v160, v134, v134
	v_fmac_f32_e32 v161, v158, v158
	v_fmac_f32_e32 v162, v156, v156
	v_add_f32_e32 v130, v130, v131
	v_add_f32_e32 v131, v141, v143
	v_add_f32_e32 v140, v148, v160
	v_add_f32_e32 v141, v161, v162
	v_add_f32_e32 v130, v130, v131
	v_add_f32_e32 v131, v140, v141
	v_add_f32_e32 v140, v130, v131
	ds_bpermute_b32 v141, v150, v140
	v_cvt_pk_bf16_f32 v130, v136, v137
	v_cvt_pk_bf16_f32 v131, v138, v139
	global_store_dwordx4 v[164:165], v[128:131], off
	s_waitcnt lgkmcnt(0)
	s_nop 0
	v_add_f32_e32 v128, v140, v141
	ds_bpermute_b32 v129, v151, v128
	v_cvt_pk_bf16_f32 v130, v132, v133
	v_cvt_pk_bf16_f32 v131, v134, v135
	v_cvt_pk_bf16_f32 v132, v158, v159
	v_cvt_pk_bf16_f32 v133, v156, v157
	global_store_dwordx4 v[164:165], v[130:133], off offset:256
	s_and_saveexec_b64 s[0:1], s[4:5]
	s_cbranch_execz .LBB0_1450
	v_lshl_add_u32 v130, v152, 4, s24
	s_waitcnt lgkmcnt(0)
	v_add_f32_e32 v128, v128, v129
	ds_write_b32 v130, v128
; DI unsigned pk_bf16(float lo, float hi) { f32x2 v = {lo, hi}; bf16x2_t b = __builtin_convertvector(v, bf16x2_t); return __builtin_bit_cast(unsigned, b); }
; DI float bflo(unsigned w) { return __uint_as_float(w << 16); }
; DI float bfhi(unsigned w) { return __uint_as_float(w & 0xffff0000u); }
;     __device__ __forceinline__ void fused(f32x4 (&acc)[2][2][4][2], const pg8::Unit& u, int wr, int wc, int fr, int fq, PG8_LAS unsigned char* lds, int wid, int lane) const {
;     ...
;                 const int rl = ai * 128 + wr * 64 + m * 16 + fr; const size_t row = (size_t)u.pm * 256 + rl;
;                 const float rm = 1.f / sqrtf(__hip_atomic_load(ssqm + row, __ATOMIC_RELAXED, __HIP_MEMORY_SCOPE_AGENT) * (1.f / DM) + RMS_EPS);
;                 float sh = 0.f;
; #pragma unroll
;                 for (int bj = 0; bj < 2; ++bj) {
;                     const size_t off = row * DM + colb + bj * 128;
;                     f32x4 h0, h1;
;                     if (IN16) { const u32x4 hw = *(const u32x4*)((const bf16_t*)hin + off); h0 = (f32x4){bflo(hw.x), bfhi(hw.x), bflo(hw.y), bfhi(hw.y)}; h1 = (f32x4){bflo(hw.z), bfhi(hw.z), bflo(hw.w), bfhi(hw.w)}; }
;                     else { h0 = *(const f32x4*)((const float*)hin + off); h1 = *(const f32x4*)((const float*)hin + off + 4); }
;                     h0 = h0 + acc[ai][bj][m][0] * rm * gv[bj][0]; h1 = h1 + acc[ai][bj][m][1] * rm * gv[bj][1];
;                     sh += ((h0[0] * h0[0] + h0[1] * h0[1]) + (h0[2] * h0[2] + h0[3] * h0[3])) + ((h1[0] * h1[0] + h1[1] * h1[1]) + (h1[2] * h1[2] + h1[3] * h1[3]));
;                     if (OUT16) { u32x4 w; w.x = pk_bf16(h0[0], h0[1]); w.y = pk_bf16(h0[2], h0[3]); w.z = pk_bf16(h1[0], h1[1]); w.w = pk_bf16(h1[2], h1[3]); *(u32x4*)((bf16_t*)hout + off) = w; }
;                     else { *(f32x4*)((float*)hout + off) = h0; *(f32x4*)((float*)hout + off + 4) = h1; }
;                 }
;                 if (ssqh) { sh += __shfl_xor(sh, 16); sh += __shfl_xor(sh, 32); if (fq == 0) red[rl * 4 + wc] = sh; }
.LBB0_1450:
	s_or_b64 exec, exec, s[0:1]
	v_or_b32_e32 v148, 16, v152
	s_waitcnt lgkmcnt(0)
	v_lshl_add_u64 v[128:129], s[14:15], 0, v[148:149]
	v_lshl_add_u64 v[130:131], v[128:129], 2, s[12:13]
	s_nop 0
	v_lshlrev_b64 v[128:129], 11, v[128:129]
	v_lshl_add_u64 v[128:129], s[10:11], 0, v[128:129]
	v_lshl_add_u64 v[136:137], v[146:147], 1, v[128:129]
	s_nop 0
	s_nop 0
	s_waitcnt vmcnt(5)
	v_fmac_f32_e32 v155, 0x3a800000, v253
	v_mul_f32_e32 v138, 0x4f800000, v155
	v_cmp_gt_f32_e32 vcc, s2, v155
	v_and_b32_e32 v139, 0xffff0000, v242
	v_lshlrev_b32_e32 v140, 16, v244
	v_cndmask_b32_e32 v149, v155, v138, vcc
	v_sqrt_f32_e32 v155, v149
	v_lshlrev_b32_e32 v138, 16, v242
	v_lshlrev_b32_e32 v128, 16, v243
	v_and_b32_e32 v129, 0xffff0000, v243
	v_add_u32_e32 v158, -1, v155
	v_add_u32_e32 v159, 1, v155
	v_fma_f32 v160, -v158, v155, v149
	v_fma_f32 v161, -v159, v155, v149
	v_cmp_ge_f32_e64 s[0:1], 0, v160
	v_and_b32_e32 v141, 0xffff0000, v244
	v_lshlrev_b32_e32 v130, 16, v245
	v_cndmask_b32_e64 v155, v155, v158, s[0:1]
	v_cmp_lt_f32_e64 s[0:1], 0, v161
	v_and_b32_e32 v131, 0xffff0000, v245
	v_lshlrev_b32_e32 v142, 16, v246
	v_cndmask_b32_e64 v155, v155, v159, s[0:1]
	v_mul_f32_e32 v158, 0x37800000, v155
	v_cndmask_b32_e32 v155, v155, v158, vcc
	v_cmp_class_f32_e32 vcc, v149, v153
	v_and_b32_e32 v143, 0xffff0000, v246
	v_lshlrev_b32_e32 v132, 16, v247
	v_cndmask_b32_e32 v149, v155, v149, vcc
	v_div_scale_f32 v153, s[0:1], v149, v149, 1.0
	v_rcp_f32_e32 v155, v153
	v_div_scale_f32 v158, vcc, 1.0, v149, 1.0
	v_and_b32_e32 v133, 0xffff0000, v247
	v_fma_f32 v159, -v153, v155, 1.0
	v_fmac_f32_e32 v155, v159, v155
	v_mul_f32_e32 v159, v158, v155
	v_fma_f32 v160, -v153, v159, v158
	v_fmac_f32_e32 v159, v160, v155
	v_fma_f32 v153, -v153, v159, v158
	v_div_fmas_f32 v153, v153, v155, v159
	v_div_fixup_f32 v158, v153, v149, 1.0
	v_lshlrev_b32_e32 v156, 16, v248
	v_and_b32_e32 v157, 0xffff0000, v248
	v_lshlrev_b32_e32 v134, 16, v249
	v_and_b32_e32 v135, 0xffff0000, v249
	v_or_b32_e32 v254, 48, v152
	v_mov_b32_e32 v255, 0
	v_lshl_add_u64 v[254:255], s[14:15], 0, v[254:255]
	v_lshlrev_b64 v[248:249], 11, v[254:255]
	v_lshl_add_u64 v[248:249], s[10:11], 0, v[248:249]
	v_lshl_add_u64 v[248:249], v[146:147], 1, v[248:249]
	v_lshl_add_u64 v[254:255], v[254:255], 2, s[12:13]
	global_load_dword v253, v[254:255], off sc1
	global_load_dwordx4 v[242:245], v[248:249], off
	global_load_dwordx4 v[246:249], v[248:249], off offset:256
	v_pk_mul_f32 v[124:125], v[124:125], v[158:159] op_sel_hi:[1,0]
	v_pk_mul_f32 v[126:127], v[126:127], v[158:159] op_sel_hi:[1,0]
	v_pk_mul_f32 v[120:121], v[120:121], v[158:159] op_sel_hi:[1,0]
	v_pk_mul_f32 v[122:123], v[122:123], v[158:159] op_sel_hi:[1,0]
	v_pk_mul_f32 v[116:117], v[116:117], v[158:159] op_sel_hi:[1,0]
	v_pk_mul_f32 v[118:119], v[118:119], v[158:159] op_sel_hi:[1,0]
	v_pk_mul_f32 v[112:113], v[112:113], v[158:159] op_sel_hi:[1,0]
	v_pk_mul_f32 v[114:115], v[114:115], v[158:159] op_sel_hi:[1,0]
	v_pk_fma_f32 v[126:127], v[106:107], v[126:127], v[128:129]
	v_pk_fma_f32 v[124:125], v[104:105], v[124:125], v[138:139]
	v_pk_fma_f32 v[122:123], v[102:103], v[122:123], v[130:131]
	v_pk_fma_f32 v[120:121], v[100:101], v[120:121], v[140:141]
	v_pk_fma_f32 v[118:119], v[110:111], v[118:119], v[132:133]
	v_pk_fma_f32 v[116:117], v[108:109], v[116:117], v[142:143]
	v_pk_fma_f32 v[128:129], v[98:99], v[114:115], v[134:135]
	v_pk_fma_f32 v[130:131], v[96:97], v[112:113], v[156:157]
	v_cvt_pk_bf16_f32 v112, v124, v125
	v_cvt_pk_bf16_f32 v113, v126, v127
	v_mul_f32_e32 v114, v125, v125
	v_mul_f32_e32 v115, v127, v127
	v_mul_f32_e32 v125, v121, v121
	v_mul_f32_e32 v127, v123, v123
	v_mul_f32_e32 v132, v117, v117
	v_mul_f32_e32 v133, v119, v119
	v_mul_f32_e32 v134, v131, v131
	v_mul_f32_e32 v135, v129, v129
	v_fmac_f32_e32 v114, v124, v124
	v_fmac_f32_e32 v115, v126, v126
	v_fmac_f32_e32 v125, v120, v120
	v_fmac_f32_e32 v127, v122, v122
	v_fmac_f32_e32 v132, v116, v116
	v_fmac_f32_e32 v133, v118, v118
	v_fmac_f32_e32 v134, v130, v130
	v_fmac_f32_e32 v135, v128, v128
	v_add_f32_e32 v114, v114, v115
	v_add_f32_e32 v115, v125, v127
	v_add_f32_e32 v124, v132, v133
	v_add_f32_e32 v125, v134, v135
	v_add_f32_e32 v114, v114, v115
	v_add_f32_e32 v115, v124, v125
	v_add_f32_e32 v124, v114, v115
	ds_bpermute_b32 v125, v150, v124
	v_cvt_pk_bf16_f32 v114, v120, v121
	v_cvt_pk_bf16_f32 v115, v122, v123
	global_store_dwordx4 v[136:137], v[112:115], off
	s_waitcnt lgkmcnt(0)
	s_nop 0
	v_add_f32_e32 v112, v124, v125
	ds_bpermute_b32 v113, v151, v112
	v_cvt_pk_bf16_f32 v114, v116, v117
	v_cvt_pk_bf16_f32 v115, v118, v119
	v_cvt_pk_bf16_f32 v116, v130, v131
	v_cvt_pk_bf16_f32 v117, v128, v129
	global_store_dwordx4 v[136:137], v[114:117], off offset:256
	s_and_saveexec_b64 s[0:1], s[4:5]
	s_cbranch_execz .LBB0_1452
	v_lshl_add_u32 v114, v148, 4, s24
	s_waitcnt lgkmcnt(0)
	v_add_f32_e32 v112, v112, v113
	ds_write_b32 v114, v112
; DI unsigned pk_bf16(float lo, float hi) { f32x2 v = {lo, hi}; bf16x2_t b = __builtin_convertvector(v, bf16x2_t); return __builtin_bit_cast(unsigned, b); }
; DI float bflo(unsigned w) { return __uint_as_float(w << 16); }
; DI float bfhi(unsigned w) { return __uint_as_float(w & 0xffff0000u); }
;     __device__ __forceinline__ void fused(f32x4 (&acc)[2][2][4][2], const pg8::Unit& u, int wr, int wc, int fr, int fq, PG8_LAS unsigned char* lds, int wid, int lane) const {
;     ...
;                 const int rl = ai * 128 + wr * 64 + m * 16 + fr; const size_t row = (size_t)u.pm * 256 + rl;
;                 const float rm = 1.f / sqrtf(__hip_atomic_load(ssqm + row, __ATOMIC_RELAXED, __HIP_MEMORY_SCOPE_AGENT) * (1.f / DM) + RMS_EPS);
;                 float sh = 0.f;
; #pragma unroll
;                 for (int bj = 0; bj < 2; ++bj) {
;                     const size_t off = row * DM + colb + bj * 128;
;                     f32x4 h0, h1;
;                     if (IN16) { const u32x4 hw = *(const u32x4*)((const bf16_t*)hin + off); h0 = (f32x4){bflo(hw.x), bfhi(hw.x), bflo(hw.y), bfhi(hw.y)}; h1 = (f32x4){bflo(hw.z), bfhi(hw.z), bflo(hw.w), bfhi(hw.w)}; }
;                     else { h0 = *(const f32x4*)((const float*)hin + off); h1 = *(const f32x4*)((const float*)hin + off + 4); }
;                     h0 = h0 + acc[ai][bj][m][0] * rm * gv[bj][0]; h1 = h1 + acc[ai][bj][m][1] * rm * gv[bj][1];
;                     sh += ((h0[0] * h0[0] + h0[1] * h0[1]) + (h0[2] * h0[2] + h0[3] * h0[3])) + ((h1[0] * h1[0] + h1[1] * h1[1]) + (h1[2] * h1[2] + h1[3] * h1[3]));
;                     if (OUT16) { u32x4 w; w.x = pk_bf16(h0[0], h0[1]); w.y = pk_bf16(h0[2], h0[3]); w.z = pk_bf16(h1[0], h1[1]); w.w = pk_bf16(h1[2], h1[3]); *(u32x4*)((bf16_t*)hout + off) = w; }
;                     else { *(f32x4*)((float*)hout + off) = h0; *(f32x4*)((float*)hout + off + 4) = h1; }
;                 }
;                 if (ssqh) { sh += __shfl_xor(sh, 16); sh += __shfl_xor(sh, 32); if (fq == 0) red[rl * 4 + wc] = sh; }
.LBB0_1452:
	s_or_b64 exec, exec, s[0:1]
	v_or_b32_e32 v112, 32, v152
	s_waitcnt lgkmcnt(0)
	v_mov_b32_e32 v113, 0
	v_lshl_add_u64 v[114:115], s[14:15], 0, v[112:113]
	v_lshl_add_u64 v[116:117], v[114:115], 2, s[12:13]
	s_nop 0
	v_lshlrev_b64 v[114:115], 11, v[114:115]
	v_lshl_add_u64 v[114:115], s[10:11], 0, v[114:115]
	v_lshl_add_u64 v[124:125], v[146:147], 1, v[114:115]
	s_nop 0
	s_nop 0
	v_mov_b32_e32 v115, 0x358637bd
	v_mov_b32_e32 v114, 0x260
	s_waitcnt vmcnt(7)
	v_fmamk_f32 v126, v252, 0x3a800000, v115
	v_mul_f32_e32 v127, 0x4f800000, v126
	v_cmp_gt_f32_e32 vcc, s2, v126
	v_lshlrev_b32_e32 v128, 16, v236
	v_and_b32_e32 v129, 0xffff0000, v236
	v_cndmask_b32_e32 v134, v126, v127, vcc
	v_sqrt_f32_e32 v135, v134
	v_lshlrev_b32_e32 v126, 16, v234
	v_and_b32_e32 v127, 0xffff0000, v234
	v_lshlrev_b32_e32 v116, 16, v235
	v_add_u32_e32 v136, -1, v135
	v_add_u32_e32 v137, 1, v135
	v_fma_f32 v138, -v136, v135, v134
	v_fma_f32 v139, -v137, v135, v134
	v_cmp_ge_f32_e64 s[0:1], 0, v138
	v_and_b32_e32 v117, 0xffff0000, v235
	v_lshlrev_b32_e32 v118, 16, v237
	v_cndmask_b32_e64 v135, v135, v136, s[0:1]
	v_cmp_lt_f32_e64 s[0:1], 0, v139
	v_and_b32_e32 v119, 0xffff0000, v237
	v_lshlrev_b32_e32 v130, 16, v238
	v_cndmask_b32_e64 v135, v135, v137, s[0:1]
	v_mul_f32_e32 v136, 0x37800000, v135
	v_cndmask_b32_e32 v135, v135, v136, vcc
	v_cmp_class_f32_e32 vcc, v134, v114
	v_and_b32_e32 v131, 0xffff0000, v238
	v_lshlrev_b32_e32 v120, 16, v239
	v_cndmask_b32_e32 v134, v135, v134, vcc
	v_div_scale_f32 v135, s[0:1], v134, v134, 1.0
	v_rcp_f32_e32 v136, v135
	v_div_scale_f32 v137, vcc, 1.0, v134, 1.0
	v_and_b32_e32 v121, 0xffff0000, v239
	v_fma_f32 v138, -v135, v136, 1.0
	v_fmac_f32_e32 v136, v138, v136
	v_mul_f32_e32 v138, v137, v136
	v_fma_f32 v139, -v135, v138, v137
	v_fmac_f32_e32 v138, v139, v136
	v_fma_f32 v135, -v135, v138, v137
	v_div_fmas_f32 v135, v135, v136, v138
	v_div_fixup_f32 v134, v135, v134, 1.0
	v_lshlrev_b32_e32 v132, 16, v240
	v_and_b32_e32 v133, 0xffff0000, v240
	v_lshlrev_b32_e32 v122, 16, v241
	v_and_b32_e32 v123, 0xffff0000, v241
	v_or_b32_e32 v254, 128, v152
	v_mov_b32_e32 v255, 0
	v_lshl_add_u64 v[254:255], s[14:15], 0, v[254:255]
	v_lshlrev_b64 v[240:241], 11, v[254:255]
	v_lshl_add_u64 v[240:241], s[10:11], 0, v[240:241]
	v_lshl_add_u64 v[240:241], v[146:147], 1, v[240:241]
	v_lshl_add_u64 v[254:255], v[254:255], 2, s[12:13]
	global_load_dword v252, v[254:255], off sc1
	global_load_dwordx4 v[234:237], v[240:241], off
	global_load_dwordx4 v[238:241], v[240:241], off offset:256
	v_pk_mul_f32 v[92:93], v[92:93], v[134:135] op_sel_hi:[1,0]
	v_pk_mul_f32 v[94:95], v[94:95], v[134:135] op_sel_hi:[1,0]
	v_pk_mul_f32 v[88:89], v[88:89], v[134:135] op_sel_hi:[1,0]
	v_pk_mul_f32 v[90:91], v[90:91], v[134:135] op_sel_hi:[1,0]
	v_pk_mul_f32 v[84:85], v[84:85], v[134:135] op_sel_hi:[1,0]
	v_pk_mul_f32 v[86:87], v[86:87], v[134:135] op_sel_hi:[1,0]
	v_pk_mul_f32 v[80:81], v[80:81], v[134:135] op_sel_hi:[1,0]
	v_pk_mul_f32 v[82:83], v[82:83], v[134:135] op_sel_hi:[1,0]
	v_pk_fma_f32 v[94:95], v[106:107], v[94:95], v[116:117]
	v_pk_fma_f32 v[92:93], v[104:105], v[92:93], v[126:127]
	v_pk_fma_f32 v[90:91], v[102:103], v[90:91], v[118:119]
	v_pk_fma_f32 v[88:89], v[100:101], v[88:89], v[128:129]
	v_pk_fma_f32 v[86:87], v[110:111], v[86:87], v[120:121]
	v_pk_fma_f32 v[84:85], v[108:109], v[84:85], v[130:131]
	v_pk_fma_f32 v[116:117], v[98:99], v[82:83], v[122:123]
	v_pk_fma_f32 v[118:119], v[96:97], v[80:81], v[132:133]
	v_cvt_pk_bf16_f32 v80, v92, v93
	v_cvt_pk_bf16_f32 v81, v94, v95
	v_mul_f32_e32 v82, v93, v93
	v_mul_f32_e32 v83, v95, v95
	v_mul_f32_e32 v93, v89, v89
	v_mul_f32_e32 v95, v91, v91
	v_mul_f32_e32 v120, v85, v85
	v_mul_f32_e32 v121, v87, v87
	v_mul_f32_e32 v122, v119, v119
	v_mul_f32_e32 v123, v117, v117
	v_fmac_f32_e32 v82, v92, v92
	v_fmac_f32_e32 v83, v94, v94
	v_fmac_f32_e32 v93, v88, v88
	v_fmac_f32_e32 v95, v90, v90
	v_fmac_f32_e32 v120, v84, v84
	v_fmac_f32_e32 v121, v86, v86
	v_fmac_f32_e32 v122, v118, v118
	v_fmac_f32_e32 v123, v116, v116
	v_add_f32_e32 v82, v82, v83
	v_add_f32_e32 v83, v93, v95
	v_add_f32_e32 v92, v120, v121
	v_add_f32_e32 v93, v122, v123
	v_add_f32_e32 v82, v82, v83
	v_add_f32_e32 v83, v92, v93
	v_add_f32_e32 v92, v82, v83
	ds_bpermute_b32 v93, v150, v92
	v_cvt_pk_bf16_f32 v82, v88, v89
	v_cvt_pk_bf16_f32 v83, v90, v91
	global_store_dwordx4 v[124:125], v[80:83], off
	s_waitcnt lgkmcnt(0)
	s_nop 0
	v_add_f32_e32 v80, v92, v93
	ds_bpermute_b32 v81, v151, v80
	v_cvt_pk_bf16_f32 v82, v84, v85
	v_cvt_pk_bf16_f32 v83, v86, v87
	v_cvt_pk_bf16_f32 v84, v118, v119
	v_cvt_pk_bf16_f32 v85, v116, v117
	global_store_dwordx4 v[124:125], v[82:85], off offset:256
	s_and_saveexec_b64 s[0:1], s[4:5]
	s_cbranch_execz .LBB0_1454
	v_lshl_add_u32 v82, v112, 4, s24
	s_waitcnt lgkmcnt(0)
	v_add_f32_e32 v80, v80, v81
	ds_write_b32 v82, v80
; DI unsigned pk_bf16(float lo, float hi) { f32x2 v = {lo, hi}; bf16x2_t b = __builtin_convertvector(v, bf16x2_t); return __builtin_bit_cast(unsigned, b); }
; DI float bflo(unsigned w) { return __uint_as_float(w << 16); }
; DI float bfhi(unsigned w) { return __uint_as_float(w & 0xffff0000u); }
;     __device__ __forceinline__ void fused(f32x4 (&acc)[2][2][4][2], const pg8::Unit& u, int wr, int wc, int fr, int fq, PG8_LAS unsigned char* lds, int wid, int lane) const {
;     ...
;                 const int rl = ai * 128 + wr * 64 + m * 16 + fr; const size_t row = (size_t)u.pm * 256 + rl;
;                 const float rm = 1.f / sqrtf(__hip_atomic_load(ssqm + row, __ATOMIC_RELAXED, __HIP_MEMORY_SCOPE_AGENT) * (1.f / DM) + RMS_EPS);
;                 float sh = 0.f;
; #pragma unroll
;                 for (int bj = 0; bj < 2; ++bj) {
;                     const size_t off = row * DM + colb + bj * 128;
;                     f32x4 h0, h1;
;                     if (IN16) { const u32x4 hw = *(const u32x4*)((const bf16_t*)hin + off); h0 = (f32x4){bflo(hw.x), bfhi(hw.x), bflo(hw.y), bfhi(hw.y)}; h1 = (f32x4){bflo(hw.z), bfhi(hw.z), bflo(hw.w), bfhi(hw.w)}; }
;                     else { h0 = *(const f32x4*)((const float*)hin + off); h1 = *(const f32x4*)((const float*)hin + off + 4); }
;                     h0 = h0 + acc[ai][bj][m][0] * rm * gv[bj][0]; h1 = h1 + acc[ai][bj][m][1] * rm * gv[bj][1];
;                     sh += ((h0[0] * h0[0] + h0[1] * h0[1]) + (h0[2] * h0[2] + h0[3] * h0[3])) + ((h1[0] * h1[0] + h1[1] * h1[1]) + (h1[2] * h1[2] + h1[3] * h1[3]));
;                     if (OUT16) { u32x4 w; w.x = pk_bf16(h0[0], h0[1]); w.y = pk_bf16(h0[2], h0[3]); w.z = pk_bf16(h1[0], h1[1]); w.w = pk_bf16(h1[2], h1[3]); *(u32x4*)((bf16_t*)hout + off) = w; }
;                     else { *(f32x4*)((float*)hout + off) = h0; *(f32x4*)((float*)hout + off + 4) = h1; }
;                 }
;                 if (ssqh) { sh += __shfl_xor(sh, 16); sh += __shfl_xor(sh, 32); if (fq == 0) red[rl * 4 + wc] = sh; }
.LBB0_1454:
	s_or_b64 exec, exec, s[0:1]
	v_or_b32_e32 v112, 48, v152
	s_waitcnt lgkmcnt(0)
	v_lshl_add_u64 v[80:81], s[14:15], 0, v[112:113]
	v_lshl_add_u64 v[82:83], v[80:81], 2, s[12:13]
	s_nop 0
	v_lshlrev_b64 v[80:81], 11, v[80:81]
	v_lshl_add_u64 v[80:81], s[10:11], 0, v[80:81]
	v_lshl_add_u64 v[88:89], v[146:147], 1, v[80:81]
	s_nop 0
	s_nop 0
	s_waitcnt vmcnt(7)
	v_fmac_f32_e32 v115, 0x3a800000, v253
	v_mul_f32_e32 v90, 0x4f800000, v115
	v_cmp_gt_f32_e32 vcc, s2, v115
	v_and_b32_e32 v91, 0xffff0000, v242
	v_lshlrev_b32_e32 v92, 16, v244
	v_cndmask_b32_e32 v113, v115, v90, vcc
	v_sqrt_f32_e32 v115, v113
	v_lshlrev_b32_e32 v90, 16, v242
	v_lshlrev_b32_e32 v80, 16, v243
	v_and_b32_e32 v81, 0xffff0000, v243
	v_add_u32_e32 v118, -1, v115
	v_add_u32_e32 v119, 1, v115
	v_fma_f32 v120, -v118, v115, v113
	v_fma_f32 v121, -v119, v115, v113
	v_cmp_ge_f32_e64 s[0:1], 0, v120
	v_and_b32_e32 v93, 0xffff0000, v244
	v_lshlrev_b32_e32 v82, 16, v245
	v_cndmask_b32_e64 v115, v115, v118, s[0:1]
	v_cmp_lt_f32_e64 s[0:1], 0, v121
	v_and_b32_e32 v83, 0xffff0000, v245
	v_lshlrev_b32_e32 v94, 16, v246
	v_cndmask_b32_e64 v115, v115, v119, s[0:1]
	v_mul_f32_e32 v118, 0x37800000, v115
	v_cndmask_b32_e32 v115, v115, v118, vcc
	v_cmp_class_f32_e32 vcc, v113, v114
	v_and_b32_e32 v95, 0xffff0000, v246
	v_lshlrev_b32_e32 v84, 16, v247
	v_cndmask_b32_e32 v113, v115, v113, vcc
	v_div_scale_f32 v114, s[0:1], v113, v113, 1.0
	v_rcp_f32_e32 v115, v114
	v_div_scale_f32 v118, vcc, 1.0, v113, 1.0
	v_and_b32_e32 v85, 0xffff0000, v247
	v_fma_f32 v119, -v114, v115, 1.0
	v_fmac_f32_e32 v115, v119, v115
	v_mul_f32_e32 v119, v118, v115
	v_fma_f32 v120, -v114, v119, v118
	v_fmac_f32_e32 v119, v120, v115
	v_fma_f32 v114, -v114, v119, v118
	v_div_fmas_f32 v114, v114, v115, v119
	v_div_fixup_f32 v114, v114, v113, 1.0
	v_lshlrev_b32_e32 v116, 16, v248
	v_and_b32_e32 v117, 0xffff0000, v248
	v_lshlrev_b32_e32 v86, 16, v249
	v_and_b32_e32 v87, 0xffff0000, v249
	v_or_b32_e32 v254, 144, v152
	v_mov_b32_e32 v255, 0
	v_lshl_add_u64 v[254:255], s[14:15], 0, v[254:255]
	v_lshlrev_b64 v[248:249], 11, v[254:255]
	v_lshl_add_u64 v[248:249], s[10:11], 0, v[248:249]
	v_lshl_add_u64 v[248:249], v[146:147], 1, v[248:249]
	v_lshl_add_u64 v[254:255], v[254:255], 2, s[12:13]
	global_load_dword v253, v[254:255], off sc1
	global_load_dwordx4 v[242:245], v[248:249], off
	global_load_dwordx4 v[246:249], v[248:249], off offset:256
	v_pk_mul_f32 v[76:77], v[76:77], v[114:115] op_sel_hi:[1,0]
	v_pk_mul_f32 v[78:79], v[78:79], v[114:115] op_sel_hi:[1,0]
	v_pk_mul_f32 v[72:73], v[72:73], v[114:115] op_sel_hi:[1,0]
	v_pk_mul_f32 v[74:75], v[74:75], v[114:115] op_sel_hi:[1,0]
	v_pk_mul_f32 v[68:69], v[68:69], v[114:115] op_sel_hi:[1,0]
	v_pk_mul_f32 v[70:71], v[70:71], v[114:115] op_sel_hi:[1,0]
	v_pk_mul_f32 v[64:65], v[64:65], v[114:115] op_sel_hi:[1,0]
	v_pk_mul_f32 v[66:67], v[66:67], v[114:115] op_sel_hi:[1,0]
	v_pk_fma_f32 v[78:79], v[106:107], v[78:79], v[80:81]
	v_pk_fma_f32 v[76:77], v[104:105], v[76:77], v[90:91]
	v_pk_fma_f32 v[74:75], v[102:103], v[74:75], v[82:83]
	v_pk_fma_f32 v[72:73], v[100:101], v[72:73], v[92:93]
	v_pk_fma_f32 v[70:71], v[110:111], v[70:71], v[84:85]
	v_pk_fma_f32 v[68:69], v[108:109], v[68:69], v[94:95]
	v_pk_fma_f32 v[80:81], v[98:99], v[66:67], v[86:87]
	v_pk_fma_f32 v[82:83], v[96:97], v[64:65], v[116:117]
	v_cvt_pk_bf16_f32 v64, v76, v77
	v_cvt_pk_bf16_f32 v65, v78, v79
	v_mul_f32_e32 v66, v77, v77
	v_mul_f32_e32 v67, v79, v79
	v_mul_f32_e32 v77, v73, v73
	v_mul_f32_e32 v79, v75, v75
	v_mul_f32_e32 v84, v69, v69
	v_mul_f32_e32 v85, v71, v71
	v_mul_f32_e32 v86, v83, v83
	v_mul_f32_e32 v87, v81, v81
	v_fmac_f32_e32 v66, v76, v76
	v_fmac_f32_e32 v67, v78, v78
	v_fmac_f32_e32 v77, v72, v72
	v_fmac_f32_e32 v79, v74, v74
	v_fmac_f32_e32 v84, v68, v68
	v_fmac_f32_e32 v85, v70, v70
	v_fmac_f32_e32 v86, v82, v82
	v_fmac_f32_e32 v87, v80, v80
	v_add_f32_e32 v66, v66, v67
	v_add_f32_e32 v67, v77, v79
	v_add_f32_e32 v76, v84, v85
	v_add_f32_e32 v77, v86, v87
	v_add_f32_e32 v66, v66, v67
	v_add_f32_e32 v67, v76, v77
	v_add_f32_e32 v76, v66, v67
	ds_bpermute_b32 v77, v150, v76
	v_cvt_pk_bf16_f32 v66, v72, v73
	v_cvt_pk_bf16_f32 v67, v74, v75
	global_store_dwordx4 v[88:89], v[64:67], off
	s_waitcnt lgkmcnt(0)
	s_nop 0
	v_add_f32_e32 v64, v76, v77
	ds_bpermute_b32 v65, v151, v64
	v_cvt_pk_bf16_f32 v66, v68, v69
	v_cvt_pk_bf16_f32 v67, v70, v71
	v_cvt_pk_bf16_f32 v68, v82, v83
	v_cvt_pk_bf16_f32 v69, v80, v81
	global_store_dwordx4 v[88:89], v[66:69], off offset:256
	s_and_saveexec_b64 s[0:1], s[4:5]
	s_cbranch_execz .LBB0_1456
	v_lshl_add_u32 v66, v112, 4, s24
	s_waitcnt lgkmcnt(0)
	v_add_f32_e32 v64, v64, v65
	ds_write_b32 v66, v64
; DI unsigned pk_bf16(float lo, float hi) { f32x2 v = {lo, hi}; bf16x2_t b = __builtin_convertvector(v, bf16x2_t); return __builtin_bit_cast(unsigned, b); }
; DI float bflo(unsigned w) { return __uint_as_float(w << 16); }
; DI float bfhi(unsigned w) { return __uint_as_float(w & 0xffff0000u); }
;     __device__ __forceinline__ void fused(f32x4 (&acc)[2][2][4][2], const pg8::Unit& u, int wr, int wc, int fr, int fq, PG8_LAS unsigned char* lds, int wid, int lane) const {
;     ...
;                 const int rl = ai * 128 + wr * 64 + m * 16 + fr; const size_t row = (size_t)u.pm * 256 + rl;
;                 const float rm = 1.f / sqrtf(__hip_atomic_load(ssqm + row, __ATOMIC_RELAXED, __HIP_MEMORY_SCOPE_AGENT) * (1.f / DM) + RMS_EPS);
;                 float sh = 0.f;
; #pragma unroll
;                 for (int bj = 0; bj < 2; ++bj) {
;                     const size_t off = row * DM + colb + bj * 128;
;                     f32x4 h0, h1;
;                     if (IN16) { const u32x4 hw = *(const u32x4*)((const bf16_t*)hin + off); h0 = (f32x4){bflo(hw.x), bfhi(hw.x), bflo(hw.y), bfhi(hw.y)}; h1 = (f32x4){bflo(hw.z), bfhi(hw.z), bflo(hw.w), bfhi(hw.w)}; }
;                     else { h0 = *(const f32x4*)((const float*)hin + off); h1 = *(const f32x4*)((const float*)hin + off + 4); }
;                     h0 = h0 + acc[ai][bj][m][0] * rm * gv[bj][0]; h1 = h1 + acc[ai][bj][m][1] * rm * gv[bj][1];
;                     sh += ((h0[0] * h0[0] + h0[1] * h0[1]) + (h0[2] * h0[2] + h0[3] * h0[3])) + ((h1[0] * h1[0] + h1[1] * h1[1]) + (h1[2] * h1[2] + h1[3] * h1[3]));
;                     if (OUT16) { u32x4 w; w.x = pk_bf16(h0[0], h0[1]); w.y = pk_bf16(h0[2], h0[3]); w.z = pk_bf16(h1[0], h1[1]); w.w = pk_bf16(h1[2], h1[3]); *(u32x4*)((bf16_t*)hout + off) = w; }
;                     else { *(f32x4*)((float*)hout + off) = h0; *(f32x4*)((float*)hout + off + 4) = h1; }
;                 }
;                 if (ssqh) { sh += __shfl_xor(sh, 16); sh += __shfl_xor(sh, 32); if (fq == 0) red[rl * 4 + wc] = sh; }
.LBB0_1456:
	s_or_b64 exec, exec, s[0:1]
	v_add_u32_e32 v64, 0x80, v152
	s_waitcnt lgkmcnt(0)
	v_mov_b32_e32 v65, 0
	v_lshl_add_u64 v[66:67], s[14:15], 0, v[64:65]
	v_lshl_add_u64 v[68:69], v[66:67], 2, s[12:13]
	s_nop 0
	v_lshlrev_b64 v[66:67], 11, v[66:67]
	v_lshl_add_u64 v[66:67], s[10:11], 0, v[66:67]
	v_lshl_add_u64 v[76:77], v[146:147], 1, v[66:67]
	s_nop 0
	s_nop 0
	v_mov_b32_e32 v67, 0x358637bd
	v_mov_b32_e32 v66, 0x260
	s_waitcnt vmcnt(7)
	v_fmamk_f32 v78, v252, 0x3a800000, v67
	v_mul_f32_e32 v79, 0x4f800000, v78
	v_cmp_gt_f32_e32 vcc, s2, v78
	v_lshlrev_b32_e32 v80, 16, v236
	v_and_b32_e32 v81, 0xffff0000, v236
	v_cndmask_b32_e32 v86, v78, v79, vcc
	v_sqrt_f32_e32 v87, v86
	v_lshlrev_b32_e32 v78, 16, v234
	v_and_b32_e32 v79, 0xffff0000, v234
	v_lshlrev_b32_e32 v68, 16, v235
	v_add_u32_e32 v88, -1, v87
	v_add_u32_e32 v89, 1, v87
	v_fma_f32 v90, -v88, v87, v86
	v_fma_f32 v91, -v89, v87, v86
	v_cmp_ge_f32_e64 s[0:1], 0, v90
	v_and_b32_e32 v69, 0xffff0000, v235
	v_lshlrev_b32_e32 v70, 16, v237
	v_cndmask_b32_e64 v87, v87, v88, s[0:1]
	v_cmp_lt_f32_e64 s[0:1], 0, v91
	v_and_b32_e32 v71, 0xffff0000, v237
	v_lshlrev_b32_e32 v82, 16, v238
	v_cndmask_b32_e64 v87, v87, v89, s[0:1]
	v_mul_f32_e32 v88, 0x37800000, v87
	v_cndmask_b32_e32 v87, v87, v88, vcc
	v_cmp_class_f32_e32 vcc, v86, v66
	v_and_b32_e32 v83, 0xffff0000, v238
	v_lshlrev_b32_e32 v72, 16, v239
	v_cndmask_b32_e32 v86, v87, v86, vcc
	v_div_scale_f32 v87, s[0:1], v86, v86, 1.0
	v_rcp_f32_e32 v88, v87
	v_div_scale_f32 v89, vcc, 1.0, v86, 1.0
	v_and_b32_e32 v73, 0xffff0000, v239
	v_fma_f32 v90, -v87, v88, 1.0
	v_fmac_f32_e32 v88, v90, v88
	v_mul_f32_e32 v90, v89, v88
	v_fma_f32 v91, -v87, v90, v89
	v_fmac_f32_e32 v90, v91, v88
	v_fma_f32 v87, -v87, v90, v89
	v_div_fmas_f32 v87, v87, v88, v90
	v_div_fixup_f32 v86, v87, v86, 1.0
	v_lshlrev_b32_e32 v84, 16, v240
	v_and_b32_e32 v85, 0xffff0000, v240
	v_lshlrev_b32_e32 v74, 16, v241
	v_and_b32_e32 v75, 0xffff0000, v241
	v_or_b32_e32 v254, 160, v152
	v_mov_b32_e32 v255, 0
	v_lshl_add_u64 v[254:255], s[14:15], 0, v[254:255]
	v_lshlrev_b64 v[240:241], 11, v[254:255]
	v_lshl_add_u64 v[240:241], s[10:11], 0, v[240:241]
	v_lshl_add_u64 v[240:241], v[146:147], 1, v[240:241]
	v_lshl_add_u64 v[254:255], v[254:255], 2, s[12:13]
	global_load_dword v252, v[254:255], off sc1
	global_load_dwordx4 v[234:237], v[240:241], off
	global_load_dwordx4 v[238:241], v[240:241], off offset:256
	v_pk_mul_f32 v[60:61], v[60:61], v[86:87] op_sel_hi:[1,0]
	v_pk_mul_f32 v[62:63], v[62:63], v[86:87] op_sel_hi:[1,0]
	v_pk_mul_f32 v[56:57], v[56:57], v[86:87] op_sel_hi:[1,0]
	v_pk_mul_f32 v[58:59], v[58:59], v[86:87] op_sel_hi:[1,0]
	v_pk_mul_f32 v[52:53], v[52:53], v[86:87] op_sel_hi:[1,0]
	v_pk_mul_f32 v[54:55], v[54:55], v[86:87] op_sel_hi:[1,0]
	v_pk_mul_f32 v[48:49], v[48:49], v[86:87] op_sel_hi:[1,0]
	v_pk_mul_f32 v[50:51], v[50:51], v[86:87] op_sel_hi:[1,0]
	v_pk_fma_f32 v[62:63], v[106:107], v[62:63], v[68:69]
	v_pk_fma_f32 v[60:61], v[104:105], v[60:61], v[78:79]
	v_pk_fma_f32 v[58:59], v[102:103], v[58:59], v[70:71]
	v_pk_fma_f32 v[56:57], v[100:101], v[56:57], v[80:81]
	v_pk_fma_f32 v[54:55], v[110:111], v[54:55], v[72:73]
	v_pk_fma_f32 v[52:53], v[108:109], v[52:53], v[82:83]
	v_pk_fma_f32 v[68:69], v[98:99], v[50:51], v[74:75]
	v_pk_fma_f32 v[70:71], v[96:97], v[48:49], v[84:85]
	v_cvt_pk_bf16_f32 v48, v60, v61
	v_cvt_pk_bf16_f32 v49, v62, v63
	v_mul_f32_e32 v50, v61, v61
	v_mul_f32_e32 v51, v63, v63
	v_mul_f32_e32 v61, v57, v57
	v_mul_f32_e32 v63, v59, v59
	v_mul_f32_e32 v72, v53, v53
	v_mul_f32_e32 v73, v55, v55
	v_mul_f32_e32 v74, v71, v71
	v_mul_f32_e32 v75, v69, v69
	v_fmac_f32_e32 v50, v60, v60
	v_fmac_f32_e32 v51, v62, v62
	v_fmac_f32_e32 v61, v56, v56
	v_fmac_f32_e32 v63, v58, v58
	v_fmac_f32_e32 v72, v52, v52
	v_fmac_f32_e32 v73, v54, v54
	v_fmac_f32_e32 v74, v70, v70
	v_fmac_f32_e32 v75, v68, v68
	v_add_f32_e32 v50, v50, v51
	v_add_f32_e32 v51, v61, v63
	v_add_f32_e32 v60, v72, v73
	v_add_f32_e32 v61, v74, v75
	v_add_f32_e32 v50, v50, v51
	v_add_f32_e32 v51, v60, v61
	v_add_f32_e32 v60, v50, v51
	ds_bpermute_b32 v61, v150, v60
	v_cvt_pk_bf16_f32 v50, v56, v57
	v_cvt_pk_bf16_f32 v51, v58, v59
	global_store_dwordx4 v[76:77], v[48:51], off
	s_waitcnt lgkmcnt(0)
	s_nop 0
	v_add_f32_e32 v48, v60, v61
	ds_bpermute_b32 v49, v151, v48
	v_cvt_pk_bf16_f32 v50, v52, v53
	v_cvt_pk_bf16_f32 v51, v54, v55
	v_cvt_pk_bf16_f32 v52, v70, v71
	v_cvt_pk_bf16_f32 v53, v68, v69
	global_store_dwordx4 v[76:77], v[50:53], off offset:256
	s_and_saveexec_b64 s[0:1], s[4:5]
	s_cbranch_execz .LBB0_1458
	v_lshl_add_u32 v50, v64, 4, s24
	s_waitcnt lgkmcnt(0)
	v_add_f32_e32 v48, v48, v49
	ds_write_b32 v50, v48
; DI unsigned pk_bf16(float lo, float hi) { f32x2 v = {lo, hi}; bf16x2_t b = __builtin_convertvector(v, bf16x2_t); return __builtin_bit_cast(unsigned, b); }
; DI float bflo(unsigned w) { return __uint_as_float(w << 16); }
; DI float bfhi(unsigned w) { return __uint_as_float(w & 0xffff0000u); }
;     __device__ __forceinline__ void fused(f32x4 (&acc)[2][2][4][2], const pg8::Unit& u, int wr, int wc, int fr, int fq, PG8_LAS unsigned char* lds, int wid, int lane) const {
;     ...
;                 const int rl = ai * 128 + wr * 64 + m * 16 + fr; const size_t row = (size_t)u.pm * 256 + rl;
;                 const float rm = 1.f / sqrtf(__hip_atomic_load(ssqm + row, __ATOMIC_RELAXED, __HIP_MEMORY_SCOPE_AGENT) * (1.f / DM) + RMS_EPS);
;                 float sh = 0.f;
; #pragma unroll
;                 for (int bj = 0; bj < 2; ++bj) {
;                     const size_t off = row * DM + colb + bj * 128;
;                     f32x4 h0, h1;
;                     if (IN16) { const u32x4 hw = *(const u32x4*)((const bf16_t*)hin + off); h0 = (f32x4){bflo(hw.x), bfhi(hw.x), bflo(hw.y), bfhi(hw.y)}; h1 = (f32x4){bflo(hw.z), bfhi(hw.z), bflo(hw.w), bfhi(hw.w)}; }
;                     else { h0 = *(const f32x4*)((const float*)hin + off); h1 = *(const f32x4*)((const float*)hin + off + 4); }
;                     h0 = h0 + acc[ai][bj][m][0] * rm * gv[bj][0]; h1 = h1 + acc[ai][bj][m][1] * rm * gv[bj][1];
;                     sh += ((h0[0] * h0[0] + h0[1] * h0[1]) + (h0[2] * h0[2] + h0[3] * h0[3])) + ((h1[0] * h1[0] + h1[1] * h1[1]) + (h1[2] * h1[2] + h1[3] * h1[3]));
;                     if (OUT16) { u32x4 w; w.x = pk_bf16(h0[0], h0[1]); w.y = pk_bf16(h0[2], h0[3]); w.z = pk_bf16(h1[0], h1[1]); w.w = pk_bf16(h1[2], h1[3]); *(u32x4*)((bf16_t*)hout + off) = w; }
;                     else { *(f32x4*)((float*)hout + off) = h0; *(f32x4*)((float*)hout + off + 4) = h1; }
;                 }
;                 if (ssqh) { sh += __shfl_xor(sh, 16); sh += __shfl_xor(sh, 32); if (fq == 0) red[rl * 4 + wc] = sh; }
.LBB0_1458:
	s_or_b64 exec, exec, s[0:1]
	v_add_u32_e32 v64, 0x90, v152
	s_waitcnt lgkmcnt(0)
	v_lshl_add_u64 v[48:49], s[14:15], 0, v[64:65]
	v_lshl_add_u64 v[50:51], v[48:49], 2, s[12:13]
	s_nop 0
	v_lshlrev_b64 v[48:49], 11, v[48:49]
	v_lshl_add_u64 v[48:49], s[10:11], 0, v[48:49]
	v_lshl_add_u64 v[56:57], v[146:147], 1, v[48:49]
	s_nop 0
	s_nop 0
	s_waitcnt vmcnt(7)
	v_fmac_f32_e32 v67, 0x3a800000, v253
	v_mul_f32_e32 v58, 0x4f800000, v67
	v_cmp_gt_f32_e32 vcc, s2, v67
	v_and_b32_e32 v59, 0xffff0000, v242
	v_lshlrev_b32_e32 v60, 16, v244
	v_cndmask_b32_e32 v65, v67, v58, vcc
	v_sqrt_f32_e32 v67, v65
	v_lshlrev_b32_e32 v58, 16, v242
	v_lshlrev_b32_e32 v48, 16, v243
	v_and_b32_e32 v49, 0xffff0000, v243
	v_add_u32_e32 v70, -1, v67
	v_add_u32_e32 v71, 1, v67
	v_fma_f32 v72, -v70, v67, v65
	v_fma_f32 v73, -v71, v67, v65
	v_cmp_ge_f32_e64 s[0:1], 0, v72
	v_and_b32_e32 v61, 0xffff0000, v244
	v_lshlrev_b32_e32 v50, 16, v245
	v_cndmask_b32_e64 v67, v67, v70, s[0:1]
	v_cmp_lt_f32_e64 s[0:1], 0, v73
	v_and_b32_e32 v51, 0xffff0000, v245
	v_lshlrev_b32_e32 v62, 16, v246
	v_cndmask_b32_e64 v67, v67, v71, s[0:1]
	v_mul_f32_e32 v70, 0x37800000, v67
	v_cndmask_b32_e32 v67, v67, v70, vcc
	v_cmp_class_f32_e32 vcc, v65, v66
	v_and_b32_e32 v63, 0xffff0000, v246
	v_lshlrev_b32_e32 v52, 16, v247
	v_cndmask_b32_e32 v65, v67, v65, vcc
	v_div_scale_f32 v66, s[0:1], v65, v65, 1.0
	v_rcp_f32_e32 v67, v66
	v_div_scale_f32 v70, vcc, 1.0, v65, 1.0
	v_and_b32_e32 v53, 0xffff0000, v247
	v_fma_f32 v71, -v66, v67, 1.0
	v_fmac_f32_e32 v67, v71, v67
	v_mul_f32_e32 v71, v70, v67
	v_fma_f32 v72, -v66, v71, v70
	v_fmac_f32_e32 v71, v72, v67
	v_fma_f32 v66, -v66, v71, v70
	v_div_fmas_f32 v66, v66, v67, v71
	v_div_fixup_f32 v66, v66, v65, 1.0
	v_lshlrev_b32_e32 v68, 16, v248
	v_and_b32_e32 v69, 0xffff0000, v248
	v_lshlrev_b32_e32 v54, 16, v249
	v_and_b32_e32 v55, 0xffff0000, v249
	v_or_b32_e32 v254, 176, v152
	v_mov_b32_e32 v255, 0
	v_lshl_add_u64 v[254:255], s[14:15], 0, v[254:255]
	v_lshlrev_b64 v[248:249], 11, v[254:255]
	v_lshl_add_u64 v[248:249], s[10:11], 0, v[248:249]
	v_lshl_add_u64 v[248:249], v[146:147], 1, v[248:249]
	v_lshl_add_u64 v[254:255], v[254:255], 2, s[12:13]
	global_load_dword v253, v[254:255], off sc1
	global_load_dwordx4 v[242:245], v[248:249], off
	global_load_dwordx4 v[246:249], v[248:249], off offset:256
	v_pk_mul_f32 v[44:45], v[44:45], v[66:67] op_sel_hi:[1,0]
	v_pk_mul_f32 v[46:47], v[46:47], v[66:67] op_sel_hi:[1,0]
	v_pk_mul_f32 v[40:41], v[40:41], v[66:67] op_sel_hi:[1,0]
	v_pk_mul_f32 v[42:43], v[42:43], v[66:67] op_sel_hi:[1,0]
	v_pk_mul_f32 v[36:37], v[36:37], v[66:67] op_sel_hi:[1,0]
	v_pk_mul_f32 v[38:39], v[38:39], v[66:67] op_sel_hi:[1,0]
	v_pk_mul_f32 v[32:33], v[32:33], v[66:67] op_sel_hi:[1,0]
	v_pk_mul_f32 v[34:35], v[34:35], v[66:67] op_sel_hi:[1,0]
	v_pk_fma_f32 v[46:47], v[106:107], v[46:47], v[48:49]
	v_pk_fma_f32 v[44:45], v[104:105], v[44:45], v[58:59]
	v_pk_fma_f32 v[42:43], v[102:103], v[42:43], v[50:51]
	v_pk_fma_f32 v[40:41], v[100:101], v[40:41], v[60:61]
	v_pk_fma_f32 v[38:39], v[110:111], v[38:39], v[52:53]
	v_pk_fma_f32 v[36:37], v[108:109], v[36:37], v[62:63]
	v_pk_fma_f32 v[48:49], v[98:99], v[34:35], v[54:55]
	v_pk_fma_f32 v[50:51], v[96:97], v[32:33], v[68:69]
	v_cvt_pk_bf16_f32 v32, v44, v45
	v_cvt_pk_bf16_f32 v33, v46, v47
	v_mul_f32_e32 v34, v45, v45
	v_mul_f32_e32 v35, v47, v47
	v_mul_f32_e32 v45, v41, v41
	v_mul_f32_e32 v47, v43, v43
	v_mul_f32_e32 v52, v37, v37
	v_mul_f32_e32 v53, v39, v39
	v_mul_f32_e32 v54, v51, v51
	v_mul_f32_e32 v55, v49, v49
	v_fmac_f32_e32 v34, v44, v44
	v_fmac_f32_e32 v35, v46, v46
	v_fmac_f32_e32 v45, v40, v40
	v_fmac_f32_e32 v47, v42, v42
	v_fmac_f32_e32 v52, v36, v36
	v_fmac_f32_e32 v53, v38, v38
	v_fmac_f32_e32 v54, v50, v50
	v_fmac_f32_e32 v55, v48, v48
	v_add_f32_e32 v34, v34, v35
	v_add_f32_e32 v35, v45, v47
	v_add_f32_e32 v44, v52, v53
	v_add_f32_e32 v45, v54, v55
	v_add_f32_e32 v34, v34, v35
	v_add_f32_e32 v35, v44, v45
	v_add_f32_e32 v44, v34, v35
	ds_bpermute_b32 v45, v150, v44
	v_cvt_pk_bf16_f32 v34, v40, v41
	v_cvt_pk_bf16_f32 v35, v42, v43
	global_store_dwordx4 v[56:57], v[32:35], off
	s_waitcnt lgkmcnt(0)
	s_nop 0
	v_add_f32_e32 v32, v44, v45
	ds_bpermute_b32 v33, v151, v32
	v_cvt_pk_bf16_f32 v34, v36, v37
	v_cvt_pk_bf16_f32 v35, v38, v39
	v_cvt_pk_bf16_f32 v36, v50, v51
	v_cvt_pk_bf16_f32 v37, v48, v49
	global_store_dwordx4 v[56:57], v[34:37], off offset:256
	s_and_saveexec_b64 s[0:1], s[4:5]
	s_cbranch_execz .LBB0_1460
	v_lshl_add_u32 v34, v64, 4, s24
	s_waitcnt lgkmcnt(0)
	v_add_f32_e32 v32, v32, v33
	ds_write_b32 v34, v32
; DI unsigned pk_bf16(float lo, float hi) { f32x2 v = {lo, hi}; bf16x2_t b = __builtin_convertvector(v, bf16x2_t); return __builtin_bit_cast(unsigned, b); }
; DI float bflo(unsigned w) { return __uint_as_float(w << 16); }
; DI float bfhi(unsigned w) { return __uint_as_float(w & 0xffff0000u); }
;     __device__ __forceinline__ void fused(f32x4 (&acc)[2][2][4][2], const pg8::Unit& u, int wr, int wc, int fr, int fq, PG8_LAS unsigned char* lds, int wid, int lane) const {
;     ...
;                 const int rl = ai * 128 + wr * 64 + m * 16 + fr; const size_t row = (size_t)u.pm * 256 + rl;
;                 const float rm = 1.f / sqrtf(__hip_atomic_load(ssqm + row, __ATOMIC_RELAXED, __HIP_MEMORY_SCOPE_AGENT) * (1.f / DM) + RMS_EPS);
;                 float sh = 0.f;
; #pragma unroll
;                 for (int bj = 0; bj < 2; ++bj) {
;                     const size_t off = row * DM + colb + bj * 128;
;                     f32x4 h0, h1;
;                     if (IN16) { const u32x4 hw = *(const u32x4*)((const bf16_t*)hin + off); h0 = (f32x4){bflo(hw.x), bfhi(hw.x), bflo(hw.y), bfhi(hw.y)}; h1 = (f32x4){bflo(hw.z), bfhi(hw.z), bflo(hw.w), bfhi(hw.w)}; }
;                     else { h0 = *(const f32x4*)((const float*)hin + off); h1 = *(const f32x4*)((const float*)hin + off + 4); }
;                     h0 = h0 + acc[ai][bj][m][0] * rm * gv[bj][0]; h1 = h1 + acc[ai][bj][m][1] * rm * gv[bj][1];
;                     sh += ((h0[0] * h0[0] + h0[1] * h0[1]) + (h0[2] * h0[2] + h0[3] * h0[3])) + ((h1[0] * h1[0] + h1[1] * h1[1]) + (h1[2] * h1[2] + h1[3] * h1[3]));
;                     if (OUT16) { u32x4 w; w.x = pk_bf16(h0[0], h0[1]); w.y = pk_bf16(h0[2], h0[3]); w.z = pk_bf16(h1[0], h1[1]); w.w = pk_bf16(h1[2], h1[3]); *(u32x4*)((bf16_t*)hout + off) = w; }
;                     else { *(f32x4*)((float*)hout + off) = h0; *(f32x4*)((float*)hout + off + 4) = h1; }
;                 }
;                 if (ssqh) { sh += __shfl_xor(sh, 16); sh += __shfl_xor(sh, 32); if (fq == 0) red[rl * 4 + wc] = sh; }
.LBB0_1460:
	s_or_b64 exec, exec, s[0:1]
	v_add_u32_e32 v32, 0xa0, v152
	s_waitcnt lgkmcnt(0)
	v_mov_b32_e32 v33, 0
	v_lshl_add_u64 v[34:35], s[14:15], 0, v[32:33]
	v_lshl_add_u64 v[36:37], v[34:35], 2, s[12:13]
	s_nop 0
	v_lshlrev_b64 v[34:35], 11, v[34:35]
	v_lshl_add_u64 v[34:35], s[10:11], 0, v[34:35]
	v_lshl_add_u64 v[44:45], v[146:147], 1, v[34:35]
	s_nop 0
	s_nop 0
	v_mov_b32_e32 v35, 0x358637bd
	v_mov_b32_e32 v34, 0x260
	s_waitcnt vmcnt(7)
	v_fmamk_f32 v46, v252, 0x3a800000, v35
	v_mul_f32_e32 v47, 0x4f800000, v46
	v_cmp_gt_f32_e32 vcc, s2, v46
	v_lshlrev_b32_e32 v48, 16, v236
	v_and_b32_e32 v49, 0xffff0000, v236
	v_cndmask_b32_e32 v54, v46, v47, vcc
	v_sqrt_f32_e32 v55, v54
	v_lshlrev_b32_e32 v46, 16, v234
	v_and_b32_e32 v47, 0xffff0000, v234
	v_lshlrev_b32_e32 v36, 16, v235
	v_add_u32_e32 v56, -1, v55
	v_add_u32_e32 v57, 1, v55
	v_fma_f32 v58, -v56, v55, v54
	v_fma_f32 v59, -v57, v55, v54
	v_cmp_ge_f32_e64 s[0:1], 0, v58
	v_and_b32_e32 v37, 0xffff0000, v235
	v_lshlrev_b32_e32 v38, 16, v237
	v_cndmask_b32_e64 v55, v55, v56, s[0:1]
	v_cmp_lt_f32_e64 s[0:1], 0, v59
	v_and_b32_e32 v39, 0xffff0000, v237
	v_lshlrev_b32_e32 v50, 16, v238
	v_cndmask_b32_e64 v55, v55, v57, s[0:1]
	v_mul_f32_e32 v56, 0x37800000, v55
	v_cndmask_b32_e32 v55, v55, v56, vcc
	v_cmp_class_f32_e32 vcc, v54, v34
	v_and_b32_e32 v51, 0xffff0000, v238
	v_lshlrev_b32_e32 v40, 16, v239
	v_cndmask_b32_e32 v54, v55, v54, vcc
	v_div_scale_f32 v55, s[0:1], v54, v54, 1.0
	v_rcp_f32_e32 v56, v55
	v_div_scale_f32 v57, vcc, 1.0, v54, 1.0
	v_and_b32_e32 v41, 0xffff0000, v239
	v_fma_f32 v58, -v55, v56, 1.0
	v_fmac_f32_e32 v56, v58, v56
	v_mul_f32_e32 v58, v57, v56
	v_fma_f32 v59, -v55, v58, v57
	v_fmac_f32_e32 v58, v59, v56
	v_fma_f32 v55, -v55, v58, v57
	v_div_fmas_f32 v55, v55, v56, v58
	v_div_fixup_f32 v54, v55, v54, 1.0
	v_lshlrev_b32_e32 v52, 16, v240
	v_and_b32_e32 v53, 0xffff0000, v240
	v_lshlrev_b32_e32 v42, 16, v241
	v_and_b32_e32 v43, 0xffff0000, v241
	v_pk_mul_f32 v[28:29], v[28:29], v[54:55] op_sel_hi:[1,0]
	v_pk_mul_f32 v[30:31], v[30:31], v[54:55] op_sel_hi:[1,0]
	v_pk_mul_f32 v[24:25], v[24:25], v[54:55] op_sel_hi:[1,0]
	v_pk_mul_f32 v[26:27], v[26:27], v[54:55] op_sel_hi:[1,0]
	v_pk_mul_f32 v[20:21], v[20:21], v[54:55] op_sel_hi:[1,0]
	v_pk_mul_f32 v[22:23], v[22:23], v[54:55] op_sel_hi:[1,0]
	v_pk_mul_f32 v[16:17], v[16:17], v[54:55] op_sel_hi:[1,0]
	v_pk_mul_f32 v[18:19], v[18:19], v[54:55] op_sel_hi:[1,0]
	v_pk_fma_f32 v[30:31], v[106:107], v[30:31], v[36:37]
	v_pk_fma_f32 v[28:29], v[104:105], v[28:29], v[46:47]
	v_pk_fma_f32 v[26:27], v[102:103], v[26:27], v[38:39]
	v_pk_fma_f32 v[24:25], v[100:101], v[24:25], v[48:49]
	v_pk_fma_f32 v[22:23], v[110:111], v[22:23], v[40:41]
	v_pk_fma_f32 v[20:21], v[108:109], v[20:21], v[50:51]
	v_pk_fma_f32 v[36:37], v[98:99], v[18:19], v[42:43]
	v_pk_fma_f32 v[38:39], v[96:97], v[16:17], v[52:53]
	v_cvt_pk_bf16_f32 v16, v28, v29
	v_cvt_pk_bf16_f32 v17, v30, v31
	v_mul_f32_e32 v18, v29, v29
	v_mul_f32_e32 v19, v31, v31
	v_mul_f32_e32 v29, v25, v25
	v_mul_f32_e32 v31, v27, v27
	v_mul_f32_e32 v40, v21, v21
	v_mul_f32_e32 v41, v23, v23
	v_mul_f32_e32 v42, v39, v39
	v_mul_f32_e32 v43, v37, v37
	v_fmac_f32_e32 v18, v28, v28
	v_fmac_f32_e32 v19, v30, v30
	v_fmac_f32_e32 v29, v24, v24
	v_fmac_f32_e32 v31, v26, v26
	v_fmac_f32_e32 v40, v20, v20
	v_fmac_f32_e32 v41, v22, v22
	v_fmac_f32_e32 v42, v38, v38
	v_fmac_f32_e32 v43, v36, v36
	v_add_f32_e32 v18, v18, v19
	v_add_f32_e32 v19, v29, v31
	v_add_f32_e32 v28, v40, v41
	v_add_f32_e32 v29, v42, v43
	v_add_f32_e32 v18, v18, v19
	v_add_f32_e32 v19, v28, v29
	v_add_f32_e32 v28, v18, v19
	ds_bpermute_b32 v29, v150, v28
	v_cvt_pk_bf16_f32 v18, v24, v25
	v_cvt_pk_bf16_f32 v19, v26, v27
	global_store_dwordx4 v[44:45], v[16:19], off
	s_waitcnt lgkmcnt(0)
	s_nop 0
	v_add_f32_e32 v16, v28, v29
	ds_bpermute_b32 v17, v151, v16
	v_cvt_pk_bf16_f32 v18, v20, v21
	v_cvt_pk_bf16_f32 v19, v22, v23
	v_cvt_pk_bf16_f32 v20, v38, v39
	v_cvt_pk_bf16_f32 v21, v36, v37
	global_store_dwordx4 v[44:45], v[18:21], off offset:256
	s_and_saveexec_b64 s[0:1], s[4:5]
	s_cbranch_execz .LBB0_1462
	v_lshl_add_u32 v18, v32, 4, s24
	s_waitcnt lgkmcnt(0)
	v_add_f32_e32 v16, v16, v17
	ds_write_b32 v18, v16
; DI unsigned pk_bf16(float lo, float hi) { f32x2 v = {lo, hi}; bf16x2_t b = __builtin_convertvector(v, bf16x2_t); return __builtin_bit_cast(unsigned, b); }
; DI float bflo(unsigned w) { return __uint_as_float(w << 16); }
; DI float bfhi(unsigned w) { return __uint_as_float(w & 0xffff0000u); }
;     __device__ __forceinline__ void fused(f32x4 (&acc)[2][2][4][2], const pg8::Unit& u, int wr, int wc, int fr, int fq, PG8_LAS unsigned char* lds, int wid, int lane) const {
;     ...
;                 const int rl = ai * 128 + wr * 64 + m * 16 + fr; const size_t row = (size_t)u.pm * 256 + rl;
;                 const float rm = 1.f / sqrtf(__hip_atomic_load(ssqm + row, __ATOMIC_RELAXED, __HIP_MEMORY_SCOPE_AGENT) * (1.f / DM) + RMS_EPS);
;                 float sh = 0.f;
; #pragma unroll
;                 for (int bj = 0; bj < 2; ++bj) {
;                     const size_t off = row * DM + colb + bj * 128;
;                     f32x4 h0, h1;
;                     if (IN16) { const u32x4 hw = *(const u32x4*)((const bf16_t*)hin + off); h0 = (f32x4){bflo(hw.x), bfhi(hw.x), bflo(hw.y), bfhi(hw.y)}; h1 = (f32x4){bflo(hw.z), bfhi(hw.z), bflo(hw.w), bfhi(hw.w)}; }
;                     else { h0 = *(const f32x4*)((const float*)hin + off); h1 = *(const f32x4*)((const float*)hin + off + 4); }
;                     h0 = h0 + acc[ai][bj][m][0] * rm * gv[bj][0]; h1 = h1 + acc[ai][bj][m][1] * rm * gv[bj][1];
;                     sh += ((h0[0] * h0[0] + h0[1] * h0[1]) + (h0[2] * h0[2] + h0[3] * h0[3])) + ((h1[0] * h1[0] + h1[1] * h1[1]) + (h1[2] * h1[2] + h1[3] * h1[3]));
;                     if (OUT16) { u32x4 w; w.x = pk_bf16(h0[0], h0[1]); w.y = pk_bf16(h0[2], h0[3]); w.z = pk_bf16(h1[0], h1[1]); w.w = pk_bf16(h1[2], h1[3]); *(u32x4*)((bf16_t*)hout + off) = w; }
;                     else { *(f32x4*)((float*)hout + off) = h0; *(f32x4*)((float*)hout + off + 4) = h1; }
;                 }
;                 if (ssqh) { sh += __shfl_xor(sh, 16); sh += __shfl_xor(sh, 32); if (fq == 0) red[rl * 4 + wc] = sh; }
.LBB0_1462:
	s_or_b64 exec, exec, s[0:1]
	v_add_u32_e32 v32, 0xb0, v152
	s_waitcnt lgkmcnt(0)
	v_lshl_add_u64 v[16:17], s[14:15], 0, v[32:33]
	v_lshl_add_u64 v[18:19], v[16:17], 2, s[12:13]
	s_nop 0
	v_lshlrev_b64 v[16:17], 11, v[16:17]
	v_lshl_add_u64 v[16:17], s[10:11], 0, v[16:17]
	v_lshl_add_u64 v[24:25], v[146:147], 1, v[16:17]
	s_nop 0
	s_nop 0
	s_waitcnt vmcnt(4)
	v_fmac_f32_e32 v35, 0x3a800000, v253
	v_mul_f32_e32 v26, 0x4f800000, v35
	v_cmp_gt_f32_e32 vcc, s2, v35
	v_and_b32_e32 v27, 0xffff0000, v242
	v_lshlrev_b32_e32 v28, 16, v244
	v_cndmask_b32_e32 v33, v35, v26, vcc
	v_sqrt_f32_e32 v35, v33
	v_lshlrev_b32_e32 v26, 16, v242
	v_lshlrev_b32_e32 v16, 16, v243
	v_and_b32_e32 v17, 0xffff0000, v243
	v_add_u32_e32 v38, -1, v35
	v_add_u32_e32 v39, 1, v35
	v_fma_f32 v40, -v38, v35, v33
	v_fma_f32 v41, -v39, v35, v33
	v_cmp_ge_f32_e64 s[0:1], 0, v40
	v_and_b32_e32 v29, 0xffff0000, v244
	v_lshlrev_b32_e32 v18, 16, v245
	v_cndmask_b32_e64 v35, v35, v38, s[0:1]
	v_cmp_lt_f32_e64 s[0:1], 0, v41
	v_and_b32_e32 v19, 0xffff0000, v245
	v_lshlrev_b32_e32 v30, 16, v246
	v_cndmask_b32_e64 v35, v35, v39, s[0:1]
	v_mul_f32_e32 v38, 0x37800000, v35
	v_cndmask_b32_e32 v35, v35, v38, vcc
	v_cmp_class_f32_e32 vcc, v33, v34
	v_and_b32_e32 v31, 0xffff0000, v246
	v_lshlrev_b32_e32 v20, 16, v247
	v_cndmask_b32_e32 v33, v35, v33, vcc
	v_div_scale_f32 v34, s[0:1], v33, v33, 1.0
	v_rcp_f32_e32 v35, v34
	v_div_scale_f32 v38, vcc, 1.0, v33, 1.0
	v_and_b32_e32 v21, 0xffff0000, v247
	v_fma_f32 v39, -v34, v35, 1.0
	v_fmac_f32_e32 v35, v39, v35
	v_mul_f32_e32 v39, v38, v35
	v_fma_f32 v40, -v34, v39, v38
	v_fmac_f32_e32 v39, v40, v35
	v_fma_f32 v34, -v34, v39, v38
	v_div_fmas_f32 v34, v34, v35, v39
	v_div_fixup_f32 v34, v34, v33, 1.0
	v_lshlrev_b32_e32 v36, 16, v248
	v_and_b32_e32 v37, 0xffff0000, v248
	v_lshlrev_b32_e32 v22, 16, v249
	v_and_b32_e32 v23, 0xffff0000, v249
	v_pk_mul_f32 v[12:13], v[12:13], v[34:35] op_sel_hi:[1,0]
	v_pk_mul_f32 v[14:15], v[14:15], v[34:35] op_sel_hi:[1,0]
	v_pk_mul_f32 v[8:9], v[8:9], v[34:35] op_sel_hi:[1,0]
	v_pk_mul_f32 v[10:11], v[10:11], v[34:35] op_sel_hi:[1,0]
	v_pk_mul_f32 v[4:5], v[4:5], v[34:35] op_sel_hi:[1,0]
	v_pk_mul_f32 v[6:7], v[6:7], v[34:35] op_sel_hi:[1,0]
	v_pk_mul_f32 v[0:1], v[0:1], v[34:35] op_sel_hi:[1,0]
	v_pk_mul_f32 v[2:3], v[2:3], v[34:35] op_sel_hi:[1,0]
	v_pk_fma_f32 v[14:15], v[106:107], v[14:15], v[16:17]
	v_pk_fma_f32 v[12:13], v[104:105], v[12:13], v[26:27]
	v_pk_fma_f32 v[10:11], v[102:103], v[10:11], v[18:19]
	v_pk_fma_f32 v[8:9], v[100:101], v[8:9], v[28:29]
	v_pk_fma_f32 v[6:7], v[110:111], v[6:7], v[20:21]
	v_pk_fma_f32 v[4:5], v[108:109], v[4:5], v[30:31]
	v_pk_fma_f32 v[16:17], v[98:99], v[2:3], v[22:23]
	v_pk_fma_f32 v[18:19], v[96:97], v[0:1], v[36:37]
	v_cvt_pk_bf16_f32 v0, v12, v13
	v_cvt_pk_bf16_f32 v1, v14, v15
	v_mul_f32_e32 v2, v13, v13
	v_mul_f32_e32 v3, v15, v15
	v_mul_f32_e32 v13, v9, v9
	v_mul_f32_e32 v15, v11, v11
	v_mul_f32_e32 v20, v5, v5
	v_mul_f32_e32 v21, v7, v7
	v_mul_f32_e32 v22, v19, v19
	v_mul_f32_e32 v23, v17, v17
	v_fmac_f32_e32 v2, v12, v12
	v_fmac_f32_e32 v3, v14, v14
	v_fmac_f32_e32 v13, v8, v8
	v_fmac_f32_e32 v15, v10, v10
	v_fmac_f32_e32 v20, v4, v4
	v_fmac_f32_e32 v21, v6, v6
	v_fmac_f32_e32 v22, v18, v18
	v_fmac_f32_e32 v23, v16, v16
	v_add_f32_e32 v2, v2, v3
	v_add_f32_e32 v3, v13, v15
	v_add_f32_e32 v12, v20, v21
	v_add_f32_e32 v13, v22, v23
	v_add_f32_e32 v2, v2, v3
	v_add_f32_e32 v3, v12, v13
	v_add_f32_e32 v12, v2, v3
	ds_bpermute_b32 v13, v150, v12
	v_cvt_pk_bf16_f32 v2, v8, v9
	v_cvt_pk_bf16_f32 v3, v10, v11
	global_store_dwordx4 v[24:25], v[0:3], off
	s_waitcnt lgkmcnt(0)
	s_nop 0
	v_add_f32_e32 v0, v12, v13
	ds_bpermute_b32 v1, v151, v0
	v_cvt_pk_bf16_f32 v2, v4, v5
	v_cvt_pk_bf16_f32 v3, v6, v7
	v_cvt_pk_bf16_f32 v4, v18, v19
	v_cvt_pk_bf16_f32 v5, v16, v17
	global_store_dwordx4 v[24:25], v[2:5], off offset:256
	s_and_saveexec_b64 s[0:1], s[4:5]
	s_cbranch_execz .LBB0_1464
	v_lshl_add_u32 v2, v32, 4, s24
	s_waitcnt lgkmcnt(0)
	v_add_f32_e32 v0, v0, v1
	ds_write_b32 v2, v0

; DI unsigned pk_bf16(float lo, float hi) { f32x2 v = {lo, hi}; bf16x2_t b = __builtin_convertvector(v, bf16x2_t); return __builtin_bit_cast(unsigned, b); }
; DI float bflo(unsigned w) { return __uint_as_float(w << 16); }
; DI float bfhi(unsigned w) { return __uint_as_float(w & 0xffff0000u); }
;     __device__ __forceinline__ void fused(f32x4 (&acc)[2][2][4][2], const pg8::Unit& u, int wr, int wc, int fr, int fq, PG8_LAS unsigned char* lds, int wid, int lane) const {
;     ...
;         const int colb = u.pn * 256 + wc * 32 + 8 * fq;
;         f32x4 gv[2][2];
; #pragma unroll
;         for (int bj = 0; bj < 2; ++bj)
; #pragma unroll
;             for (int n = 0; n < 2; ++n) gv[bj][n] = *(const f32x4*)(gA + colb + bj * 128 + 4 * n);
; #pragma unroll
;         for (int ai = 0; ai < 2; ++ai)
; #pragma unroll
;             for (int m = 0; m < 4; ++m) {
;                 const int rl = ai * 128 + wr * 64 + m * 16 + fr; const size_t row = (size_t)u.pm * 256 + rl;
;                 const float rm = 1.f / sqrtf(__hip_atomic_load(ssqm + row, __ATOMIC_RELAXED, __HIP_MEMORY_SCOPE_AGENT) * (1.f / DM) + RMS_EPS);
;                 float sh = 0.f;
; #pragma unroll
;                 for (int bj = 0; bj < 2; ++bj) {
;                     const size_t off = row * DM + colb + bj * 128;
;                     f32x4 h0, h1;
;                     if (IN16) { const u32x4 hw = *(const u32x4*)((const bf16_t*)hin + off); h0 = (f32x4){bflo(hw.x), bfhi(hw.x), bflo(hw.y), bfhi(hw.y)}; h1 = (f32x4){bflo(hw.z), bfhi(hw.z), bflo(hw.w), bfhi(hw.w)}; }
;                     else { h0 = *(const f32x4*)((const float*)hin + off); h1 = *(const f32x4*)((const float*)hin + off + 4); }
;                     h0 = h0 + acc[ai][bj][m][0] * rm * gv[bj][0]; h1 = h1 + acc[ai][bj][m][1] * rm * gv[bj][1];
;                     sh += ((h0[0] * h0[0] + h0[1] * h0[1]) + (h0[2] * h0[2] + h0[3] * h0[3])) + ((h1[0] * h1[0] + h1[1] * h1[1]) + (h1[2] * h1[2] + h1[3] * h1[3]));
;                     if (OUT16) { u32x4 w; w.x = pk_bf16(h0[0], h0[1]); w.y = pk_bf16(h0[2], h0[3]); w.z = pk_bf16(h1[0], h1[1]); w.w = pk_bf16(h1[2], h1[3]); *(u32x4*)((bf16_t*)hout + off) = w; }
;                     else { *(f32x4*)((float*)hout + off) = h0; *(f32x4*)((float*)hout + off + 4) = h1; }
.LBB0_1629:
	s_or_b64 exec, exec, s[2:3]
	s_lshl_b32 s2, s33, 5
	s_lshl_b32 s3, s30, 8
	s_or_b32 s2, s3, s2
	v_or_b32_e32 v154, s2, v156
	s_lshl_b64 s[10:11], s[0:1], 8
	v_mov_b32_e32 v153, 0
	v_ashrrev_i32_e32 v155, 31, v154
	v_lshl_add_u64 v[164:165], s[10:11], 0, v[152:153]
	v_lshl_add_u64 v[116:117], v[154:155], 2, s[8:9]
	v_lshl_add_u64 v[166:167], v[164:165], 2, s[6:7]
	s_barrier
	global_load_dwordx4 v[120:123], v[116:117], off offset:16
	global_load_dwordx4 v[124:127], v[116:117], off
	global_load_dwordx4 v[108:111], v[116:117], off offset:528
	s_nop 0
	global_load_dwordx4 v[116:119], v[116:117], off offset:512
	v_lshlrev_b64 v[164:165], 10, v[164:165]
	v_or_b32_e32 v254, 0, v152
	v_mov_b32_e32 v255, 0
	v_lshl_add_u64 v[254:255], s[10:11], 0, v[254:255]
	v_lshlrev_b64 v[240:241], 10, v[254:255]
	v_lshl_add_u64 v[240:241], v[240:241], 0, v[154:155]
	v_lshlrev_b64 v[240:241], 1, v[240:241]
	v_lshl_add_u64 v[240:241], s[4:5], 0, v[240:241]
	v_lshl_add_u64 v[254:255], v[254:255], 2, s[6:7]
	global_load_dword v252, v[254:255], off sc1
	global_load_dwordx4 v[234:237], v[240:241], off
	global_load_dwordx4 v[238:241], v[240:241], off offset:256
	v_or_b32_e32 v254, 16, v152
	v_mov_b32_e32 v255, 0
	v_lshl_add_u64 v[254:255], s[10:11], 0, v[254:255]
	v_lshlrev_b64 v[248:249], 10, v[254:255]
	v_lshl_add_u64 v[248:249], v[248:249], 0, v[154:155]
	v_lshlrev_b64 v[248:249], 1, v[248:249]
	v_lshl_add_u64 v[248:249], s[4:5], 0, v[248:249]
	v_lshl_add_u64 v[254:255], v[254:255], 2, s[6:7]
	global_load_dword v253, v[254:255], off sc1
	global_load_dwordx4 v[242:245], v[248:249], off
	global_load_dwordx4 v[246:249], v[248:249], off offset:256
	s_nop 0
	v_lshl_add_u64 v[168:169], v[164:165], 0, v[154:155]
	v_lshlrev_b64 v[170:171], 1, v[168:169]
	v_lshl_add_u64 v[164:165], s[4:5], 0, v[170:171]
	s_nop 0
	v_mov_b32_e32 v147, 0x358637bd
	s_mov_b32 s2, 0xf800000
	v_mov_b32_e32 v145, 0x260
	v_readlane_b32 s12, v251, 0
	v_readlane_b32 s14, v251, 2
	v_readlane_b32 s15, v251, 3
	v_or_b32_e32 v170, 0x100, v170
	v_lshl_add_u64 v[170:171], s[4:5], 0, v[170:171]
	v_lshl_add_u64 v[168:169], v[168:169], 2, s[14:15]
	v_readlane_b32 s13, v251, 1
	s_waitcnt vmcnt(3)
	v_fmamk_f32 v149, v252, 0x3a800000, v147
	v_mul_f32_e32 v151, 0x4f800000, v149
	v_cmp_gt_f32_e32 vcc, s2, v149
	v_lshlrev_b32_e32 v172, 16, v234
	v_cndmask_b32_e32 v149, v149, v151, vcc
	v_sqrt_f32_e32 v151, v149
	v_and_b32_e32 v173, 0xffff0000, v234
	v_lshlrev_b32_e32 v164, 16, v235
	v_and_b32_e32 v165, 0xffff0000, v235
	v_add_u32_e32 v176, -1, v151
	v_add_u32_e32 v177, 1, v151
	v_fma_f32 v178, -v176, v151, v149
	v_fma_f32 v179, -v177, v151, v149
	v_cmp_ge_f32_e64 s[0:1], 0, v178
	v_lshlrev_b32_e32 v174, 16, v236
	v_and_b32_e32 v175, 0xffff0000, v236
	v_cndmask_b32_e64 v151, v151, v176, s[0:1]
	v_cmp_lt_f32_e64 s[0:1], 0, v179
	v_lshlrev_b32_e32 v166, 16, v237
	v_and_b32_e32 v167, 0xffff0000, v237
	v_cndmask_b32_e64 v151, v151, v177, s[0:1]
	v_mul_f32_e32 v176, 0x37800000, v151
	v_cndmask_b32_e32 v151, v151, v176, vcc
	v_cmp_class_f32_e32 vcc, v149, v145
	s_nop 1
	v_cndmask_b32_e32 v149, v151, v149, vcc
	v_div_scale_f32 v151, s[0:1], v149, v149, 1.0
	v_rcp_f32_e32 v176, v151
	v_div_scale_f32 v177, vcc, 1.0, v149, 1.0
	v_fma_f32 v178, -v151, v176, 1.0
	v_fmac_f32_e32 v176, v178, v176
	v_mul_f32_e32 v178, v177, v176
	v_fma_f32 v179, -v151, v178, v177
	v_fmac_f32_e32 v178, v179, v176
	v_fma_f32 v151, -v151, v178, v177
	v_div_fmas_f32 v151, v151, v176, v178
	v_div_fixup_f32 v176, v151, v149, 1.0
	v_pk_mul_f32 v[140:141], v[140:141], v[176:177] op_sel_hi:[1,0]
	v_pk_mul_f32 v[142:143], v[142:143], v[176:177] op_sel_hi:[1,0]
	v_pk_mul_f32 v[178:179], v[136:137], v[176:177] op_sel_hi:[1,0]
	v_pk_mul_f32 v[180:181], v[138:139], v[176:177] op_sel_hi:[1,0]
	v_pk_fma_f32 v[138:139], v[126:127], v[142:143], v[164:165]
	v_pk_fma_f32 v[136:137], v[124:125], v[140:141], v[172:173]
	v_pk_fma_f32 v[142:143], v[122:123], v[180:181], v[166:167]
	v_pk_fma_f32 v[140:141], v[120:121], v[178:179], v[174:175]
	global_store_dwordx4 v[168:169], v[136:139], off
	global_store_dwordx4 v[168:169], v[140:143], off offset:16
	s_nop 0
	v_pk_mul_f32 v[132:133], v[132:133], v[176:177] op_sel_hi:[1,0]
	v_or_b32_e32 v140, 16, v152
	v_mov_b32_e32 v141, v153
	v_lshl_add_u64 v[140:141], s[10:11], 0, v[140:141]
	v_lshl_add_u64 v[142:143], v[140:141], 2, s[6:7]
	v_lshlrev_b64 v[140:141], 10, v[140:141]
	v_pk_mul_f32 v[134:135], v[134:135], v[176:177] op_sel_hi:[1,0]
	v_pk_mul_f32 v[170:171], v[128:129], v[176:177] op_sel_hi:[1,0]
	v_pk_mul_f32 v[172:173], v[130:131], v[176:177] op_sel_hi:[1,0]
	v_lshl_add_u64 v[140:141], v[140:141], 0, v[154:155]
	v_lshlrev_b64 v[164:165], 1, v[140:141]
	v_lshl_add_u64 v[166:167], s[4:5], 0, v[164:165]
	v_or_b32_e32 v164, 0x100, v164
	v_lshlrev_b32_e32 v128, 16, v238
	v_and_b32_e32 v129, 0xffff0000, v238
	v_lshlrev_b32_e32 v130, 16, v239
	v_and_b32_e32 v131, 0xffff0000, v239
	v_lshlrev_b32_e32 v136, 16, v240
	v_and_b32_e32 v137, 0xffff0000, v240
	v_lshlrev_b32_e32 v138, 16, v241
	v_and_b32_e32 v139, 0xffff0000, v241
	v_or_b32_e32 v254, 32, v152
	v_mov_b32_e32 v255, 0
	v_lshl_add_u64 v[254:255], s[10:11], 0, v[254:255]
	v_lshlrev_b64 v[240:241], 10, v[254:255]
	v_lshl_add_u64 v[240:241], v[240:241], 0, v[154:155]
	v_lshlrev_b64 v[240:241], 1, v[240:241]
	v_lshl_add_u64 v[240:241], s[4:5], 0, v[240:241]
	v_lshl_add_u64 v[254:255], v[254:255], 2, s[6:7]
	global_load_dword v252, v[254:255], off sc1
	global_load_dwordx4 v[234:237], v[240:241], off
	global_load_dwordx4 v[238:241], v[240:241], off offset:256
	v_pk_fma_f32 v[130:131], v[118:119], v[134:135], v[130:131]
	v_pk_fma_f32 v[128:129], v[116:117], v[132:133], v[128:129]
	v_pk_fma_f32 v[134:135], v[110:111], v[172:173], v[138:139]
	v_pk_fma_f32 v[132:133], v[108:109], v[170:171], v[136:137]
	global_store_dwordx4 v[168:169], v[128:131], off offset:512
	global_store_dwordx4 v[168:169], v[132:135], off offset:528
	s_nop 0
	s_nop 0
	s_nop 0
	v_lshl_add_u64 v[132:133], v[140:141], 2, s[14:15]
	v_lshl_add_u64 v[134:135], s[4:5], 0, v[164:165]
	s_waitcnt vmcnt(7)
; DI unsigned pk_bf16(float lo, float hi) { f32x2 v = {lo, hi}; bf16x2_t b = __builtin_convertvector(v, bf16x2_t); return __builtin_bit_cast(unsigned, b); }
; DI float bflo(unsigned w) { return __uint_as_float(w << 16); }
; DI float bfhi(unsigned w) { return __uint_as_float(w & 0xffff0000u); }
;     __device__ __forceinline__ void fused(f32x4 (&acc)[2][2][4][2], const pg8::Unit& u, int wr, int wc, int fr, int fq, PG8_LAS unsigned char* lds, int wid, int lane) const {
;     ...
;                 const int rl = ai * 128 + wr * 64 + m * 16 + fr; const size_t row = (size_t)u.pm * 256 + rl;
;                 const float rm = 1.f / sqrtf(__hip_atomic_load(ssqm + row, __ATOMIC_RELAXED, __HIP_MEMORY_SCOPE_AGENT) * (1.f / DM) + RMS_EPS);
;                 float sh = 0.f;
; #pragma unroll
;                 for (int bj = 0; bj < 2; ++bj) {
;                     const size_t off = row * DM + colb + bj * 128;
;                     f32x4 h0, h1;
;                     if (IN16) { const u32x4 hw = *(const u32x4*)((const bf16_t*)hin + off); h0 = (f32x4){bflo(hw.x), bfhi(hw.x), bflo(hw.y), bfhi(hw.y)}; h1 = (f32x4){bflo(hw.z), bfhi(hw.z), bflo(hw.w), bfhi(hw.w)}; }
;                     else { h0 = *(const f32x4*)((const float*)hin + off); h1 = *(const f32x4*)((const float*)hin + off + 4); }
;                     h0 = h0 + acc[ai][bj][m][0] * rm * gv[bj][0]; h1 = h1 + acc[ai][bj][m][1] * rm * gv[bj][1];
;                     sh += ((h0[0] * h0[0] + h0[1] * h0[1]) + (h0[2] * h0[2] + h0[3] * h0[3])) + ((h1[0] * h1[0] + h1[1] * h1[1]) + (h1[2] * h1[2] + h1[3] * h1[3]));
;                     if (OUT16) { u32x4 w; w.x = pk_bf16(h0[0], h0[1]); w.y = pk_bf16(h0[2], h0[3]); w.z = pk_bf16(h1[0], h1[1]); w.w = pk_bf16(h1[2], h1[3]); *(u32x4*)((bf16_t*)hout + off) = w; }
;                     else { *(f32x4*)((float*)hout + off) = h0; *(f32x4*)((float*)hout + off + 4) = h1; }
	v_fmamk_f32 v138, v253, 0x3a800000, v147
	v_mul_f32_e32 v139, 0x4f800000, v138
	v_cmp_gt_f32_e32 vcc, s2, v138
	v_lshlrev_b32_e32 v136, 16, v242
	v_and_b32_e32 v137, 0xffff0000, v242
	v_cndmask_b32_e32 v140, v138, v139, vcc
	v_sqrt_f32_e32 v141, v140
	v_lshlrev_b32_e32 v128, 16, v243
	v_and_b32_e32 v129, 0xffff0000, v243
	v_lshlrev_b32_e32 v138, 16, v244
	v_add_u32_e32 v142, -1, v141
	v_add_u32_e32 v143, 1, v141
	v_fma_f32 v149, -v142, v141, v140
	v_fma_f32 v151, -v143, v141, v140
	v_cmp_ge_f32_e64 s[0:1], 0, v149
	v_and_b32_e32 v139, 0xffff0000, v244
	v_lshlrev_b32_e32 v130, 16, v245
	v_cndmask_b32_e64 v141, v141, v142, s[0:1]
	v_cmp_lt_f32_e64 s[0:1], 0, v151
	v_and_b32_e32 v131, 0xffff0000, v245
	s_nop 0
	v_cndmask_b32_e64 v141, v141, v143, s[0:1]
	v_mul_f32_e32 v142, 0x37800000, v141
	v_cndmask_b32_e32 v141, v141, v142, vcc
	v_cmp_class_f32_e32 vcc, v140, v145
	s_nop 1
	v_cndmask_b32_e32 v140, v141, v140, vcc
	v_div_scale_f32 v141, s[0:1], v140, v140, 1.0
	v_rcp_f32_e32 v142, v141
	v_div_scale_f32 v143, vcc, 1.0, v140, 1.0
	v_fma_f32 v149, -v141, v142, 1.0
	v_fmac_f32_e32 v142, v149, v142
	v_mul_f32_e32 v149, v143, v142
	v_fma_f32 v151, -v141, v149, v143
	v_fmac_f32_e32 v149, v151, v142
	v_fma_f32 v141, -v141, v149, v143
	v_div_fmas_f32 v141, v141, v142, v149
	v_div_fixup_f32 v140, v141, v140, 1.0
	v_pk_mul_f32 v[112:113], v[112:113], v[140:141] op_sel_hi:[1,0]
	v_pk_mul_f32 v[114:115], v[114:115], v[140:141] op_sel_hi:[1,0]
	v_pk_mul_f32 v[142:143], v[104:105], v[140:141] op_sel_hi:[1,0]
	v_pk_mul_f32 v[164:165], v[106:107], v[140:141] op_sel_hi:[1,0]
	v_pk_fma_f32 v[106:107], v[126:127], v[114:115], v[128:129]
	v_pk_fma_f32 v[104:105], v[124:125], v[112:113], v[136:137]
	v_pk_fma_f32 v[114:115], v[122:123], v[164:165], v[130:131]
	v_pk_fma_f32 v[112:113], v[120:121], v[142:143], v[138:139]
	global_store_dwordx4 v[132:133], v[104:107], off
	global_store_dwordx4 v[132:133], v[112:115], off offset:16
	s_nop 0
	v_pk_mul_f32 v[100:101], v[100:101], v[140:141] op_sel_hi:[1,0]
	v_or_b32_e32 v112, 32, v152
	v_mov_b32_e32 v113, v153
	v_lshl_add_u64 v[112:113], s[10:11], 0, v[112:113]
	v_lshl_add_u64 v[114:115], v[112:113], 2, s[6:7]
	v_lshlrev_b64 v[112:113], 10, v[112:113]
	v_pk_mul_f32 v[102:103], v[102:103], v[140:141] op_sel_hi:[1,0]
	v_pk_mul_f32 v[134:135], v[96:97], v[140:141] op_sel_hi:[1,0]
	v_pk_mul_f32 v[136:137], v[98:99], v[140:141] op_sel_hi:[1,0]
	v_lshl_add_u64 v[112:113], v[112:113], 0, v[154:155]
	v_lshlrev_b64 v[128:129], 1, v[112:113]
	v_lshl_add_u64 v[130:131], s[4:5], 0, v[128:129]
	v_or_b32_e32 v128, 0x100, v128
	v_lshlrev_b32_e32 v96, 16, v246
	v_and_b32_e32 v97, 0xffff0000, v246
	v_lshlrev_b32_e32 v98, 16, v247
	v_and_b32_e32 v99, 0xffff0000, v247
	v_lshlrev_b32_e32 v104, 16, v248
	v_and_b32_e32 v105, 0xffff0000, v248
	v_lshlrev_b32_e32 v106, 16, v249
	v_and_b32_e32 v107, 0xffff0000, v249
	v_or_b32_e32 v254, 48, v152
	v_mov_b32_e32 v255, 0
	v_lshl_add_u64 v[254:255], s[10:11], 0, v[254:255]
	v_lshlrev_b64 v[248:249], 10, v[254:255]
	v_lshl_add_u64 v[248:249], v[248:249], 0, v[154:155]
	v_lshlrev_b64 v[248:249], 1, v[248:249]
	v_lshl_add_u64 v[248:249], s[4:5], 0, v[248:249]
	v_lshl_add_u64 v[254:255], v[254:255], 2, s[6:7]
	global_load_dword v253, v[254:255], off sc1
	global_load_dwordx4 v[242:245], v[248:249], off
	global_load_dwordx4 v[246:249], v[248:249], off offset:256
	v_pk_fma_f32 v[98:99], v[118:119], v[102:103], v[98:99]
	v_pk_fma_f32 v[96:97], v[116:117], v[100:101], v[96:97]
	v_pk_fma_f32 v[102:103], v[110:111], v[136:137], v[106:107]
	v_pk_fma_f32 v[100:101], v[108:109], v[134:135], v[104:105]
	global_store_dwordx4 v[132:133], v[96:99], off offset:512
	global_store_dwordx4 v[132:133], v[100:103], off offset:528
	s_nop 0
	s_nop 0
	s_nop 0
	v_lshl_add_u64 v[100:101], v[112:113], 2, s[14:15]
	v_lshl_add_u64 v[102:103], s[4:5], 0, v[128:129]
	s_waitcnt vmcnt(9)
	v_fmamk_f32 v106, v252, 0x3a800000, v147
	v_mul_f32_e32 v107, 0x4f800000, v106
	v_cmp_gt_f32_e32 vcc, s2, v106
	v_lshlrev_b32_e32 v104, 16, v234
	v_and_b32_e32 v105, 0xffff0000, v234
	v_cndmask_b32_e32 v112, v106, v107, vcc
	v_sqrt_f32_e32 v113, v112
	v_lshlrev_b32_e32 v96, 16, v235
	v_and_b32_e32 v97, 0xffff0000, v235
	v_lshlrev_b32_e32 v106, 16, v236
	v_add_u32_e32 v114, -1, v113
	v_add_u32_e32 v115, 1, v113
	v_fma_f32 v128, -v114, v113, v112
	v_fma_f32 v129, -v115, v113, v112
	v_cmp_ge_f32_e64 s[0:1], 0, v128
	v_and_b32_e32 v107, 0xffff0000, v236
	v_lshlrev_b32_e32 v98, 16, v237
	v_cndmask_b32_e64 v113, v113, v114, s[0:1]
	v_cmp_lt_f32_e64 s[0:1], 0, v129
	v_and_b32_e32 v99, 0xffff0000, v237
	s_nop 0
	v_cndmask_b32_e64 v113, v113, v115, s[0:1]
	v_mul_f32_e32 v114, 0x37800000, v113
	v_cndmask_b32_e32 v113, v113, v114, vcc
	v_cmp_class_f32_e32 vcc, v112, v145
	s_nop 1
	v_cndmask_b32_e32 v112, v113, v112, vcc
	v_div_scale_f32 v113, s[0:1], v112, v112, 1.0
	v_rcp_f32_e32 v114, v113
	v_div_scale_f32 v115, vcc, 1.0, v112, 1.0
	v_fma_f32 v128, -v113, v114, 1.0
	v_fmac_f32_e32 v114, v128, v114
	v_mul_f32_e32 v128, v115, v114
	v_fma_f32 v129, -v113, v128, v115
	v_fmac_f32_e32 v128, v129, v114
	v_fma_f32 v113, -v113, v128, v115
	v_div_fmas_f32 v113, v113, v114, v128
	v_div_fixup_f32 v112, v113, v112, 1.0
	v_pk_mul_f32 v[92:93], v[92:93], v[112:113] op_sel_hi:[1,0]
	v_pk_mul_f32 v[94:95], v[94:95], v[112:113] op_sel_hi:[1,0]
	v_pk_mul_f32 v[114:115], v[88:89], v[112:113] op_sel_hi:[1,0]
	v_pk_mul_f32 v[128:129], v[90:91], v[112:113] op_sel_hi:[1,0]
	v_pk_fma_f32 v[90:91], v[126:127], v[94:95], v[96:97]
	v_pk_fma_f32 v[88:89], v[124:125], v[92:93], v[104:105]
	v_pk_fma_f32 v[94:95], v[122:123], v[128:129], v[98:99]
	v_pk_fma_f32 v[92:93], v[120:121], v[114:115], v[106:107]
; DI unsigned pk_bf16(float lo, float hi) { f32x2 v = {lo, hi}; bf16x2_t b = __builtin_convertvector(v, bf16x2_t); return __builtin_bit_cast(unsigned, b); }
; DI float bflo(unsigned w) { return __uint_as_float(w << 16); }
; DI float bfhi(unsigned w) { return __uint_as_float(w & 0xffff0000u); }
;     __device__ __forceinline__ void fused(f32x4 (&acc)[2][2][4][2], const pg8::Unit& u, int wr, int wc, int fr, int fq, PG8_LAS unsigned char* lds, int wid, int lane) const {
;     ...
;                 const int rl = ai * 128 + wr * 64 + m * 16 + fr; const size_t row = (size_t)u.pm * 256 + rl;
;                 const float rm = 1.f / sqrtf(__hip_atomic_load(ssqm + row, __ATOMIC_RELAXED, __HIP_MEMORY_SCOPE_AGENT) * (1.f / DM) + RMS_EPS);
;                 float sh = 0.f;
; #pragma unroll
;                 for (int bj = 0; bj < 2; ++bj) {
;                     const size_t off = row * DM + colb + bj * 128;
;                     f32x4 h0, h1;
;                     if (IN16) { const u32x4 hw = *(const u32x4*)((const bf16_t*)hin + off); h0 = (f32x4){bflo(hw.x), bfhi(hw.x), bflo(hw.y), bfhi(hw.y)}; h1 = (f32x4){bflo(hw.z), bfhi(hw.z), bflo(hw.w), bfhi(hw.w)}; }
;                     else { h0 = *(const f32x4*)((const float*)hin + off); h1 = *(const f32x4*)((const float*)hin + off + 4); }
;                     h0 = h0 + acc[ai][bj][m][0] * rm * gv[bj][0]; h1 = h1 + acc[ai][bj][m][1] * rm * gv[bj][1];
;                     sh += ((h0[0] * h0[0] + h0[1] * h0[1]) + (h0[2] * h0[2] + h0[3] * h0[3])) + ((h1[0] * h1[0] + h1[1] * h1[1]) + (h1[2] * h1[2] + h1[3] * h1[3]));
;                     if (OUT16) { u32x4 w; w.x = pk_bf16(h0[0], h0[1]); w.y = pk_bf16(h0[2], h0[3]); w.z = pk_bf16(h1[0], h1[1]); w.w = pk_bf16(h1[2], h1[3]); *(u32x4*)((bf16_t*)hout + off) = w; }
;                     else { *(f32x4*)((float*)hout + off) = h0; *(f32x4*)((float*)hout + off + 4) = h1; }
	global_store_dwordx4 v[100:101], v[88:91], off
	global_store_dwordx4 v[100:101], v[92:95], off offset:16
	s_nop 0
	v_pk_mul_f32 v[84:85], v[84:85], v[112:113] op_sel_hi:[1,0]
	v_or_b32_e32 v92, 48, v152
	v_mov_b32_e32 v93, v153
	v_lshl_add_u64 v[92:93], s[10:11], 0, v[92:93]
	v_lshl_add_u64 v[94:95], v[92:93], 2, s[6:7]
	v_lshlrev_b64 v[92:93], 10, v[92:93]
	v_pk_mul_f32 v[86:87], v[86:87], v[112:113] op_sel_hi:[1,0]
	v_pk_mul_f32 v[102:103], v[80:81], v[112:113] op_sel_hi:[1,0]
	v_pk_mul_f32 v[104:105], v[82:83], v[112:113] op_sel_hi:[1,0]
	v_lshl_add_u64 v[92:93], v[92:93], 0, v[154:155]
	v_lshlrev_b64 v[96:97], 1, v[92:93]
	v_lshl_add_u64 v[98:99], s[4:5], 0, v[96:97]
	v_or_b32_e32 v96, 0x100, v96
	v_lshlrev_b32_e32 v80, 16, v238
	v_and_b32_e32 v81, 0xffff0000, v238
	v_lshlrev_b32_e32 v82, 16, v239
	v_and_b32_e32 v83, 0xffff0000, v239
	v_lshlrev_b32_e32 v88, 16, v240
	v_and_b32_e32 v89, 0xffff0000, v240
	v_lshlrev_b32_e32 v90, 16, v241
	v_and_b32_e32 v91, 0xffff0000, v241
	v_or_b32_e32 v254, 128, v152
	v_mov_b32_e32 v255, 0
	v_lshl_add_u64 v[254:255], s[10:11], 0, v[254:255]
	v_lshlrev_b64 v[240:241], 10, v[254:255]
	v_lshl_add_u64 v[240:241], v[240:241], 0, v[154:155]
	v_lshlrev_b64 v[240:241], 1, v[240:241]
	v_lshl_add_u64 v[240:241], s[4:5], 0, v[240:241]
	v_lshl_add_u64 v[254:255], v[254:255], 2, s[6:7]
	global_load_dword v252, v[254:255], off sc1
	global_load_dwordx4 v[234:237], v[240:241], off
	global_load_dwordx4 v[238:241], v[240:241], off offset:256
	v_pk_fma_f32 v[82:83], v[118:119], v[86:87], v[82:83]
	v_pk_fma_f32 v[80:81], v[116:117], v[84:85], v[80:81]
	v_pk_fma_f32 v[86:87], v[110:111], v[104:105], v[90:91]
	v_pk_fma_f32 v[84:85], v[108:109], v[102:103], v[88:89]
	global_store_dwordx4 v[100:101], v[80:83], off offset:512
	global_store_dwordx4 v[100:101], v[84:87], off offset:528
	s_nop 0
	s_nop 0
	s_nop 0
	v_lshl_add_u64 v[84:85], v[92:93], 2, s[14:15]
	v_lshl_add_u64 v[86:87], s[4:5], 0, v[96:97]
	s_waitcnt vmcnt(9)
	v_fmamk_f32 v90, v253, 0x3a800000, v147
	v_mul_f32_e32 v91, 0x4f800000, v90
	v_cmp_gt_f32_e32 vcc, s2, v90
	v_lshlrev_b32_e32 v88, 16, v242
	v_and_b32_e32 v89, 0xffff0000, v242
	v_cndmask_b32_e32 v92, v90, v91, vcc
	v_sqrt_f32_e32 v93, v92
	v_lshlrev_b32_e32 v80, 16, v243
	v_and_b32_e32 v81, 0xffff0000, v243
	v_lshlrev_b32_e32 v90, 16, v244
	v_add_u32_e32 v94, -1, v93
	v_add_u32_e32 v95, 1, v93
	v_fma_f32 v96, -v94, v93, v92
	v_fma_f32 v97, -v95, v93, v92
	v_cmp_ge_f32_e64 s[0:1], 0, v96
	v_and_b32_e32 v91, 0xffff0000, v244
	v_lshlrev_b32_e32 v82, 16, v245
	v_cndmask_b32_e64 v93, v93, v94, s[0:1]
	v_cmp_lt_f32_e64 s[0:1], 0, v97
	v_and_b32_e32 v83, 0xffff0000, v245
	s_nop 0
	v_cndmask_b32_e64 v93, v93, v95, s[0:1]
	v_mul_f32_e32 v94, 0x37800000, v93
	v_cndmask_b32_e32 v93, v93, v94, vcc
	v_cmp_class_f32_e32 vcc, v92, v145
	s_nop 1
	v_cndmask_b32_e32 v92, v93, v92, vcc
	v_div_scale_f32 v93, s[0:1], v92, v92, 1.0
	v_rcp_f32_e32 v94, v93
	v_div_scale_f32 v95, vcc, 1.0, v92, 1.0
	v_fma_f32 v96, -v93, v94, 1.0
	v_fmac_f32_e32 v94, v96, v94
	v_mul_f32_e32 v96, v95, v94
	v_fma_f32 v97, -v93, v96, v95
	v_fmac_f32_e32 v96, v97, v94
	v_fma_f32 v93, -v93, v96, v95
	v_div_fmas_f32 v93, v93, v94, v96
	v_div_fixup_f32 v92, v93, v92, 1.0
	v_pk_mul_f32 v[76:77], v[76:77], v[92:93] op_sel_hi:[1,0]
	v_pk_mul_f32 v[78:79], v[78:79], v[92:93] op_sel_hi:[1,0]
	v_pk_mul_f32 v[94:95], v[72:73], v[92:93] op_sel_hi:[1,0]
	v_pk_mul_f32 v[96:97], v[74:75], v[92:93] op_sel_hi:[1,0]
	v_pk_fma_f32 v[74:75], v[126:127], v[78:79], v[80:81]
	v_pk_fma_f32 v[72:73], v[124:125], v[76:77], v[88:89]
	v_pk_fma_f32 v[78:79], v[122:123], v[96:97], v[82:83]
	v_pk_fma_f32 v[76:77], v[120:121], v[94:95], v[90:91]
	global_store_dwordx4 v[84:85], v[72:75], off
	global_store_dwordx4 v[84:85], v[76:79], off offset:16
	s_nop 0
	v_pk_mul_f32 v[68:69], v[68:69], v[92:93] op_sel_hi:[1,0]
	v_add_u32_e32 v76, 0x80, v152
	v_mov_b32_e32 v77, v153
	v_lshl_add_u64 v[76:77], s[10:11], 0, v[76:77]
	v_lshl_add_u64 v[78:79], v[76:77], 2, s[6:7]
	v_lshlrev_b64 v[76:77], 10, v[76:77]
	v_pk_mul_f32 v[70:71], v[70:71], v[92:93] op_sel_hi:[1,0]
	v_pk_mul_f32 v[86:87], v[64:65], v[92:93] op_sel_hi:[1,0]
	v_pk_mul_f32 v[88:89], v[66:67], v[92:93] op_sel_hi:[1,0]
	v_lshl_add_u64 v[76:77], v[76:77], 0, v[154:155]
	v_lshlrev_b64 v[80:81], 1, v[76:77]
	v_lshl_add_u64 v[82:83], s[4:5], 0, v[80:81]
	v_or_b32_e32 v80, 0x100, v80
	v_lshlrev_b32_e32 v64, 16, v246
	v_and_b32_e32 v65, 0xffff0000, v246
	v_lshlrev_b32_e32 v66, 16, v247
	v_and_b32_e32 v67, 0xffff0000, v247
	v_lshlrev_b32_e32 v72, 16, v248
	v_and_b32_e32 v73, 0xffff0000, v248
	v_lshlrev_b32_e32 v74, 16, v249
	v_and_b32_e32 v75, 0xffff0000, v249
	v_or_b32_e32 v254, 144, v152
	v_mov_b32_e32 v255, 0
	v_lshl_add_u64 v[254:255], s[10:11], 0, v[254:255]
	v_lshlrev_b64 v[248:249], 10, v[254:255]
	v_lshl_add_u64 v[248:249], v[248:249], 0, v[154:155]
	v_lshlrev_b64 v[248:249], 1, v[248:249]
	v_lshl_add_u64 v[248:249], s[4:5], 0, v[248:249]
	v_lshl_add_u64 v[254:255], v[254:255], 2, s[6:7]
	global_load_dword v253, v[254:255], off sc1
	global_load_dwordx4 v[242:245], v[248:249], off
	global_load_dwordx4 v[246:249], v[248:249], off offset:256
	v_pk_fma_f32 v[66:67], v[118:119], v[70:71], v[66:67]
	v_pk_fma_f32 v[64:65], v[116:117], v[68:69], v[64:65]
	v_pk_fma_f32 v[70:71], v[110:111], v[88:89], v[74:75]
	v_pk_fma_f32 v[68:69], v[108:109], v[86:87], v[72:73]
	global_store_dwordx4 v[84:85], v[64:67], off offset:512
	global_store_dwordx4 v[84:85], v[68:71], off offset:528
	s_nop 0
	s_nop 0
	s_nop 0
	v_lshl_add_u64 v[68:69], v[76:77], 2, s[14:15]
	v_lshl_add_u64 v[70:71], s[4:5], 0, v[80:81]
	s_waitcnt vmcnt(9)
; DI unsigned pk_bf16(float lo, float hi) { f32x2 v = {lo, hi}; bf16x2_t b = __builtin_convertvector(v, bf16x2_t); return __builtin_bit_cast(unsigned, b); }
; DI float bflo(unsigned w) { return __uint_as_float(w << 16); }
; DI float bfhi(unsigned w) { return __uint_as_float(w & 0xffff0000u); }
;     __device__ __forceinline__ void fused(f32x4 (&acc)[2][2][4][2], const pg8::Unit& u, int wr, int wc, int fr, int fq, PG8_LAS unsigned char* lds, int wid, int lane) const {
;     ...
;                 const int rl = ai * 128 + wr * 64 + m * 16 + fr; const size_t row = (size_t)u.pm * 256 + rl;
;                 const float rm = 1.f / sqrtf(__hip_atomic_load(ssqm + row, __ATOMIC_RELAXED, __HIP_MEMORY_SCOPE_AGENT) * (1.f / DM) + RMS_EPS);
;                 float sh = 0.f;
; #pragma unroll
;                 for (int bj = 0; bj < 2; ++bj) {
;                     const size_t off = row * DM + colb + bj * 128;
;                     f32x4 h0, h1;
;                     if (IN16) { const u32x4 hw = *(const u32x4*)((const bf16_t*)hin + off); h0 = (f32x4){bflo(hw.x), bfhi(hw.x), bflo(hw.y), bfhi(hw.y)}; h1 = (f32x4){bflo(hw.z), bfhi(hw.z), bflo(hw.w), bfhi(hw.w)}; }
;                     else { h0 = *(const f32x4*)((const float*)hin + off); h1 = *(const f32x4*)((const float*)hin + off + 4); }
;                     h0 = h0 + acc[ai][bj][m][0] * rm * gv[bj][0]; h1 = h1 + acc[ai][bj][m][1] * rm * gv[bj][1];
;                     sh += ((h0[0] * h0[0] + h0[1] * h0[1]) + (h0[2] * h0[2] + h0[3] * h0[3])) + ((h1[0] * h1[0] + h1[1] * h1[1]) + (h1[2] * h1[2] + h1[3] * h1[3]));
;                     if (OUT16) { u32x4 w; w.x = pk_bf16(h0[0], h0[1]); w.y = pk_bf16(h0[2], h0[3]); w.z = pk_bf16(h1[0], h1[1]); w.w = pk_bf16(h1[2], h1[3]); *(u32x4*)((bf16_t*)hout + off) = w; }
;                     else { *(f32x4*)((float*)hout + off) = h0; *(f32x4*)((float*)hout + off + 4) = h1; }
	v_fmamk_f32 v74, v252, 0x3a800000, v147
	v_mul_f32_e32 v75, 0x4f800000, v74
	v_cmp_gt_f32_e32 vcc, s2, v74
	v_lshlrev_b32_e32 v72, 16, v234
	v_and_b32_e32 v73, 0xffff0000, v234
	v_cndmask_b32_e32 v76, v74, v75, vcc
	v_sqrt_f32_e32 v77, v76
	v_lshlrev_b32_e32 v64, 16, v235
	v_and_b32_e32 v65, 0xffff0000, v235
	v_lshlrev_b32_e32 v74, 16, v236
	v_add_u32_e32 v78, -1, v77
	v_add_u32_e32 v79, 1, v77
	v_fma_f32 v80, -v78, v77, v76
	v_fma_f32 v81, -v79, v77, v76
	v_cmp_ge_f32_e64 s[0:1], 0, v80
	v_and_b32_e32 v75, 0xffff0000, v236
	v_lshlrev_b32_e32 v66, 16, v237
	v_cndmask_b32_e64 v77, v77, v78, s[0:1]
	v_cmp_lt_f32_e64 s[0:1], 0, v81
	v_and_b32_e32 v67, 0xffff0000, v237
	s_nop 0
	v_cndmask_b32_e64 v77, v77, v79, s[0:1]
	v_mul_f32_e32 v78, 0x37800000, v77
	v_cndmask_b32_e32 v77, v77, v78, vcc
	v_cmp_class_f32_e32 vcc, v76, v145
	s_nop 1
	v_cndmask_b32_e32 v76, v77, v76, vcc
	v_div_scale_f32 v77, s[0:1], v76, v76, 1.0
	v_rcp_f32_e32 v78, v77
	v_div_scale_f32 v79, vcc, 1.0, v76, 1.0
	v_fma_f32 v80, -v77, v78, 1.0
	v_fmac_f32_e32 v78, v80, v78
	v_mul_f32_e32 v80, v79, v78
	v_fma_f32 v81, -v77, v80, v79
	v_fmac_f32_e32 v80, v81, v78
	v_fma_f32 v77, -v77, v80, v79
	v_div_fmas_f32 v77, v77, v78, v80
	v_div_fixup_f32 v76, v77, v76, 1.0
	v_pk_mul_f32 v[60:61], v[60:61], v[76:77] op_sel_hi:[1,0]
	v_pk_mul_f32 v[62:63], v[62:63], v[76:77] op_sel_hi:[1,0]
	v_pk_mul_f32 v[78:79], v[56:57], v[76:77] op_sel_hi:[1,0]
	v_pk_mul_f32 v[80:81], v[58:59], v[76:77] op_sel_hi:[1,0]
	v_pk_fma_f32 v[58:59], v[126:127], v[62:63], v[64:65]
	v_pk_fma_f32 v[56:57], v[124:125], v[60:61], v[72:73]
	v_pk_fma_f32 v[62:63], v[122:123], v[80:81], v[66:67]
	v_pk_fma_f32 v[60:61], v[120:121], v[78:79], v[74:75]
	global_store_dwordx4 v[68:69], v[56:59], off
	global_store_dwordx4 v[68:69], v[60:63], off offset:16
	s_nop 0
	v_pk_mul_f32 v[52:53], v[52:53], v[76:77] op_sel_hi:[1,0]
	v_add_u32_e32 v60, 0x90, v152
	v_mov_b32_e32 v61, v153
	v_lshl_add_u64 v[60:61], s[10:11], 0, v[60:61]
	v_lshl_add_u64 v[62:63], v[60:61], 2, s[6:7]
	v_lshlrev_b64 v[60:61], 10, v[60:61]
	v_pk_mul_f32 v[54:55], v[54:55], v[76:77] op_sel_hi:[1,0]
	v_pk_mul_f32 v[70:71], v[48:49], v[76:77] op_sel_hi:[1,0]
	v_pk_mul_f32 v[72:73], v[50:51], v[76:77] op_sel_hi:[1,0]
	v_lshl_add_u64 v[60:61], v[60:61], 0, v[154:155]
	v_lshlrev_b64 v[64:65], 1, v[60:61]
	v_lshl_add_u64 v[66:67], s[4:5], 0, v[64:65]
	v_or_b32_e32 v64, 0x100, v64
	v_lshlrev_b32_e32 v48, 16, v238
	v_and_b32_e32 v49, 0xffff0000, v238
	v_lshlrev_b32_e32 v50, 16, v239
	v_and_b32_e32 v51, 0xffff0000, v239
	v_lshlrev_b32_e32 v56, 16, v240
	v_and_b32_e32 v57, 0xffff0000, v240
	v_lshlrev_b32_e32 v58, 16, v241
	v_and_b32_e32 v59, 0xffff0000, v241
	v_or_b32_e32 v254, 160, v152
	v_mov_b32_e32 v255, 0
	v_lshl_add_u64 v[254:255], s[10:11], 0, v[254:255]
	v_lshlrev_b64 v[240:241], 10, v[254:255]
	v_lshl_add_u64 v[240:241], v[240:241], 0, v[154:155]
	v_lshlrev_b64 v[240:241], 1, v[240:241]
	v_lshl_add_u64 v[240:241], s[4:5], 0, v[240:241]
	v_lshl_add_u64 v[254:255], v[254:255], 2, s[6:7]
	global_load_dword v252, v[254:255], off sc1
	global_load_dwordx4 v[234:237], v[240:241], off
	global_load_dwordx4 v[238:241], v[240:241], off offset:256
	v_pk_fma_f32 v[50:51], v[118:119], v[54:55], v[50:51]
	v_pk_fma_f32 v[48:49], v[116:117], v[52:53], v[48:49]
	v_pk_fma_f32 v[54:55], v[110:111], v[72:73], v[58:59]
	v_pk_fma_f32 v[52:53], v[108:109], v[70:71], v[56:57]
	global_store_dwordx4 v[68:69], v[48:51], off offset:512
	global_store_dwordx4 v[68:69], v[52:55], off offset:528
	s_nop 0
	s_nop 0
	s_nop 0
	v_lshl_add_u64 v[52:53], v[60:61], 2, s[14:15]
	v_lshl_add_u64 v[54:55], s[4:5], 0, v[64:65]
	s_waitcnt vmcnt(9)
	v_fmamk_f32 v58, v253, 0x3a800000, v147
	v_mul_f32_e32 v59, 0x4f800000, v58
	v_cmp_gt_f32_e32 vcc, s2, v58
	v_lshlrev_b32_e32 v56, 16, v242
	v_and_b32_e32 v57, 0xffff0000, v242
	v_cndmask_b32_e32 v60, v58, v59, vcc
	v_sqrt_f32_e32 v61, v60
	v_lshlrev_b32_e32 v48, 16, v243
	v_and_b32_e32 v49, 0xffff0000, v243
	v_lshlrev_b32_e32 v58, 16, v244
	v_add_u32_e32 v62, -1, v61
	v_add_u32_e32 v63, 1, v61
	v_fma_f32 v64, -v62, v61, v60
	v_fma_f32 v65, -v63, v61, v60
	v_cmp_ge_f32_e64 s[0:1], 0, v64
	v_and_b32_e32 v59, 0xffff0000, v244
	v_lshlrev_b32_e32 v50, 16, v245
	v_cndmask_b32_e64 v61, v61, v62, s[0:1]
	v_cmp_lt_f32_e64 s[0:1], 0, v65
	v_and_b32_e32 v51, 0xffff0000, v245
	s_nop 0
	v_cndmask_b32_e64 v61, v61, v63, s[0:1]
	v_mul_f32_e32 v62, 0x37800000, v61
	v_cndmask_b32_e32 v61, v61, v62, vcc
	v_cmp_class_f32_e32 vcc, v60, v145
	s_nop 1
	v_cndmask_b32_e32 v60, v61, v60, vcc
	v_div_scale_f32 v61, s[0:1], v60, v60, 1.0
	v_rcp_f32_e32 v62, v61
	v_div_scale_f32 v63, vcc, 1.0, v60, 1.0
	v_fma_f32 v64, -v61, v62, 1.0
	v_fmac_f32_e32 v62, v64, v62
	v_mul_f32_e32 v64, v63, v62
	v_fma_f32 v65, -v61, v64, v63
	v_fmac_f32_e32 v64, v65, v62
	v_fma_f32 v61, -v61, v64, v63
	v_div_fmas_f32 v61, v61, v62, v64
	v_div_fixup_f32 v60, v61, v60, 1.0
	v_pk_mul_f32 v[44:45], v[44:45], v[60:61] op_sel_hi:[1,0]
	v_pk_mul_f32 v[46:47], v[46:47], v[60:61] op_sel_hi:[1,0]
	v_pk_mul_f32 v[62:63], v[40:41], v[60:61] op_sel_hi:[1,0]
	v_pk_mul_f32 v[64:65], v[42:43], v[60:61] op_sel_hi:[1,0]
	v_pk_fma_f32 v[42:43], v[126:127], v[46:47], v[48:49]
	v_pk_fma_f32 v[40:41], v[124:125], v[44:45], v[56:57]
	v_pk_fma_f32 v[46:47], v[122:123], v[64:65], v[50:51]
	v_pk_fma_f32 v[44:45], v[120:121], v[62:63], v[58:59]
	global_store_dwordx4 v[52:53], v[40:43], off
	global_store_dwordx4 v[52:53], v[44:47], off offset:16
	s_nop 0
	v_pk_mul_f32 v[36:37], v[36:37], v[60:61] op_sel_hi:[1,0]
	v_add_u32_e32 v44, 0xa0, v152
	v_mov_b32_e32 v45, v153
	v_lshl_add_u64 v[44:45], s[10:11], 0, v[44:45]
; DI unsigned pk_bf16(float lo, float hi) { f32x2 v = {lo, hi}; bf16x2_t b = __builtin_convertvector(v, bf16x2_t); return __builtin_bit_cast(unsigned, b); }
; DI float bflo(unsigned w) { return __uint_as_float(w << 16); }
; DI float bfhi(unsigned w) { return __uint_as_float(w & 0xffff0000u); }
;     __device__ __forceinline__ void fused(f32x4 (&acc)[2][2][4][2], const pg8::Unit& u, int wr, int wc, int fr, int fq, PG8_LAS unsigned char* lds, int wid, int lane) const {
;     ...
;                 const int rl = ai * 128 + wr * 64 + m * 16 + fr; const size_t row = (size_t)u.pm * 256 + rl;
;                 const float rm = 1.f / sqrtf(__hip_atomic_load(ssqm + row, __ATOMIC_RELAXED, __HIP_MEMORY_SCOPE_AGENT) * (1.f / DM) + RMS_EPS);
;                 float sh = 0.f;
; #pragma unroll
;                 for (int bj = 0; bj < 2; ++bj) {
;                     const size_t off = row * DM + colb + bj * 128;
;                     f32x4 h0, h1;
;                     if (IN16) { const u32x4 hw = *(const u32x4*)((const bf16_t*)hin + off); h0 = (f32x4){bflo(hw.x), bfhi(hw.x), bflo(hw.y), bfhi(hw.y)}; h1 = (f32x4){bflo(hw.z), bfhi(hw.z), bflo(hw.w), bfhi(hw.w)}; }
;                     else { h0 = *(const f32x4*)((const float*)hin + off); h1 = *(const f32x4*)((const float*)hin + off + 4); }
;                     h0 = h0 + acc[ai][bj][m][0] * rm * gv[bj][0]; h1 = h1 + acc[ai][bj][m][1] * rm * gv[bj][1];
;                     sh += ((h0[0] * h0[0] + h0[1] * h0[1]) + (h0[2] * h0[2] + h0[3] * h0[3])) + ((h1[0] * h1[0] + h1[1] * h1[1]) + (h1[2] * h1[2] + h1[3] * h1[3]));
;                     if (OUT16) { u32x4 w; w.x = pk_bf16(h0[0], h0[1]); w.y = pk_bf16(h0[2], h0[3]); w.z = pk_bf16(h1[0], h1[1]); w.w = pk_bf16(h1[2], h1[3]); *(u32x4*)((bf16_t*)hout + off) = w; }
;                     else { *(f32x4*)((float*)hout + off) = h0; *(f32x4*)((float*)hout + off + 4) = h1; }
	v_lshl_add_u64 v[46:47], v[44:45], 2, s[6:7]
	v_lshlrev_b64 v[44:45], 10, v[44:45]
	v_pk_mul_f32 v[38:39], v[38:39], v[60:61] op_sel_hi:[1,0]
	v_pk_mul_f32 v[54:55], v[32:33], v[60:61] op_sel_hi:[1,0]
	v_pk_mul_f32 v[56:57], v[34:35], v[60:61] op_sel_hi:[1,0]
	v_lshl_add_u64 v[44:45], v[44:45], 0, v[154:155]
	v_lshlrev_b64 v[48:49], 1, v[44:45]
	v_lshl_add_u64 v[50:51], s[4:5], 0, v[48:49]
	v_or_b32_e32 v48, 0x100, v48
	v_add_u32_e32 v152, 0xb0, v152
	v_lshlrev_b32_e32 v32, 16, v246
	v_and_b32_e32 v33, 0xffff0000, v246
	v_lshlrev_b32_e32 v34, 16, v247
	v_and_b32_e32 v35, 0xffff0000, v247
	v_lshlrev_b32_e32 v40, 16, v248
	v_and_b32_e32 v41, 0xffff0000, v248
	v_lshlrev_b32_e32 v42, 16, v249
	v_and_b32_e32 v43, 0xffff0000, v249
	v_or_b32_e32 v254, 176, v152
	v_mov_b32_e32 v255, 0
	v_lshl_add_u64 v[254:255], s[10:11], 0, v[254:255]
	v_lshlrev_b64 v[248:249], 10, v[254:255]
	v_lshl_add_u64 v[248:249], v[248:249], 0, v[154:155]
	v_lshlrev_b64 v[248:249], 1, v[248:249]
	v_lshl_add_u64 v[248:249], s[4:5], 0, v[248:249]
	v_lshl_add_u64 v[254:255], v[254:255], 2, s[6:7]
	global_load_dword v253, v[254:255], off sc1
	global_load_dwordx4 v[242:245], v[248:249], off
	global_load_dwordx4 v[246:249], v[248:249], off offset:256
	v_pk_fma_f32 v[34:35], v[118:119], v[38:39], v[34:35]
	v_pk_fma_f32 v[32:33], v[116:117], v[36:37], v[32:33]
	v_pk_fma_f32 v[38:39], v[110:111], v[56:57], v[42:43]
	v_pk_fma_f32 v[36:37], v[108:109], v[54:55], v[40:41]
	global_store_dwordx4 v[52:53], v[32:35], off offset:512
	global_store_dwordx4 v[52:53], v[36:39], off offset:528
	s_nop 0
	s_nop 0
	s_nop 0
	v_lshl_add_u64 v[36:37], v[44:45], 2, s[14:15]
	v_lshl_add_u64 v[38:39], s[4:5], 0, v[48:49]
	s_waitcnt vmcnt(9)
	v_fmamk_f32 v42, v252, 0x3a800000, v147
	v_mul_f32_e32 v43, 0x4f800000, v42
	v_cmp_gt_f32_e32 vcc, s2, v42
	v_lshlrev_b32_e32 v40, 16, v234
	v_and_b32_e32 v41, 0xffff0000, v234
	v_cndmask_b32_e32 v44, v42, v43, vcc
	v_sqrt_f32_e32 v45, v44
	v_lshlrev_b32_e32 v32, 16, v235
	v_and_b32_e32 v33, 0xffff0000, v235
	v_lshlrev_b32_e32 v42, 16, v236
	v_add_u32_e32 v46, -1, v45
	v_add_u32_e32 v47, 1, v45
	v_fma_f32 v48, -v46, v45, v44
	v_fma_f32 v49, -v47, v45, v44
	v_cmp_ge_f32_e64 s[0:1], 0, v48
	v_and_b32_e32 v43, 0xffff0000, v236
	v_lshlrev_b32_e32 v34, 16, v237
	v_cndmask_b32_e64 v45, v45, v46, s[0:1]
	v_cmp_lt_f32_e64 s[0:1], 0, v49
	v_and_b32_e32 v35, 0xffff0000, v237
	s_nop 0
	v_cndmask_b32_e64 v45, v45, v47, s[0:1]
	v_mul_f32_e32 v46, 0x37800000, v45
	v_cndmask_b32_e32 v45, v45, v46, vcc
	v_cmp_class_f32_e32 vcc, v44, v145
	s_nop 1
	v_cndmask_b32_e32 v44, v45, v44, vcc
	v_div_scale_f32 v45, s[0:1], v44, v44, 1.0
	v_rcp_f32_e32 v46, v45
	v_div_scale_f32 v47, vcc, 1.0, v44, 1.0
	v_fma_f32 v48, -v45, v46, 1.0
	v_fmac_f32_e32 v46, v48, v46
	v_mul_f32_e32 v48, v47, v46
	v_fma_f32 v49, -v45, v48, v47
	v_fmac_f32_e32 v48, v49, v46
	v_fma_f32 v45, -v45, v48, v47
	v_div_fmas_f32 v45, v45, v46, v48
	v_div_fixup_f32 v44, v45, v44, 1.0
	v_pk_mul_f32 v[28:29], v[28:29], v[44:45] op_sel_hi:[1,0]
	v_pk_mul_f32 v[30:31], v[30:31], v[44:45] op_sel_hi:[1,0]
	v_pk_mul_f32 v[46:47], v[24:25], v[44:45] op_sel_hi:[1,0]
	v_pk_mul_f32 v[48:49], v[26:27], v[44:45] op_sel_hi:[1,0]
	v_pk_fma_f32 v[26:27], v[126:127], v[30:31], v[32:33]
	v_pk_fma_f32 v[24:25], v[124:125], v[28:29], v[40:41]
	v_pk_fma_f32 v[30:31], v[122:123], v[48:49], v[34:35]
	v_pk_fma_f32 v[28:29], v[120:121], v[46:47], v[42:43]
	global_store_dwordx4 v[36:37], v[24:27], off
	global_store_dwordx4 v[36:37], v[28:31], off offset:16
	s_nop 0
	v_pk_mul_f32 v[20:21], v[20:21], v[44:45] op_sel_hi:[1,0]
	v_lshl_add_u64 v[28:29], s[10:11], 0, v[152:153]
	v_lshl_add_u64 v[30:31], v[28:29], 2, s[6:7]
	v_lshlrev_b64 v[28:29], 10, v[28:29]
	v_pk_mul_f32 v[22:23], v[22:23], v[44:45] op_sel_hi:[1,0]
	v_pk_mul_f32 v[38:39], v[16:17], v[44:45] op_sel_hi:[1,0]
	v_pk_mul_f32 v[40:41], v[18:19], v[44:45] op_sel_hi:[1,0]
	v_lshl_add_u64 v[28:29], v[28:29], 0, v[154:155]
	v_lshlrev_b64 v[32:33], 1, v[28:29]
	v_lshl_add_u64 v[34:35], s[4:5], 0, v[32:33]
	v_or_b32_e32 v32, 0x100, v32
	v_lshlrev_b32_e32 v16, 16, v238
	v_and_b32_e32 v17, 0xffff0000, v238
	v_lshlrev_b32_e32 v18, 16, v239
	v_and_b32_e32 v19, 0xffff0000, v239
	v_lshlrev_b32_e32 v24, 16, v240
	v_and_b32_e32 v25, 0xffff0000, v240
	v_lshlrev_b32_e32 v26, 16, v241
	v_and_b32_e32 v27, 0xffff0000, v241
	v_pk_fma_f32 v[18:19], v[118:119], v[22:23], v[18:19]
	v_pk_fma_f32 v[16:17], v[116:117], v[20:21], v[16:17]
	v_pk_fma_f32 v[22:23], v[110:111], v[40:41], v[26:27]
	v_pk_fma_f32 v[20:21], v[108:109], v[38:39], v[24:25]
	global_store_dwordx4 v[36:37], v[16:19], off offset:512
	global_store_dwordx4 v[36:37], v[20:23], off offset:528
	s_nop 0
	s_nop 0
	s_nop 0
	v_lshl_add_u64 v[20:21], v[28:29], 2, s[14:15]
	v_lshl_add_u64 v[22:23], s[4:5], 0, v[32:33]
	s_waitcnt vmcnt(6)
; DI unsigned pk_bf16(float lo, float hi) { f32x2 v = {lo, hi}; bf16x2_t b = __builtin_convertvector(v, bf16x2_t); return __builtin_bit_cast(unsigned, b); }
; DI float bflo(unsigned w) { return __uint_as_float(w << 16); }
; DI float bfhi(unsigned w) { return __uint_as_float(w & 0xffff0000u); }
;     __device__ __forceinline__ void fused(f32x4 (&acc)[2][2][4][2], const pg8::Unit& u, int wr, int wc, int fr, int fq, PG8_LAS unsigned char* lds, int wid, int lane) const {
;     ...
;                 const int rl = ai * 128 + wr * 64 + m * 16 + fr; const size_t row = (size_t)u.pm * 256 + rl;
;                 const float rm = 1.f / sqrtf(__hip_atomic_load(ssqm + row, __ATOMIC_RELAXED, __HIP_MEMORY_SCOPE_AGENT) * (1.f / DM) + RMS_EPS);
;                 float sh = 0.f;
; #pragma unroll
;                 for (int bj = 0; bj < 2; ++bj) {
;                     const size_t off = row * DM + colb + bj * 128;
;                     f32x4 h0, h1;
;                     if (IN16) { const u32x4 hw = *(const u32x4*)((const bf16_t*)hin + off); h0 = (f32x4){bflo(hw.x), bfhi(hw.x), bflo(hw.y), bfhi(hw.y)}; h1 = (f32x4){bflo(hw.z), bfhi(hw.z), bflo(hw.w), bfhi(hw.w)}; }
;                     else { h0 = *(const f32x4*)((const float*)hin + off); h1 = *(const f32x4*)((const float*)hin + off + 4); }
;                     h0 = h0 + acc[ai][bj][m][0] * rm * gv[bj][0]; h1 = h1 + acc[ai][bj][m][1] * rm * gv[bj][1];
;                     sh += ((h0[0] * h0[0] + h0[1] * h0[1]) + (h0[2] * h0[2] + h0[3] * h0[3])) + ((h1[0] * h1[0] + h1[1] * h1[1]) + (h1[2] * h1[2] + h1[3] * h1[3]));
;                     if (OUT16) { u32x4 w; w.x = pk_bf16(h0[0], h0[1]); w.y = pk_bf16(h0[2], h0[3]); w.z = pk_bf16(h1[0], h1[1]); w.w = pk_bf16(h1[2], h1[3]); *(u32x4*)((bf16_t*)hout + off) = w; }
;                     else { *(f32x4*)((float*)hout + off) = h0; *(f32x4*)((float*)hout + off + 4) = h1; }
;                 }
;                 if (ssqh) { sh += __shfl_xor(sh, 16); sh += __shfl_xor(sh, 32); if (fq == 0) red[rl * 4 + wc] = sh; }
;             }
;         if (ssqh) { __syncthreads(); if (tid < 256) atomicAdd(ssqh + u.pm * 256 + tid, (red[tid * 4] + red[tid * 4 + 1]) + (red[tid * 4 + 2] + red[tid * 4 + 3])); }
;         __syncthreads();
	v_fmac_f32_e32 v147, 0x3a800000, v253
	v_mul_f32_e32 v26, 0x4f800000, v147
	v_cmp_gt_f32_e32 vcc, s2, v147
	v_lshlrev_b32_e32 v24, 16, v242
	v_and_b32_e32 v25, 0xffff0000, v242
	v_cndmask_b32_e32 v28, v147, v26, vcc
	v_sqrt_f32_e32 v29, v28
	v_lshlrev_b32_e32 v16, 16, v243
	v_and_b32_e32 v17, 0xffff0000, v243
	v_lshlrev_b32_e32 v26, 16, v244
	v_add_u32_e32 v30, -1, v29
	v_add_u32_e32 v31, 1, v29
	v_fma_f32 v32, -v30, v29, v28
	v_fma_f32 v33, -v31, v29, v28
	v_cmp_ge_f32_e64 s[0:1], 0, v32
	v_and_b32_e32 v27, 0xffff0000, v244
	v_lshlrev_b32_e32 v18, 16, v245
	v_cndmask_b32_e64 v29, v29, v30, s[0:1]
	v_cmp_lt_f32_e64 s[0:1], 0, v33
	v_and_b32_e32 v19, 0xffff0000, v245
	s_nop 0
	v_cndmask_b32_e64 v29, v29, v31, s[0:1]
	v_mul_f32_e32 v30, 0x37800000, v29
	v_cndmask_b32_e32 v29, v29, v30, vcc
	v_cmp_class_f32_e32 vcc, v28, v145
	s_nop 1
	v_cndmask_b32_e32 v28, v29, v28, vcc
	v_div_scale_f32 v29, s[0:1], v28, v28, 1.0
	v_rcp_f32_e32 v30, v29
	v_div_scale_f32 v31, vcc, 1.0, v28, 1.0
	v_fma_f32 v32, -v29, v30, 1.0
	v_fmac_f32_e32 v30, v32, v30
	v_mul_f32_e32 v32, v31, v30
	v_fma_f32 v33, -v29, v32, v31
	v_fmac_f32_e32 v32, v33, v30
	v_fma_f32 v29, -v29, v32, v31
	v_div_fmas_f32 v29, v29, v30, v32
	v_div_fixup_f32 v28, v29, v28, 1.0
	v_pk_mul_f32 v[12:13], v[12:13], v[28:29] op_sel_hi:[1,0]
	v_pk_mul_f32 v[14:15], v[14:15], v[28:29] op_sel_hi:[1,0]
	v_pk_mul_f32 v[30:31], v[8:9], v[28:29] op_sel_hi:[1,0]
	v_pk_mul_f32 v[32:33], v[10:11], v[28:29] op_sel_hi:[1,0]
	v_pk_fma_f32 v[10:11], v[126:127], v[14:15], v[16:17]
	v_pk_fma_f32 v[8:9], v[124:125], v[12:13], v[24:25]
	v_pk_fma_f32 v[14:15], v[122:123], v[32:33], v[18:19]
	v_pk_fma_f32 v[12:13], v[120:121], v[30:31], v[26:27]
	global_store_dwordx4 v[20:21], v[8:11], off
	global_store_dwordx4 v[20:21], v[12:15], off offset:16
	s_nop 0
	v_pk_mul_f32 v[4:5], v[4:5], v[28:29] op_sel_hi:[1,0]
	v_pk_mul_f32 v[6:7], v[6:7], v[28:29] op_sel_hi:[1,0]
	v_pk_mul_f32 v[12:13], v[0:1], v[28:29] op_sel_hi:[1,0]
	v_pk_mul_f32 v[14:15], v[2:3], v[28:29] op_sel_hi:[1,0]
	v_lshlrev_b32_e32 v0, 16, v246
	v_and_b32_e32 v1, 0xffff0000, v246
	v_lshlrev_b32_e32 v2, 16, v247
	v_and_b32_e32 v3, 0xffff0000, v247
	v_lshlrev_b32_e32 v8, 16, v248
	v_and_b32_e32 v9, 0xffff0000, v248
	v_lshlrev_b32_e32 v10, 16, v249
	v_and_b32_e32 v11, 0xffff0000, v249
	v_pk_fma_f32 v[2:3], v[118:119], v[6:7], v[2:3]
	v_pk_fma_f32 v[0:1], v[116:117], v[4:5], v[0:1]
	v_pk_fma_f32 v[6:7], v[110:111], v[14:15], v[10:11]
	v_pk_fma_f32 v[4:5], v[108:109], v[12:13], v[8:9]
	global_store_dwordx4 v[20:21], v[0:3], off offset:512
	global_store_dwordx4 v[20:21], v[4:7], off offset:528
	s_barrier

; DI unsigned pk_bf16(float lo, float hi) { f32x2 v = {lo, hi}; bf16x2_t b = __builtin_convertvector(v, bf16x2_t); return __builtin_bit_cast(unsigned, b); }
; DI float bflo(unsigned w) { return __uint_as_float(w << 16); }
; DI float bfhi(unsigned w) { return __uint_as_float(w & 0xffff0000u); }
;     __device__ __forceinline__ void fused(f32x4 (&acc)[2][2][4][2], const pg8::Unit& u, int wr, int wc, int fr, int fq, PG8_LAS unsigned char* lds, int wid, int lane) const {
;     ...
;         const int colb = u.pn * 256 + wc * 32 + 8 * fq;
;         f32x4 gv[2][2];
; #pragma unroll
;         for (int bj = 0; bj < 2; ++bj)
; #pragma unroll
;             for (int n = 0; n < 2; ++n) gv[bj][n] = *(const f32x4*)(gA + colb + bj * 128 + 4 * n);
; #pragma unroll
;         for (int ai = 0; ai < 2; ++ai)
; #pragma unroll
;             for (int m = 0; m < 4; ++m) {
;                 const int rl = ai * 128 + wr * 64 + m * 16 + fr; const size_t row = (size_t)u.pm * 256 + rl;
;                 const float rm = 1.f / sqrtf(__hip_atomic_load(ssqm + row, __ATOMIC_RELAXED, __HIP_MEMORY_SCOPE_AGENT) * (1.f / DM) + RMS_EPS);
;                 float sh = 0.f;
; #pragma unroll
;                 for (int bj = 0; bj < 2; ++bj) {
;                     const size_t off = row * DM + colb + bj * 128;
;                     f32x4 h0, h1;
;                     if (IN16) { const u32x4 hw = *(const u32x4*)((const bf16_t*)hin + off); h0 = (f32x4){bflo(hw.x), bfhi(hw.x), bflo(hw.y), bfhi(hw.y)}; h1 = (f32x4){bflo(hw.z), bfhi(hw.z), bflo(hw.w), bfhi(hw.w)}; }
;                     else { h0 = *(const f32x4*)((const float*)hin + off); h1 = *(const f32x4*)((const float*)hin + off + 4); }
;                     h0 = h0 + acc[ai][bj][m][0] * rm * gv[bj][0]; h1 = h1 + acc[ai][bj][m][1] * rm * gv[bj][1];
;                     sh += ((h0[0] * h0[0] + h0[1] * h0[1]) + (h0[2] * h0[2] + h0[3] * h0[3])) + ((h1[0] * h1[0] + h1[1] * h1[1]) + (h1[2] * h1[2] + h1[3] * h1[3]));
;                     if (OUT16) { u32x4 w; w.x = pk_bf16(h0[0], h0[1]); w.y = pk_bf16(h0[2], h0[3]); w.z = pk_bf16(h1[0], h1[1]); w.w = pk_bf16(h1[2], h1[3]); *(u32x4*)((bf16_t*)hout + off) = w; }
;                     else { *(f32x4*)((float*)hout + off) = h0; *(f32x4*)((float*)hout + off + 4) = h1; }
.LBB0_1666:
	s_or_b64 exec, exec, s[0:1]
	s_lshl_b32 s0, s26, 5
	s_lshl_b32 s1, s22, 8
	s_or_b32 s0, s1, s0
	v_or_b32_e32 v144, s0, v156
	s_lshl_b64 s[2:3], s[2:3], 8
	v_mov_b32_e32 v153, 0
	v_ashrrev_i32_e32 v145, 31, v144
	v_lshl_add_u64 v[146:147], s[2:3], 0, v[152:153]
	v_lshl_add_u64 v[116:117], v[144:145], 2, s[8:9]
	v_lshl_add_u64 v[148:149], v[146:147], 2, s[6:7]
	s_barrier
	global_load_dwordx4 v[120:123], v[116:117], off offset:16
	global_load_dwordx4 v[124:127], v[116:117], off
	global_load_dwordx4 v[112:115], v[116:117], off offset:528
	s_nop 0
	global_load_dwordx4 v[116:119], v[116:117], off offset:512
	v_lshlrev_b64 v[146:147], 10, v[146:147]
	v_or_b32_e32 v254, 0, v152
	v_mov_b32_e32 v255, 0
	v_lshl_add_u64 v[254:255], s[2:3], 0, v[254:255]
	v_lshlrev_b64 v[240:241], 10, v[254:255]
	v_lshl_add_u64 v[240:241], v[240:241], 0, v[144:145]
	v_lshlrev_b64 v[240:241], 1, v[240:241]
	v_lshl_add_u64 v[240:241], s[4:5], 0, v[240:241]
	v_lshl_add_u64 v[254:255], v[254:255], 2, s[6:7]
	global_load_dword v252, v[254:255], off sc1
	global_load_dwordx4 v[234:237], v[240:241], off
	global_load_dwordx4 v[238:241], v[240:241], off offset:256
	v_or_b32_e32 v254, 16, v152
	v_mov_b32_e32 v255, 0
	v_lshl_add_u64 v[254:255], s[2:3], 0, v[254:255]
	v_lshlrev_b64 v[248:249], 10, v[254:255]
	v_lshl_add_u64 v[248:249], v[248:249], 0, v[144:145]
	v_lshlrev_b64 v[248:249], 1, v[248:249]
	v_lshl_add_u64 v[248:249], s[4:5], 0, v[248:249]
	v_lshl_add_u64 v[254:255], v[254:255], 2, s[6:7]
	global_load_dword v253, v[254:255], off sc1
	global_load_dwordx4 v[242:245], v[248:249], off
	global_load_dwordx4 v[246:249], v[248:249], off offset:256
	s_nop 0
	v_lshl_add_u64 v[154:155], v[146:147], 0, v[144:145]
	v_lshlrev_b64 v[156:157], 1, v[154:155]
	v_lshl_add_u64 v[146:147], s[4:5], 0, v[156:157]
	s_nop 0
	v_mov_b32_e32 v147, 0x358637bd
	s_mov_b32 s8, 0xf800000
	v_mov_b32_e32 v146, 0x260
	v_readlane_b32 s12, v251, 0
	v_readlane_b32 s14, v251, 2
	v_readlane_b32 s15, v251, 3
	s_mov_b64 s[10:11], s[14:15]
	v_lshl_add_u64 v[154:155], v[154:155], 2, s[10:11]
	v_or_b32_e32 v156, 0x100, v156
	v_lshl_add_u64 v[156:157], s[4:5], 0, v[156:157]
	v_readlane_b32 s13, v251, 1
	s_waitcnt vmcnt(3)
	v_fmamk_f32 v158, v252, 0x3a800000, v147
	v_mul_f32_e32 v159, 0x4f800000, v158
	v_cmp_gt_f32_e32 vcc, s8, v158
	v_lshlrev_b32_e32 v160, 16, v236
	v_cndmask_b32_e32 v162, v158, v159, vcc
	v_sqrt_f32_e32 v163, v162
	v_lshlrev_b32_e32 v158, 16, v234
	v_and_b32_e32 v159, 0xffff0000, v234
	v_lshlrev_b32_e32 v148, 16, v235
	v_add_u32_e32 v164, -1, v163
	v_add_u32_e32 v165, 1, v163
	v_fma_f32 v166, -v164, v163, v162
	v_fma_f32 v167, -v165, v163, v162
	v_cmp_ge_f32_e64 s[0:1], 0, v166
	v_and_b32_e32 v149, 0xffff0000, v235
	v_and_b32_e32 v161, 0xffff0000, v236
	v_cndmask_b32_e64 v163, v163, v164, s[0:1]
	v_cmp_lt_f32_e64 s[0:1], 0, v167
	v_lshlrev_b32_e32 v150, 16, v237
	v_and_b32_e32 v151, 0xffff0000, v237
	v_cndmask_b32_e64 v163, v163, v165, s[0:1]
	v_mul_f32_e32 v164, 0x37800000, v163
	v_cndmask_b32_e32 v163, v163, v164, vcc
	v_cmp_class_f32_e32 vcc, v162, v146
	s_nop 1
	v_cndmask_b32_e32 v162, v163, v162, vcc
	v_div_scale_f32 v163, s[0:1], v162, v162, 1.0
	v_rcp_f32_e32 v164, v163
	v_div_scale_f32 v165, vcc, 1.0, v162, 1.0
	v_fma_f32 v166, -v163, v164, 1.0
	v_fmac_f32_e32 v164, v166, v164
	v_mul_f32_e32 v166, v165, v164
	v_fma_f32 v167, -v163, v166, v165
	v_fmac_f32_e32 v166, v167, v164
	v_fma_f32 v163, -v163, v166, v165
	v_div_fmas_f32 v163, v163, v164, v166
	v_div_fixup_f32 v162, v163, v162, 1.0
	v_pk_mul_f32 v[140:141], v[140:141], v[162:163] op_sel_hi:[1,0]
	v_pk_mul_f32 v[142:143], v[142:143], v[162:163] op_sel_hi:[1,0]
	v_pk_mul_f32 v[164:165], v[136:137], v[162:163] op_sel_hi:[1,0]
	v_pk_mul_f32 v[166:167], v[138:139], v[162:163] op_sel_hi:[1,0]
	v_pk_fma_f32 v[138:139], v[126:127], v[142:143], v[148:149]
	v_pk_fma_f32 v[136:137], v[124:125], v[140:141], v[158:159]
	v_pk_fma_f32 v[142:143], v[122:123], v[166:167], v[150:151]
	v_pk_fma_f32 v[140:141], v[120:121], v[164:165], v[160:161]
	global_store_dwordx4 v[154:155], v[136:139], off
	global_store_dwordx4 v[154:155], v[140:143], off offset:16
	s_nop 0
	v_pk_mul_f32 v[132:133], v[132:133], v[162:163] op_sel_hi:[1,0]
	v_or_b32_e32 v140, 16, v152
	v_mov_b32_e32 v141, v153
	v_lshl_add_u64 v[140:141], s[2:3], 0, v[140:141]
	v_lshl_add_u64 v[142:143], v[140:141], 2, s[6:7]
	v_lshlrev_b64 v[140:141], 10, v[140:141]
	v_pk_mul_f32 v[134:135], v[134:135], v[162:163] op_sel_hi:[1,0]
	v_pk_mul_f32 v[156:157], v[128:129], v[162:163] op_sel_hi:[1,0]
	v_pk_mul_f32 v[158:159], v[130:131], v[162:163] op_sel_hi:[1,0]
	v_lshl_add_u64 v[140:141], v[140:141], 0, v[144:145]
	v_lshlrev_b64 v[148:149], 1, v[140:141]
	v_lshl_add_u64 v[150:151], s[4:5], 0, v[148:149]
	v_or_b32_e32 v148, 0x100, v148
	v_lshlrev_b32_e32 v128, 16, v238
	v_and_b32_e32 v129, 0xffff0000, v238
	v_lshlrev_b32_e32 v130, 16, v239
	v_and_b32_e32 v131, 0xffff0000, v239
	v_lshlrev_b32_e32 v136, 16, v240
	v_and_b32_e32 v137, 0xffff0000, v240
	v_lshlrev_b32_e32 v138, 16, v241
	v_and_b32_e32 v139, 0xffff0000, v241
	v_or_b32_e32 v254, 32, v152
	v_mov_b32_e32 v255, 0
	v_lshl_add_u64 v[254:255], s[2:3], 0, v[254:255]
	v_lshlrev_b64 v[240:241], 10, v[254:255]
	v_lshl_add_u64 v[240:241], v[240:241], 0, v[144:145]
	v_lshlrev_b64 v[240:241], 1, v[240:241]
	v_lshl_add_u64 v[240:241], s[4:5], 0, v[240:241]
	v_lshl_add_u64 v[254:255], v[254:255], 2, s[6:7]
	global_load_dword v252, v[254:255], off sc1
	global_load_dwordx4 v[234:237], v[240:241], off
	global_load_dwordx4 v[238:241], v[240:241], off offset:256
	v_pk_fma_f32 v[130:131], v[118:119], v[134:135], v[130:131]
	v_pk_fma_f32 v[128:129], v[116:117], v[132:133], v[128:129]
	v_pk_fma_f32 v[134:135], v[114:115], v[158:159], v[138:139]
	v_pk_fma_f32 v[132:133], v[112:113], v[156:157], v[136:137]
	global_store_dwordx4 v[154:155], v[128:131], off offset:512
	global_store_dwordx4 v[154:155], v[132:135], off offset:528
	s_nop 0
	s_nop 0
	s_nop 0
	v_lshl_add_u64 v[132:133], v[140:141], 2, s[10:11]
	v_lshl_add_u64 v[134:135], s[4:5], 0, v[148:149]
	s_waitcnt vmcnt(7)
; DI unsigned pk_bf16(float lo, float hi) { f32x2 v = {lo, hi}; bf16x2_t b = __builtin_convertvector(v, bf16x2_t); return __builtin_bit_cast(unsigned, b); }
; DI float bflo(unsigned w) { return __uint_as_float(w << 16); }
; DI float bfhi(unsigned w) { return __uint_as_float(w & 0xffff0000u); }
;     __device__ __forceinline__ void fused(f32x4 (&acc)[2][2][4][2], const pg8::Unit& u, int wr, int wc, int fr, int fq, PG8_LAS unsigned char* lds, int wid, int lane) const {
;     ...
;                 const int rl = ai * 128 + wr * 64 + m * 16 + fr; const size_t row = (size_t)u.pm * 256 + rl;
;                 const float rm = 1.f / sqrtf(__hip_atomic_load(ssqm + row, __ATOMIC_RELAXED, __HIP_MEMORY_SCOPE_AGENT) * (1.f / DM) + RMS_EPS);
;                 float sh = 0.f;
; #pragma unroll
;                 for (int bj = 0; bj < 2; ++bj) {
;                     const size_t off = row * DM + colb + bj * 128;
;                     f32x4 h0, h1;
;                     if (IN16) { const u32x4 hw = *(const u32x4*)((const bf16_t*)hin + off); h0 = (f32x4){bflo(hw.x), bfhi(hw.x), bflo(hw.y), bfhi(hw.y)}; h1 = (f32x4){bflo(hw.z), bfhi(hw.z), bflo(hw.w), bfhi(hw.w)}; }
;                     else { h0 = *(const f32x4*)((const float*)hin + off); h1 = *(const f32x4*)((const float*)hin + off + 4); }
;                     h0 = h0 + acc[ai][bj][m][0] * rm * gv[bj][0]; h1 = h1 + acc[ai][bj][m][1] * rm * gv[bj][1];
;                     sh += ((h0[0] * h0[0] + h0[1] * h0[1]) + (h0[2] * h0[2] + h0[3] * h0[3])) + ((h1[0] * h1[0] + h1[1] * h1[1]) + (h1[2] * h1[2] + h1[3] * h1[3]));
;                     if (OUT16) { u32x4 w; w.x = pk_bf16(h0[0], h0[1]); w.y = pk_bf16(h0[2], h0[3]); w.z = pk_bf16(h1[0], h1[1]); w.w = pk_bf16(h1[2], h1[3]); *(u32x4*)((bf16_t*)hout + off) = w; }
;                     else { *(f32x4*)((float*)hout + off) = h0; *(f32x4*)((float*)hout + off + 4) = h1; }
	v_fmamk_f32 v138, v253, 0x3a800000, v147
	v_mul_f32_e32 v139, 0x4f800000, v138
	v_cmp_gt_f32_e32 vcc, s8, v138
	v_lshlrev_b32_e32 v136, 16, v242
	v_and_b32_e32 v137, 0xffff0000, v242
	v_cndmask_b32_e32 v140, v138, v139, vcc
	v_sqrt_f32_e32 v141, v140
	v_lshlrev_b32_e32 v128, 16, v243
	v_and_b32_e32 v129, 0xffff0000, v243
	v_lshlrev_b32_e32 v138, 16, v244
	v_add_u32_e32 v142, -1, v141
	v_add_u32_e32 v143, 1, v141
	v_fma_f32 v148, -v142, v141, v140
	v_fma_f32 v149, -v143, v141, v140
	v_cmp_ge_f32_e64 s[0:1], 0, v148
	v_and_b32_e32 v139, 0xffff0000, v244
	v_lshlrev_b32_e32 v130, 16, v245
	v_cndmask_b32_e64 v141, v141, v142, s[0:1]
	v_cmp_lt_f32_e64 s[0:1], 0, v149
	v_and_b32_e32 v131, 0xffff0000, v245
	s_nop 0
	v_cndmask_b32_e64 v141, v141, v143, s[0:1]
	v_mul_f32_e32 v142, 0x37800000, v141
	v_cndmask_b32_e32 v141, v141, v142, vcc
	v_cmp_class_f32_e32 vcc, v140, v146
	s_nop 1
	v_cndmask_b32_e32 v140, v141, v140, vcc
	v_div_scale_f32 v141, s[0:1], v140, v140, 1.0
	v_rcp_f32_e32 v142, v141
	v_div_scale_f32 v143, vcc, 1.0, v140, 1.0
	v_fma_f32 v148, -v141, v142, 1.0
	v_fmac_f32_e32 v142, v148, v142
	v_mul_f32_e32 v148, v143, v142
	v_fma_f32 v149, -v141, v148, v143
	v_fmac_f32_e32 v148, v149, v142
	v_fma_f32 v141, -v141, v148, v143
	v_div_fmas_f32 v141, v141, v142, v148
	v_div_fixup_f32 v140, v141, v140, 1.0
	v_pk_mul_f32 v[108:109], v[108:109], v[140:141] op_sel_hi:[1,0]
	v_pk_mul_f32 v[110:111], v[110:111], v[140:141] op_sel_hi:[1,0]
	v_pk_mul_f32 v[142:143], v[104:105], v[140:141] op_sel_hi:[1,0]
	v_pk_mul_f32 v[148:149], v[106:107], v[140:141] op_sel_hi:[1,0]
	v_pk_fma_f32 v[106:107], v[126:127], v[110:111], v[128:129]
	v_pk_fma_f32 v[104:105], v[124:125], v[108:109], v[136:137]
	v_pk_fma_f32 v[110:111], v[122:123], v[148:149], v[130:131]
	v_pk_fma_f32 v[108:109], v[120:121], v[142:143], v[138:139]
	global_store_dwordx4 v[132:133], v[104:107], off
	global_store_dwordx4 v[132:133], v[108:111], off offset:16
	s_nop 0
	v_pk_mul_f32 v[100:101], v[100:101], v[140:141] op_sel_hi:[1,0]
	v_or_b32_e32 v108, 32, v152
	v_mov_b32_e32 v109, v153
	v_lshl_add_u64 v[108:109], s[2:3], 0, v[108:109]
	v_lshl_add_u64 v[110:111], v[108:109], 2, s[6:7]
	v_lshlrev_b64 v[108:109], 10, v[108:109]
	v_pk_mul_f32 v[102:103], v[102:103], v[140:141] op_sel_hi:[1,0]
	v_pk_mul_f32 v[134:135], v[96:97], v[140:141] op_sel_hi:[1,0]
	v_pk_mul_f32 v[136:137], v[98:99], v[140:141] op_sel_hi:[1,0]
	v_lshl_add_u64 v[108:109], v[108:109], 0, v[144:145]
	v_lshlrev_b64 v[128:129], 1, v[108:109]
	v_lshl_add_u64 v[130:131], s[4:5], 0, v[128:129]
	v_or_b32_e32 v128, 0x100, v128
	v_lshlrev_b32_e32 v96, 16, v246
	v_and_b32_e32 v97, 0xffff0000, v246
	v_lshlrev_b32_e32 v98, 16, v247
	v_and_b32_e32 v99, 0xffff0000, v247
	v_lshlrev_b32_e32 v104, 16, v248
	v_and_b32_e32 v105, 0xffff0000, v248
	v_lshlrev_b32_e32 v106, 16, v249
	v_and_b32_e32 v107, 0xffff0000, v249
	v_or_b32_e32 v254, 48, v152
	v_mov_b32_e32 v255, 0
	v_lshl_add_u64 v[254:255], s[2:3], 0, v[254:255]
	v_lshlrev_b64 v[248:249], 10, v[254:255]
	v_lshl_add_u64 v[248:249], v[248:249], 0, v[144:145]
	v_lshlrev_b64 v[248:249], 1, v[248:249]
	v_lshl_add_u64 v[248:249], s[4:5], 0, v[248:249]
	v_lshl_add_u64 v[254:255], v[254:255], 2, s[6:7]
	global_load_dword v253, v[254:255], off sc1
	global_load_dwordx4 v[242:245], v[248:249], off
	global_load_dwordx4 v[246:249], v[248:249], off offset:256
	v_pk_fma_f32 v[98:99], v[118:119], v[102:103], v[98:99]
	v_pk_fma_f32 v[96:97], v[116:117], v[100:101], v[96:97]
	v_pk_fma_f32 v[102:103], v[114:115], v[136:137], v[106:107]
	v_pk_fma_f32 v[100:101], v[112:113], v[134:135], v[104:105]
	global_store_dwordx4 v[132:133], v[96:99], off offset:512
	global_store_dwordx4 v[132:133], v[100:103], off offset:528
	s_nop 0
	s_nop 0
	s_nop 0
	v_lshl_add_u64 v[100:101], v[108:109], 2, s[10:11]
	v_lshl_add_u64 v[102:103], s[4:5], 0, v[128:129]
	s_waitcnt vmcnt(9)
	v_fmamk_f32 v106, v252, 0x3a800000, v147
	v_mul_f32_e32 v107, 0x4f800000, v106
	v_cmp_gt_f32_e32 vcc, s8, v106
	v_lshlrev_b32_e32 v104, 16, v234
	v_and_b32_e32 v105, 0xffff0000, v234
	v_cndmask_b32_e32 v108, v106, v107, vcc
	v_sqrt_f32_e32 v109, v108
	v_lshlrev_b32_e32 v96, 16, v235
	v_and_b32_e32 v97, 0xffff0000, v235
	v_lshlrev_b32_e32 v106, 16, v236
	v_add_u32_e32 v110, -1, v109
	v_add_u32_e32 v111, 1, v109
	v_fma_f32 v128, -v110, v109, v108
	v_fma_f32 v129, -v111, v109, v108
	v_cmp_ge_f32_e64 s[0:1], 0, v128
	v_and_b32_e32 v107, 0xffff0000, v236
	v_lshlrev_b32_e32 v98, 16, v237
	v_cndmask_b32_e64 v109, v109, v110, s[0:1]
	v_cmp_lt_f32_e64 s[0:1], 0, v129
	v_and_b32_e32 v99, 0xffff0000, v237
	s_nop 0
	v_cndmask_b32_e64 v109, v109, v111, s[0:1]
	v_mul_f32_e32 v110, 0x37800000, v109
	v_cndmask_b32_e32 v109, v109, v110, vcc
	v_cmp_class_f32_e32 vcc, v108, v146
	s_nop 1
	v_cndmask_b32_e32 v108, v109, v108, vcc
	v_div_scale_f32 v109, s[0:1], v108, v108, 1.0
	v_rcp_f32_e32 v110, v109
	v_div_scale_f32 v111, vcc, 1.0, v108, 1.0
	v_fma_f32 v128, -v109, v110, 1.0
	v_fmac_f32_e32 v110, v128, v110
	v_mul_f32_e32 v128, v111, v110
	v_fma_f32 v129, -v109, v128, v111
	v_fmac_f32_e32 v128, v129, v110
	v_fma_f32 v109, -v109, v128, v111
	v_div_fmas_f32 v109, v109, v110, v128
	v_div_fixup_f32 v108, v109, v108, 1.0
	v_pk_mul_f32 v[92:93], v[92:93], v[108:109] op_sel_hi:[1,0]
	v_pk_mul_f32 v[94:95], v[94:95], v[108:109] op_sel_hi:[1,0]
	v_pk_mul_f32 v[110:111], v[88:89], v[108:109] op_sel_hi:[1,0]
	v_pk_mul_f32 v[128:129], v[90:91], v[108:109] op_sel_hi:[1,0]
	v_pk_fma_f32 v[90:91], v[126:127], v[94:95], v[96:97]
	v_pk_fma_f32 v[88:89], v[124:125], v[92:93], v[104:105]
	v_pk_fma_f32 v[94:95], v[122:123], v[128:129], v[98:99]
	v_pk_fma_f32 v[92:93], v[120:121], v[110:111], v[106:107]
; DI unsigned pk_bf16(float lo, float hi) { f32x2 v = {lo, hi}; bf16x2_t b = __builtin_convertvector(v, bf16x2_t); return __builtin_bit_cast(unsigned, b); }
; DI float bflo(unsigned w) { return __uint_as_float(w << 16); }
; DI float bfhi(unsigned w) { return __uint_as_float(w & 0xffff0000u); }
;     __device__ __forceinline__ void fused(f32x4 (&acc)[2][2][4][2], const pg8::Unit& u, int wr, int wc, int fr, int fq, PG8_LAS unsigned char* lds, int wid, int lane) const {
;     ...
;                 const int rl = ai * 128 + wr * 64 + m * 16 + fr; const size_t row = (size_t)u.pm * 256 + rl;
;                 const float rm = 1.f / sqrtf(__hip_atomic_load(ssqm + row, __ATOMIC_RELAXED, __HIP_MEMORY_SCOPE_AGENT) * (1.f / DM) + RMS_EPS);
;                 float sh = 0.f;
; #pragma unroll
;                 for (int bj = 0; bj < 2; ++bj) {
;                     const size_t off = row * DM + colb + bj * 128;
;                     f32x4 h0, h1;
;                     if (IN16) { const u32x4 hw = *(const u32x4*)((const bf16_t*)hin + off); h0 = (f32x4){bflo(hw.x), bfhi(hw.x), bflo(hw.y), bfhi(hw.y)}; h1 = (f32x4){bflo(hw.z), bfhi(hw.z), bflo(hw.w), bfhi(hw.w)}; }
;                     else { h0 = *(const f32x4*)((const float*)hin + off); h1 = *(const f32x4*)((const float*)hin + off + 4); }
;                     h0 = h0 + acc[ai][bj][m][0] * rm * gv[bj][0]; h1 = h1 + acc[ai][bj][m][1] * rm * gv[bj][1];
;                     sh += ((h0[0] * h0[0] + h0[1] * h0[1]) + (h0[2] * h0[2] + h0[3] * h0[3])) + ((h1[0] * h1[0] + h1[1] * h1[1]) + (h1[2] * h1[2] + h1[3] * h1[3]));
;                     if (OUT16) { u32x4 w; w.x = pk_bf16(h0[0], h0[1]); w.y = pk_bf16(h0[2], h0[3]); w.z = pk_bf16(h1[0], h1[1]); w.w = pk_bf16(h1[2], h1[3]); *(u32x4*)((bf16_t*)hout + off) = w; }
;                     else { *(f32x4*)((float*)hout + off) = h0; *(f32x4*)((float*)hout + off + 4) = h1; }
	global_store_dwordx4 v[100:101], v[88:91], off
	global_store_dwordx4 v[100:101], v[92:95], off offset:16
	s_nop 0
	v_pk_mul_f32 v[84:85], v[84:85], v[108:109] op_sel_hi:[1,0]
	v_or_b32_e32 v92, 48, v152
	v_mov_b32_e32 v93, v153
	v_lshl_add_u64 v[92:93], s[2:3], 0, v[92:93]
	v_lshl_add_u64 v[94:95], v[92:93], 2, s[6:7]
	v_lshlrev_b64 v[92:93], 10, v[92:93]
	v_pk_mul_f32 v[86:87], v[86:87], v[108:109] op_sel_hi:[1,0]
	v_pk_mul_f32 v[102:103], v[80:81], v[108:109] op_sel_hi:[1,0]
	v_pk_mul_f32 v[104:105], v[82:83], v[108:109] op_sel_hi:[1,0]
	v_lshl_add_u64 v[92:93], v[92:93], 0, v[144:145]
	v_lshlrev_b64 v[96:97], 1, v[92:93]
	v_lshl_add_u64 v[98:99], s[4:5], 0, v[96:97]
	v_or_b32_e32 v96, 0x100, v96
	v_lshlrev_b32_e32 v80, 16, v238
	v_and_b32_e32 v81, 0xffff0000, v238
	v_lshlrev_b32_e32 v82, 16, v239
	v_and_b32_e32 v83, 0xffff0000, v239
	v_lshlrev_b32_e32 v88, 16, v240
	v_and_b32_e32 v89, 0xffff0000, v240
	v_lshlrev_b32_e32 v90, 16, v241
	v_and_b32_e32 v91, 0xffff0000, v241
	v_or_b32_e32 v254, 128, v152
	v_mov_b32_e32 v255, 0
	v_lshl_add_u64 v[254:255], s[2:3], 0, v[254:255]
	v_lshlrev_b64 v[240:241], 10, v[254:255]
	v_lshl_add_u64 v[240:241], v[240:241], 0, v[144:145]
	v_lshlrev_b64 v[240:241], 1, v[240:241]
	v_lshl_add_u64 v[240:241], s[4:5], 0, v[240:241]
	v_lshl_add_u64 v[254:255], v[254:255], 2, s[6:7]
	global_load_dword v252, v[254:255], off sc1
	global_load_dwordx4 v[234:237], v[240:241], off
	global_load_dwordx4 v[238:241], v[240:241], off offset:256
	v_pk_fma_f32 v[82:83], v[118:119], v[86:87], v[82:83]
	v_pk_fma_f32 v[80:81], v[116:117], v[84:85], v[80:81]
	v_pk_fma_f32 v[86:87], v[114:115], v[104:105], v[90:91]
	v_pk_fma_f32 v[84:85], v[112:113], v[102:103], v[88:89]
	global_store_dwordx4 v[100:101], v[80:83], off offset:512
	global_store_dwordx4 v[100:101], v[84:87], off offset:528
	s_nop 0
	s_nop 0
	s_nop 0
	v_lshl_add_u64 v[84:85], v[92:93], 2, s[10:11]
	v_lshl_add_u64 v[86:87], s[4:5], 0, v[96:97]
	s_waitcnt vmcnt(9)
	v_fmamk_f32 v90, v253, 0x3a800000, v147
	v_mul_f32_e32 v91, 0x4f800000, v90
	v_cmp_gt_f32_e32 vcc, s8, v90
	v_lshlrev_b32_e32 v88, 16, v242
	v_and_b32_e32 v89, 0xffff0000, v242
	v_cndmask_b32_e32 v92, v90, v91, vcc
	v_sqrt_f32_e32 v93, v92
	v_lshlrev_b32_e32 v80, 16, v243
	v_and_b32_e32 v81, 0xffff0000, v243
	v_lshlrev_b32_e32 v90, 16, v244
	v_add_u32_e32 v94, -1, v93
	v_add_u32_e32 v95, 1, v93
	v_fma_f32 v96, -v94, v93, v92
	v_fma_f32 v97, -v95, v93, v92
	v_cmp_ge_f32_e64 s[0:1], 0, v96
	v_and_b32_e32 v91, 0xffff0000, v244
	v_lshlrev_b32_e32 v82, 16, v245
	v_cndmask_b32_e64 v93, v93, v94, s[0:1]
	v_cmp_lt_f32_e64 s[0:1], 0, v97
	v_and_b32_e32 v83, 0xffff0000, v245
	s_nop 0
	v_cndmask_b32_e64 v93, v93, v95, s[0:1]
	v_mul_f32_e32 v94, 0x37800000, v93
	v_cndmask_b32_e32 v93, v93, v94, vcc
	v_cmp_class_f32_e32 vcc, v92, v146
	s_nop 1
	v_cndmask_b32_e32 v92, v93, v92, vcc
	v_div_scale_f32 v93, s[0:1], v92, v92, 1.0
	v_rcp_f32_e32 v94, v93
	v_div_scale_f32 v95, vcc, 1.0, v92, 1.0
	v_fma_f32 v96, -v93, v94, 1.0
	v_fmac_f32_e32 v94, v96, v94
	v_mul_f32_e32 v96, v95, v94
	v_fma_f32 v97, -v93, v96, v95
	v_fmac_f32_e32 v96, v97, v94
	v_fma_f32 v93, -v93, v96, v95
	v_div_fmas_f32 v93, v93, v94, v96
	v_div_fixup_f32 v92, v93, v92, 1.0
	v_pk_mul_f32 v[76:77], v[76:77], v[92:93] op_sel_hi:[1,0]
	v_pk_mul_f32 v[78:79], v[78:79], v[92:93] op_sel_hi:[1,0]
	v_pk_mul_f32 v[94:95], v[72:73], v[92:93] op_sel_hi:[1,0]
	v_pk_mul_f32 v[96:97], v[74:75], v[92:93] op_sel_hi:[1,0]
	v_pk_fma_f32 v[74:75], v[126:127], v[78:79], v[80:81]
	v_pk_fma_f32 v[72:73], v[124:125], v[76:77], v[88:89]
	v_pk_fma_f32 v[78:79], v[122:123], v[96:97], v[82:83]
	v_pk_fma_f32 v[76:77], v[120:121], v[94:95], v[90:91]
	global_store_dwordx4 v[84:85], v[72:75], off
	global_store_dwordx4 v[84:85], v[76:79], off offset:16
	s_nop 0
	v_pk_mul_f32 v[68:69], v[68:69], v[92:93] op_sel_hi:[1,0]
	v_add_u32_e32 v76, 0x80, v152
	v_mov_b32_e32 v77, v153
	v_lshl_add_u64 v[76:77], s[2:3], 0, v[76:77]
	v_lshl_add_u64 v[78:79], v[76:77], 2, s[6:7]
	v_lshlrev_b64 v[76:77], 10, v[76:77]
	v_pk_mul_f32 v[70:71], v[70:71], v[92:93] op_sel_hi:[1,0]
	v_pk_mul_f32 v[86:87], v[64:65], v[92:93] op_sel_hi:[1,0]
	v_pk_mul_f32 v[88:89], v[66:67], v[92:93] op_sel_hi:[1,0]
	v_lshl_add_u64 v[76:77], v[76:77], 0, v[144:145]
	v_lshlrev_b64 v[80:81], 1, v[76:77]
	v_lshl_add_u64 v[82:83], s[4:5], 0, v[80:81]
	v_or_b32_e32 v80, 0x100, v80
	v_lshlrev_b32_e32 v64, 16, v246
	v_and_b32_e32 v65, 0xffff0000, v246
	v_lshlrev_b32_e32 v66, 16, v247
	v_and_b32_e32 v67, 0xffff0000, v247
	v_lshlrev_b32_e32 v72, 16, v248
	v_and_b32_e32 v73, 0xffff0000, v248
	v_lshlrev_b32_e32 v74, 16, v249
	v_and_b32_e32 v75, 0xffff0000, v249
	v_or_b32_e32 v254, 144, v152
	v_mov_b32_e32 v255, 0
	v_lshl_add_u64 v[254:255], s[2:3], 0, v[254:255]
	v_lshlrev_b64 v[248:249], 10, v[254:255]
	v_lshl_add_u64 v[248:249], v[248:249], 0, v[144:145]
	v_lshlrev_b64 v[248:249], 1, v[248:249]
	v_lshl_add_u64 v[248:249], s[4:5], 0, v[248:249]
	v_lshl_add_u64 v[254:255], v[254:255], 2, s[6:7]
	global_load_dword v253, v[254:255], off sc1
	global_load_dwordx4 v[242:245], v[248:249], off
	global_load_dwordx4 v[246:249], v[248:249], off offset:256
	v_pk_fma_f32 v[66:67], v[118:119], v[70:71], v[66:67]
	v_pk_fma_f32 v[64:65], v[116:117], v[68:69], v[64:65]
	v_pk_fma_f32 v[70:71], v[114:115], v[88:89], v[74:75]
	v_pk_fma_f32 v[68:69], v[112:113], v[86:87], v[72:73]
	global_store_dwordx4 v[84:85], v[64:67], off offset:512
	global_store_dwordx4 v[84:85], v[68:71], off offset:528
	s_nop 0
	s_nop 0
	s_nop 0
	v_lshl_add_u64 v[68:69], v[76:77], 2, s[10:11]
	v_lshl_add_u64 v[70:71], s[4:5], 0, v[80:81]
	s_waitcnt vmcnt(9)
; DI unsigned pk_bf16(float lo, float hi) { f32x2 v = {lo, hi}; bf16x2_t b = __builtin_convertvector(v, bf16x2_t); return __builtin_bit_cast(unsigned, b); }
; DI float bflo(unsigned w) { return __uint_as_float(w << 16); }
; DI float bfhi(unsigned w) { return __uint_as_float(w & 0xffff0000u); }
;     __device__ __forceinline__ void fused(f32x4 (&acc)[2][2][4][2], const pg8::Unit& u, int wr, int wc, int fr, int fq, PG8_LAS unsigned char* lds, int wid, int lane) const {
;     ...
;                 const int rl = ai * 128 + wr * 64 + m * 16 + fr; const size_t row = (size_t)u.pm * 256 + rl;
;                 const float rm = 1.f / sqrtf(__hip_atomic_load(ssqm + row, __ATOMIC_RELAXED, __HIP_MEMORY_SCOPE_AGENT) * (1.f / DM) + RMS_EPS);
;                 float sh = 0.f;
; #pragma unroll
;                 for (int bj = 0; bj < 2; ++bj) {
;                     const size_t off = row * DM + colb + bj * 128;
;                     f32x4 h0, h1;
;                     if (IN16) { const u32x4 hw = *(const u32x4*)((const bf16_t*)hin + off); h0 = (f32x4){bflo(hw.x), bfhi(hw.x), bflo(hw.y), bfhi(hw.y)}; h1 = (f32x4){bflo(hw.z), bfhi(hw.z), bflo(hw.w), bfhi(hw.w)}; }
;                     else { h0 = *(const f32x4*)((const float*)hin + off); h1 = *(const f32x4*)((const float*)hin + off + 4); }
;                     h0 = h0 + acc[ai][bj][m][0] * rm * gv[bj][0]; h1 = h1 + acc[ai][bj][m][1] * rm * gv[bj][1];
;                     sh += ((h0[0] * h0[0] + h0[1] * h0[1]) + (h0[2] * h0[2] + h0[3] * h0[3])) + ((h1[0] * h1[0] + h1[1] * h1[1]) + (h1[2] * h1[2] + h1[3] * h1[3]));
;                     if (OUT16) { u32x4 w; w.x = pk_bf16(h0[0], h0[1]); w.y = pk_bf16(h0[2], h0[3]); w.z = pk_bf16(h1[0], h1[1]); w.w = pk_bf16(h1[2], h1[3]); *(u32x4*)((bf16_t*)hout + off) = w; }
;                     else { *(f32x4*)((float*)hout + off) = h0; *(f32x4*)((float*)hout + off + 4) = h1; }
	v_fmamk_f32 v74, v252, 0x3a800000, v147
	v_mul_f32_e32 v75, 0x4f800000, v74
	v_cmp_gt_f32_e32 vcc, s8, v74
	v_lshlrev_b32_e32 v72, 16, v234
	v_and_b32_e32 v73, 0xffff0000, v234
	v_cndmask_b32_e32 v76, v74, v75, vcc
	v_sqrt_f32_e32 v77, v76
	v_lshlrev_b32_e32 v64, 16, v235
	v_and_b32_e32 v65, 0xffff0000, v235
	v_lshlrev_b32_e32 v74, 16, v236
	v_add_u32_e32 v78, -1, v77
	v_add_u32_e32 v79, 1, v77
	v_fma_f32 v80, -v78, v77, v76
	v_fma_f32 v81, -v79, v77, v76
	v_cmp_ge_f32_e64 s[0:1], 0, v80
	v_and_b32_e32 v75, 0xffff0000, v236
	v_lshlrev_b32_e32 v66, 16, v237
	v_cndmask_b32_e64 v77, v77, v78, s[0:1]
	v_cmp_lt_f32_e64 s[0:1], 0, v81
	v_and_b32_e32 v67, 0xffff0000, v237
	s_nop 0
	v_cndmask_b32_e64 v77, v77, v79, s[0:1]
	v_mul_f32_e32 v78, 0x37800000, v77
	v_cndmask_b32_e32 v77, v77, v78, vcc
	v_cmp_class_f32_e32 vcc, v76, v146
	s_nop 1
	v_cndmask_b32_e32 v76, v77, v76, vcc
	v_div_scale_f32 v77, s[0:1], v76, v76, 1.0
	v_rcp_f32_e32 v78, v77
	v_div_scale_f32 v79, vcc, 1.0, v76, 1.0
	v_fma_f32 v80, -v77, v78, 1.0
	v_fmac_f32_e32 v78, v80, v78
	v_mul_f32_e32 v80, v79, v78
	v_fma_f32 v81, -v77, v80, v79
	v_fmac_f32_e32 v80, v81, v78
	v_fma_f32 v77, -v77, v80, v79
	v_div_fmas_f32 v77, v77, v78, v80
	v_div_fixup_f32 v76, v77, v76, 1.0
	v_pk_mul_f32 v[60:61], v[60:61], v[76:77] op_sel_hi:[1,0]
	v_pk_mul_f32 v[62:63], v[62:63], v[76:77] op_sel_hi:[1,0]
	v_pk_mul_f32 v[78:79], v[56:57], v[76:77] op_sel_hi:[1,0]
	v_pk_mul_f32 v[80:81], v[58:59], v[76:77] op_sel_hi:[1,0]
	v_pk_fma_f32 v[58:59], v[126:127], v[62:63], v[64:65]
	v_pk_fma_f32 v[56:57], v[124:125], v[60:61], v[72:73]
	v_pk_fma_f32 v[62:63], v[122:123], v[80:81], v[66:67]
	v_pk_fma_f32 v[60:61], v[120:121], v[78:79], v[74:75]
	global_store_dwordx4 v[68:69], v[56:59], off
	global_store_dwordx4 v[68:69], v[60:63], off offset:16
	s_nop 0
	v_pk_mul_f32 v[52:53], v[52:53], v[76:77] op_sel_hi:[1,0]
	v_add_u32_e32 v60, 0x90, v152
	v_mov_b32_e32 v61, v153
	v_lshl_add_u64 v[60:61], s[2:3], 0, v[60:61]
	v_lshl_add_u64 v[62:63], v[60:61], 2, s[6:7]
	v_lshlrev_b64 v[60:61], 10, v[60:61]
	v_pk_mul_f32 v[54:55], v[54:55], v[76:77] op_sel_hi:[1,0]
	v_pk_mul_f32 v[70:71], v[48:49], v[76:77] op_sel_hi:[1,0]
	v_pk_mul_f32 v[72:73], v[50:51], v[76:77] op_sel_hi:[1,0]
	v_lshl_add_u64 v[60:61], v[60:61], 0, v[144:145]
	v_lshlrev_b64 v[64:65], 1, v[60:61]
	v_lshl_add_u64 v[66:67], s[4:5], 0, v[64:65]
	v_or_b32_e32 v64, 0x100, v64
	v_lshlrev_b32_e32 v48, 16, v238
	v_and_b32_e32 v49, 0xffff0000, v238
	v_lshlrev_b32_e32 v50, 16, v239
	v_and_b32_e32 v51, 0xffff0000, v239
	v_lshlrev_b32_e32 v56, 16, v240
	v_and_b32_e32 v57, 0xffff0000, v240
	v_lshlrev_b32_e32 v58, 16, v241
	v_and_b32_e32 v59, 0xffff0000, v241
	v_or_b32_e32 v254, 160, v152
	v_mov_b32_e32 v255, 0
	v_lshl_add_u64 v[254:255], s[2:3], 0, v[254:255]
	v_lshlrev_b64 v[240:241], 10, v[254:255]
	v_lshl_add_u64 v[240:241], v[240:241], 0, v[144:145]
	v_lshlrev_b64 v[240:241], 1, v[240:241]
	v_lshl_add_u64 v[240:241], s[4:5], 0, v[240:241]
	v_lshl_add_u64 v[254:255], v[254:255], 2, s[6:7]
	global_load_dword v252, v[254:255], off sc1
	global_load_dwordx4 v[234:237], v[240:241], off
	global_load_dwordx4 v[238:241], v[240:241], off offset:256
	v_pk_fma_f32 v[50:51], v[118:119], v[54:55], v[50:51]
	v_pk_fma_f32 v[48:49], v[116:117], v[52:53], v[48:49]
	v_pk_fma_f32 v[54:55], v[114:115], v[72:73], v[58:59]
	v_pk_fma_f32 v[52:53], v[112:113], v[70:71], v[56:57]
	global_store_dwordx4 v[68:69], v[48:51], off offset:512
	global_store_dwordx4 v[68:69], v[52:55], off offset:528
	s_nop 0
	s_nop 0
	s_nop 0
	v_lshl_add_u64 v[52:53], v[60:61], 2, s[10:11]
	v_lshl_add_u64 v[54:55], s[4:5], 0, v[64:65]
	s_waitcnt vmcnt(9)
	v_fmamk_f32 v58, v253, 0x3a800000, v147
	v_mul_f32_e32 v59, 0x4f800000, v58
	v_cmp_gt_f32_e32 vcc, s8, v58
	v_lshlrev_b32_e32 v56, 16, v242
	v_and_b32_e32 v57, 0xffff0000, v242
	v_cndmask_b32_e32 v60, v58, v59, vcc
	v_sqrt_f32_e32 v61, v60
	v_lshlrev_b32_e32 v48, 16, v243
	v_and_b32_e32 v49, 0xffff0000, v243
	v_lshlrev_b32_e32 v58, 16, v244
	v_add_u32_e32 v62, -1, v61
	v_add_u32_e32 v63, 1, v61
	v_fma_f32 v64, -v62, v61, v60
	v_fma_f32 v65, -v63, v61, v60
	v_cmp_ge_f32_e64 s[0:1], 0, v64
	v_and_b32_e32 v59, 0xffff0000, v244
	v_lshlrev_b32_e32 v50, 16, v245
	v_cndmask_b32_e64 v61, v61, v62, s[0:1]
	v_cmp_lt_f32_e64 s[0:1], 0, v65
	v_and_b32_e32 v51, 0xffff0000, v245
	s_nop 0
	v_cndmask_b32_e64 v61, v61, v63, s[0:1]
	v_mul_f32_e32 v62, 0x37800000, v61
	v_cndmask_b32_e32 v61, v61, v62, vcc
	v_cmp_class_f32_e32 vcc, v60, v146
	s_nop 1
	v_cndmask_b32_e32 v60, v61, v60, vcc
	v_div_scale_f32 v61, s[0:1], v60, v60, 1.0
	v_rcp_f32_e32 v62, v61
	v_div_scale_f32 v63, vcc, 1.0, v60, 1.0
	v_fma_f32 v64, -v61, v62, 1.0
	v_fmac_f32_e32 v62, v64, v62
	v_mul_f32_e32 v64, v63, v62
	v_fma_f32 v65, -v61, v64, v63
	v_fmac_f32_e32 v64, v65, v62
	v_fma_f32 v61, -v61, v64, v63
	v_div_fmas_f32 v61, v61, v62, v64
	v_div_fixup_f32 v60, v61, v60, 1.0
	v_pk_mul_f32 v[44:45], v[44:45], v[60:61] op_sel_hi:[1,0]
	v_pk_mul_f32 v[46:47], v[46:47], v[60:61] op_sel_hi:[1,0]
	v_pk_mul_f32 v[62:63], v[40:41], v[60:61] op_sel_hi:[1,0]
	v_pk_mul_f32 v[64:65], v[42:43], v[60:61] op_sel_hi:[1,0]
	v_pk_fma_f32 v[42:43], v[126:127], v[46:47], v[48:49]
	v_pk_fma_f32 v[40:41], v[124:125], v[44:45], v[56:57]
	v_pk_fma_f32 v[46:47], v[122:123], v[64:65], v[50:51]
	v_pk_fma_f32 v[44:45], v[120:121], v[62:63], v[58:59]
	global_store_dwordx4 v[52:53], v[40:43], off
	global_store_dwordx4 v[52:53], v[44:47], off offset:16
	s_nop 0
	v_pk_mul_f32 v[36:37], v[36:37], v[60:61] op_sel_hi:[1,0]
	v_add_u32_e32 v44, 0xa0, v152
	v_mov_b32_e32 v45, v153
	v_lshl_add_u64 v[44:45], s[2:3], 0, v[44:45]
; DI unsigned pk_bf16(float lo, float hi) { f32x2 v = {lo, hi}; bf16x2_t b = __builtin_convertvector(v, bf16x2_t); return __builtin_bit_cast(unsigned, b); }
; DI float bflo(unsigned w) { return __uint_as_float(w << 16); }
; DI float bfhi(unsigned w) { return __uint_as_float(w & 0xffff0000u); }
;     __device__ __forceinline__ void fused(f32x4 (&acc)[2][2][4][2], const pg8::Unit& u, int wr, int wc, int fr, int fq, PG8_LAS unsigned char* lds, int wid, int lane) const {
;     ...
;                 const int rl = ai * 128 + wr * 64 + m * 16 + fr; const size_t row = (size_t)u.pm * 256 + rl;
;                 const float rm = 1.f / sqrtf(__hip_atomic_load(ssqm + row, __ATOMIC_RELAXED, __HIP_MEMORY_SCOPE_AGENT) * (1.f / DM) + RMS_EPS);
;                 float sh = 0.f;
; #pragma unroll
;                 for (int bj = 0; bj < 2; ++bj) {
;                     const size_t off = row * DM + colb + bj * 128;
;                     f32x4 h0, h1;
;                     if (IN16) { const u32x4 hw = *(const u32x4*)((const bf16_t*)hin + off); h0 = (f32x4){bflo(hw.x), bfhi(hw.x), bflo(hw.y), bfhi(hw.y)}; h1 = (f32x4){bflo(hw.z), bfhi(hw.z), bflo(hw.w), bfhi(hw.w)}; }
;                     else { h0 = *(const f32x4*)((const float*)hin + off); h1 = *(const f32x4*)((const float*)hin + off + 4); }
;                     h0 = h0 + acc[ai][bj][m][0] * rm * gv[bj][0]; h1 = h1 + acc[ai][bj][m][1] * rm * gv[bj][1];
;                     sh += ((h0[0] * h0[0] + h0[1] * h0[1]) + (h0[2] * h0[2] + h0[3] * h0[3])) + ((h1[0] * h1[0] + h1[1] * h1[1]) + (h1[2] * h1[2] + h1[3] * h1[3]));
;                     if (OUT16) { u32x4 w; w.x = pk_bf16(h0[0], h0[1]); w.y = pk_bf16(h0[2], h0[3]); w.z = pk_bf16(h1[0], h1[1]); w.w = pk_bf16(h1[2], h1[3]); *(u32x4*)((bf16_t*)hout + off) = w; }
;                     else { *(f32x4*)((float*)hout + off) = h0; *(f32x4*)((float*)hout + off + 4) = h1; }
	v_lshl_add_u64 v[46:47], v[44:45], 2, s[6:7]
	v_lshlrev_b64 v[44:45], 10, v[44:45]
	v_pk_mul_f32 v[38:39], v[38:39], v[60:61] op_sel_hi:[1,0]
	v_pk_mul_f32 v[54:55], v[32:33], v[60:61] op_sel_hi:[1,0]
	v_pk_mul_f32 v[56:57], v[34:35], v[60:61] op_sel_hi:[1,0]
	v_lshl_add_u64 v[44:45], v[44:45], 0, v[144:145]
	v_lshlrev_b64 v[48:49], 1, v[44:45]
	v_lshl_add_u64 v[50:51], s[4:5], 0, v[48:49]
	v_or_b32_e32 v48, 0x100, v48
	v_add_u32_e32 v152, 0xb0, v152
	v_lshlrev_b32_e32 v32, 16, v246
	v_and_b32_e32 v33, 0xffff0000, v246
	v_lshlrev_b32_e32 v34, 16, v247
	v_and_b32_e32 v35, 0xffff0000, v247
	v_lshlrev_b32_e32 v40, 16, v248
	v_and_b32_e32 v41, 0xffff0000, v248
	v_lshlrev_b32_e32 v42, 16, v249
	v_and_b32_e32 v43, 0xffff0000, v249
	v_or_b32_e32 v254, 176, v152
	v_mov_b32_e32 v255, 0
	v_lshl_add_u64 v[254:255], s[2:3], 0, v[254:255]
	v_lshlrev_b64 v[248:249], 10, v[254:255]
	v_lshl_add_u64 v[248:249], v[248:249], 0, v[144:145]
	v_lshlrev_b64 v[248:249], 1, v[248:249]
	v_lshl_add_u64 v[248:249], s[4:5], 0, v[248:249]
	v_lshl_add_u64 v[254:255], v[254:255], 2, s[6:7]
	global_load_dword v253, v[254:255], off sc1
	global_load_dwordx4 v[242:245], v[248:249], off
	global_load_dwordx4 v[246:249], v[248:249], off offset:256
	v_pk_fma_f32 v[34:35], v[118:119], v[38:39], v[34:35]
	v_pk_fma_f32 v[32:33], v[116:117], v[36:37], v[32:33]
	v_pk_fma_f32 v[38:39], v[114:115], v[56:57], v[42:43]
	v_pk_fma_f32 v[36:37], v[112:113], v[54:55], v[40:41]
	global_store_dwordx4 v[52:53], v[32:35], off offset:512
	global_store_dwordx4 v[52:53], v[36:39], off offset:528
	s_nop 0
	s_nop 0
	s_nop 0
	v_lshl_add_u64 v[36:37], v[44:45], 2, s[10:11]
	v_lshl_add_u64 v[38:39], s[4:5], 0, v[48:49]
	s_waitcnt vmcnt(9)
	v_fmamk_f32 v42, v252, 0x3a800000, v147
	v_mul_f32_e32 v43, 0x4f800000, v42
	v_cmp_gt_f32_e32 vcc, s8, v42
	v_lshlrev_b32_e32 v40, 16, v234
	v_and_b32_e32 v41, 0xffff0000, v234
	v_cndmask_b32_e32 v44, v42, v43, vcc
	v_sqrt_f32_e32 v45, v44
	v_lshlrev_b32_e32 v32, 16, v235
	v_and_b32_e32 v33, 0xffff0000, v235
	v_lshlrev_b32_e32 v42, 16, v236
	v_add_u32_e32 v46, -1, v45
	v_add_u32_e32 v47, 1, v45
	v_fma_f32 v48, -v46, v45, v44
	v_fma_f32 v49, -v47, v45, v44
	v_cmp_ge_f32_e64 s[0:1], 0, v48
	v_and_b32_e32 v43, 0xffff0000, v236
	v_lshlrev_b32_e32 v34, 16, v237
	v_cndmask_b32_e64 v45, v45, v46, s[0:1]
	v_cmp_lt_f32_e64 s[0:1], 0, v49
	v_and_b32_e32 v35, 0xffff0000, v237
	s_nop 0
	v_cndmask_b32_e64 v45, v45, v47, s[0:1]
	v_mul_f32_e32 v46, 0x37800000, v45
	v_cndmask_b32_e32 v45, v45, v46, vcc
	v_cmp_class_f32_e32 vcc, v44, v146
	s_nop 1
	v_cndmask_b32_e32 v44, v45, v44, vcc
	v_div_scale_f32 v45, s[0:1], v44, v44, 1.0
	v_rcp_f32_e32 v46, v45
	v_div_scale_f32 v47, vcc, 1.0, v44, 1.0
	v_fma_f32 v48, -v45, v46, 1.0
	v_fmac_f32_e32 v46, v48, v46
	v_mul_f32_e32 v48, v47, v46
	v_fma_f32 v49, -v45, v48, v47
	v_fmac_f32_e32 v48, v49, v46
	v_fma_f32 v45, -v45, v48, v47
	v_div_fmas_f32 v45, v45, v46, v48
	v_div_fixup_f32 v44, v45, v44, 1.0
	v_pk_mul_f32 v[28:29], v[28:29], v[44:45] op_sel_hi:[1,0]
	v_pk_mul_f32 v[30:31], v[30:31], v[44:45] op_sel_hi:[1,0]
	v_pk_mul_f32 v[46:47], v[24:25], v[44:45] op_sel_hi:[1,0]
	v_pk_mul_f32 v[48:49], v[26:27], v[44:45] op_sel_hi:[1,0]
	v_pk_fma_f32 v[26:27], v[126:127], v[30:31], v[32:33]
	v_pk_fma_f32 v[24:25], v[124:125], v[28:29], v[40:41]
	v_pk_fma_f32 v[30:31], v[122:123], v[48:49], v[34:35]
	v_pk_fma_f32 v[28:29], v[120:121], v[46:47], v[42:43]
	global_store_dwordx4 v[36:37], v[24:27], off
	global_store_dwordx4 v[36:37], v[28:31], off offset:16
	s_nop 0
	v_pk_mul_f32 v[20:21], v[20:21], v[44:45] op_sel_hi:[1,0]
	v_lshl_add_u64 v[28:29], s[2:3], 0, v[152:153]
	v_lshl_add_u64 v[30:31], v[28:29], 2, s[6:7]
	v_lshlrev_b64 v[28:29], 10, v[28:29]
	v_pk_mul_f32 v[22:23], v[22:23], v[44:45] op_sel_hi:[1,0]
	v_pk_mul_f32 v[38:39], v[16:17], v[44:45] op_sel_hi:[1,0]
	v_pk_mul_f32 v[40:41], v[18:19], v[44:45] op_sel_hi:[1,0]
	v_lshl_add_u64 v[28:29], v[28:29], 0, v[144:145]
	v_lshlrev_b64 v[32:33], 1, v[28:29]
	v_lshl_add_u64 v[34:35], s[4:5], 0, v[32:33]
	v_or_b32_e32 v32, 0x100, v32
	v_lshlrev_b32_e32 v16, 16, v238
	v_and_b32_e32 v17, 0xffff0000, v238
	v_lshlrev_b32_e32 v18, 16, v239
	v_and_b32_e32 v19, 0xffff0000, v239
	v_lshlrev_b32_e32 v24, 16, v240
	v_and_b32_e32 v25, 0xffff0000, v240
	v_lshlrev_b32_e32 v26, 16, v241
	v_and_b32_e32 v27, 0xffff0000, v241
	v_pk_fma_f32 v[18:19], v[118:119], v[22:23], v[18:19]
	v_pk_fma_f32 v[16:17], v[116:117], v[20:21], v[16:17]
	v_pk_fma_f32 v[22:23], v[114:115], v[40:41], v[26:27]
	v_pk_fma_f32 v[20:21], v[112:113], v[38:39], v[24:25]
	global_store_dwordx4 v[36:37], v[16:19], off offset:512
	global_store_dwordx4 v[36:37], v[20:23], off offset:528
	s_nop 0
	s_nop 0
	s_nop 0
	v_lshl_add_u64 v[20:21], v[28:29], 2, s[10:11]
	v_lshl_add_u64 v[22:23], s[4:5], 0, v[32:33]
	s_waitcnt vmcnt(6)
; DI unsigned pk_bf16(float lo, float hi) { f32x2 v = {lo, hi}; bf16x2_t b = __builtin_convertvector(v, bf16x2_t); return __builtin_bit_cast(unsigned, b); }
; DI float bflo(unsigned w) { return __uint_as_float(w << 16); }
; DI float bfhi(unsigned w) { return __uint_as_float(w & 0xffff0000u); }
;     __device__ __forceinline__ void fused(f32x4 (&acc)[2][2][4][2], const pg8::Unit& u, int wr, int wc, int fr, int fq, PG8_LAS unsigned char* lds, int wid, int lane) const {
;     ...
;                 const int rl = ai * 128 + wr * 64 + m * 16 + fr; const size_t row = (size_t)u.pm * 256 + rl;
;                 const float rm = 1.f / sqrtf(__hip_atomic_load(ssqm + row, __ATOMIC_RELAXED, __HIP_MEMORY_SCOPE_AGENT) * (1.f / DM) + RMS_EPS);
;                 float sh = 0.f;
; #pragma unroll
;                 for (int bj = 0; bj < 2; ++bj) {
;                     const size_t off = row * DM + colb + bj * 128;
;                     f32x4 h0, h1;
;                     if (IN16) { const u32x4 hw = *(const u32x4*)((const bf16_t*)hin + off); h0 = (f32x4){bflo(hw.x), bfhi(hw.x), bflo(hw.y), bfhi(hw.y)}; h1 = (f32x4){bflo(hw.z), bfhi(hw.z), bflo(hw.w), bfhi(hw.w)}; }
;                     else { h0 = *(const f32x4*)((const float*)hin + off); h1 = *(const f32x4*)((const float*)hin + off + 4); }
;                     h0 = h0 + acc[ai][bj][m][0] * rm * gv[bj][0]; h1 = h1 + acc[ai][bj][m][1] * rm * gv[bj][1];
;                     sh += ((h0[0] * h0[0] + h0[1] * h0[1]) + (h0[2] * h0[2] + h0[3] * h0[3])) + ((h1[0] * h1[0] + h1[1] * h1[1]) + (h1[2] * h1[2] + h1[3] * h1[3]));
;                     if (OUT16) { u32x4 w; w.x = pk_bf16(h0[0], h0[1]); w.y = pk_bf16(h0[2], h0[3]); w.z = pk_bf16(h1[0], h1[1]); w.w = pk_bf16(h1[2], h1[3]); *(u32x4*)((bf16_t*)hout + off) = w; }
;                     else { *(f32x4*)((float*)hout + off) = h0; *(f32x4*)((float*)hout + off + 4) = h1; }
;                 }
;                 if (ssqh) { sh += __shfl_xor(sh, 16); sh += __shfl_xor(sh, 32); if (fq == 0) red[rl * 4 + wc] = sh; }
;             }
;         if (ssqh) { __syncthreads(); if (tid < 256) atomicAdd(ssqh + u.pm * 256 + tid, (red[tid * 4] + red[tid * 4 + 1]) + (red[tid * 4 + 2] + red[tid * 4 + 3])); }
;         __syncthreads();
	v_fmac_f32_e32 v147, 0x3a800000, v253
	v_mul_f32_e32 v26, 0x4f800000, v147
	v_cmp_gt_f32_e32 vcc, s8, v147
	v_lshlrev_b32_e32 v24, 16, v242
	v_and_b32_e32 v25, 0xffff0000, v242
	v_cndmask_b32_e32 v28, v147, v26, vcc
	v_sqrt_f32_e32 v29, v28
	v_lshlrev_b32_e32 v16, 16, v243
	v_and_b32_e32 v17, 0xffff0000, v243
	v_lshlrev_b32_e32 v26, 16, v244
	v_add_u32_e32 v30, -1, v29
	v_add_u32_e32 v31, 1, v29
	v_fma_f32 v32, -v30, v29, v28
	v_fma_f32 v33, -v31, v29, v28
	v_cmp_ge_f32_e64 s[0:1], 0, v32
	v_and_b32_e32 v27, 0xffff0000, v244
	v_lshlrev_b32_e32 v18, 16, v245
	v_cndmask_b32_e64 v29, v29, v30, s[0:1]
	v_cmp_lt_f32_e64 s[0:1], 0, v33
	v_and_b32_e32 v19, 0xffff0000, v245
	s_nop 0
	v_cndmask_b32_e64 v29, v29, v31, s[0:1]
	v_mul_f32_e32 v30, 0x37800000, v29
	v_cndmask_b32_e32 v29, v29, v30, vcc
	v_cmp_class_f32_e32 vcc, v28, v146
	s_nop 1
	v_cndmask_b32_e32 v28, v29, v28, vcc
	v_div_scale_f32 v29, s[0:1], v28, v28, 1.0
	v_rcp_f32_e32 v30, v29
	v_div_scale_f32 v31, vcc, 1.0, v28, 1.0
	v_fma_f32 v32, -v29, v30, 1.0
	v_fmac_f32_e32 v30, v32, v30
	v_mul_f32_e32 v32, v31, v30
	v_fma_f32 v33, -v29, v32, v31
	v_fmac_f32_e32 v32, v33, v30
	v_fma_f32 v29, -v29, v32, v31
	v_div_fmas_f32 v29, v29, v30, v32
	v_div_fixup_f32 v28, v29, v28, 1.0
	v_pk_mul_f32 v[12:13], v[12:13], v[28:29] op_sel_hi:[1,0]
	v_pk_mul_f32 v[14:15], v[14:15], v[28:29] op_sel_hi:[1,0]
	v_pk_mul_f32 v[30:31], v[8:9], v[28:29] op_sel_hi:[1,0]
	v_pk_mul_f32 v[32:33], v[10:11], v[28:29] op_sel_hi:[1,0]
	v_pk_fma_f32 v[10:11], v[126:127], v[14:15], v[16:17]
	v_pk_fma_f32 v[8:9], v[124:125], v[12:13], v[24:25]
	v_pk_fma_f32 v[14:15], v[122:123], v[32:33], v[18:19]
	v_pk_fma_f32 v[12:13], v[120:121], v[30:31], v[26:27]
	global_store_dwordx4 v[20:21], v[8:11], off
	global_store_dwordx4 v[20:21], v[12:15], off offset:16
	s_nop 0
	v_pk_mul_f32 v[4:5], v[4:5], v[28:29] op_sel_hi:[1,0]
	v_pk_mul_f32 v[6:7], v[6:7], v[28:29] op_sel_hi:[1,0]
	v_pk_mul_f32 v[12:13], v[0:1], v[28:29] op_sel_hi:[1,0]
	v_pk_mul_f32 v[14:15], v[2:3], v[28:29] op_sel_hi:[1,0]
	v_lshlrev_b32_e32 v0, 16, v246
	v_and_b32_e32 v1, 0xffff0000, v246
	v_lshlrev_b32_e32 v2, 16, v247
	v_and_b32_e32 v3, 0xffff0000, v247
	v_lshlrev_b32_e32 v8, 16, v248
	v_and_b32_e32 v9, 0xffff0000, v248
	v_lshlrev_b32_e32 v10, 16, v249
	v_and_b32_e32 v11, 0xffff0000, v249
	v_pk_fma_f32 v[2:3], v[118:119], v[6:7], v[2:3]
	v_pk_fma_f32 v[0:1], v[116:117], v[4:5], v[0:1]
	v_pk_fma_f32 v[6:7], v[114:115], v[14:15], v[10:11]
	v_pk_fma_f32 v[4:5], v[112:113], v[12:13], v[8:9]
	global_store_dwordx4 v[20:21], v[0:3], off offset:512
	global_store_dwordx4 v[20:21], v[4:7], off offset:528
	s_barrier
